# K-loops back-edge rotation: counter/pointer increments and exit test moved before the last barrier; on top of v44
# baseline (speedup 1.0000x reference)
; #define PG8_STAGE(bufoff, gbase, voff) do { _Pragma("unroll") for (int _i = 0; _i < 2; ++_i) \
;         __builtin_amdgcn_global_load_lds((const unsigned*)((const char*)(gbase) + (voff)[_i]), (PG8_LAS unsigned*)(lds + (bufoff) + ldsw + _i * 8192), 16, 0, 0); } while (0)
; #define PG8_LDA(dst, b, h) do { _Pragma("unroll") for (int m = 0; m < 4; ++m) _Pragma("unroll") for (int k = 0; k < 2; ++k) dst[m][k] = *(const PG8_LAS bf16x8*)(lds + PG8_SA(b, h) + aoff + m * 2048 + k * 1024); } while (0)
; #define PG8_LDB(dst, b, h) do { _Pragma("unroll") for (int n = 0; n < 2; ++n) _Pragma("unroll") for (int k = 0; k < 2; ++k) dst[n][k] = *(const PG8_LAS bf16x8*)(lds + PG8_SB(b, h) + boff + n * 2048 + k * 1024); } while (0)
; #define PG8_SCHED __builtin_amdgcn_sched_barrier(0)
; template <class Epi, class Sched, bool ALIGN_EPI = false, bool SP2 = false>
; __device__ __forceinline__ void gemm_phase(PG8_LAS unsigned char* lds, const Gemm g, const Sched& S, const Epi& E) {
;     ...
;             const bool last = (t == nt - 2);
;             const char* a1 = cA + (size_t)(t + 1) * kstep;
;             const char* a2 = last ? nA : cA + (size_t)(t + 2) * kstep; const char* b2 = last ? nB : cB + (size_t)(t + 2) * kstep;
;             const char* a3 = a2 + kstep; const char* b3 = b2 + kstep;
;             if (last && has_next) S.a_ready(nxt);
;             if constexpr (SP2) {
;             PG8_LDB(B0, 0, 0); PG8_LDB(B1, 0, 1); PG8_SCHED; PG8_LDA(At, 0, 0); PG8_STAGE(PG8_SA(1, 1), a1 + hstep, voffA);
.LBB0_66:
	ds_read_b128 v[152:155], v149
	ds_read_b128 v[156:159], v149 offset:1024
	ds_read_b128 v[160:163], v149 offset:2048
	ds_read_b128 v[164:167], v149 offset:3072
	ds_read_b128 v[168:171], v150
	ds_read_b128 v[172:175], v150 offset:1024
	ds_read_b128 v[176:179], v150 offset:2048
	ds_read_b128 v[180:183], v150 offset:3072
	s_add_u32 s42, s40, 0xfff80080
	s_addc_u32 s43, s41, -1
	s_cmp_eq_u32 s68, 28
	s_cselect_b32 s45, s35, s43
	s_cselect_b32 s44, s63, s42
	s_cselect_b32 s43, s31, s67
	s_cselect_b32 s42, s64, s65

; #define PG8_STAGE(bufoff, gbase, voff) do { _Pragma("unroll") for (int _i = 0; _i < 2; ++_i) \
;         __builtin_amdgcn_global_load_lds((const unsigned*)((const char*)(gbase) + (voff)[_i]), (PG8_LAS unsigned*)(lds + (bufoff) + ldsw + _i * 8192), 16, 0, 0); } while (0)
; #define PG8_LDA(dst, b, h) do { _Pragma("unroll") for (int m = 0; m < 4; ++m) _Pragma("unroll") for (int k = 0; k < 2; ++k) dst[m][k] = *(const PG8_LAS bf16x8*)(lds + PG8_SA(b, h) + aoff + m * 2048 + k * 1024); } while (0)
; #define PG8_LDB(dst, b, h) do { _Pragma("unroll") for (int n = 0; n < 2; ++n) _Pragma("unroll") for (int k = 0; k < 2; ++k) dst[n][k] = *(const PG8_LAS bf16x8*)(lds + PG8_SB(b, h) + boff + n * 2048 + k * 1024); } while (0)
; #define PG8_SCHED __builtin_amdgcn_sched_barrier(0)
; template <class Epi, class Sched, bool ALIGN_EPI = false, bool SP2 = false>
; __device__ __forceinline__ void gemm_phase(PG8_LAS unsigned char* lds, const Gemm g, const Sched& S, const Epi& E) {
;     ...
;             PG8_LDB(B0, 0, 0); PG8_LDB(B1, 0, 1); PG8_SCHED; PG8_LDA(At, 0, 0); PG8_STAGE(PG8_SA(1, 1), a1 + hstep, voffA);
	s_add_i32 m0, s29, 0xc000
	ds_read_b128 v[184:187], v151
	ds_read_b128 v[188:191], v151 offset:1024
	ds_read_b128 v[192:195], v151 offset:2048
	ds_read_b128 v[196:199], v151 offset:3072
	ds_read_b128 v[200:203], v151 offset:4096
	ds_read_b128 v[204:207], v151 offset:5120
	ds_read_b128 v[208:211], v151 offset:6144
	ds_read_b128 v[212:215], v151 offset:7168
	global_load_lds_dwordx4 v136, s[40:41]

; #define PG8_STAGE(bufoff, gbase, voff) do { _Pragma("unroll") for (int _i = 0; _i < 2; ++_i) \
;         __builtin_amdgcn_global_load_lds((const unsigned*)((const char*)(gbase) + (voff)[_i]), (PG8_LAS unsigned*)(lds + (bufoff) + ldsw + _i * 8192), 16, 0, 0); } while (0)
; #define PG8_LDA(dst, b, h) do { _Pragma("unroll") for (int m = 0; m < 4; ++m) _Pragma("unroll") for (int k = 0; k < 2; ++k) dst[m][k] = *(const PG8_LAS bf16x8*)(lds + PG8_SA(b, h) + aoff + m * 2048 + k * 1024); } while (0)
; #define PG8_LDB(dst, b, h) do { _Pragma("unroll") for (int n = 0; n < 2; ++n) _Pragma("unroll") for (int k = 0; k < 2; ++k) dst[n][k] = *(const PG8_LAS bf16x8*)(lds + PG8_SB(b, h) + boff + n * 2048 + k * 1024); } while (0)
; #define PG8_MMA(ai, bj, At, Bt) do { __builtin_amdgcn_s_setprio(1); _Pragma("unroll") for (int m = 0; m < 4; ++m) _Pragma("unroll") for (int n = 0; n < 2; ++n) _Pragma("unroll") for (int k = 0; k < 2; ++k) \
;         acc[ai][bj][m][n] = __builtin_amdgcn_mfma_f32_16x16x32_bf16(Bt[n][k], At[m][k], acc[ai][bj][m][n], 0, 0, 0); __builtin_amdgcn_s_setprio(0); } while (0)
; #define PG8_WAIT_V(n) asm volatile("s_waitcnt vmcnt(" #n ")" ::: "memory")
; #define PG8_WAIT_L(n) asm volatile("s_waitcnt lgkmcnt(" #n ")" ::: "memory")
; #define PG8_BAR __builtin_amdgcn_s_barrier()
; #define PG8_SCHED __builtin_amdgcn_sched_barrier(0)
; template <class Epi, class Sched, bool ALIGN_EPI = false, bool SP2 = false>
; __device__ __forceinline__ void gemm_phase(PG8_LAS unsigned char* lds, const Gemm g, const Sched& S, const Epi& E) {
;     ...
;             PG8_LDB(B0, 0, 0); PG8_LDB(B1, 0, 1); PG8_SCHED; PG8_LDA(At, 0, 0); PG8_STAGE(PG8_SA(1, 1), a1 + hstep, voffA);
;             PG8_WAIT_V(8); PG8_WAIT_L(0); PG8_BAR; PG8_MMA(0, 0, At, B0); PG8_MMA(0, 1, At, B1); PG8_BAR; PG8_SCHED;
	s_add_i32 m0, s29, 0xe000
	s_nop 0
	global_load_lds_dwordx4 v138, s[40:41]
	s_waitcnt vmcnt(8)
	s_waitcnt lgkmcnt(0)
	s_setprio 1
	s_barrier

; #define PG8_MMA(ai, bj, At, Bt) do { __builtin_amdgcn_s_setprio(1); _Pragma("unroll") for (int m = 0; m < 4; ++m) _Pragma("unroll") for (int n = 0; n < 2; ++n) _Pragma("unroll") for (int k = 0; k < 2; ++k) \
;         acc[ai][bj][m][n] = __builtin_amdgcn_mfma_f32_16x16x32_bf16(Bt[n][k], At[m][k], acc[ai][bj][m][n], 0, 0, 0); __builtin_amdgcn_s_setprio(0); } while (0)
; #define PG8_WAIT_V(n) asm volatile("s_waitcnt vmcnt(" #n ")" ::: "memory")
; #define PG8_WAIT_L(n) asm volatile("s_waitcnt lgkmcnt(" #n ")" ::: "memory")
; #define PG8_BAR __builtin_amdgcn_s_barrier()
; #define PG8_SCHED __builtin_amdgcn_sched_barrier(0)
; template <class Epi, class Sched, bool ALIGN_EPI = false, bool SP2 = false>
; __device__ __forceinline__ void gemm_phase(PG8_LAS unsigned char* lds, const Gemm g, const Sched& S, const Epi& E) {
;     ...
;             PG8_WAIT_V(8); PG8_WAIT_L(0); PG8_BAR; PG8_MMA(0, 0, At, B0); PG8_MMA(0, 1, At, B1); PG8_BAR; PG8_SCHED;
	v_mfma_f32_16x16x32_bf16 v[124:127], v[152:155], v[184:187], v[124:127]
	v_mfma_f32_16x16x32_bf16 v[120:123], v[160:163], v[184:187], v[120:123]
	v_mfma_f32_16x16x32_bf16 v[116:119], v[152:155], v[192:195], v[116:119]
	v_mfma_f32_16x16x32_bf16 v[112:115], v[160:163], v[192:195], v[112:115]
	v_mfma_f32_16x16x32_bf16 v[100:103], v[152:155], v[200:203], v[100:103]
	v_mfma_f32_16x16x32_bf16 v[96:99], v[160:163], v[200:203], v[96:99]
	v_mfma_f32_16x16x32_bf16 v[84:87], v[152:155], v[208:211], v[84:87]
	v_mfma_f32_16x16x32_bf16 v[80:83], v[160:163], v[208:211], v[80:83]
	v_mfma_f32_16x16x32_bf16 v[124:127], v[156:159], v[188:191], v[124:127]
	v_mfma_f32_16x16x32_bf16 v[120:123], v[164:167], v[188:191], v[120:123]
	v_mfma_f32_16x16x32_bf16 v[116:119], v[156:159], v[196:199], v[116:119]
	v_mfma_f32_16x16x32_bf16 v[112:115], v[164:167], v[196:199], v[112:115]
	v_mfma_f32_16x16x32_bf16 v[100:103], v[156:159], v[204:207], v[100:103]
	v_mfma_f32_16x16x32_bf16 v[96:99], v[164:167], v[204:207], v[96:99]
	v_mfma_f32_16x16x32_bf16 v[84:87], v[156:159], v[212:215], v[84:87]
	v_mfma_f32_16x16x32_bf16 v[80:83], v[164:167], v[212:215], v[80:83]


; #define PG8_MMA(ai, bj, At, Bt) do { __builtin_amdgcn_s_setprio(1); _Pragma("unroll") for (int m = 0; m < 4; ++m) _Pragma("unroll") for (int n = 0; n < 2; ++n) _Pragma("unroll") for (int k = 0; k < 2; ++k) \
;         acc[ai][bj][m][n] = __builtin_amdgcn_mfma_f32_16x16x32_bf16(Bt[n][k], At[m][k], acc[ai][bj][m][n], 0, 0, 0); __builtin_amdgcn_s_setprio(0); } while (0)
; #define PG8_WAIT_V(n) asm volatile("s_waitcnt vmcnt(" #n ")" ::: "memory")
; #define PG8_WAIT_L(n) asm volatile("s_waitcnt lgkmcnt(" #n ")" ::: "memory")
; #define PG8_BAR __builtin_amdgcn_s_barrier()
; #define PG8_SCHED __builtin_amdgcn_sched_barrier(0)
; template <class Epi, class Sched, bool ALIGN_EPI = false, bool SP2 = false>
; __device__ __forceinline__ void gemm_phase(PG8_LAS unsigned char* lds, const Gemm g, const Sched& S, const Epi& E) {
;     ...
;             PG8_WAIT_V(8); PG8_WAIT_L(0); PG8_BAR; PG8_MMA(0, 0, At, B0); PG8_MMA(0, 1, At, B1); PG8_BAR; PG8_SCHED;
	v_mfma_f32_16x16x32_bf16 v[108:111], v[168:171], v[184:187], v[108:111]
	v_mfma_f32_16x16x32_bf16 v[104:107], v[176:179], v[184:187], v[104:107]
	v_mfma_f32_16x16x32_bf16 v[92:95], v[168:171], v[192:195], v[92:95]
	v_mfma_f32_16x16x32_bf16 v[88:91], v[176:179], v[192:195], v[88:91]
	v_mfma_f32_16x16x32_bf16 v[76:79], v[168:171], v[200:203], v[76:79]
	v_mfma_f32_16x16x32_bf16 v[72:75], v[176:179], v[200:203], v[72:75]
	v_mfma_f32_16x16x32_bf16 v[68:71], v[168:171], v[208:211], v[68:71]
	v_mfma_f32_16x16x32_bf16 v[64:67], v[176:179], v[208:211], v[64:67]
	v_mfma_f32_16x16x32_bf16 v[108:111], v[172:175], v[188:191], v[108:111]
	v_mfma_f32_16x16x32_bf16 v[104:107], v[180:183], v[188:191], v[104:107]
	v_mfma_f32_16x16x32_bf16 v[92:95], v[172:175], v[196:199], v[92:95]
	v_mfma_f32_16x16x32_bf16 v[88:91], v[180:183], v[196:199], v[88:91]
	v_mfma_f32_16x16x32_bf16 v[76:79], v[172:175], v[204:207], v[76:79]
	v_mfma_f32_16x16x32_bf16 v[72:75], v[180:183], v[204:207], v[72:75]
	v_mfma_f32_16x16x32_bf16 v[68:71], v[172:175], v[212:215], v[68:71]
	v_mfma_f32_16x16x32_bf16 v[64:67], v[180:183], v[212:215], v[64:67]
	s_setprio 0
	s_barrier
	s_add_i32 s69, s59, s48
	s_mov_b64 s[96:97], s[42:43]

; #define PG8_STAGE(bufoff, gbase, voff) do { _Pragma("unroll") for (int _i = 0; _i < 2; ++_i) \
;         __builtin_amdgcn_global_load_lds((const unsigned*)((const char*)(gbase) + (voff)[_i]), (PG8_LAS unsigned*)(lds + (bufoff) + ldsw + _i * 8192), 16, 0, 0); } while (0)
; #define PG8_LDA(dst, b, h) do { _Pragma("unroll") for (int m = 0; m < 4; ++m) _Pragma("unroll") for (int k = 0; k < 2; ++k) dst[m][k] = *(const PG8_LAS bf16x8*)(lds + PG8_SA(b, h) + aoff + m * 2048 + k * 1024); } while (0)
; template <class Epi, class Sched, bool ALIGN_EPI = false, bool SP2 = false>
; __device__ __forceinline__ void gemm_phase(PG8_LAS unsigned char* lds, const Gemm g, const Sched& S, const Epi& E) {
;     ...
;             PG8_LDA(At, 0, 1); PG8_STAGE(PG8_SB(0, 0), b2, voffB); PG8_STAGE(PG8_SB(0, 1), b2 + hstep, voffB); PG8_STAGE(PG8_SA(0, 0), a2, voffA);
	s_mov_b32 m0, s69
	ds_read_b128 v[184:187], v151 offset:16384
	ds_read_b128 v[188:191], v151 offset:17408
	ds_read_b128 v[192:195], v151 offset:18432
	ds_read_b128 v[196:199], v151 offset:19456
	ds_read_b128 v[200:203], v151 offset:20480
	ds_read_b128 v[204:207], v151 offset:21504
	ds_read_b128 v[208:211], v151 offset:22528
	ds_read_b128 v[212:215], v151 offset:23552
	global_load_lds_dwordx4 v132, s[42:43]
	s_add_i32 m0, s69, 0x2000
	s_add_u32 s70, s42, 0x80000

; #define PG8_STAGE(bufoff, gbase, voff) do { _Pragma("unroll") for (int _i = 0; _i < 2; ++_i) \
;         __builtin_amdgcn_global_load_lds((const unsigned*)((const char*)(gbase) + (voff)[_i]), (PG8_LAS unsigned*)(lds + (bufoff) + ldsw + _i * 8192), 16, 0, 0); } while (0)
; #define PG8_LDA(dst, b, h) do { _Pragma("unroll") for (int m = 0; m < 4; ++m) _Pragma("unroll") for (int k = 0; k < 2; ++k) dst[m][k] = *(const PG8_LAS bf16x8*)(lds + PG8_SA(b, h) + aoff + m * 2048 + k * 1024); } while (0)
; template <class Epi, class Sched, bool ALIGN_EPI = false, bool SP2 = false>
; __device__ __forceinline__ void gemm_phase(PG8_LAS unsigned char* lds, const Gemm g, const Sched& S, const Epi& E) {
;     ...
;             PG8_LDA(At, 0, 1); PG8_STAGE(PG8_SB(0, 0), b2, voffB); PG8_STAGE(PG8_SB(0, 1), b2 + hstep, voffB); PG8_STAGE(PG8_SA(0, 0), a2, voffA);
	s_addc_u32 s71, s43, 0
	s_add_i32 s69, s60, s48
	global_load_lds_dwordx4 v128, s[42:43]

; #define PG8_STAGE(bufoff, gbase, voff) do { _Pragma("unroll") for (int _i = 0; _i < 2; ++_i) \
;         __builtin_amdgcn_global_load_lds((const unsigned*)((const char*)(gbase) + (voff)[_i]), (PG8_LAS unsigned*)(lds + (bufoff) + ldsw + _i * 8192), 16, 0, 0); } while (0)
; #define PG8_LDA(dst, b, h) do { _Pragma("unroll") for (int m = 0; m < 4; ++m) _Pragma("unroll") for (int k = 0; k < 2; ++k) dst[m][k] = *(const PG8_LAS bf16x8*)(lds + PG8_SA(b, h) + aoff + m * 2048 + k * 1024); } while (0)
; template <class Epi, class Sched, bool ALIGN_EPI = false, bool SP2 = false>
; __device__ __forceinline__ void gemm_phase(PG8_LAS unsigned char* lds, const Gemm g, const Sched& S, const Epi& E) {
;     ...
;             PG8_LDA(At, 0, 1); PG8_STAGE(PG8_SB(0, 0), b2, voffB); PG8_STAGE(PG8_SB(0, 1), b2 + hstep, voffB); PG8_STAGE(PG8_SA(0, 0), a2, voffA);
	s_mov_b32 m0, s69
	s_nop 0
	global_load_lds_dwordx4 v132, s[70:71]

; #define PG8_STAGE(bufoff, gbase, voff) do { _Pragma("unroll") for (int _i = 0; _i < 2; ++_i) \
;         __builtin_amdgcn_global_load_lds((const unsigned*)((const char*)(gbase) + (voff)[_i]), (PG8_LAS unsigned*)(lds + (bufoff) + ldsw + _i * 8192), 16, 0, 0); } while (0)
; #define PG8_LDA(dst, b, h) do { _Pragma("unroll") for (int m = 0; m < 4; ++m) _Pragma("unroll") for (int k = 0; k < 2; ++k) dst[m][k] = *(const PG8_LAS bf16x8*)(lds + PG8_SA(b, h) + aoff + m * 2048 + k * 1024); } while (0)
; template <class Epi, class Sched, bool ALIGN_EPI = false, bool SP2 = false>
; __device__ __forceinline__ void gemm_phase(PG8_LAS unsigned char* lds, const Gemm g, const Sched& S, const Epi& E) {
;     ...
;             PG8_LDA(At, 0, 1); PG8_STAGE(PG8_SB(0, 0), b2, voffB); PG8_STAGE(PG8_SB(0, 1), b2 + hstep, voffB); PG8_STAGE(PG8_SA(0, 0), a2, voffA);
	s_add_i32 m0, s69, 0x2000
	s_nop 0
	global_load_lds_dwordx4 v128, s[70:71]
	s_mov_b64 s[98:99], s[44:45]

; #define PG8_STAGE(bufoff, gbase, voff) do { _Pragma("unroll") for (int _i = 0; _i < 2; ++_i) \
;         __builtin_amdgcn_global_load_lds((const unsigned*)((const char*)(gbase) + (voff)[_i]), (PG8_LAS unsigned*)(lds + (bufoff) + ldsw + _i * 8192), 16, 0, 0); } while (0)
; #define PG8_LDA(dst, b, h) do { _Pragma("unroll") for (int m = 0; m < 4; ++m) _Pragma("unroll") for (int k = 0; k < 2; ++k) dst[m][k] = *(const PG8_LAS bf16x8*)(lds + PG8_SA(b, h) + aoff + m * 2048 + k * 1024); } while (0)
; #define PG8_MMA(ai, bj, At, Bt) do { __builtin_amdgcn_s_setprio(1); _Pragma("unroll") for (int m = 0; m < 4; ++m) _Pragma("unroll") for (int n = 0; n < 2; ++n) _Pragma("unroll") for (int k = 0; k < 2; ++k) \
;         acc[ai][bj][m][n] = __builtin_amdgcn_mfma_f32_16x16x32_bf16(Bt[n][k], At[m][k], acc[ai][bj][m][n], 0, 0, 0); __builtin_amdgcn_s_setprio(0); } while (0)
; #define PG8_WAIT_V(n) asm volatile("s_waitcnt vmcnt(" #n ")" ::: "memory")
; #define PG8_WAIT_L(n) asm volatile("s_waitcnt lgkmcnt(" #n ")" ::: "memory")
; #define PG8_BAR __builtin_amdgcn_s_barrier()
; #define PG8_SCHED __builtin_amdgcn_sched_barrier(0)
; template <class Epi, class Sched, bool ALIGN_EPI = false, bool SP2 = false>
; __device__ __forceinline__ void gemm_phase(PG8_LAS unsigned char* lds, const Gemm g, const Sched& S, const Epi& E) {
;     ...
;             PG8_LDA(At, 0, 1); PG8_STAGE(PG8_SB(0, 0), b2, voffB); PG8_STAGE(PG8_SB(0, 1), b2 + hstep, voffB); PG8_STAGE(PG8_SA(0, 0), a2, voffA);
;             PG8_WAIT_V(8); PG8_WAIT_L(0); PG8_BAR; PG8_MMA(1, 0, At, B0); PG8_MMA(1, 1, At, B1); PG8_BAR; PG8_SCHED;
	s_mov_b32 m0, s29
	s_nop 0
	global_load_lds_dwordx4 v134, s[44:45]
	s_mov_b32 m0, s51
	s_nop 0
	global_load_lds_dwordx4 v130, s[44:45]
	s_waitcnt vmcnt(8)
	s_waitcnt lgkmcnt(0)
	s_setprio 1
	s_barrier

; #define PG8_MMA(ai, bj, At, Bt) do { __builtin_amdgcn_s_setprio(1); _Pragma("unroll") for (int m = 0; m < 4; ++m) _Pragma("unroll") for (int n = 0; n < 2; ++n) _Pragma("unroll") for (int k = 0; k < 2; ++k) \
;         acc[ai][bj][m][n] = __builtin_amdgcn_mfma_f32_16x16x32_bf16(Bt[n][k], At[m][k], acc[ai][bj][m][n], 0, 0, 0); __builtin_amdgcn_s_setprio(0); } while (0)
; #define PG8_WAIT_V(n) asm volatile("s_waitcnt vmcnt(" #n ")" ::: "memory")
; #define PG8_WAIT_L(n) asm volatile("s_waitcnt lgkmcnt(" #n ")" ::: "memory")
; #define PG8_BAR __builtin_amdgcn_s_barrier()
; #define PG8_SCHED __builtin_amdgcn_sched_barrier(0)
; template <class Epi, class Sched, bool ALIGN_EPI = false, bool SP2 = false>
; __device__ __forceinline__ void gemm_phase(PG8_LAS unsigned char* lds, const Gemm g, const Sched& S, const Epi& E) {
;     ...
;             PG8_WAIT_V(8); PG8_WAIT_L(0); PG8_BAR; PG8_MMA(1, 0, At, B0); PG8_MMA(1, 1, At, B1); PG8_BAR; PG8_SCHED;
	v_mfma_f32_16x16x32_bf16 v[60:63], v[152:155], v[184:187], v[60:63]
	v_mfma_f32_16x16x32_bf16 v[56:59], v[160:163], v[184:187], v[56:59]
	v_mfma_f32_16x16x32_bf16 v[52:55], v[152:155], v[192:195], v[52:55]
	v_mfma_f32_16x16x32_bf16 v[48:51], v[160:163], v[192:195], v[48:51]
	v_mfma_f32_16x16x32_bf16 v[36:39], v[152:155], v[200:203], v[36:39]
	v_mfma_f32_16x16x32_bf16 v[32:35], v[160:163], v[200:203], v[32:35]
	v_mfma_f32_16x16x32_bf16 v[20:23], v[152:155], v[208:211], v[20:23]
	v_mfma_f32_16x16x32_bf16 v[16:19], v[160:163], v[208:211], v[16:19]
	v_mfma_f32_16x16x32_bf16 v[60:63], v[156:159], v[188:191], v[60:63]
	v_mfma_f32_16x16x32_bf16 v[56:59], v[164:167], v[188:191], v[56:59]
	v_mfma_f32_16x16x32_bf16 v[52:55], v[156:159], v[196:199], v[52:55]
	v_mfma_f32_16x16x32_bf16 v[48:51], v[164:167], v[196:199], v[48:51]
	v_mfma_f32_16x16x32_bf16 v[36:39], v[156:159], v[204:207], v[36:39]
	v_mfma_f32_16x16x32_bf16 v[32:35], v[164:167], v[204:207], v[32:35]
	v_mfma_f32_16x16x32_bf16 v[20:23], v[156:159], v[212:215], v[20:23]
	v_mfma_f32_16x16x32_bf16 v[16:19], v[164:167], v[212:215], v[16:19]


; #define PG8_STAGE(bufoff, gbase, voff) do { _Pragma("unroll") for (int _i = 0; _i < 2; ++_i) \
;         __builtin_amdgcn_global_load_lds((const unsigned*)((const char*)(gbase) + (voff)[_i]), (PG8_LAS unsigned*)(lds + (bufoff) + ldsw + _i * 8192), 16, 0, 0); } while (0)
; #define PG8_LDA(dst, b, h) do { _Pragma("unroll") for (int m = 0; m < 4; ++m) _Pragma("unroll") for (int k = 0; k < 2; ++k) dst[m][k] = *(const PG8_LAS bf16x8*)(lds + PG8_SA(b, h) + aoff + m * 2048 + k * 1024); } while (0)
; #define PG8_LDB(dst, b, h) do { _Pragma("unroll") for (int n = 0; n < 2; ++n) _Pragma("unroll") for (int k = 0; k < 2; ++k) dst[n][k] = *(const PG8_LAS bf16x8*)(lds + PG8_SB(b, h) + boff + n * 2048 + k * 1024); } while (0)
; #define PG8_MMA(ai, bj, At, Bt) do { __builtin_amdgcn_s_setprio(1); _Pragma("unroll") for (int m = 0; m < 4; ++m) _Pragma("unroll") for (int n = 0; n < 2; ++n) _Pragma("unroll") for (int k = 0; k < 2; ++k) \
;         acc[ai][bj][m][n] = __builtin_amdgcn_mfma_f32_16x16x32_bf16(Bt[n][k], At[m][k], acc[ai][bj][m][n], 0, 0, 0); __builtin_amdgcn_s_setprio(0); } while (0)
; #define PG8_WAIT_V(n) asm volatile("s_waitcnt vmcnt(" #n ")" ::: "memory")
; #define PG8_WAIT_L(n) asm volatile("s_waitcnt lgkmcnt(" #n ")" ::: "memory")
; #define PG8_BAR __builtin_amdgcn_s_barrier()
; #define PG8_SCHED __builtin_amdgcn_sched_barrier(0)
; template <class Epi, class Sched, bool ALIGN_EPI = false, bool SP2 = false>
; __device__ __forceinline__ void gemm_phase(PG8_LAS unsigned char* lds, const Gemm g, const Sched& S, const Epi& E) {
;     ...
;             PG8_WAIT_V(8); PG8_WAIT_L(0); PG8_BAR; PG8_MMA(1, 0, At, B0); PG8_MMA(1, 1, At, B1); PG8_BAR; PG8_SCHED;
;             PG8_LDB(B0, 1, 0); PG8_LDB(B1, 1, 1); PG8_SCHED; PG8_LDA(At, 1, 0); PG8_STAGE(PG8_SA(0, 1), a2 + hstep, voffA);
	v_mfma_f32_16x16x32_bf16 v[44:47], v[168:171], v[184:187], v[44:47]
	v_mfma_f32_16x16x32_bf16 v[40:43], v[176:179], v[184:187], v[40:43]
	v_mfma_f32_16x16x32_bf16 v[28:31], v[168:171], v[192:195], v[28:31]
	v_mfma_f32_16x16x32_bf16 v[24:27], v[176:179], v[192:195], v[24:27]
	v_mfma_f32_16x16x32_bf16 v[12:15], v[168:171], v[200:203], v[12:15]
	v_mfma_f32_16x16x32_bf16 v[8:11], v[176:179], v[200:203], v[8:11]
	v_mfma_f32_16x16x32_bf16 v[4:7], v[168:171], v[208:211], v[4:7]
	v_mfma_f32_16x16x32_bf16 v[0:3], v[176:179], v[208:211], v[0:3]
	v_mfma_f32_16x16x32_bf16 v[44:47], v[172:175], v[188:191], v[44:47]
	v_mfma_f32_16x16x32_bf16 v[40:43], v[180:183], v[188:191], v[40:43]
	v_mfma_f32_16x16x32_bf16 v[28:31], v[172:175], v[196:199], v[28:31]
	v_mfma_f32_16x16x32_bf16 v[24:27], v[180:183], v[196:199], v[24:27]
	v_mfma_f32_16x16x32_bf16 v[12:15], v[172:175], v[204:207], v[12:15]
	v_mfma_f32_16x16x32_bf16 v[8:11], v[180:183], v[204:207], v[8:11]
	v_mfma_f32_16x16x32_bf16 v[4:7], v[172:175], v[212:215], v[4:7]
	v_mfma_f32_16x16x32_bf16 v[0:3], v[180:183], v[212:215], v[0:3]
	s_setprio 0
	s_barrier
	s_add_i32 s69, 0, 0x18000
	s_add_i32 s70, 0, 0x1c000


; #define PG8_STAGE(bufoff, gbase, voff) do { _Pragma("unroll") for (int _i = 0; _i < 2; ++_i) \
;         __builtin_amdgcn_global_load_lds((const unsigned*)((const char*)(gbase) + (voff)[_i]), (PG8_LAS unsigned*)(lds + (bufoff) + ldsw + _i * 8192), 16, 0, 0); } while (0)
; #define PG8_LDA(dst, b, h) do { _Pragma("unroll") for (int m = 0; m < 4; ++m) _Pragma("unroll") for (int k = 0; k < 2; ++k) dst[m][k] = *(const PG8_LAS bf16x8*)(lds + PG8_SA(b, h) + aoff + m * 2048 + k * 1024); } while (0)
; #define PG8_LDB(dst, b, h) do { _Pragma("unroll") for (int n = 0; n < 2; ++n) _Pragma("unroll") for (int k = 0; k < 2; ++k) dst[n][k] = *(const PG8_LAS bf16x8*)(lds + PG8_SB(b, h) + boff + n * 2048 + k * 1024); } while (0)
; #define PG8_SCHED __builtin_amdgcn_sched_barrier(0)
; template <class Epi, class Sched, bool ALIGN_EPI = false, bool SP2 = false>
; __device__ __forceinline__ void gemm_phase(PG8_LAS unsigned char* lds, const Gemm g, const Sched& S, const Epi& E) {
;     ...
;             PG8_LDB(B0, 1, 0); PG8_LDB(B1, 1, 1); PG8_SCHED; PG8_LDA(At, 1, 0); PG8_STAGE(PG8_SA(0, 1), a2 + hstep, voffA);
	ds_read_b128 v[152:155], v254
	ds_read_b128 v[156:159], v254 offset:1024
	ds_read_b128 v[160:163], v254 offset:2048
	ds_read_b128 v[164:167], v254 offset:3072
	ds_read_b128 v[168:171], v255
	ds_read_b128 v[172:175], v255 offset:1024
	ds_read_b128 v[176:179], v255 offset:2048
	ds_read_b128 v[180:183], v255 offset:3072
	s_add_u32 s44, s44, 0x80000
	s_addc_u32 s45, s45, 0
	s_mov_b32 m0, s52

; #define PG8_STAGE(bufoff, gbase, voff) do { _Pragma("unroll") for (int _i = 0; _i < 2; ++_i) \
;         __builtin_amdgcn_global_load_lds((const unsigned*)((const char*)(gbase) + (voff)[_i]), (PG8_LAS unsigned*)(lds + (bufoff) + ldsw + _i * 8192), 16, 0, 0); } while (0)
; #define PG8_LDA(dst, b, h) do { _Pragma("unroll") for (int m = 0; m < 4; ++m) _Pragma("unroll") for (int k = 0; k < 2; ++k) dst[m][k] = *(const PG8_LAS bf16x8*)(lds + PG8_SA(b, h) + aoff + m * 2048 + k * 1024); } while (0)
; #define PG8_LDB(dst, b, h) do { _Pragma("unroll") for (int n = 0; n < 2; ++n) _Pragma("unroll") for (int k = 0; k < 2; ++k) dst[n][k] = *(const PG8_LAS bf16x8*)(lds + PG8_SB(b, h) + boff + n * 2048 + k * 1024); } while (0)
; #define PG8_SCHED __builtin_amdgcn_sched_barrier(0)
; template <class Epi, class Sched, bool ALIGN_EPI = false, bool SP2 = false>
; __device__ __forceinline__ void gemm_phase(PG8_LAS unsigned char* lds, const Gemm g, const Sched& S, const Epi& E) {
;     ...
;             PG8_LDB(B0, 1, 0); PG8_LDB(B1, 1, 1); PG8_SCHED; PG8_LDA(At, 1, 0); PG8_STAGE(PG8_SA(0, 1), a2 + hstep, voffA);
	ds_read_b128 v[184:187], v151 offset:32768
	ds_read_b128 v[188:191], v151 offset:33792
	ds_read_b128 v[192:195], v151 offset:34816
	ds_read_b128 v[196:199], v151 offset:35840
	ds_read_b128 v[200:203], v151 offset:36864
	ds_read_b128 v[204:207], v151 offset:37888
	ds_read_b128 v[208:211], v151 offset:38912
	ds_read_b128 v[212:215], v151 offset:39936
	global_load_lds_dwordx4 v134, s[44:45]

; #define PG8_STAGE(bufoff, gbase, voff) do { _Pragma("unroll") for (int _i = 0; _i < 2; ++_i) \
;         __builtin_amdgcn_global_load_lds((const unsigned*)((const char*)(gbase) + (voff)[_i]), (PG8_LAS unsigned*)(lds + (bufoff) + ldsw + _i * 8192), 16, 0, 0); } while (0)
; #define PG8_LDA(dst, b, h) do { _Pragma("unroll") for (int m = 0; m < 4; ++m) _Pragma("unroll") for (int k = 0; k < 2; ++k) dst[m][k] = *(const PG8_LAS bf16x8*)(lds + PG8_SA(b, h) + aoff + m * 2048 + k * 1024); } while (0)
; #define PG8_LDB(dst, b, h) do { _Pragma("unroll") for (int n = 0; n < 2; ++n) _Pragma("unroll") for (int k = 0; k < 2; ++k) dst[n][k] = *(const PG8_LAS bf16x8*)(lds + PG8_SB(b, h) + boff + n * 2048 + k * 1024); } while (0)
; #define PG8_MMA(ai, bj, At, Bt) do { __builtin_amdgcn_s_setprio(1); _Pragma("unroll") for (int m = 0; m < 4; ++m) _Pragma("unroll") for (int n = 0; n < 2; ++n) _Pragma("unroll") for (int k = 0; k < 2; ++k) \
;         acc[ai][bj][m][n] = __builtin_amdgcn_mfma_f32_16x16x32_bf16(Bt[n][k], At[m][k], acc[ai][bj][m][n], 0, 0, 0); __builtin_amdgcn_s_setprio(0); } while (0)
; #define PG8_WAIT_V(n) asm volatile("s_waitcnt vmcnt(" #n ")" ::: "memory")
; #define PG8_WAIT_L(n) asm volatile("s_waitcnt lgkmcnt(" #n ")" ::: "memory")
; #define PG8_BAR __builtin_amdgcn_s_barrier()
; #define PG8_SCHED __builtin_amdgcn_sched_barrier(0)
; template <class Epi, class Sched, bool ALIGN_EPI = false, bool SP2 = false>
; __device__ __forceinline__ void gemm_phase(PG8_LAS unsigned char* lds, const Gemm g, const Sched& S, const Epi& E) {
;     ...
;             PG8_LDB(B0, 1, 0); PG8_LDB(B1, 1, 1); PG8_SCHED; PG8_LDA(At, 1, 0); PG8_STAGE(PG8_SA(0, 1), a2 + hstep, voffA);
;             PG8_WAIT_V(8); PG8_WAIT_L(0); PG8_BAR; PG8_MMA(0, 0, At, B0); PG8_MMA(0, 1, At, B1); PG8_BAR; PG8_SCHED;
	s_mov_b32 m0, s53
	s_nop 0
	global_load_lds_dwordx4 v130, s[44:45]
	s_waitcnt vmcnt(8)
	s_waitcnt lgkmcnt(0)
	s_setprio 1
	s_barrier

; #define PG8_MMA(ai, bj, At, Bt) do { __builtin_amdgcn_s_setprio(1); _Pragma("unroll") for (int m = 0; m < 4; ++m) _Pragma("unroll") for (int n = 0; n < 2; ++n) _Pragma("unroll") for (int k = 0; k < 2; ++k) \
;         acc[ai][bj][m][n] = __builtin_amdgcn_mfma_f32_16x16x32_bf16(Bt[n][k], At[m][k], acc[ai][bj][m][n], 0, 0, 0); __builtin_amdgcn_s_setprio(0); } while (0)
; #define PG8_WAIT_V(n) asm volatile("s_waitcnt vmcnt(" #n ")" ::: "memory")
; #define PG8_WAIT_L(n) asm volatile("s_waitcnt lgkmcnt(" #n ")" ::: "memory")
; #define PG8_BAR __builtin_amdgcn_s_barrier()
; #define PG8_SCHED __builtin_amdgcn_sched_barrier(0)
; template <class Epi, class Sched, bool ALIGN_EPI = false, bool SP2 = false>
; __device__ __forceinline__ void gemm_phase(PG8_LAS unsigned char* lds, const Gemm g, const Sched& S, const Epi& E) {
;     ...
;             PG8_WAIT_V(8); PG8_WAIT_L(0); PG8_BAR; PG8_MMA(0, 0, At, B0); PG8_MMA(0, 1, At, B1); PG8_BAR; PG8_SCHED;
	v_mfma_f32_16x16x32_bf16 v[124:127], v[152:155], v[184:187], v[124:127]
	v_mfma_f32_16x16x32_bf16 v[120:123], v[160:163], v[184:187], v[120:123]
	v_mfma_f32_16x16x32_bf16 v[116:119], v[152:155], v[192:195], v[116:119]
	v_mfma_f32_16x16x32_bf16 v[112:115], v[160:163], v[192:195], v[112:115]
	v_mfma_f32_16x16x32_bf16 v[100:103], v[152:155], v[200:203], v[100:103]
	v_mfma_f32_16x16x32_bf16 v[96:99], v[160:163], v[200:203], v[96:99]
	v_mfma_f32_16x16x32_bf16 v[84:87], v[152:155], v[208:211], v[84:87]
	v_mfma_f32_16x16x32_bf16 v[80:83], v[160:163], v[208:211], v[80:83]
	v_mfma_f32_16x16x32_bf16 v[124:127], v[156:159], v[188:191], v[124:127]
	v_mfma_f32_16x16x32_bf16 v[120:123], v[164:167], v[188:191], v[120:123]
	v_mfma_f32_16x16x32_bf16 v[116:119], v[156:159], v[196:199], v[116:119]
	v_mfma_f32_16x16x32_bf16 v[112:115], v[164:167], v[196:199], v[112:115]
	v_mfma_f32_16x16x32_bf16 v[100:103], v[156:159], v[204:207], v[100:103]
	v_mfma_f32_16x16x32_bf16 v[96:99], v[164:167], v[204:207], v[96:99]
	v_mfma_f32_16x16x32_bf16 v[84:87], v[156:159], v[212:215], v[84:87]
	v_mfma_f32_16x16x32_bf16 v[80:83], v[164:167], v[212:215], v[80:83]


; #define PG8_STAGE(bufoff, gbase, voff) do { _Pragma("unroll") for (int _i = 0; _i < 2; ++_i) \
;         __builtin_amdgcn_global_load_lds((const unsigned*)((const char*)(gbase) + (voff)[_i]), (PG8_LAS unsigned*)(lds + (bufoff) + ldsw + _i * 8192), 16, 0, 0); } while (0)
; #define PG8_LDA(dst, b, h) do { _Pragma("unroll") for (int m = 0; m < 4; ++m) _Pragma("unroll") for (int k = 0; k < 2; ++k) dst[m][k] = *(const PG8_LAS bf16x8*)(lds + PG8_SA(b, h) + aoff + m * 2048 + k * 1024); } while (0)
; #define PG8_MMA(ai, bj, At, Bt) do { __builtin_amdgcn_s_setprio(1); _Pragma("unroll") for (int m = 0; m < 4; ++m) _Pragma("unroll") for (int n = 0; n < 2; ++n) _Pragma("unroll") for (int k = 0; k < 2; ++k) \
;         acc[ai][bj][m][n] = __builtin_amdgcn_mfma_f32_16x16x32_bf16(Bt[n][k], At[m][k], acc[ai][bj][m][n], 0, 0, 0); __builtin_amdgcn_s_setprio(0); } while (0)
; #define PG8_WAIT_V(n) asm volatile("s_waitcnt vmcnt(" #n ")" ::: "memory")
; #define PG8_WAIT_L(n) asm volatile("s_waitcnt lgkmcnt(" #n ")" ::: "memory")
; #define PG8_BAR __builtin_amdgcn_s_barrier()
; #define PG8_SCHED __builtin_amdgcn_sched_barrier(0)
; template <class Epi, class Sched, bool ALIGN_EPI = false, bool SP2 = false>
; __device__ __forceinline__ void gemm_phase(PG8_LAS unsigned char* lds, const Gemm g, const Sched& S, const Epi& E) {
;     ...
;             PG8_WAIT_V(8); PG8_WAIT_L(0); PG8_BAR; PG8_MMA(0, 0, At, B0); PG8_MMA(0, 1, At, B1); PG8_BAR; PG8_SCHED;
;             PG8_LDA(At, 1, 1); PG8_STAGE(PG8_SB(1, 0), b3, voffB); PG8_STAGE(PG8_SB(1, 1), b3 + hstep, voffB); PG8_STAGE(PG8_SA(1, 0), a3, voffA);
	v_mfma_f32_16x16x32_bf16 v[108:111], v[168:171], v[184:187], v[108:111]
	v_mfma_f32_16x16x32_bf16 v[104:107], v[176:179], v[184:187], v[104:107]
	v_mfma_f32_16x16x32_bf16 v[92:95], v[168:171], v[192:195], v[92:95]
	v_mfma_f32_16x16x32_bf16 v[88:91], v[176:179], v[192:195], v[88:91]
	v_mfma_f32_16x16x32_bf16 v[76:79], v[168:171], v[200:203], v[76:79]
	v_mfma_f32_16x16x32_bf16 v[72:75], v[176:179], v[200:203], v[72:75]
	v_mfma_f32_16x16x32_bf16 v[68:71], v[168:171], v[208:211], v[68:71]
	v_mfma_f32_16x16x32_bf16 v[64:67], v[176:179], v[208:211], v[64:67]
	v_mfma_f32_16x16x32_bf16 v[108:111], v[172:175], v[188:191], v[108:111]
	v_mfma_f32_16x16x32_bf16 v[104:107], v[180:183], v[188:191], v[104:107]
	v_mfma_f32_16x16x32_bf16 v[92:95], v[172:175], v[196:199], v[92:95]
	v_mfma_f32_16x16x32_bf16 v[88:91], v[180:183], v[196:199], v[88:91]
	v_mfma_f32_16x16x32_bf16 v[76:79], v[172:175], v[204:207], v[76:79]
	v_mfma_f32_16x16x32_bf16 v[72:75], v[180:183], v[204:207], v[72:75]
	v_mfma_f32_16x16x32_bf16 v[68:71], v[172:175], v[212:215], v[68:71]
	v_mfma_f32_16x16x32_bf16 v[64:67], v[180:183], v[212:215], v[64:67]
	s_setprio 0
	s_barrier
	s_add_i32 s44, s69, s48

; #define PG8_STAGE(bufoff, gbase, voff) do { _Pragma("unroll") for (int _i = 0; _i < 2; ++_i) \
;         __builtin_amdgcn_global_load_lds((const unsigned*)((const char*)(gbase) + (voff)[_i]), (PG8_LAS unsigned*)(lds + (bufoff) + ldsw + _i * 8192), 16, 0, 0); } while (0)
; #define PG8_LDA(dst, b, h) do { _Pragma("unroll") for (int m = 0; m < 4; ++m) _Pragma("unroll") for (int k = 0; k < 2; ++k) dst[m][k] = *(const PG8_LAS bf16x8*)(lds + PG8_SA(b, h) + aoff + m * 2048 + k * 1024); } while (0)
; template <class Epi, class Sched, bool ALIGN_EPI = false, bool SP2 = false>
; __device__ __forceinline__ void gemm_phase(PG8_LAS unsigned char* lds, const Gemm g, const Sched& S, const Epi& E) {
;     ...
;             PG8_LDA(At, 1, 1); PG8_STAGE(PG8_SB(1, 0), b3, voffB); PG8_STAGE(PG8_SB(1, 1), b3 + hstep, voffB); PG8_STAGE(PG8_SA(1, 0), a3, voffA);
	s_mov_b32 m0, s44
	ds_read_b128 v[184:187], v151 offset:49152
	ds_read_b128 v[188:191], v151 offset:50176
	ds_read_b128 v[192:195], v151 offset:51200
	ds_read_b128 v[196:199], v151 offset:52224
	ds_read_b128 v[200:203], v151 offset:53248
	ds_read_b128 v[204:207], v151 offset:54272
	ds_read_b128 v[208:211], v151 offset:55296
	ds_read_b128 v[212:215], v151 offset:56320
	global_load_lds_dwordx4 v250, s[96:97]
	s_add_i32 m0, s44, 0x2000
	s_add_u32 s42, s42, 0x80080

; #define PG8_STAGE(bufoff, gbase, voff) do { _Pragma("unroll") for (int _i = 0; _i < 2; ++_i) \
;         __builtin_amdgcn_global_load_lds((const unsigned*)((const char*)(gbase) + (voff)[_i]), (PG8_LAS unsigned*)(lds + (bufoff) + ldsw + _i * 8192), 16, 0, 0); } while (0)
; #define PG8_LDA(dst, b, h) do { _Pragma("unroll") for (int m = 0; m < 4; ++m) _Pragma("unroll") for (int k = 0; k < 2; ++k) dst[m][k] = *(const PG8_LAS bf16x8*)(lds + PG8_SA(b, h) + aoff + m * 2048 + k * 1024); } while (0)
; template <class Epi, class Sched, bool ALIGN_EPI = false, bool SP2 = false>
; __device__ __forceinline__ void gemm_phase(PG8_LAS unsigned char* lds, const Gemm g, const Sched& S, const Epi& E) {
;     ...
;             PG8_LDA(At, 1, 1); PG8_STAGE(PG8_SB(1, 0), b3, voffB); PG8_STAGE(PG8_SB(1, 1), b3 + hstep, voffB); PG8_STAGE(PG8_SA(1, 0), a3, voffA);
	s_addc_u32 s43, s43, 0
	s_add_i32 s44, s70, s48
	global_load_lds_dwordx4 v251, s[96:97]

; #define PG8_STAGE(bufoff, gbase, voff) do { _Pragma("unroll") for (int _i = 0; _i < 2; ++_i) \
;         __builtin_amdgcn_global_load_lds((const unsigned*)((const char*)(gbase) + (voff)[_i]), (PG8_LAS unsigned*)(lds + (bufoff) + ldsw + _i * 8192), 16, 0, 0); } while (0)
; #define PG8_LDA(dst, b, h) do { _Pragma("unroll") for (int m = 0; m < 4; ++m) _Pragma("unroll") for (int k = 0; k < 2; ++k) dst[m][k] = *(const PG8_LAS bf16x8*)(lds + PG8_SA(b, h) + aoff + m * 2048 + k * 1024); } while (0)
; template <class Epi, class Sched, bool ALIGN_EPI = false, bool SP2 = false>
; __device__ __forceinline__ void gemm_phase(PG8_LAS unsigned char* lds, const Gemm g, const Sched& S, const Epi& E) {
;     ...
;             PG8_LDA(At, 1, 1); PG8_STAGE(PG8_SB(1, 0), b3, voffB); PG8_STAGE(PG8_SB(1, 1), b3 + hstep, voffB); PG8_STAGE(PG8_SA(1, 0), a3, voffA);
	s_mov_b32 m0, s44
	s_nop 0
	global_load_lds_dwordx4 v132, s[42:43]

; #define PG8_STAGE(bufoff, gbase, voff) do { _Pragma("unroll") for (int _i = 0; _i < 2; ++_i) \
;         __builtin_amdgcn_global_load_lds((const unsigned*)((const char*)(gbase) + (voff)[_i]), (PG8_LAS unsigned*)(lds + (bufoff) + ldsw + _i * 8192), 16, 0, 0); } while (0)
; #define PG8_LDA(dst, b, h) do { _Pragma("unroll") for (int m = 0; m < 4; ++m) _Pragma("unroll") for (int k = 0; k < 2; ++k) dst[m][k] = *(const PG8_LAS bf16x8*)(lds + PG8_SA(b, h) + aoff + m * 2048 + k * 1024); } while (0)
; template <class Epi, class Sched, bool ALIGN_EPI = false, bool SP2 = false>
; __device__ __forceinline__ void gemm_phase(PG8_LAS unsigned char* lds, const Gemm g, const Sched& S, const Epi& E) {
;     ...
;             PG8_LDA(At, 1, 1); PG8_STAGE(PG8_SB(1, 0), b3, voffB); PG8_STAGE(PG8_SB(1, 1), b3 + hstep, voffB); PG8_STAGE(PG8_SA(1, 0), a3, voffA);
	s_add_i32 m0, s44, 0x2000
	s_nop 0
	global_load_lds_dwordx4 v128, s[42:43]

; #define PG8_STAGE(bufoff, gbase, voff) do { _Pragma("unroll") for (int _i = 0; _i < 2; ++_i) \
;         __builtin_amdgcn_global_load_lds((const unsigned*)((const char*)(gbase) + (voff)[_i]), (PG8_LAS unsigned*)(lds + (bufoff) + ldsw + _i * 8192), 16, 0, 0); } while (0)
; #define PG8_LDA(dst, b, h) do { _Pragma("unroll") for (int m = 0; m < 4; ++m) _Pragma("unroll") for (int k = 0; k < 2; ++k) dst[m][k] = *(const PG8_LAS bf16x8*)(lds + PG8_SA(b, h) + aoff + m * 2048 + k * 1024); } while (0)
; template <class Epi, class Sched, bool ALIGN_EPI = false, bool SP2 = false>
; __device__ __forceinline__ void gemm_phase(PG8_LAS unsigned char* lds, const Gemm g, const Sched& S, const Epi& E) {
;     ...
;             PG8_LDA(At, 1, 1); PG8_STAGE(PG8_SB(1, 0), b3, voffB); PG8_STAGE(PG8_SB(1, 1), b3 + hstep, voffB); PG8_STAGE(PG8_SA(1, 0), a3, voffA);
	s_mov_b32 m0, s55
	s_nop 0
	global_load_lds_dwordx4 v252, s[98:99]

; #define PG8_STAGE(bufoff, gbase, voff) do { _Pragma("unroll") for (int _i = 0; _i < 2; ++_i) \
;         __builtin_amdgcn_global_load_lds((const unsigned*)((const char*)(gbase) + (voff)[_i]), (PG8_LAS unsigned*)(lds + (bufoff) + ldsw + _i * 8192), 16, 0, 0); } while (0)
; #define PG8_LDA(dst, b, h) do { _Pragma("unroll") for (int m = 0; m < 4; ++m) _Pragma("unroll") for (int k = 0; k < 2; ++k) dst[m][k] = *(const PG8_LAS bf16x8*)(lds + PG8_SA(b, h) + aoff + m * 2048 + k * 1024); } while (0)
; #define PG8_MMA(ai, bj, At, Bt) do { __builtin_amdgcn_s_setprio(1); _Pragma("unroll") for (int m = 0; m < 4; ++m) _Pragma("unroll") for (int n = 0; n < 2; ++n) _Pragma("unroll") for (int k = 0; k < 2; ++k) \
;         acc[ai][bj][m][n] = __builtin_amdgcn_mfma_f32_16x16x32_bf16(Bt[n][k], At[m][k], acc[ai][bj][m][n], 0, 0, 0); __builtin_amdgcn_s_setprio(0); } while (0)
; #define PG8_WAIT_V(n) asm volatile("s_waitcnt vmcnt(" #n ")" ::: "memory")
; #define PG8_WAIT_L(n) asm volatile("s_waitcnt lgkmcnt(" #n ")" ::: "memory")
; #define PG8_BAR __builtin_amdgcn_s_barrier()
; #define PG8_SCHED __builtin_amdgcn_sched_barrier(0)
; template <class Epi, class Sched, bool ALIGN_EPI = false, bool SP2 = false>
; __device__ __forceinline__ void gemm_phase(PG8_LAS unsigned char* lds, const Gemm g, const Sched& S, const Epi& E) {
;     ...
;             PG8_LDA(At, 1, 1); PG8_STAGE(PG8_SB(1, 0), b3, voffB); PG8_STAGE(PG8_SB(1, 1), b3 + hstep, voffB); PG8_STAGE(PG8_SA(1, 0), a3, voffA);
;             PG8_WAIT_V(8); PG8_WAIT_L(0); PG8_BAR; PG8_MMA(1, 0, At, B0); PG8_MMA(1, 1, At, B1); PG8_BAR; PG8_SCHED;
	s_mov_b32 m0, s56
	s_nop 0
	global_load_lds_dwordx4 v253, s[98:99]
	s_waitcnt vmcnt(8)
	s_waitcnt lgkmcnt(0)
	s_setprio 1
	s_barrier

; #define PG8_MMA(ai, bj, At, Bt) do { __builtin_amdgcn_s_setprio(1); _Pragma("unroll") for (int m = 0; m < 4; ++m) _Pragma("unroll") for (int n = 0; n < 2; ++n) _Pragma("unroll") for (int k = 0; k < 2; ++k) \
;         acc[ai][bj][m][n] = __builtin_amdgcn_mfma_f32_16x16x32_bf16(Bt[n][k], At[m][k], acc[ai][bj][m][n], 0, 0, 0); __builtin_amdgcn_s_setprio(0); } while (0)
; #define PG8_WAIT_V(n) asm volatile("s_waitcnt vmcnt(" #n ")" ::: "memory")
; #define PG8_WAIT_L(n) asm volatile("s_waitcnt lgkmcnt(" #n ")" ::: "memory")
; #define PG8_BAR __builtin_amdgcn_s_barrier()
; #define PG8_SCHED __builtin_amdgcn_sched_barrier(0)
; template <class Epi, class Sched, bool ALIGN_EPI = false, bool SP2 = false>
; __device__ __forceinline__ void gemm_phase(PG8_LAS unsigned char* lds, const Gemm g, const Sched& S, const Epi& E) {
;     ...
;             PG8_WAIT_V(8); PG8_WAIT_L(0); PG8_BAR; PG8_MMA(1, 0, At, B0); PG8_MMA(1, 1, At, B1); PG8_BAR; PG8_SCHED;
	v_mfma_f32_16x16x32_bf16 v[60:63], v[152:155], v[184:187], v[60:63]
	v_mfma_f32_16x16x32_bf16 v[56:59], v[160:163], v[184:187], v[56:59]
	v_mfma_f32_16x16x32_bf16 v[52:55], v[152:155], v[192:195], v[52:55]
	v_mfma_f32_16x16x32_bf16 v[48:51], v[160:163], v[192:195], v[48:51]
	v_mfma_f32_16x16x32_bf16 v[36:39], v[152:155], v[200:203], v[36:39]
	v_mfma_f32_16x16x32_bf16 v[32:35], v[160:163], v[200:203], v[32:35]
	v_mfma_f32_16x16x32_bf16 v[20:23], v[152:155], v[208:211], v[20:23]
	v_mfma_f32_16x16x32_bf16 v[16:19], v[160:163], v[208:211], v[16:19]
	v_mfma_f32_16x16x32_bf16 v[60:63], v[156:159], v[188:191], v[60:63]
	v_mfma_f32_16x16x32_bf16 v[56:59], v[164:167], v[188:191], v[56:59]
	v_mfma_f32_16x16x32_bf16 v[52:55], v[156:159], v[196:199], v[52:55]
	v_mfma_f32_16x16x32_bf16 v[48:51], v[164:167], v[196:199], v[48:51]
	v_mfma_f32_16x16x32_bf16 v[36:39], v[156:159], v[204:207], v[36:39]
	v_mfma_f32_16x16x32_bf16 v[32:35], v[164:167], v[204:207], v[32:35]
	v_mfma_f32_16x16x32_bf16 v[20:23], v[156:159], v[212:215], v[20:23]
	v_mfma_f32_16x16x32_bf16 v[16:19], v[164:167], v[212:215], v[16:19]


; #define PG8_MMA(ai, bj, At, Bt) do { __builtin_amdgcn_s_setprio(1); _Pragma("unroll") for (int m = 0; m < 4; ++m) _Pragma("unroll") for (int n = 0; n < 2; ++n) _Pragma("unroll") for (int k = 0; k < 2; ++k) \
;         acc[ai][bj][m][n] = __builtin_amdgcn_mfma_f32_16x16x32_bf16(Bt[n][k], At[m][k], acc[ai][bj][m][n], 0, 0, 0); __builtin_amdgcn_s_setprio(0); } while (0)
; #define PG8_WAIT_V(n) asm volatile("s_waitcnt vmcnt(" #n ")" ::: "memory")
; #define PG8_WAIT_L(n) asm volatile("s_waitcnt lgkmcnt(" #n ")" ::: "memory")
; #define PG8_BAR __builtin_amdgcn_s_barrier()
; #define PG8_SCHED __builtin_amdgcn_sched_barrier(0)
; template <class Epi, class Sched, bool ALIGN_EPI = false, bool SP2 = false>
; __device__ __forceinline__ void gemm_phase(PG8_LAS unsigned char* lds, const Gemm g, const Sched& S, const Epi& E) {
;     ...
;         for (int t = 0; t < nt; t += 2) {
;     ...
;             PG8_WAIT_V(8); PG8_WAIT_L(0); PG8_BAR; PG8_MMA(1, 0, At, B0); PG8_MMA(1, 1, At, B1); PG8_BAR; PG8_SCHED;
	v_mfma_f32_16x16x32_bf16 v[44:47], v[168:171], v[184:187], v[44:47]
	v_mfma_f32_16x16x32_bf16 v[40:43], v[176:179], v[184:187], v[40:43]
	v_mfma_f32_16x16x32_bf16 v[28:31], v[168:171], v[192:195], v[28:31]
	v_mfma_f32_16x16x32_bf16 v[24:27], v[176:179], v[192:195], v[24:27]
	v_mfma_f32_16x16x32_bf16 v[12:15], v[168:171], v[200:203], v[12:15]
	v_mfma_f32_16x16x32_bf16 v[8:11], v[176:179], v[200:203], v[8:11]
	v_mfma_f32_16x16x32_bf16 v[4:7], v[168:171], v[208:211], v[4:7]
	v_mfma_f32_16x16x32_bf16 v[0:3], v[176:179], v[208:211], v[0:3]
	v_mfma_f32_16x16x32_bf16 v[44:47], v[172:175], v[188:191], v[44:47]
	v_mfma_f32_16x16x32_bf16 v[40:43], v[180:183], v[188:191], v[40:43]
	v_mfma_f32_16x16x32_bf16 v[28:31], v[172:175], v[196:199], v[28:31]
	v_mfma_f32_16x16x32_bf16 v[24:27], v[180:183], v[196:199], v[24:27]
	v_mfma_f32_16x16x32_bf16 v[12:15], v[172:175], v[204:207], v[12:15]
	v_mfma_f32_16x16x32_bf16 v[8:11], v[180:183], v[204:207], v[8:11]
	v_mfma_f32_16x16x32_bf16 v[4:7], v[172:175], v[212:215], v[4:7]
	v_mfma_f32_16x16x32_bf16 v[0:3], v[180:183], v[212:215], v[0:3]
	s_setprio 0
	s_add_i32 s68, s68, 2
	s_add_u32 s40, s40, 0x100
	s_addc_u32 s41, s41, 0
	s_add_u32 s65, s65, 0x100
	s_addc_u32 s67, s67, 0
	s_cmp_gt_u32 s68, 29
	s_barrier


; #define PG8_BAR __builtin_amdgcn_s_barrier()
; template <class Epi, class Sched, bool ALIGN_EPI = false, bool SP2 = false>
; __device__ __forceinline__ void gemm_phase(PG8_LAS unsigned char* lds, const Gemm g, const Sched& S, const Epi& E) {
;     ...
;         for (int t = 0; t < nt; t += 2) {
;     ...
;         if constexpr (ALIGN_EPI) { if (wr == 0) PG8_BAR; }
	s_cbranch_scc0 .LBB0_66
	s_and_b64 vcc, exec, s[26:27]
	s_cbranch_vccz .LBB0_69
	s_barrier

; #define PG8_STAGE(bufoff, gbase, voff) do { _Pragma("unroll") for (int _i = 0; _i < 2; ++_i) \
;         __builtin_amdgcn_global_load_lds((const unsigned*)((const char*)(gbase) + (voff)[_i]), (PG8_LAS unsigned*)(lds + (bufoff) + ldsw + _i * 8192), 16, 0, 0); } while (0)
; #define PG8_LDA(dst, b, h) do { _Pragma("unroll") for (int m = 0; m < 4; ++m) _Pragma("unroll") for (int k = 0; k < 2; ++k) dst[m][k] = *(const PG8_LAS bf16x8*)(lds + PG8_SA(b, h) + aoff + m * 2048 + k * 1024); } while (0)
; #define PG8_LDB(dst, b, h) do { _Pragma("unroll") for (int n = 0; n < 2; ++n) _Pragma("unroll") for (int k = 0; k < 2; ++k) dst[n][k] = *(const PG8_LAS bf16x8*)(lds + PG8_SB(b, h) + boff + n * 2048 + k * 1024); } while (0)
; #define PG8_SCHED __builtin_amdgcn_sched_barrier(0)
; template <class Epi, class Sched, bool ALIGN_EPI = false, bool SP2 = false>
; __device__ __forceinline__ void gemm_phase(PG8_LAS unsigned char* lds, const Gemm g, const Sched& S, const Epi& E) {
;     ...
;             const bool last = (t == nt - 2);
;             const char* a1 = cA + (size_t)(t + 1) * kstep;
;             const char* a2 = last ? nA : cA + (size_t)(t + 2) * kstep; const char* b2 = last ? nB : cB + (size_t)(t + 2) * kstep;
;             const char* a3 = a2 + kstep; const char* b3 = b2 + kstep;
;             if (last && has_next) S.a_ready(nxt);
;             if constexpr (SP2) {
;             PG8_LDB(B0, 0, 0); PG8_LDB(B1, 0, 1); PG8_SCHED; PG8_LDA(At, 0, 0); PG8_STAGE(PG8_SA(1, 1), a1 + hstep, voffA);
.LBB0_333:
	ds_read_b128 v[64:67], v211
	ds_read_b128 v[68:71], v211 offset:1024
	ds_read_b128 v[72:75], v211 offset:2048
	ds_read_b128 v[76:79], v211 offset:3072
	ds_read_b128 v[144:147], v212
	ds_read_b128 v[148:151], v212 offset:1024
	ds_read_b128 v[152:155], v212 offset:2048
	ds_read_b128 v[156:159], v212 offset:3072
	s_add_u32 s60, s58, 0xfff80080
	s_addc_u32 s61, s59, -1
	s_cmp_eq_u32 s81, 28
	s_cselect_b32 s63, s11, s61
	s_cselect_b32 s62, s51, s60
	s_cselect_b32 s61, s49, s80
	s_cselect_b32 s60, s78, s79

; #define PG8_STAGE(bufoff, gbase, voff) do { _Pragma("unroll") for (int _i = 0; _i < 2; ++_i) \
;         __builtin_amdgcn_global_load_lds((const unsigned*)((const char*)(gbase) + (voff)[_i]), (PG8_LAS unsigned*)(lds + (bufoff) + ldsw + _i * 8192), 16, 0, 0); } while (0)
; #define PG8_LDA(dst, b, h) do { _Pragma("unroll") for (int m = 0; m < 4; ++m) _Pragma("unroll") for (int k = 0; k < 2; ++k) dst[m][k] = *(const PG8_LAS bf16x8*)(lds + PG8_SA(b, h) + aoff + m * 2048 + k * 1024); } while (0)
; #define PG8_LDB(dst, b, h) do { _Pragma("unroll") for (int n = 0; n < 2; ++n) _Pragma("unroll") for (int k = 0; k < 2; ++k) dst[n][k] = *(const PG8_LAS bf16x8*)(lds + PG8_SB(b, h) + boff + n * 2048 + k * 1024); } while (0)
; #define PG8_SCHED __builtin_amdgcn_sched_barrier(0)
; template <class Epi, class Sched, bool ALIGN_EPI = false, bool SP2 = false>
; __device__ __forceinline__ void gemm_phase(PG8_LAS unsigned char* lds, const Gemm g, const Sched& S, const Epi& E) {
;     ...
;             PG8_LDB(B0, 0, 0); PG8_LDB(B1, 0, 1); PG8_SCHED; PG8_LDA(At, 0, 0); PG8_STAGE(PG8_SA(1, 1), a1 + hstep, voffA);
	s_add_i32 m0, s57, 0xc000
	ds_read_b128 v[176:179], v213
	ds_read_b128 v[180:183], v213 offset:1024
	ds_read_b128 v[184:187], v213 offset:2048
	ds_read_b128 v[188:191], v213 offset:3072
	ds_read_b128 v[192:195], v213 offset:4096
	ds_read_b128 v[196:199], v213 offset:5120
	ds_read_b128 v[200:203], v213 offset:6144
	ds_read_b128 v[204:207], v213 offset:7168
	global_load_lds_dwordx4 v168, s[58:59]

; #define PG8_STAGE(bufoff, gbase, voff) do { _Pragma("unroll") for (int _i = 0; _i < 2; ++_i) \
;         __builtin_amdgcn_global_load_lds((const unsigned*)((const char*)(gbase) + (voff)[_i]), (PG8_LAS unsigned*)(lds + (bufoff) + ldsw + _i * 8192), 16, 0, 0); } while (0)
; #define PG8_LDA(dst, b, h) do { _Pragma("unroll") for (int m = 0; m < 4; ++m) _Pragma("unroll") for (int k = 0; k < 2; ++k) dst[m][k] = *(const PG8_LAS bf16x8*)(lds + PG8_SA(b, h) + aoff + m * 2048 + k * 1024); } while (0)
; #define PG8_LDB(dst, b, h) do { _Pragma("unroll") for (int n = 0; n < 2; ++n) _Pragma("unroll") for (int k = 0; k < 2; ++k) dst[n][k] = *(const PG8_LAS bf16x8*)(lds + PG8_SB(b, h) + boff + n * 2048 + k * 1024); } while (0)
; #define PG8_MMA(ai, bj, At, Bt) do { __builtin_amdgcn_s_setprio(1); _Pragma("unroll") for (int m = 0; m < 4; ++m) _Pragma("unroll") for (int n = 0; n < 2; ++n) _Pragma("unroll") for (int k = 0; k < 2; ++k) \
;         acc[ai][bj][m][n] = __builtin_amdgcn_mfma_f32_16x16x32_bf16(Bt[n][k], At[m][k], acc[ai][bj][m][n], 0, 0, 0); __builtin_amdgcn_s_setprio(0); } while (0)
; #define PG8_WAIT_V(n) asm volatile("s_waitcnt vmcnt(" #n ")" ::: "memory")
; #define PG8_WAIT_L(n) asm volatile("s_waitcnt lgkmcnt(" #n ")" ::: "memory")
; #define PG8_BAR __builtin_amdgcn_s_barrier()
; #define PG8_SCHED __builtin_amdgcn_sched_barrier(0)
; template <class Epi, class Sched, bool ALIGN_EPI = false, bool SP2 = false>
; __device__ __forceinline__ void gemm_phase(PG8_LAS unsigned char* lds, const Gemm g, const Sched& S, const Epi& E) {
;     ...
;             PG8_LDB(B0, 0, 0); PG8_LDB(B1, 0, 1); PG8_SCHED; PG8_LDA(At, 0, 0); PG8_STAGE(PG8_SA(1, 1), a1 + hstep, voffA);
;             PG8_WAIT_V(8); PG8_WAIT_L(0); PG8_BAR; PG8_MMA(0, 0, At, B0); PG8_MMA(0, 1, At, B1); PG8_BAR; PG8_SCHED;
	s_add_i32 m0, s57, 0xe000
	s_nop 0
	global_load_lds_dwordx4 v170, s[58:59]
	s_waitcnt vmcnt(8)
	s_waitcnt lgkmcnt(0)
	s_setprio 1
	s_barrier

; #define PG8_MMA(ai, bj, At, Bt) do { __builtin_amdgcn_s_setprio(1); _Pragma("unroll") for (int m = 0; m < 4; ++m) _Pragma("unroll") for (int n = 0; n < 2; ++n) _Pragma("unroll") for (int k = 0; k < 2; ++k) \
;         acc[ai][bj][m][n] = __builtin_amdgcn_mfma_f32_16x16x32_bf16(Bt[n][k], At[m][k], acc[ai][bj][m][n], 0, 0, 0); __builtin_amdgcn_s_setprio(0); } while (0)
; #define PG8_WAIT_V(n) asm volatile("s_waitcnt vmcnt(" #n ")" ::: "memory")
; #define PG8_WAIT_L(n) asm volatile("s_waitcnt lgkmcnt(" #n ")" ::: "memory")
; #define PG8_BAR __builtin_amdgcn_s_barrier()
; #define PG8_SCHED __builtin_amdgcn_sched_barrier(0)
; template <class Epi, class Sched, bool ALIGN_EPI = false, bool SP2 = false>
; __device__ __forceinline__ void gemm_phase(PG8_LAS unsigned char* lds, const Gemm g, const Sched& S, const Epi& E) {
;     ...
;             PG8_WAIT_V(8); PG8_WAIT_L(0); PG8_BAR; PG8_MMA(0, 0, At, B0); PG8_MMA(0, 1, At, B1); PG8_BAR; PG8_SCHED;
	v_mfma_f32_16x16x32_bf16 v[140:143], v[64:67], v[176:179], v[140:143]
	v_mfma_f32_16x16x32_bf16 v[136:139], v[72:75], v[176:179], v[136:139]
	v_mfma_f32_16x16x32_bf16 v[124:127], v[64:67], v[184:187], v[124:127]
	v_mfma_f32_16x16x32_bf16 v[120:123], v[72:75], v[184:187], v[120:123]
	v_mfma_f32_16x16x32_bf16 v[108:111], v[64:67], v[192:195], v[108:111]
	v_mfma_f32_16x16x32_bf16 v[104:107], v[72:75], v[192:195], v[104:107]
	v_mfma_f32_16x16x32_bf16 v[92:95], v[64:67], v[200:203], v[92:95]
	v_mfma_f32_16x16x32_bf16 v[88:91], v[72:75], v[200:203], v[88:91]
	v_mfma_f32_16x16x32_bf16 v[140:143], v[68:71], v[180:183], v[140:143]
	v_mfma_f32_16x16x32_bf16 v[136:139], v[76:79], v[180:183], v[136:139]
	v_mfma_f32_16x16x32_bf16 v[124:127], v[68:71], v[188:191], v[124:127]
	v_mfma_f32_16x16x32_bf16 v[120:123], v[76:79], v[188:191], v[120:123]
	v_mfma_f32_16x16x32_bf16 v[108:111], v[68:71], v[196:199], v[108:111]
	v_mfma_f32_16x16x32_bf16 v[104:107], v[76:79], v[196:199], v[104:107]
	v_mfma_f32_16x16x32_bf16 v[92:95], v[68:71], v[204:207], v[92:95]
	v_mfma_f32_16x16x32_bf16 v[88:91], v[76:79], v[204:207], v[88:91]


; #define PG8_MMA(ai, bj, At, Bt) do { __builtin_amdgcn_s_setprio(1); _Pragma("unroll") for (int m = 0; m < 4; ++m) _Pragma("unroll") for (int n = 0; n < 2; ++n) _Pragma("unroll") for (int k = 0; k < 2; ++k) \
;         acc[ai][bj][m][n] = __builtin_amdgcn_mfma_f32_16x16x32_bf16(Bt[n][k], At[m][k], acc[ai][bj][m][n], 0, 0, 0); __builtin_amdgcn_s_setprio(0); } while (0)
; #define PG8_WAIT_V(n) asm volatile("s_waitcnt vmcnt(" #n ")" ::: "memory")
; #define PG8_WAIT_L(n) asm volatile("s_waitcnt lgkmcnt(" #n ")" ::: "memory")
; #define PG8_BAR __builtin_amdgcn_s_barrier()
; #define PG8_SCHED __builtin_amdgcn_sched_barrier(0)
; template <class Epi, class Sched, bool ALIGN_EPI = false, bool SP2 = false>
; __device__ __forceinline__ void gemm_phase(PG8_LAS unsigned char* lds, const Gemm g, const Sched& S, const Epi& E) {
;     ...
;             PG8_WAIT_V(8); PG8_WAIT_L(0); PG8_BAR; PG8_MMA(0, 0, At, B0); PG8_MMA(0, 1, At, B1); PG8_BAR; PG8_SCHED;
	v_mfma_f32_16x16x32_bf16 v[132:135], v[144:147], v[176:179], v[132:135]
	v_mfma_f32_16x16x32_bf16 v[128:131], v[152:155], v[176:179], v[128:131]
	v_mfma_f32_16x16x32_bf16 v[116:119], v[144:147], v[184:187], v[116:119]
	v_mfma_f32_16x16x32_bf16 v[112:115], v[152:155], v[184:187], v[112:115]
	v_mfma_f32_16x16x32_bf16 v[100:103], v[144:147], v[192:195], v[100:103]
	v_mfma_f32_16x16x32_bf16 v[96:99], v[152:155], v[192:195], v[96:99]
	v_mfma_f32_16x16x32_bf16 v[84:87], v[144:147], v[200:203], v[84:87]
	v_mfma_f32_16x16x32_bf16 v[80:83], v[152:155], v[200:203], v[80:83]
	v_mfma_f32_16x16x32_bf16 v[132:135], v[148:151], v[180:183], v[132:135]
	v_mfma_f32_16x16x32_bf16 v[128:131], v[156:159], v[180:183], v[128:131]
	v_mfma_f32_16x16x32_bf16 v[116:119], v[148:151], v[188:191], v[116:119]
	v_mfma_f32_16x16x32_bf16 v[112:115], v[156:159], v[188:191], v[112:115]
	v_mfma_f32_16x16x32_bf16 v[100:103], v[148:151], v[196:199], v[100:103]
	v_mfma_f32_16x16x32_bf16 v[96:99], v[156:159], v[196:199], v[96:99]
	v_mfma_f32_16x16x32_bf16 v[84:87], v[148:151], v[204:207], v[84:87]
	v_mfma_f32_16x16x32_bf16 v[80:83], v[156:159], v[204:207], v[80:83]
	s_setprio 0
	s_barrier
	s_add_i32 s82, s75, s64
	s_mov_b64 s[96:97], s[60:61]

; #define PG8_STAGE(bufoff, gbase, voff) do { _Pragma("unroll") for (int _i = 0; _i < 2; ++_i) \
;         __builtin_amdgcn_global_load_lds((const unsigned*)((const char*)(gbase) + (voff)[_i]), (PG8_LAS unsigned*)(lds + (bufoff) + ldsw + _i * 8192), 16, 0, 0); } while (0)
; #define PG8_LDA(dst, b, h) do { _Pragma("unroll") for (int m = 0; m < 4; ++m) _Pragma("unroll") for (int k = 0; k < 2; ++k) dst[m][k] = *(const PG8_LAS bf16x8*)(lds + PG8_SA(b, h) + aoff + m * 2048 + k * 1024); } while (0)
; template <class Epi, class Sched, bool ALIGN_EPI = false, bool SP2 = false>
; __device__ __forceinline__ void gemm_phase(PG8_LAS unsigned char* lds, const Gemm g, const Sched& S, const Epi& E) {
;     ...
;             PG8_LDA(At, 0, 1); PG8_STAGE(PG8_SB(0, 0), b2, voffB); PG8_STAGE(PG8_SB(0, 1), b2 + hstep, voffB); PG8_STAGE(PG8_SA(0, 0), a2, voffA);
	s_mov_b32 m0, s82
	ds_read_b128 v[176:179], v213 offset:16384
	ds_read_b128 v[180:183], v213 offset:17408
	ds_read_b128 v[184:187], v213 offset:18432
	ds_read_b128 v[188:191], v213 offset:19456
	ds_read_b128 v[192:195], v213 offset:20480
	ds_read_b128 v[196:199], v213 offset:21504
	ds_read_b128 v[200:203], v213 offset:22528
	ds_read_b128 v[204:207], v213 offset:23552
	global_load_lds_dwordx4 v162, s[60:61]
	s_add_i32 m0, s82, 0x2000
	s_add_u32 s82, s60, 0x80000

; #define PG8_STAGE(bufoff, gbase, voff) do { _Pragma("unroll") for (int _i = 0; _i < 2; ++_i) \
;         __builtin_amdgcn_global_load_lds((const unsigned*)((const char*)(gbase) + (voff)[_i]), (PG8_LAS unsigned*)(lds + (bufoff) + ldsw + _i * 8192), 16, 0, 0); } while (0)
; #define PG8_LDA(dst, b, h) do { _Pragma("unroll") for (int m = 0; m < 4; ++m) _Pragma("unroll") for (int k = 0; k < 2; ++k) dst[m][k] = *(const PG8_LAS bf16x8*)(lds + PG8_SA(b, h) + aoff + m * 2048 + k * 1024); } while (0)
; template <class Epi, class Sched, bool ALIGN_EPI = false, bool SP2 = false>
; __device__ __forceinline__ void gemm_phase(PG8_LAS unsigned char* lds, const Gemm g, const Sched& S, const Epi& E) {
;     ...
;             PG8_LDA(At, 0, 1); PG8_STAGE(PG8_SB(0, 0), b2, voffB); PG8_STAGE(PG8_SB(0, 1), b2 + hstep, voffB); PG8_STAGE(PG8_SA(0, 0), a2, voffA);
	s_addc_u32 s83, s61, 0
	s_add_i32 s84, s76, s64
	global_load_lds_dwordx4 v166, s[60:61]

; #define PG8_STAGE(bufoff, gbase, voff) do { _Pragma("unroll") for (int _i = 0; _i < 2; ++_i) \
;         __builtin_amdgcn_global_load_lds((const unsigned*)((const char*)(gbase) + (voff)[_i]), (PG8_LAS unsigned*)(lds + (bufoff) + ldsw + _i * 8192), 16, 0, 0); } while (0)
; #define PG8_LDA(dst, b, h) do { _Pragma("unroll") for (int m = 0; m < 4; ++m) _Pragma("unroll") for (int k = 0; k < 2; ++k) dst[m][k] = *(const PG8_LAS bf16x8*)(lds + PG8_SA(b, h) + aoff + m * 2048 + k * 1024); } while (0)
; template <class Epi, class Sched, bool ALIGN_EPI = false, bool SP2 = false>
; __device__ __forceinline__ void gemm_phase(PG8_LAS unsigned char* lds, const Gemm g, const Sched& S, const Epi& E) {
;     ...
;             PG8_LDA(At, 0, 1); PG8_STAGE(PG8_SB(0, 0), b2, voffB); PG8_STAGE(PG8_SB(0, 1), b2 + hstep, voffB); PG8_STAGE(PG8_SA(0, 0), a2, voffA);
	s_mov_b32 m0, s84
	s_nop 0
	global_load_lds_dwordx4 v162, s[82:83]

; #define PG8_STAGE(bufoff, gbase, voff) do { _Pragma("unroll") for (int _i = 0; _i < 2; ++_i) \
;         __builtin_amdgcn_global_load_lds((const unsigned*)((const char*)(gbase) + (voff)[_i]), (PG8_LAS unsigned*)(lds + (bufoff) + ldsw + _i * 8192), 16, 0, 0); } while (0)
; #define PG8_LDA(dst, b, h) do { _Pragma("unroll") for (int m = 0; m < 4; ++m) _Pragma("unroll") for (int k = 0; k < 2; ++k) dst[m][k] = *(const PG8_LAS bf16x8*)(lds + PG8_SA(b, h) + aoff + m * 2048 + k * 1024); } while (0)
; template <class Epi, class Sched, bool ALIGN_EPI = false, bool SP2 = false>
; __device__ __forceinline__ void gemm_phase(PG8_LAS unsigned char* lds, const Gemm g, const Sched& S, const Epi& E) {
;     ...
;             PG8_LDA(At, 0, 1); PG8_STAGE(PG8_SB(0, 0), b2, voffB); PG8_STAGE(PG8_SB(0, 1), b2 + hstep, voffB); PG8_STAGE(PG8_SA(0, 0), a2, voffA);
	s_add_i32 m0, s84, 0x2000
	s_nop 0
	global_load_lds_dwordx4 v166, s[82:83]
	s_mov_b64 s[98:99], s[62:63]

; #define PG8_STAGE(bufoff, gbase, voff) do { _Pragma("unroll") for (int _i = 0; _i < 2; ++_i) \
;         __builtin_amdgcn_global_load_lds((const unsigned*)((const char*)(gbase) + (voff)[_i]), (PG8_LAS unsigned*)(lds + (bufoff) + ldsw + _i * 8192), 16, 0, 0); } while (0)
; #define PG8_LDA(dst, b, h) do { _Pragma("unroll") for (int m = 0; m < 4; ++m) _Pragma("unroll") for (int k = 0; k < 2; ++k) dst[m][k] = *(const PG8_LAS bf16x8*)(lds + PG8_SA(b, h) + aoff + m * 2048 + k * 1024); } while (0)
; #define PG8_MMA(ai, bj, At, Bt) do { __builtin_amdgcn_s_setprio(1); _Pragma("unroll") for (int m = 0; m < 4; ++m) _Pragma("unroll") for (int n = 0; n < 2; ++n) _Pragma("unroll") for (int k = 0; k < 2; ++k) \
;         acc[ai][bj][m][n] = __builtin_amdgcn_mfma_f32_16x16x32_bf16(Bt[n][k], At[m][k], acc[ai][bj][m][n], 0, 0, 0); __builtin_amdgcn_s_setprio(0); } while (0)
; #define PG8_WAIT_V(n) asm volatile("s_waitcnt vmcnt(" #n ")" ::: "memory")
; #define PG8_WAIT_L(n) asm volatile("s_waitcnt lgkmcnt(" #n ")" ::: "memory")
; #define PG8_BAR __builtin_amdgcn_s_barrier()
; #define PG8_SCHED __builtin_amdgcn_sched_barrier(0)
; template <class Epi, class Sched, bool ALIGN_EPI = false, bool SP2 = false>
; __device__ __forceinline__ void gemm_phase(PG8_LAS unsigned char* lds, const Gemm g, const Sched& S, const Epi& E) {
;     ...
;             PG8_LDA(At, 0, 1); PG8_STAGE(PG8_SB(0, 0), b2, voffB); PG8_STAGE(PG8_SB(0, 1), b2 + hstep, voffB); PG8_STAGE(PG8_SA(0, 0), a2, voffA);
;             PG8_WAIT_V(8); PG8_WAIT_L(0); PG8_BAR; PG8_MMA(1, 0, At, B0); PG8_MMA(1, 1, At, B1); PG8_BAR; PG8_SCHED;
	s_mov_b32 m0, s57
	s_nop 0
	global_load_lds_dwordx4 v160, s[62:63]
	s_mov_b32 m0, s65
	s_nop 0
	global_load_lds_dwordx4 v164, s[62:63]
	s_waitcnt vmcnt(8)
	s_waitcnt lgkmcnt(0)
	s_setprio 1
	s_barrier

; #define PG8_MMA(ai, bj, At, Bt) do { __builtin_amdgcn_s_setprio(1); _Pragma("unroll") for (int m = 0; m < 4; ++m) _Pragma("unroll") for (int n = 0; n < 2; ++n) _Pragma("unroll") for (int k = 0; k < 2; ++k) \
;         acc[ai][bj][m][n] = __builtin_amdgcn_mfma_f32_16x16x32_bf16(Bt[n][k], At[m][k], acc[ai][bj][m][n], 0, 0, 0); __builtin_amdgcn_s_setprio(0); } while (0)
; #define PG8_WAIT_V(n) asm volatile("s_waitcnt vmcnt(" #n ")" ::: "memory")
; #define PG8_WAIT_L(n) asm volatile("s_waitcnt lgkmcnt(" #n ")" ::: "memory")
; #define PG8_BAR __builtin_amdgcn_s_barrier()
; #define PG8_SCHED __builtin_amdgcn_sched_barrier(0)
; template <class Epi, class Sched, bool ALIGN_EPI = false, bool SP2 = false>
; __device__ __forceinline__ void gemm_phase(PG8_LAS unsigned char* lds, const Gemm g, const Sched& S, const Epi& E) {
;     ...
;             PG8_WAIT_V(8); PG8_WAIT_L(0); PG8_BAR; PG8_MMA(1, 0, At, B0); PG8_MMA(1, 1, At, B1); PG8_BAR; PG8_SCHED;
	v_mfma_f32_16x16x32_bf16 v[60:63], v[64:67], v[176:179], v[60:63]
	v_mfma_f32_16x16x32_bf16 v[56:59], v[72:75], v[176:179], v[56:59]
	v_mfma_f32_16x16x32_bf16 v[44:47], v[64:67], v[184:187], v[44:47]
	v_mfma_f32_16x16x32_bf16 v[40:43], v[72:75], v[184:187], v[40:43]
	v_mfma_f32_16x16x32_bf16 v[28:31], v[64:67], v[192:195], v[28:31]
	v_mfma_f32_16x16x32_bf16 v[24:27], v[72:75], v[192:195], v[24:27]
	v_mfma_f32_16x16x32_bf16 v[12:15], v[64:67], v[200:203], v[12:15]
	v_mfma_f32_16x16x32_bf16 v[8:11], v[72:75], v[200:203], v[8:11]
	v_mfma_f32_16x16x32_bf16 v[60:63], v[68:71], v[180:183], v[60:63]
	v_mfma_f32_16x16x32_bf16 v[56:59], v[76:79], v[180:183], v[56:59]
	v_mfma_f32_16x16x32_bf16 v[44:47], v[68:71], v[188:191], v[44:47]
	v_mfma_f32_16x16x32_bf16 v[40:43], v[76:79], v[188:191], v[40:43]
	v_mfma_f32_16x16x32_bf16 v[28:31], v[68:71], v[196:199], v[28:31]
	v_mfma_f32_16x16x32_bf16 v[24:27], v[76:79], v[196:199], v[24:27]
	v_mfma_f32_16x16x32_bf16 v[12:15], v[68:71], v[204:207], v[12:15]
	v_mfma_f32_16x16x32_bf16 v[8:11], v[76:79], v[204:207], v[8:11]


; #define PG8_MMA(ai, bj, At, Bt) do { __builtin_amdgcn_s_setprio(1); _Pragma("unroll") for (int m = 0; m < 4; ++m) _Pragma("unroll") for (int n = 0; n < 2; ++n) _Pragma("unroll") for (int k = 0; k < 2; ++k) \
;         acc[ai][bj][m][n] = __builtin_amdgcn_mfma_f32_16x16x32_bf16(Bt[n][k], At[m][k], acc[ai][bj][m][n], 0, 0, 0); __builtin_amdgcn_s_setprio(0); } while (0)
; #define PG8_WAIT_V(n) asm volatile("s_waitcnt vmcnt(" #n ")" ::: "memory")
; #define PG8_WAIT_L(n) asm volatile("s_waitcnt lgkmcnt(" #n ")" ::: "memory")
; #define PG8_BAR __builtin_amdgcn_s_barrier()
; #define PG8_SCHED __builtin_amdgcn_sched_barrier(0)
; template <class Epi, class Sched, bool ALIGN_EPI = false, bool SP2 = false>
; __device__ __forceinline__ void gemm_phase(PG8_LAS unsigned char* lds, const Gemm g, const Sched& S, const Epi& E) {
;     ...
;             PG8_WAIT_V(8); PG8_WAIT_L(0); PG8_BAR; PG8_MMA(1, 0, At, B0); PG8_MMA(1, 1, At, B1); PG8_BAR; PG8_SCHED;
	v_mfma_f32_16x16x32_bf16 v[52:55], v[144:147], v[176:179], v[52:55]
	v_mfma_f32_16x16x32_bf16 v[48:51], v[152:155], v[176:179], v[48:51]
	v_mfma_f32_16x16x32_bf16 v[36:39], v[144:147], v[184:187], v[36:39]
	v_mfma_f32_16x16x32_bf16 v[32:35], v[152:155], v[184:187], v[32:35]
	v_mfma_f32_16x16x32_bf16 v[20:23], v[144:147], v[192:195], v[20:23]
	v_mfma_f32_16x16x32_bf16 v[16:19], v[152:155], v[192:195], v[16:19]
	v_mfma_f32_16x16x32_bf16 v[4:7], v[144:147], v[200:203], v[4:7]
	v_mfma_f32_16x16x32_bf16 v[0:3], v[152:155], v[200:203], v[0:3]
	v_mfma_f32_16x16x32_bf16 v[52:55], v[148:151], v[180:183], v[52:55]
	v_mfma_f32_16x16x32_bf16 v[48:51], v[156:159], v[180:183], v[48:51]
	v_mfma_f32_16x16x32_bf16 v[36:39], v[148:151], v[188:191], v[36:39]
	v_mfma_f32_16x16x32_bf16 v[32:35], v[156:159], v[188:191], v[32:35]
	v_mfma_f32_16x16x32_bf16 v[20:23], v[148:151], v[196:199], v[20:23]
	v_mfma_f32_16x16x32_bf16 v[16:19], v[156:159], v[196:199], v[16:19]
	v_mfma_f32_16x16x32_bf16 v[4:7], v[148:151], v[204:207], v[4:7]
	v_mfma_f32_16x16x32_bf16 v[0:3], v[156:159], v[204:207], v[0:3]
	s_setprio 0
	s_barrier
	s_add_i32 s82, 0, 0x18000
	s_add_i32 s83, 0, 0x1c000


; #define PG8_STAGE(bufoff, gbase, voff) do { _Pragma("unroll") for (int _i = 0; _i < 2; ++_i) \
;         __builtin_amdgcn_global_load_lds((const unsigned*)((const char*)(gbase) + (voff)[_i]), (PG8_LAS unsigned*)(lds + (bufoff) + ldsw + _i * 8192), 16, 0, 0); } while (0)
; #define PG8_LDA(dst, b, h) do { _Pragma("unroll") for (int m = 0; m < 4; ++m) _Pragma("unroll") for (int k = 0; k < 2; ++k) dst[m][k] = *(const PG8_LAS bf16x8*)(lds + PG8_SA(b, h) + aoff + m * 2048 + k * 1024); } while (0)
; #define PG8_LDB(dst, b, h) do { _Pragma("unroll") for (int n = 0; n < 2; ++n) _Pragma("unroll") for (int k = 0; k < 2; ++k) dst[n][k] = *(const PG8_LAS bf16x8*)(lds + PG8_SB(b, h) + boff + n * 2048 + k * 1024); } while (0)
; #define PG8_SCHED __builtin_amdgcn_sched_barrier(0)
; template <class Epi, class Sched, bool ALIGN_EPI = false, bool SP2 = false>
; __device__ __forceinline__ void gemm_phase(PG8_LAS unsigned char* lds, const Gemm g, const Sched& S, const Epi& E) {
;     ...
;             PG8_LDB(B0, 1, 0); PG8_LDB(B1, 1, 1); PG8_SCHED; PG8_LDA(At, 1, 0); PG8_STAGE(PG8_SA(0, 1), a2 + hstep, voffA);
	ds_read_b128 v[64:67], v254
	ds_read_b128 v[68:71], v254 offset:1024
	ds_read_b128 v[72:75], v254 offset:2048
	ds_read_b128 v[76:79], v254 offset:3072
	ds_read_b128 v[144:147], v255
	ds_read_b128 v[148:151], v255 offset:1024
	ds_read_b128 v[152:155], v255 offset:2048
	ds_read_b128 v[156:159], v255 offset:3072
	s_add_u32 s62, s62, 0x80000
	s_addc_u32 s63, s63, 0
	s_mov_b32 m0, s67

; #define PG8_STAGE(bufoff, gbase, voff) do { _Pragma("unroll") for (int _i = 0; _i < 2; ++_i) \
;         __builtin_amdgcn_global_load_lds((const unsigned*)((const char*)(gbase) + (voff)[_i]), (PG8_LAS unsigned*)(lds + (bufoff) + ldsw + _i * 8192), 16, 0, 0); } while (0)
; #define PG8_LDA(dst, b, h) do { _Pragma("unroll") for (int m = 0; m < 4; ++m) _Pragma("unroll") for (int k = 0; k < 2; ++k) dst[m][k] = *(const PG8_LAS bf16x8*)(lds + PG8_SA(b, h) + aoff + m * 2048 + k * 1024); } while (0)
; #define PG8_LDB(dst, b, h) do { _Pragma("unroll") for (int n = 0; n < 2; ++n) _Pragma("unroll") for (int k = 0; k < 2; ++k) dst[n][k] = *(const PG8_LAS bf16x8*)(lds + PG8_SB(b, h) + boff + n * 2048 + k * 1024); } while (0)
; #define PG8_SCHED __builtin_amdgcn_sched_barrier(0)
; template <class Epi, class Sched, bool ALIGN_EPI = false, bool SP2 = false>
; __device__ __forceinline__ void gemm_phase(PG8_LAS unsigned char* lds, const Gemm g, const Sched& S, const Epi& E) {
;     ...
;             PG8_LDB(B0, 1, 0); PG8_LDB(B1, 1, 1); PG8_SCHED; PG8_LDA(At, 1, 0); PG8_STAGE(PG8_SA(0, 1), a2 + hstep, voffA);
	ds_read_b128 v[176:179], v213 offset:32768
	ds_read_b128 v[180:183], v213 offset:33792
	ds_read_b128 v[184:187], v213 offset:34816
	ds_read_b128 v[188:191], v213 offset:35840
	ds_read_b128 v[192:195], v213 offset:36864
	ds_read_b128 v[196:199], v213 offset:37888
	ds_read_b128 v[200:203], v213 offset:38912
	ds_read_b128 v[204:207], v213 offset:39936
	global_load_lds_dwordx4 v160, s[62:63]

; #define PG8_STAGE(bufoff, gbase, voff) do { _Pragma("unroll") for (int _i = 0; _i < 2; ++_i) \
;         __builtin_amdgcn_global_load_lds((const unsigned*)((const char*)(gbase) + (voff)[_i]), (PG8_LAS unsigned*)(lds + (bufoff) + ldsw + _i * 8192), 16, 0, 0); } while (0)
; #define PG8_LDA(dst, b, h) do { _Pragma("unroll") for (int m = 0; m < 4; ++m) _Pragma("unroll") for (int k = 0; k < 2; ++k) dst[m][k] = *(const PG8_LAS bf16x8*)(lds + PG8_SA(b, h) + aoff + m * 2048 + k * 1024); } while (0)
; #define PG8_LDB(dst, b, h) do { _Pragma("unroll") for (int n = 0; n < 2; ++n) _Pragma("unroll") for (int k = 0; k < 2; ++k) dst[n][k] = *(const PG8_LAS bf16x8*)(lds + PG8_SB(b, h) + boff + n * 2048 + k * 1024); } while (0)
; #define PG8_MMA(ai, bj, At, Bt) do { __builtin_amdgcn_s_setprio(1); _Pragma("unroll") for (int m = 0; m < 4; ++m) _Pragma("unroll") for (int n = 0; n < 2; ++n) _Pragma("unroll") for (int k = 0; k < 2; ++k) \
;         acc[ai][bj][m][n] = __builtin_amdgcn_mfma_f32_16x16x32_bf16(Bt[n][k], At[m][k], acc[ai][bj][m][n], 0, 0, 0); __builtin_amdgcn_s_setprio(0); } while (0)
; #define PG8_WAIT_V(n) asm volatile("s_waitcnt vmcnt(" #n ")" ::: "memory")
; #define PG8_WAIT_L(n) asm volatile("s_waitcnt lgkmcnt(" #n ")" ::: "memory")
; #define PG8_BAR __builtin_amdgcn_s_barrier()
; #define PG8_SCHED __builtin_amdgcn_sched_barrier(0)
; template <class Epi, class Sched, bool ALIGN_EPI = false, bool SP2 = false>
; __device__ __forceinline__ void gemm_phase(PG8_LAS unsigned char* lds, const Gemm g, const Sched& S, const Epi& E) {
;     ...
;             PG8_LDB(B0, 1, 0); PG8_LDB(B1, 1, 1); PG8_SCHED; PG8_LDA(At, 1, 0); PG8_STAGE(PG8_SA(0, 1), a2 + hstep, voffA);
;             PG8_WAIT_V(8); PG8_WAIT_L(0); PG8_BAR; PG8_MMA(0, 0, At, B0); PG8_MMA(0, 1, At, B1); PG8_BAR; PG8_SCHED;
	s_mov_b32 m0, s68
	s_nop 0
	global_load_lds_dwordx4 v164, s[62:63]
	s_waitcnt vmcnt(8)
	s_waitcnt lgkmcnt(0)
	s_setprio 1
	s_barrier

; #define PG8_MMA(ai, bj, At, Bt) do { __builtin_amdgcn_s_setprio(1); _Pragma("unroll") for (int m = 0; m < 4; ++m) _Pragma("unroll") for (int n = 0; n < 2; ++n) _Pragma("unroll") for (int k = 0; k < 2; ++k) \
;         acc[ai][bj][m][n] = __builtin_amdgcn_mfma_f32_16x16x32_bf16(Bt[n][k], At[m][k], acc[ai][bj][m][n], 0, 0, 0); __builtin_amdgcn_s_setprio(0); } while (0)
; #define PG8_WAIT_V(n) asm volatile("s_waitcnt vmcnt(" #n ")" ::: "memory")
; #define PG8_WAIT_L(n) asm volatile("s_waitcnt lgkmcnt(" #n ")" ::: "memory")
; #define PG8_BAR __builtin_amdgcn_s_barrier()
; #define PG8_SCHED __builtin_amdgcn_sched_barrier(0)
; template <class Epi, class Sched, bool ALIGN_EPI = false, bool SP2 = false>
; __device__ __forceinline__ void gemm_phase(PG8_LAS unsigned char* lds, const Gemm g, const Sched& S, const Epi& E) {
;     ...
;             PG8_WAIT_V(8); PG8_WAIT_L(0); PG8_BAR; PG8_MMA(0, 0, At, B0); PG8_MMA(0, 1, At, B1); PG8_BAR; PG8_SCHED;
	v_mfma_f32_16x16x32_bf16 v[140:143], v[64:67], v[176:179], v[140:143]
	v_mfma_f32_16x16x32_bf16 v[136:139], v[72:75], v[176:179], v[136:139]
	v_mfma_f32_16x16x32_bf16 v[124:127], v[64:67], v[184:187], v[124:127]
	v_mfma_f32_16x16x32_bf16 v[120:123], v[72:75], v[184:187], v[120:123]
	v_mfma_f32_16x16x32_bf16 v[108:111], v[64:67], v[192:195], v[108:111]
	v_mfma_f32_16x16x32_bf16 v[104:107], v[72:75], v[192:195], v[104:107]
	v_mfma_f32_16x16x32_bf16 v[92:95], v[64:67], v[200:203], v[92:95]
	v_mfma_f32_16x16x32_bf16 v[88:91], v[72:75], v[200:203], v[88:91]
	v_mfma_f32_16x16x32_bf16 v[140:143], v[68:71], v[180:183], v[140:143]
	v_mfma_f32_16x16x32_bf16 v[136:139], v[76:79], v[180:183], v[136:139]
	v_mfma_f32_16x16x32_bf16 v[124:127], v[68:71], v[188:191], v[124:127]
	v_mfma_f32_16x16x32_bf16 v[120:123], v[76:79], v[188:191], v[120:123]
	v_mfma_f32_16x16x32_bf16 v[108:111], v[68:71], v[196:199], v[108:111]
	v_mfma_f32_16x16x32_bf16 v[104:107], v[76:79], v[196:199], v[104:107]
	v_mfma_f32_16x16x32_bf16 v[92:95], v[68:71], v[204:207], v[92:95]
	v_mfma_f32_16x16x32_bf16 v[88:91], v[76:79], v[204:207], v[88:91]


; #define PG8_MMA(ai, bj, At, Bt) do { __builtin_amdgcn_s_setprio(1); _Pragma("unroll") for (int m = 0; m < 4; ++m) _Pragma("unroll") for (int n = 0; n < 2; ++n) _Pragma("unroll") for (int k = 0; k < 2; ++k) \
;         acc[ai][bj][m][n] = __builtin_amdgcn_mfma_f32_16x16x32_bf16(Bt[n][k], At[m][k], acc[ai][bj][m][n], 0, 0, 0); __builtin_amdgcn_s_setprio(0); } while (0)
; #define PG8_WAIT_V(n) asm volatile("s_waitcnt vmcnt(" #n ")" ::: "memory")
; #define PG8_WAIT_L(n) asm volatile("s_waitcnt lgkmcnt(" #n ")" ::: "memory")
; #define PG8_BAR __builtin_amdgcn_s_barrier()
; #define PG8_SCHED __builtin_amdgcn_sched_barrier(0)
; template <class Epi, class Sched, bool ALIGN_EPI = false, bool SP2 = false>
; __device__ __forceinline__ void gemm_phase(PG8_LAS unsigned char* lds, const Gemm g, const Sched& S, const Epi& E) {
;     ...
;             PG8_WAIT_V(8); PG8_WAIT_L(0); PG8_BAR; PG8_MMA(0, 0, At, B0); PG8_MMA(0, 1, At, B1); PG8_BAR; PG8_SCHED;
	v_mfma_f32_16x16x32_bf16 v[132:135], v[144:147], v[176:179], v[132:135]
	v_mfma_f32_16x16x32_bf16 v[128:131], v[152:155], v[176:179], v[128:131]
	v_mfma_f32_16x16x32_bf16 v[116:119], v[144:147], v[184:187], v[116:119]
	v_mfma_f32_16x16x32_bf16 v[112:115], v[152:155], v[184:187], v[112:115]
	v_mfma_f32_16x16x32_bf16 v[100:103], v[144:147], v[192:195], v[100:103]
	v_mfma_f32_16x16x32_bf16 v[96:99], v[152:155], v[192:195], v[96:99]
	v_mfma_f32_16x16x32_bf16 v[84:87], v[144:147], v[200:203], v[84:87]
	v_mfma_f32_16x16x32_bf16 v[80:83], v[152:155], v[200:203], v[80:83]
	v_mfma_f32_16x16x32_bf16 v[132:135], v[148:151], v[180:183], v[132:135]
	v_mfma_f32_16x16x32_bf16 v[128:131], v[156:159], v[180:183], v[128:131]
	v_mfma_f32_16x16x32_bf16 v[116:119], v[148:151], v[188:191], v[116:119]
	v_mfma_f32_16x16x32_bf16 v[112:115], v[156:159], v[188:191], v[112:115]
	v_mfma_f32_16x16x32_bf16 v[100:103], v[148:151], v[196:199], v[100:103]
	v_mfma_f32_16x16x32_bf16 v[96:99], v[156:159], v[196:199], v[96:99]
	v_mfma_f32_16x16x32_bf16 v[84:87], v[148:151], v[204:207], v[84:87]
	v_mfma_f32_16x16x32_bf16 v[80:83], v[156:159], v[204:207], v[80:83]
	s_setprio 0
	s_barrier
	s_add_i32 s62, s82, s64

; #define PG8_STAGE(bufoff, gbase, voff) do { _Pragma("unroll") for (int _i = 0; _i < 2; ++_i) \
;         __builtin_amdgcn_global_load_lds((const unsigned*)((const char*)(gbase) + (voff)[_i]), (PG8_LAS unsigned*)(lds + (bufoff) + ldsw + _i * 8192), 16, 0, 0); } while (0)
; #define PG8_LDA(dst, b, h) do { _Pragma("unroll") for (int m = 0; m < 4; ++m) _Pragma("unroll") for (int k = 0; k < 2; ++k) dst[m][k] = *(const PG8_LAS bf16x8*)(lds + PG8_SA(b, h) + aoff + m * 2048 + k * 1024); } while (0)
; template <class Epi, class Sched, bool ALIGN_EPI = false, bool SP2 = false>
; __device__ __forceinline__ void gemm_phase(PG8_LAS unsigned char* lds, const Gemm g, const Sched& S, const Epi& E) {
;     ...
;             PG8_LDA(At, 1, 1); PG8_STAGE(PG8_SB(1, 0), b3, voffB); PG8_STAGE(PG8_SB(1, 1), b3 + hstep, voffB); PG8_STAGE(PG8_SA(1, 0), a3, voffA);
	s_mov_b32 m0, s62
	ds_read_b128 v[176:179], v213 offset:49152
	ds_read_b128 v[180:183], v213 offset:50176
	ds_read_b128 v[184:187], v213 offset:51200
	ds_read_b128 v[188:191], v213 offset:52224
	ds_read_b128 v[192:195], v213 offset:53248
	ds_read_b128 v[196:199], v213 offset:54272
	ds_read_b128 v[200:203], v213 offset:55296
	ds_read_b128 v[204:207], v213 offset:56320
	global_load_lds_dwordx4 v250, s[96:97]
	s_add_i32 m0, s62, 0x2000
	s_add_u32 s60, s60, 0x80080

; #define PG8_STAGE(bufoff, gbase, voff) do { _Pragma("unroll") for (int _i = 0; _i < 2; ++_i) \
;         __builtin_amdgcn_global_load_lds((const unsigned*)((const char*)(gbase) + (voff)[_i]), (PG8_LAS unsigned*)(lds + (bufoff) + ldsw + _i * 8192), 16, 0, 0); } while (0)
; #define PG8_LDA(dst, b, h) do { _Pragma("unroll") for (int m = 0; m < 4; ++m) _Pragma("unroll") for (int k = 0; k < 2; ++k) dst[m][k] = *(const PG8_LAS bf16x8*)(lds + PG8_SA(b, h) + aoff + m * 2048 + k * 1024); } while (0)
; template <class Epi, class Sched, bool ALIGN_EPI = false, bool SP2 = false>
; __device__ __forceinline__ void gemm_phase(PG8_LAS unsigned char* lds, const Gemm g, const Sched& S, const Epi& E) {
;     ...
;             PG8_LDA(At, 1, 1); PG8_STAGE(PG8_SB(1, 0), b3, voffB); PG8_STAGE(PG8_SB(1, 1), b3 + hstep, voffB); PG8_STAGE(PG8_SA(1, 0), a3, voffA);
	s_addc_u32 s61, s61, 0
	s_add_i32 s62, s83, s64
	global_load_lds_dwordx4 v251, s[96:97]

; #define PG8_STAGE(bufoff, gbase, voff) do { _Pragma("unroll") for (int _i = 0; _i < 2; ++_i) \
;         __builtin_amdgcn_global_load_lds((const unsigned*)((const char*)(gbase) + (voff)[_i]), (PG8_LAS unsigned*)(lds + (bufoff) + ldsw + _i * 8192), 16, 0, 0); } while (0)
; #define PG8_LDA(dst, b, h) do { _Pragma("unroll") for (int m = 0; m < 4; ++m) _Pragma("unroll") for (int k = 0; k < 2; ++k) dst[m][k] = *(const PG8_LAS bf16x8*)(lds + PG8_SA(b, h) + aoff + m * 2048 + k * 1024); } while (0)
; template <class Epi, class Sched, bool ALIGN_EPI = false, bool SP2 = false>
; __device__ __forceinline__ void gemm_phase(PG8_LAS unsigned char* lds, const Gemm g, const Sched& S, const Epi& E) {
;     ...
;             PG8_LDA(At, 1, 1); PG8_STAGE(PG8_SB(1, 0), b3, voffB); PG8_STAGE(PG8_SB(1, 1), b3 + hstep, voffB); PG8_STAGE(PG8_SA(1, 0), a3, voffA);
	s_mov_b32 m0, s62
	s_nop 0
	global_load_lds_dwordx4 v162, s[60:61]

; #define PG8_STAGE(bufoff, gbase, voff) do { _Pragma("unroll") for (int _i = 0; _i < 2; ++_i) \
;         __builtin_amdgcn_global_load_lds((const unsigned*)((const char*)(gbase) + (voff)[_i]), (PG8_LAS unsigned*)(lds + (bufoff) + ldsw + _i * 8192), 16, 0, 0); } while (0)
; #define PG8_LDA(dst, b, h) do { _Pragma("unroll") for (int m = 0; m < 4; ++m) _Pragma("unroll") for (int k = 0; k < 2; ++k) dst[m][k] = *(const PG8_LAS bf16x8*)(lds + PG8_SA(b, h) + aoff + m * 2048 + k * 1024); } while (0)
; template <class Epi, class Sched, bool ALIGN_EPI = false, bool SP2 = false>
; __device__ __forceinline__ void gemm_phase(PG8_LAS unsigned char* lds, const Gemm g, const Sched& S, const Epi& E) {
;     ...
;             PG8_LDA(At, 1, 1); PG8_STAGE(PG8_SB(1, 0), b3, voffB); PG8_STAGE(PG8_SB(1, 1), b3 + hstep, voffB); PG8_STAGE(PG8_SA(1, 0), a3, voffA);
	s_add_i32 m0, s62, 0x2000
	s_nop 0
	global_load_lds_dwordx4 v166, s[60:61]

; #define PG8_STAGE(bufoff, gbase, voff) do { _Pragma("unroll") for (int _i = 0; _i < 2; ++_i) \
;         __builtin_amdgcn_global_load_lds((const unsigned*)((const char*)(gbase) + (voff)[_i]), (PG8_LAS unsigned*)(lds + (bufoff) + ldsw + _i * 8192), 16, 0, 0); } while (0)
; #define PG8_LDA(dst, b, h) do { _Pragma("unroll") for (int m = 0; m < 4; ++m) _Pragma("unroll") for (int k = 0; k < 2; ++k) dst[m][k] = *(const PG8_LAS bf16x8*)(lds + PG8_SA(b, h) + aoff + m * 2048 + k * 1024); } while (0)
; template <class Epi, class Sched, bool ALIGN_EPI = false, bool SP2 = false>
; __device__ __forceinline__ void gemm_phase(PG8_LAS unsigned char* lds, const Gemm g, const Sched& S, const Epi& E) {
;     ...
;             PG8_LDA(At, 1, 1); PG8_STAGE(PG8_SB(1, 0), b3, voffB); PG8_STAGE(PG8_SB(1, 1), b3 + hstep, voffB); PG8_STAGE(PG8_SA(1, 0), a3, voffA);
	s_mov_b32 m0, s70
	s_nop 0
	global_load_lds_dwordx4 v252, s[98:99]

; #define PG8_STAGE(bufoff, gbase, voff) do { _Pragma("unroll") for (int _i = 0; _i < 2; ++_i) \
;         __builtin_amdgcn_global_load_lds((const unsigned*)((const char*)(gbase) + (voff)[_i]), (PG8_LAS unsigned*)(lds + (bufoff) + ldsw + _i * 8192), 16, 0, 0); } while (0)
; #define PG8_LDA(dst, b, h) do { _Pragma("unroll") for (int m = 0; m < 4; ++m) _Pragma("unroll") for (int k = 0; k < 2; ++k) dst[m][k] = *(const PG8_LAS bf16x8*)(lds + PG8_SA(b, h) + aoff + m * 2048 + k * 1024); } while (0)
; #define PG8_MMA(ai, bj, At, Bt) do { __builtin_amdgcn_s_setprio(1); _Pragma("unroll") for (int m = 0; m < 4; ++m) _Pragma("unroll") for (int n = 0; n < 2; ++n) _Pragma("unroll") for (int k = 0; k < 2; ++k) \
;         acc[ai][bj][m][n] = __builtin_amdgcn_mfma_f32_16x16x32_bf16(Bt[n][k], At[m][k], acc[ai][bj][m][n], 0, 0, 0); __builtin_amdgcn_s_setprio(0); } while (0)
; #define PG8_WAIT_V(n) asm volatile("s_waitcnt vmcnt(" #n ")" ::: "memory")
; #define PG8_WAIT_L(n) asm volatile("s_waitcnt lgkmcnt(" #n ")" ::: "memory")
; #define PG8_BAR __builtin_amdgcn_s_barrier()
; #define PG8_SCHED __builtin_amdgcn_sched_barrier(0)
; template <class Epi, class Sched, bool ALIGN_EPI = false, bool SP2 = false>
; __device__ __forceinline__ void gemm_phase(PG8_LAS unsigned char* lds, const Gemm g, const Sched& S, const Epi& E) {
;     ...
;             PG8_LDA(At, 1, 1); PG8_STAGE(PG8_SB(1, 0), b3, voffB); PG8_STAGE(PG8_SB(1, 1), b3 + hstep, voffB); PG8_STAGE(PG8_SA(1, 0), a3, voffA);
;             PG8_WAIT_V(8); PG8_WAIT_L(0); PG8_BAR; PG8_MMA(1, 0, At, B0); PG8_MMA(1, 1, At, B1); PG8_BAR; PG8_SCHED;
	s_mov_b32 m0, s71
	s_nop 0
	global_load_lds_dwordx4 v253, s[98:99]
	s_waitcnt vmcnt(8)
	s_waitcnt lgkmcnt(0)
	s_setprio 1
	s_barrier

; #define PG8_MMA(ai, bj, At, Bt) do { __builtin_amdgcn_s_setprio(1); _Pragma("unroll") for (int m = 0; m < 4; ++m) _Pragma("unroll") for (int n = 0; n < 2; ++n) _Pragma("unroll") for (int k = 0; k < 2; ++k) \
;         acc[ai][bj][m][n] = __builtin_amdgcn_mfma_f32_16x16x32_bf16(Bt[n][k], At[m][k], acc[ai][bj][m][n], 0, 0, 0); __builtin_amdgcn_s_setprio(0); } while (0)
; #define PG8_WAIT_V(n) asm volatile("s_waitcnt vmcnt(" #n ")" ::: "memory")
; #define PG8_WAIT_L(n) asm volatile("s_waitcnt lgkmcnt(" #n ")" ::: "memory")
; #define PG8_BAR __builtin_amdgcn_s_barrier()
; #define PG8_SCHED __builtin_amdgcn_sched_barrier(0)
; template <class Epi, class Sched, bool ALIGN_EPI = false, bool SP2 = false>
; __device__ __forceinline__ void gemm_phase(PG8_LAS unsigned char* lds, const Gemm g, const Sched& S, const Epi& E) {
;     ...
;             PG8_WAIT_V(8); PG8_WAIT_L(0); PG8_BAR; PG8_MMA(1, 0, At, B0); PG8_MMA(1, 1, At, B1); PG8_BAR; PG8_SCHED;
	v_mfma_f32_16x16x32_bf16 v[60:63], v[64:67], v[176:179], v[60:63]
	v_mfma_f32_16x16x32_bf16 v[56:59], v[72:75], v[176:179], v[56:59]
	v_mfma_f32_16x16x32_bf16 v[44:47], v[64:67], v[184:187], v[44:47]
	v_mfma_f32_16x16x32_bf16 v[40:43], v[72:75], v[184:187], v[40:43]
	v_mfma_f32_16x16x32_bf16 v[28:31], v[64:67], v[192:195], v[28:31]
	v_mfma_f32_16x16x32_bf16 v[24:27], v[72:75], v[192:195], v[24:27]
	v_mfma_f32_16x16x32_bf16 v[12:15], v[64:67], v[200:203], v[12:15]
	v_mfma_f32_16x16x32_bf16 v[8:11], v[72:75], v[200:203], v[8:11]
	v_mfma_f32_16x16x32_bf16 v[60:63], v[68:71], v[180:183], v[60:63]
	v_mfma_f32_16x16x32_bf16 v[56:59], v[76:79], v[180:183], v[56:59]
	v_mfma_f32_16x16x32_bf16 v[44:47], v[68:71], v[188:191], v[44:47]
	v_mfma_f32_16x16x32_bf16 v[40:43], v[76:79], v[188:191], v[40:43]
	v_mfma_f32_16x16x32_bf16 v[28:31], v[68:71], v[196:199], v[28:31]
	v_mfma_f32_16x16x32_bf16 v[24:27], v[76:79], v[196:199], v[24:27]
	v_mfma_f32_16x16x32_bf16 v[12:15], v[68:71], v[204:207], v[12:15]
	v_mfma_f32_16x16x32_bf16 v[8:11], v[76:79], v[204:207], v[8:11]


; #define PG8_MMA(ai, bj, At, Bt) do { __builtin_amdgcn_s_setprio(1); _Pragma("unroll") for (int m = 0; m < 4; ++m) _Pragma("unroll") for (int n = 0; n < 2; ++n) _Pragma("unroll") for (int k = 0; k < 2; ++k) \
;         acc[ai][bj][m][n] = __builtin_amdgcn_mfma_f32_16x16x32_bf16(Bt[n][k], At[m][k], acc[ai][bj][m][n], 0, 0, 0); __builtin_amdgcn_s_setprio(0); } while (0)
; #define PG8_WAIT_V(n) asm volatile("s_waitcnt vmcnt(" #n ")" ::: "memory")
; #define PG8_WAIT_L(n) asm volatile("s_waitcnt lgkmcnt(" #n ")" ::: "memory")
; #define PG8_BAR __builtin_amdgcn_s_barrier()
; #define PG8_SCHED __builtin_amdgcn_sched_barrier(0)
; template <class Epi, class Sched, bool ALIGN_EPI = false, bool SP2 = false>
; __device__ __forceinline__ void gemm_phase(PG8_LAS unsigned char* lds, const Gemm g, const Sched& S, const Epi& E) {
;     ...
;         for (int t = 0; t < nt; t += 2) {
;     ...
;             PG8_WAIT_V(8); PG8_WAIT_L(0); PG8_BAR; PG8_MMA(1, 0, At, B0); PG8_MMA(1, 1, At, B1); PG8_BAR; PG8_SCHED;
	v_mfma_f32_16x16x32_bf16 v[52:55], v[144:147], v[176:179], v[52:55]
	v_mfma_f32_16x16x32_bf16 v[48:51], v[152:155], v[176:179], v[48:51]
	v_mfma_f32_16x16x32_bf16 v[36:39], v[144:147], v[184:187], v[36:39]
	v_mfma_f32_16x16x32_bf16 v[32:35], v[152:155], v[184:187], v[32:35]
	v_mfma_f32_16x16x32_bf16 v[20:23], v[144:147], v[192:195], v[20:23]
	v_mfma_f32_16x16x32_bf16 v[16:19], v[152:155], v[192:195], v[16:19]
	v_mfma_f32_16x16x32_bf16 v[4:7], v[144:147], v[200:203], v[4:7]
	v_mfma_f32_16x16x32_bf16 v[0:3], v[152:155], v[200:203], v[0:3]
	v_mfma_f32_16x16x32_bf16 v[52:55], v[148:151], v[180:183], v[52:55]
	v_mfma_f32_16x16x32_bf16 v[48:51], v[156:159], v[180:183], v[48:51]
	v_mfma_f32_16x16x32_bf16 v[36:39], v[148:151], v[188:191], v[36:39]
	v_mfma_f32_16x16x32_bf16 v[32:35], v[156:159], v[188:191], v[32:35]
	v_mfma_f32_16x16x32_bf16 v[20:23], v[148:151], v[196:199], v[20:23]
	v_mfma_f32_16x16x32_bf16 v[16:19], v[156:159], v[196:199], v[16:19]
	v_mfma_f32_16x16x32_bf16 v[4:7], v[148:151], v[204:207], v[4:7]
	v_mfma_f32_16x16x32_bf16 v[0:3], v[156:159], v[204:207], v[0:3]
	s_setprio 0
	s_add_i32 s81, s81, 2
	s_add_u32 s58, s58, 0x100
	s_addc_u32 s59, s59, 0
	s_add_u32 s79, s79, 0x100
	s_addc_u32 s80, s80, 0
	s_cmp_gt_u32 s81, 29
	s_barrier


; #define PG8_BAR __builtin_amdgcn_s_barrier()
; template <class Epi, class Sched, bool ALIGN_EPI = false, bool SP2 = false>
; __device__ __forceinline__ void gemm_phase(PG8_LAS unsigned char* lds, const Gemm g, const Sched& S, const Epi& E) {
;     ...
;         for (int t = 0; t < nt; t += 2) {
;     ...
;         if constexpr (ALIGN_EPI) { if (wr == 0) PG8_BAR; }
	s_cbranch_scc0 .LBB0_333
	s_and_b64 vcc, exec, s[42:43]
	s_cbranch_vccz .LBB0_336
	s_barrier

; #define PG8_STAGE(bufoff, gbase, voff) do { _Pragma("unroll") for (int _i = 0; _i < 2; ++_i) \
;         __builtin_amdgcn_global_load_lds((const unsigned*)((const char*)(gbase) + (voff)[_i]), (PG8_LAS unsigned*)(lds + (bufoff) + ldsw + _i * 8192), 16, 0, 0); } while (0)
; #define PG8_LDA(dst, b, h) do { _Pragma("unroll") for (int m = 0; m < 4; ++m) _Pragma("unroll") for (int k = 0; k < 2; ++k) dst[m][k] = *(const PG8_LAS bf16x8*)(lds + PG8_SA(b, h) + aoff + m * 2048 + k * 1024); } while (0)
; #define PG8_LDB(dst, b, h) do { _Pragma("unroll") for (int n = 0; n < 2; ++n) _Pragma("unroll") for (int k = 0; k < 2; ++k) dst[n][k] = *(const PG8_LAS bf16x8*)(lds + PG8_SB(b, h) + boff + n * 2048 + k * 1024); } while (0)
; #define PG8_SCHED __builtin_amdgcn_sched_barrier(0)
; template <class Epi, class Sched, bool ALIGN_EPI = false, bool SP2 = false>
; __device__ __forceinline__ void gemm_phase(PG8_LAS unsigned char* lds, const Gemm g, const Sched& S, const Epi& E) {
;     ...
;             const bool last = (t == nt - 2);
;             const char* a1 = cA + (size_t)(t + 1) * kstep;
;             const char* a2 = last ? nA : cA + (size_t)(t + 2) * kstep; const char* b2 = last ? nB : cB + (size_t)(t + 2) * kstep;
;             const char* a3 = a2 + kstep; const char* b3 = b2 + kstep;
;             if (last && has_next) S.a_ready(nxt);
;             if constexpr (SP2) {
;             PG8_LDB(B0, 0, 0); PG8_LDB(B1, 0, 1); PG8_SCHED; PG8_LDA(At, 0, 0); PG8_STAGE(PG8_SA(1, 1), a1 + hstep, voffA);
.LBB0_428:
	ds_read_b128 v[128:131], v201
	ds_read_b128 v[132:135], v201 offset:1024
	ds_read_b128 v[136:139], v201 offset:2048
	ds_read_b128 v[140:143], v201 offset:3072
	ds_read_b128 v[144:147], v205
	ds_read_b128 v[148:151], v205 offset:1024
	ds_read_b128 v[152:155], v205 offset:2048
	ds_read_b128 v[156:159], v205 offset:3072
	s_add_u32 s12, s10, 0xfff80080
	s_addc_u32 s13, s11, -1
	s_cmp_eq_u32 s85, 28
	s_cselect_b32 s61, s55, s13
	s_cselect_b32 s60, s81, s12
	s_cselect_b32 s13, s53, s84
	s_cselect_b32 s12, s82, s83

; #define PG8_STAGE(bufoff, gbase, voff) do { _Pragma("unroll") for (int _i = 0; _i < 2; ++_i) \
;         __builtin_amdgcn_global_load_lds((const unsigned*)((const char*)(gbase) + (voff)[_i]), (PG8_LAS unsigned*)(lds + (bufoff) + ldsw + _i * 8192), 16, 0, 0); } while (0)
; #define PG8_LDA(dst, b, h) do { _Pragma("unroll") for (int m = 0; m < 4; ++m) _Pragma("unroll") for (int k = 0; k < 2; ++k) dst[m][k] = *(const PG8_LAS bf16x8*)(lds + PG8_SA(b, h) + aoff + m * 2048 + k * 1024); } while (0)
; #define PG8_LDB(dst, b, h) do { _Pragma("unroll") for (int n = 0; n < 2; ++n) _Pragma("unroll") for (int k = 0; k < 2; ++k) dst[n][k] = *(const PG8_LAS bf16x8*)(lds + PG8_SB(b, h) + boff + n * 2048 + k * 1024); } while (0)
; #define PG8_SCHED __builtin_amdgcn_sched_barrier(0)
; template <class Epi, class Sched, bool ALIGN_EPI = false, bool SP2 = false>
; __device__ __forceinline__ void gemm_phase(PG8_LAS unsigned char* lds, const Gemm g, const Sched& S, const Epi& E) {
;     ...
;             PG8_LDB(B0, 0, 0); PG8_LDB(B1, 0, 1); PG8_SCHED; PG8_LDA(At, 0, 0); PG8_STAGE(PG8_SA(1, 1), a1 + hstep, voffA);
	s_add_i32 m0, s65, 0xc000
	ds_read_b128 v[176:179], v207
	ds_read_b128 v[184:187], v207 offset:1024
	ds_read_b128 v[190:193], v207 offset:2048
	ds_read_b128 v[210:213], v207 offset:3072
	ds_read_b128 v[214:217], v207 offset:4096
	ds_read_b128 v[218:221], v207 offset:5120
	ds_read_b128 v[222:225], v207 offset:6144
	ds_read_b128 v[226:229], v207 offset:7168
	global_load_lds_dwordx4 v168, s[10:11]

; #define PG8_STAGE(bufoff, gbase, voff) do { _Pragma("unroll") for (int _i = 0; _i < 2; ++_i) \
;         __builtin_amdgcn_global_load_lds((const unsigned*)((const char*)(gbase) + (voff)[_i]), (PG8_LAS unsigned*)(lds + (bufoff) + ldsw + _i * 8192), 16, 0, 0); } while (0)
; #define PG8_LDA(dst, b, h) do { _Pragma("unroll") for (int m = 0; m < 4; ++m) _Pragma("unroll") for (int k = 0; k < 2; ++k) dst[m][k] = *(const PG8_LAS bf16x8*)(lds + PG8_SA(b, h) + aoff + m * 2048 + k * 1024); } while (0)
; #define PG8_LDB(dst, b, h) do { _Pragma("unroll") for (int n = 0; n < 2; ++n) _Pragma("unroll") for (int k = 0; k < 2; ++k) dst[n][k] = *(const PG8_LAS bf16x8*)(lds + PG8_SB(b, h) + boff + n * 2048 + k * 1024); } while (0)
; #define PG8_MMA(ai, bj, At, Bt) do { __builtin_amdgcn_s_setprio(1); _Pragma("unroll") for (int m = 0; m < 4; ++m) _Pragma("unroll") for (int n = 0; n < 2; ++n) _Pragma("unroll") for (int k = 0; k < 2; ++k) \
;         acc[ai][bj][m][n] = __builtin_amdgcn_mfma_f32_16x16x32_bf16(Bt[n][k], At[m][k], acc[ai][bj][m][n], 0, 0, 0); __builtin_amdgcn_s_setprio(0); } while (0)
; #define PG8_WAIT_V(n) asm volatile("s_waitcnt vmcnt(" #n ")" ::: "memory")
; #define PG8_WAIT_L(n) asm volatile("s_waitcnt lgkmcnt(" #n ")" ::: "memory")
; #define PG8_BAR __builtin_amdgcn_s_barrier()
; #define PG8_SCHED __builtin_amdgcn_sched_barrier(0)
; template <class Epi, class Sched, bool ALIGN_EPI = false, bool SP2 = false>
; __device__ __forceinline__ void gemm_phase(PG8_LAS unsigned char* lds, const Gemm g, const Sched& S, const Epi& E) {
;     ...
;             PG8_LDB(B0, 0, 0); PG8_LDB(B1, 0, 1); PG8_SCHED; PG8_LDA(At, 0, 0); PG8_STAGE(PG8_SA(1, 1), a1 + hstep, voffA);
;             PG8_WAIT_V(8); PG8_WAIT_L(0); PG8_BAR; PG8_MMA(0, 0, At, B0); PG8_MMA(0, 1, At, B1); PG8_BAR; PG8_SCHED;
	s_add_i32 m0, s65, 0xe000
	s_nop 0
	global_load_lds_dwordx4 v170, s[10:11]
	s_waitcnt vmcnt(8)
	s_waitcnt lgkmcnt(0)
	s_setprio 1
	s_barrier

; #define PG8_MMA(ai, bj, At, Bt) do { __builtin_amdgcn_s_setprio(1); _Pragma("unroll") for (int m = 0; m < 4; ++m) _Pragma("unroll") for (int n = 0; n < 2; ++n) _Pragma("unroll") for (int k = 0; k < 2; ++k) \
;         acc[ai][bj][m][n] = __builtin_amdgcn_mfma_f32_16x16x32_bf16(Bt[n][k], At[m][k], acc[ai][bj][m][n], 0, 0, 0); __builtin_amdgcn_s_setprio(0); } while (0)
; #define PG8_WAIT_V(n) asm volatile("s_waitcnt vmcnt(" #n ")" ::: "memory")
; #define PG8_WAIT_L(n) asm volatile("s_waitcnt lgkmcnt(" #n ")" ::: "memory")
; #define PG8_BAR __builtin_amdgcn_s_barrier()
; #define PG8_SCHED __builtin_amdgcn_sched_barrier(0)
; template <class Epi, class Sched, bool ALIGN_EPI = false, bool SP2 = false>
; __device__ __forceinline__ void gemm_phase(PG8_LAS unsigned char* lds, const Gemm g, const Sched& S, const Epi& E) {
;     ...
;             PG8_WAIT_V(8); PG8_WAIT_L(0); PG8_BAR; PG8_MMA(0, 0, At, B0); PG8_MMA(0, 1, At, B1); PG8_BAR; PG8_SCHED;
	v_mfma_f32_16x16x32_bf16 v[124:127], v[128:131], v[176:179], v[124:127]
	v_mfma_f32_16x16x32_bf16 v[120:123], v[136:139], v[176:179], v[120:123]
	v_mfma_f32_16x16x32_bf16 v[108:111], v[128:131], v[190:193], v[108:111]
	v_mfma_f32_16x16x32_bf16 v[104:107], v[136:139], v[190:193], v[104:107]
	v_mfma_f32_16x16x32_bf16 v[92:95], v[128:131], v[214:217], v[92:95]
	v_mfma_f32_16x16x32_bf16 v[88:91], v[136:139], v[214:217], v[88:91]
	v_mfma_f32_16x16x32_bf16 v[76:79], v[128:131], v[222:225], v[76:79]
	v_mfma_f32_16x16x32_bf16 v[72:75], v[136:139], v[222:225], v[72:75]
	v_mfma_f32_16x16x32_bf16 v[124:127], v[132:135], v[184:187], v[124:127]
	v_mfma_f32_16x16x32_bf16 v[120:123], v[140:143], v[184:187], v[120:123]
	v_mfma_f32_16x16x32_bf16 v[108:111], v[132:135], v[210:213], v[108:111]
	v_mfma_f32_16x16x32_bf16 v[104:107], v[140:143], v[210:213], v[104:107]
	v_mfma_f32_16x16x32_bf16 v[92:95], v[132:135], v[218:221], v[92:95]
	v_mfma_f32_16x16x32_bf16 v[88:91], v[140:143], v[218:221], v[88:91]
	v_mfma_f32_16x16x32_bf16 v[76:79], v[132:135], v[226:229], v[76:79]
	v_mfma_f32_16x16x32_bf16 v[72:75], v[140:143], v[226:229], v[72:75]


; #define PG8_MMA(ai, bj, At, Bt) do { __builtin_amdgcn_s_setprio(1); _Pragma("unroll") for (int m = 0; m < 4; ++m) _Pragma("unroll") for (int n = 0; n < 2; ++n) _Pragma("unroll") for (int k = 0; k < 2; ++k) \
;         acc[ai][bj][m][n] = __builtin_amdgcn_mfma_f32_16x16x32_bf16(Bt[n][k], At[m][k], acc[ai][bj][m][n], 0, 0, 0); __builtin_amdgcn_s_setprio(0); } while (0)
; #define PG8_WAIT_V(n) asm volatile("s_waitcnt vmcnt(" #n ")" ::: "memory")
; #define PG8_WAIT_L(n) asm volatile("s_waitcnt lgkmcnt(" #n ")" ::: "memory")
; #define PG8_BAR __builtin_amdgcn_s_barrier()
; #define PG8_SCHED __builtin_amdgcn_sched_barrier(0)
; template <class Epi, class Sched, bool ALIGN_EPI = false, bool SP2 = false>
; __device__ __forceinline__ void gemm_phase(PG8_LAS unsigned char* lds, const Gemm g, const Sched& S, const Epi& E) {
;     ...
;             PG8_WAIT_V(8); PG8_WAIT_L(0); PG8_BAR; PG8_MMA(0, 0, At, B0); PG8_MMA(0, 1, At, B1); PG8_BAR; PG8_SCHED;
	v_mfma_f32_16x16x32_bf16 v[116:119], v[144:147], v[176:179], v[116:119]
	v_mfma_f32_16x16x32_bf16 v[112:115], v[152:155], v[176:179], v[112:115]
	v_mfma_f32_16x16x32_bf16 v[100:103], v[144:147], v[190:193], v[100:103]
	v_mfma_f32_16x16x32_bf16 v[96:99], v[152:155], v[190:193], v[96:99]
	v_mfma_f32_16x16x32_bf16 v[84:87], v[144:147], v[214:217], v[84:87]
	v_mfma_f32_16x16x32_bf16 v[80:83], v[152:155], v[214:217], v[80:83]
	v_mfma_f32_16x16x32_bf16 v[68:71], v[144:147], v[222:225], v[68:71]
	v_mfma_f32_16x16x32_bf16 v[64:67], v[152:155], v[222:225], v[64:67]
	v_mfma_f32_16x16x32_bf16 v[116:119], v[148:151], v[184:187], v[116:119]
	v_mfma_f32_16x16x32_bf16 v[112:115], v[156:159], v[184:187], v[112:115]
	v_mfma_f32_16x16x32_bf16 v[100:103], v[148:151], v[210:213], v[100:103]
	v_mfma_f32_16x16x32_bf16 v[96:99], v[156:159], v[210:213], v[96:99]
	v_mfma_f32_16x16x32_bf16 v[84:87], v[148:151], v[218:221], v[84:87]
	v_mfma_f32_16x16x32_bf16 v[80:83], v[156:159], v[218:221], v[80:83]
	v_mfma_f32_16x16x32_bf16 v[68:71], v[148:151], v[226:229], v[68:71]
	v_mfma_f32_16x16x32_bf16 v[64:67], v[156:159], v[226:229], v[64:67]
	s_setprio 0
	s_barrier
	s_add_i32 s86, s75, s64
	s_mov_b64 s[96:97], s[12:13]

; #define PG8_STAGE(bufoff, gbase, voff) do { _Pragma("unroll") for (int _i = 0; _i < 2; ++_i) \
;         __builtin_amdgcn_global_load_lds((const unsigned*)((const char*)(gbase) + (voff)[_i]), (PG8_LAS unsigned*)(lds + (bufoff) + ldsw + _i * 8192), 16, 0, 0); } while (0)
; #define PG8_LDA(dst, b, h) do { _Pragma("unroll") for (int m = 0; m < 4; ++m) _Pragma("unroll") for (int k = 0; k < 2; ++k) dst[m][k] = *(const PG8_LAS bf16x8*)(lds + PG8_SA(b, h) + aoff + m * 2048 + k * 1024); } while (0)
; template <class Epi, class Sched, bool ALIGN_EPI = false, bool SP2 = false>
; __device__ __forceinline__ void gemm_phase(PG8_LAS unsigned char* lds, const Gemm g, const Sched& S, const Epi& E) {
;     ...
;             PG8_LDA(At, 0, 1); PG8_STAGE(PG8_SB(0, 0), b2, voffB); PG8_STAGE(PG8_SB(0, 1), b2 + hstep, voffB); PG8_STAGE(PG8_SA(0, 0), a2, voffA);
	s_mov_b32 m0, s86
	ds_read_b128 v[176:179], v207 offset:16384
	ds_read_b128 v[184:187], v207 offset:17408
	ds_read_b128 v[190:193], v207 offset:18432
	ds_read_b128 v[210:213], v207 offset:19456
	ds_read_b128 v[214:217], v207 offset:20480
	ds_read_b128 v[218:221], v207 offset:21504
	ds_read_b128 v[222:225], v207 offset:22528
	ds_read_b128 v[226:229], v207 offset:23552
	global_load_lds_dwordx4 v162, s[12:13]
	s_add_i32 m0, s86, 0x2000
	s_add_u32 s86, s12, 0x80000

; #define PG8_STAGE(bufoff, gbase, voff) do { _Pragma("unroll") for (int _i = 0; _i < 2; ++_i) \
;         __builtin_amdgcn_global_load_lds((const unsigned*)((const char*)(gbase) + (voff)[_i]), (PG8_LAS unsigned*)(lds + (bufoff) + ldsw + _i * 8192), 16, 0, 0); } while (0)
; #define PG8_LDA(dst, b, h) do { _Pragma("unroll") for (int m = 0; m < 4; ++m) _Pragma("unroll") for (int k = 0; k < 2; ++k) dst[m][k] = *(const PG8_LAS bf16x8*)(lds + PG8_SA(b, h) + aoff + m * 2048 + k * 1024); } while (0)
; template <class Epi, class Sched, bool ALIGN_EPI = false, bool SP2 = false>
; __device__ __forceinline__ void gemm_phase(PG8_LAS unsigned char* lds, const Gemm g, const Sched& S, const Epi& E) {
;     ...
;             PG8_LDA(At, 0, 1); PG8_STAGE(PG8_SB(0, 0), b2, voffB); PG8_STAGE(PG8_SB(0, 1), b2 + hstep, voffB); PG8_STAGE(PG8_SA(0, 0), a2, voffA);
	s_addc_u32 s87, s13, 0
	s_add_i32 s88, s76, s64
	global_load_lds_dwordx4 v166, s[12:13]

; #define PG8_STAGE(bufoff, gbase, voff) do { _Pragma("unroll") for (int _i = 0; _i < 2; ++_i) \
;         __builtin_amdgcn_global_load_lds((const unsigned*)((const char*)(gbase) + (voff)[_i]), (PG8_LAS unsigned*)(lds + (bufoff) + ldsw + _i * 8192), 16, 0, 0); } while (0)
; #define PG8_LDA(dst, b, h) do { _Pragma("unroll") for (int m = 0; m < 4; ++m) _Pragma("unroll") for (int k = 0; k < 2; ++k) dst[m][k] = *(const PG8_LAS bf16x8*)(lds + PG8_SA(b, h) + aoff + m * 2048 + k * 1024); } while (0)
; template <class Epi, class Sched, bool ALIGN_EPI = false, bool SP2 = false>
; __device__ __forceinline__ void gemm_phase(PG8_LAS unsigned char* lds, const Gemm g, const Sched& S, const Epi& E) {
;     ...
;             PG8_LDA(At, 0, 1); PG8_STAGE(PG8_SB(0, 0), b2, voffB); PG8_STAGE(PG8_SB(0, 1), b2 + hstep, voffB); PG8_STAGE(PG8_SA(0, 0), a2, voffA);
	s_mov_b32 m0, s88
	s_nop 0
	global_load_lds_dwordx4 v162, s[86:87]

; #define PG8_STAGE(bufoff, gbase, voff) do { _Pragma("unroll") for (int _i = 0; _i < 2; ++_i) \
;         __builtin_amdgcn_global_load_lds((const unsigned*)((const char*)(gbase) + (voff)[_i]), (PG8_LAS unsigned*)(lds + (bufoff) + ldsw + _i * 8192), 16, 0, 0); } while (0)
; #define PG8_LDA(dst, b, h) do { _Pragma("unroll") for (int m = 0; m < 4; ++m) _Pragma("unroll") for (int k = 0; k < 2; ++k) dst[m][k] = *(const PG8_LAS bf16x8*)(lds + PG8_SA(b, h) + aoff + m * 2048 + k * 1024); } while (0)
; template <class Epi, class Sched, bool ALIGN_EPI = false, bool SP2 = false>
; __device__ __forceinline__ void gemm_phase(PG8_LAS unsigned char* lds, const Gemm g, const Sched& S, const Epi& E) {
;     ...
;             PG8_LDA(At, 0, 1); PG8_STAGE(PG8_SB(0, 0), b2, voffB); PG8_STAGE(PG8_SB(0, 1), b2 + hstep, voffB); PG8_STAGE(PG8_SA(0, 0), a2, voffA);
	s_add_i32 m0, s88, 0x2000
	s_nop 0
	global_load_lds_dwordx4 v166, s[86:87]
	s_mov_b64 s[98:99], s[60:61]

; #define PG8_STAGE(bufoff, gbase, voff) do { _Pragma("unroll") for (int _i = 0; _i < 2; ++_i) \
;         __builtin_amdgcn_global_load_lds((const unsigned*)((const char*)(gbase) + (voff)[_i]), (PG8_LAS unsigned*)(lds + (bufoff) + ldsw + _i * 8192), 16, 0, 0); } while (0)
; #define PG8_LDA(dst, b, h) do { _Pragma("unroll") for (int m = 0; m < 4; ++m) _Pragma("unroll") for (int k = 0; k < 2; ++k) dst[m][k] = *(const PG8_LAS bf16x8*)(lds + PG8_SA(b, h) + aoff + m * 2048 + k * 1024); } while (0)
; #define PG8_MMA(ai, bj, At, Bt) do { __builtin_amdgcn_s_setprio(1); _Pragma("unroll") for (int m = 0; m < 4; ++m) _Pragma("unroll") for (int n = 0; n < 2; ++n) _Pragma("unroll") for (int k = 0; k < 2; ++k) \
;         acc[ai][bj][m][n] = __builtin_amdgcn_mfma_f32_16x16x32_bf16(Bt[n][k], At[m][k], acc[ai][bj][m][n], 0, 0, 0); __builtin_amdgcn_s_setprio(0); } while (0)
; #define PG8_WAIT_V(n) asm volatile("s_waitcnt vmcnt(" #n ")" ::: "memory")
; #define PG8_WAIT_L(n) asm volatile("s_waitcnt lgkmcnt(" #n ")" ::: "memory")
; #define PG8_BAR __builtin_amdgcn_s_barrier()
; #define PG8_SCHED __builtin_amdgcn_sched_barrier(0)
; template <class Epi, class Sched, bool ALIGN_EPI = false, bool SP2 = false>
; __device__ __forceinline__ void gemm_phase(PG8_LAS unsigned char* lds, const Gemm g, const Sched& S, const Epi& E) {
;     ...
;             PG8_LDA(At, 0, 1); PG8_STAGE(PG8_SB(0, 0), b2, voffB); PG8_STAGE(PG8_SB(0, 1), b2 + hstep, voffB); PG8_STAGE(PG8_SA(0, 0), a2, voffA);
;             PG8_WAIT_V(8); PG8_WAIT_L(0); PG8_BAR; PG8_MMA(1, 0, At, B0); PG8_MMA(1, 1, At, B1); PG8_BAR; PG8_SCHED;
	s_mov_b32 m0, s65
	s_nop 0
	global_load_lds_dwordx4 v160, s[60:61]
	s_mov_b32 m0, s67
	s_nop 0
	global_load_lds_dwordx4 v164, s[60:61]
	s_waitcnt vmcnt(8)
	s_waitcnt lgkmcnt(0)
	s_setprio 1
	s_barrier

; #define PG8_MMA(ai, bj, At, Bt) do { __builtin_amdgcn_s_setprio(1); _Pragma("unroll") for (int m = 0; m < 4; ++m) _Pragma("unroll") for (int n = 0; n < 2; ++n) _Pragma("unroll") for (int k = 0; k < 2; ++k) \
;         acc[ai][bj][m][n] = __builtin_amdgcn_mfma_f32_16x16x32_bf16(Bt[n][k], At[m][k], acc[ai][bj][m][n], 0, 0, 0); __builtin_amdgcn_s_setprio(0); } while (0)
; #define PG8_WAIT_V(n) asm volatile("s_waitcnt vmcnt(" #n ")" ::: "memory")
; #define PG8_WAIT_L(n) asm volatile("s_waitcnt lgkmcnt(" #n ")" ::: "memory")
; #define PG8_BAR __builtin_amdgcn_s_barrier()
; #define PG8_SCHED __builtin_amdgcn_sched_barrier(0)
; template <class Epi, class Sched, bool ALIGN_EPI = false, bool SP2 = false>
; __device__ __forceinline__ void gemm_phase(PG8_LAS unsigned char* lds, const Gemm g, const Sched& S, const Epi& E) {
;     ...
;             PG8_WAIT_V(8); PG8_WAIT_L(0); PG8_BAR; PG8_MMA(1, 0, At, B0); PG8_MMA(1, 1, At, B1); PG8_BAR; PG8_SCHED;
	v_mfma_f32_16x16x32_bf16 v[60:63], v[128:131], v[176:179], v[60:63]
	v_mfma_f32_16x16x32_bf16 v[56:59], v[136:139], v[176:179], v[56:59]
	v_mfma_f32_16x16x32_bf16 v[44:47], v[128:131], v[190:193], v[44:47]
	v_mfma_f32_16x16x32_bf16 v[40:43], v[136:139], v[190:193], v[40:43]
	v_mfma_f32_16x16x32_bf16 v[28:31], v[128:131], v[214:217], v[28:31]
	v_mfma_f32_16x16x32_bf16 v[24:27], v[136:139], v[214:217], v[24:27]
	v_mfma_f32_16x16x32_bf16 v[12:15], v[128:131], v[222:225], v[12:15]
	v_mfma_f32_16x16x32_bf16 v[8:11], v[136:139], v[222:225], v[8:11]
	v_mfma_f32_16x16x32_bf16 v[60:63], v[132:135], v[184:187], v[60:63]
	v_mfma_f32_16x16x32_bf16 v[56:59], v[140:143], v[184:187], v[56:59]
	v_mfma_f32_16x16x32_bf16 v[44:47], v[132:135], v[210:213], v[44:47]
	v_mfma_f32_16x16x32_bf16 v[40:43], v[140:143], v[210:213], v[40:43]
	v_mfma_f32_16x16x32_bf16 v[28:31], v[132:135], v[218:221], v[28:31]
	v_mfma_f32_16x16x32_bf16 v[24:27], v[140:143], v[218:221], v[24:27]
	v_mfma_f32_16x16x32_bf16 v[12:15], v[132:135], v[226:229], v[12:15]
	v_mfma_f32_16x16x32_bf16 v[8:11], v[140:143], v[226:229], v[8:11]


; #define PG8_MMA(ai, bj, At, Bt) do { __builtin_amdgcn_s_setprio(1); _Pragma("unroll") for (int m = 0; m < 4; ++m) _Pragma("unroll") for (int n = 0; n < 2; ++n) _Pragma("unroll") for (int k = 0; k < 2; ++k) \
;         acc[ai][bj][m][n] = __builtin_amdgcn_mfma_f32_16x16x32_bf16(Bt[n][k], At[m][k], acc[ai][bj][m][n], 0, 0, 0); __builtin_amdgcn_s_setprio(0); } while (0)
; #define PG8_WAIT_V(n) asm volatile("s_waitcnt vmcnt(" #n ")" ::: "memory")
; #define PG8_WAIT_L(n) asm volatile("s_waitcnt lgkmcnt(" #n ")" ::: "memory")
; #define PG8_BAR __builtin_amdgcn_s_barrier()
; #define PG8_SCHED __builtin_amdgcn_sched_barrier(0)
; template <class Epi, class Sched, bool ALIGN_EPI = false, bool SP2 = false>
; __device__ __forceinline__ void gemm_phase(PG8_LAS unsigned char* lds, const Gemm g, const Sched& S, const Epi& E) {
;     ...
;             PG8_WAIT_V(8); PG8_WAIT_L(0); PG8_BAR; PG8_MMA(1, 0, At, B0); PG8_MMA(1, 1, At, B1); PG8_BAR; PG8_SCHED;
	v_mfma_f32_16x16x32_bf16 v[52:55], v[144:147], v[176:179], v[52:55]
	v_mfma_f32_16x16x32_bf16 v[48:51], v[152:155], v[176:179], v[48:51]
	v_mfma_f32_16x16x32_bf16 v[36:39], v[144:147], v[190:193], v[36:39]
	v_mfma_f32_16x16x32_bf16 v[32:35], v[152:155], v[190:193], v[32:35]
	v_mfma_f32_16x16x32_bf16 v[20:23], v[144:147], v[214:217], v[20:23]
	v_mfma_f32_16x16x32_bf16 v[16:19], v[152:155], v[214:217], v[16:19]
	v_mfma_f32_16x16x32_bf16 v[4:7], v[144:147], v[222:225], v[4:7]
	v_mfma_f32_16x16x32_bf16 v[0:3], v[152:155], v[222:225], v[0:3]
	v_mfma_f32_16x16x32_bf16 v[52:55], v[148:151], v[184:187], v[52:55]
	v_mfma_f32_16x16x32_bf16 v[48:51], v[156:159], v[184:187], v[48:51]
	v_mfma_f32_16x16x32_bf16 v[36:39], v[148:151], v[210:213], v[36:39]
	v_mfma_f32_16x16x32_bf16 v[32:35], v[156:159], v[210:213], v[32:35]
	v_mfma_f32_16x16x32_bf16 v[20:23], v[148:151], v[218:221], v[20:23]
	v_mfma_f32_16x16x32_bf16 v[16:19], v[156:159], v[218:221], v[16:19]
	v_mfma_f32_16x16x32_bf16 v[4:7], v[148:151], v[226:229], v[4:7]
	v_mfma_f32_16x16x32_bf16 v[0:3], v[156:159], v[226:229], v[0:3]
	s_setprio 0
	s_barrier
	s_add_i32 s86, 0, 0x18000
	s_add_i32 s87, 0, 0x1c000


; #define PG8_STAGE(bufoff, gbase, voff) do { _Pragma("unroll") for (int _i = 0; _i < 2; ++_i) \
;         __builtin_amdgcn_global_load_lds((const unsigned*)((const char*)(gbase) + (voff)[_i]), (PG8_LAS unsigned*)(lds + (bufoff) + ldsw + _i * 8192), 16, 0, 0); } while (0)
; #define PG8_LDA(dst, b, h) do { _Pragma("unroll") for (int m = 0; m < 4; ++m) _Pragma("unroll") for (int k = 0; k < 2; ++k) dst[m][k] = *(const PG8_LAS bf16x8*)(lds + PG8_SA(b, h) + aoff + m * 2048 + k * 1024); } while (0)
; #define PG8_LDB(dst, b, h) do { _Pragma("unroll") for (int n = 0; n < 2; ++n) _Pragma("unroll") for (int k = 0; k < 2; ++k) dst[n][k] = *(const PG8_LAS bf16x8*)(lds + PG8_SB(b, h) + boff + n * 2048 + k * 1024); } while (0)
; #define PG8_SCHED __builtin_amdgcn_sched_barrier(0)
; template <class Epi, class Sched, bool ALIGN_EPI = false, bool SP2 = false>
; __device__ __forceinline__ void gemm_phase(PG8_LAS unsigned char* lds, const Gemm g, const Sched& S, const Epi& E) {
;     ...
;             PG8_LDB(B0, 1, 0); PG8_LDB(B1, 1, 1); PG8_SCHED; PG8_LDA(At, 1, 0); PG8_STAGE(PG8_SA(0, 1), a2 + hstep, voffA);
	ds_read_b128 v[128:131], v254
	ds_read_b128 v[132:135], v254 offset:1024
	ds_read_b128 v[136:139], v254 offset:2048
	ds_read_b128 v[140:143], v254 offset:3072
	ds_read_b128 v[144:147], v255
	ds_read_b128 v[148:151], v255 offset:1024
	ds_read_b128 v[152:155], v255 offset:2048
	ds_read_b128 v[156:159], v255 offset:3072
	s_add_u32 s60, s60, 0x80000
	s_addc_u32 s61, s61, 0
	s_mov_b32 m0, s68

; #define PG8_STAGE(bufoff, gbase, voff) do { _Pragma("unroll") for (int _i = 0; _i < 2; ++_i) \
;         __builtin_amdgcn_global_load_lds((const unsigned*)((const char*)(gbase) + (voff)[_i]), (PG8_LAS unsigned*)(lds + (bufoff) + ldsw + _i * 8192), 16, 0, 0); } while (0)
; #define PG8_LDA(dst, b, h) do { _Pragma("unroll") for (int m = 0; m < 4; ++m) _Pragma("unroll") for (int k = 0; k < 2; ++k) dst[m][k] = *(const PG8_LAS bf16x8*)(lds + PG8_SA(b, h) + aoff + m * 2048 + k * 1024); } while (0)
; #define PG8_LDB(dst, b, h) do { _Pragma("unroll") for (int n = 0; n < 2; ++n) _Pragma("unroll") for (int k = 0; k < 2; ++k) dst[n][k] = *(const PG8_LAS bf16x8*)(lds + PG8_SB(b, h) + boff + n * 2048 + k * 1024); } while (0)
; #define PG8_SCHED __builtin_amdgcn_sched_barrier(0)
; template <class Epi, class Sched, bool ALIGN_EPI = false, bool SP2 = false>
; __device__ __forceinline__ void gemm_phase(PG8_LAS unsigned char* lds, const Gemm g, const Sched& S, const Epi& E) {
;     ...
;             PG8_LDB(B0, 1, 0); PG8_LDB(B1, 1, 1); PG8_SCHED; PG8_LDA(At, 1, 0); PG8_STAGE(PG8_SA(0, 1), a2 + hstep, voffA);
	ds_read_b128 v[176:179], v207 offset:32768
	ds_read_b128 v[184:187], v207 offset:33792
	ds_read_b128 v[190:193], v207 offset:34816
	ds_read_b128 v[210:213], v207 offset:35840
	ds_read_b128 v[214:217], v207 offset:36864
	ds_read_b128 v[218:221], v207 offset:37888
	ds_read_b128 v[222:225], v207 offset:38912
	ds_read_b128 v[226:229], v207 offset:39936
	global_load_lds_dwordx4 v160, s[60:61]

; #define PG8_STAGE(bufoff, gbase, voff) do { _Pragma("unroll") for (int _i = 0; _i < 2; ++_i) \
;         __builtin_amdgcn_global_load_lds((const unsigned*)((const char*)(gbase) + (voff)[_i]), (PG8_LAS unsigned*)(lds + (bufoff) + ldsw + _i * 8192), 16, 0, 0); } while (0)
; #define PG8_LDA(dst, b, h) do { _Pragma("unroll") for (int m = 0; m < 4; ++m) _Pragma("unroll") for (int k = 0; k < 2; ++k) dst[m][k] = *(const PG8_LAS bf16x8*)(lds + PG8_SA(b, h) + aoff + m * 2048 + k * 1024); } while (0)
; #define PG8_LDB(dst, b, h) do { _Pragma("unroll") for (int n = 0; n < 2; ++n) _Pragma("unroll") for (int k = 0; k < 2; ++k) dst[n][k] = *(const PG8_LAS bf16x8*)(lds + PG8_SB(b, h) + boff + n * 2048 + k * 1024); } while (0)
; #define PG8_MMA(ai, bj, At, Bt) do { __builtin_amdgcn_s_setprio(1); _Pragma("unroll") for (int m = 0; m < 4; ++m) _Pragma("unroll") for (int n = 0; n < 2; ++n) _Pragma("unroll") for (int k = 0; k < 2; ++k) \
;         acc[ai][bj][m][n] = __builtin_amdgcn_mfma_f32_16x16x32_bf16(Bt[n][k], At[m][k], acc[ai][bj][m][n], 0, 0, 0); __builtin_amdgcn_s_setprio(0); } while (0)
; #define PG8_WAIT_V(n) asm volatile("s_waitcnt vmcnt(" #n ")" ::: "memory")
; #define PG8_WAIT_L(n) asm volatile("s_waitcnt lgkmcnt(" #n ")" ::: "memory")
; #define PG8_BAR __builtin_amdgcn_s_barrier()
; #define PG8_SCHED __builtin_amdgcn_sched_barrier(0)
; template <class Epi, class Sched, bool ALIGN_EPI = false, bool SP2 = false>
; __device__ __forceinline__ void gemm_phase(PG8_LAS unsigned char* lds, const Gemm g, const Sched& S, const Epi& E) {
;     ...
;             PG8_LDB(B0, 1, 0); PG8_LDB(B1, 1, 1); PG8_SCHED; PG8_LDA(At, 1, 0); PG8_STAGE(PG8_SA(0, 1), a2 + hstep, voffA);
;             PG8_WAIT_V(8); PG8_WAIT_L(0); PG8_BAR; PG8_MMA(0, 0, At, B0); PG8_MMA(0, 1, At, B1); PG8_BAR; PG8_SCHED;
	s_mov_b32 m0, s69
	s_nop 0
	global_load_lds_dwordx4 v164, s[60:61]
	s_waitcnt vmcnt(8)
	s_waitcnt lgkmcnt(0)
	s_setprio 1
	s_barrier

; #define PG8_MMA(ai, bj, At, Bt) do { __builtin_amdgcn_s_setprio(1); _Pragma("unroll") for (int m = 0; m < 4; ++m) _Pragma("unroll") for (int n = 0; n < 2; ++n) _Pragma("unroll") for (int k = 0; k < 2; ++k) \
;         acc[ai][bj][m][n] = __builtin_amdgcn_mfma_f32_16x16x32_bf16(Bt[n][k], At[m][k], acc[ai][bj][m][n], 0, 0, 0); __builtin_amdgcn_s_setprio(0); } while (0)
; #define PG8_WAIT_V(n) asm volatile("s_waitcnt vmcnt(" #n ")" ::: "memory")
; #define PG8_WAIT_L(n) asm volatile("s_waitcnt lgkmcnt(" #n ")" ::: "memory")
; #define PG8_BAR __builtin_amdgcn_s_barrier()
; #define PG8_SCHED __builtin_amdgcn_sched_barrier(0)
; template <class Epi, class Sched, bool ALIGN_EPI = false, bool SP2 = false>
; __device__ __forceinline__ void gemm_phase(PG8_LAS unsigned char* lds, const Gemm g, const Sched& S, const Epi& E) {
;     ...
;             PG8_WAIT_V(8); PG8_WAIT_L(0); PG8_BAR; PG8_MMA(0, 0, At, B0); PG8_MMA(0, 1, At, B1); PG8_BAR; PG8_SCHED;
	v_mfma_f32_16x16x32_bf16 v[124:127], v[128:131], v[176:179], v[124:127]
	v_mfma_f32_16x16x32_bf16 v[120:123], v[136:139], v[176:179], v[120:123]
	v_mfma_f32_16x16x32_bf16 v[108:111], v[128:131], v[190:193], v[108:111]
	v_mfma_f32_16x16x32_bf16 v[104:107], v[136:139], v[190:193], v[104:107]
	v_mfma_f32_16x16x32_bf16 v[92:95], v[128:131], v[214:217], v[92:95]
	v_mfma_f32_16x16x32_bf16 v[88:91], v[136:139], v[214:217], v[88:91]
	v_mfma_f32_16x16x32_bf16 v[76:79], v[128:131], v[222:225], v[76:79]
	v_mfma_f32_16x16x32_bf16 v[72:75], v[136:139], v[222:225], v[72:75]
	v_mfma_f32_16x16x32_bf16 v[124:127], v[132:135], v[184:187], v[124:127]
	v_mfma_f32_16x16x32_bf16 v[120:123], v[140:143], v[184:187], v[120:123]
	v_mfma_f32_16x16x32_bf16 v[108:111], v[132:135], v[210:213], v[108:111]
	v_mfma_f32_16x16x32_bf16 v[104:107], v[140:143], v[210:213], v[104:107]
	v_mfma_f32_16x16x32_bf16 v[92:95], v[132:135], v[218:221], v[92:95]
	v_mfma_f32_16x16x32_bf16 v[88:91], v[140:143], v[218:221], v[88:91]
	v_mfma_f32_16x16x32_bf16 v[76:79], v[132:135], v[226:229], v[76:79]
	v_mfma_f32_16x16x32_bf16 v[72:75], v[140:143], v[226:229], v[72:75]


; #define PG8_MMA(ai, bj, At, Bt) do { __builtin_amdgcn_s_setprio(1); _Pragma("unroll") for (int m = 0; m < 4; ++m) _Pragma("unroll") for (int n = 0; n < 2; ++n) _Pragma("unroll") for (int k = 0; k < 2; ++k) \
;         acc[ai][bj][m][n] = __builtin_amdgcn_mfma_f32_16x16x32_bf16(Bt[n][k], At[m][k], acc[ai][bj][m][n], 0, 0, 0); __builtin_amdgcn_s_setprio(0); } while (0)
; #define PG8_WAIT_V(n) asm volatile("s_waitcnt vmcnt(" #n ")" ::: "memory")
; #define PG8_WAIT_L(n) asm volatile("s_waitcnt lgkmcnt(" #n ")" ::: "memory")
; #define PG8_BAR __builtin_amdgcn_s_barrier()
; #define PG8_SCHED __builtin_amdgcn_sched_barrier(0)
; template <class Epi, class Sched, bool ALIGN_EPI = false, bool SP2 = false>
; __device__ __forceinline__ void gemm_phase(PG8_LAS unsigned char* lds, const Gemm g, const Sched& S, const Epi& E) {
;     ...
;             PG8_WAIT_V(8); PG8_WAIT_L(0); PG8_BAR; PG8_MMA(0, 0, At, B0); PG8_MMA(0, 1, At, B1); PG8_BAR; PG8_SCHED;
	v_mfma_f32_16x16x32_bf16 v[116:119], v[144:147], v[176:179], v[116:119]
	v_mfma_f32_16x16x32_bf16 v[112:115], v[152:155], v[176:179], v[112:115]
	v_mfma_f32_16x16x32_bf16 v[100:103], v[144:147], v[190:193], v[100:103]
	v_mfma_f32_16x16x32_bf16 v[96:99], v[152:155], v[190:193], v[96:99]
	v_mfma_f32_16x16x32_bf16 v[84:87], v[144:147], v[214:217], v[84:87]
	v_mfma_f32_16x16x32_bf16 v[80:83], v[152:155], v[214:217], v[80:83]
	v_mfma_f32_16x16x32_bf16 v[68:71], v[144:147], v[222:225], v[68:71]
	v_mfma_f32_16x16x32_bf16 v[64:67], v[152:155], v[222:225], v[64:67]
	v_mfma_f32_16x16x32_bf16 v[116:119], v[148:151], v[184:187], v[116:119]
	v_mfma_f32_16x16x32_bf16 v[112:115], v[156:159], v[184:187], v[112:115]
	v_mfma_f32_16x16x32_bf16 v[100:103], v[148:151], v[210:213], v[100:103]
	v_mfma_f32_16x16x32_bf16 v[96:99], v[156:159], v[210:213], v[96:99]
	v_mfma_f32_16x16x32_bf16 v[84:87], v[148:151], v[218:221], v[84:87]
	v_mfma_f32_16x16x32_bf16 v[80:83], v[156:159], v[218:221], v[80:83]
	v_mfma_f32_16x16x32_bf16 v[68:71], v[148:151], v[226:229], v[68:71]
	v_mfma_f32_16x16x32_bf16 v[64:67], v[156:159], v[226:229], v[64:67]
	s_setprio 0
	s_barrier
	s_add_i32 s60, s86, s64

; #define PG8_STAGE(bufoff, gbase, voff) do { _Pragma("unroll") for (int _i = 0; _i < 2; ++_i) \
;         __builtin_amdgcn_global_load_lds((const unsigned*)((const char*)(gbase) + (voff)[_i]), (PG8_LAS unsigned*)(lds + (bufoff) + ldsw + _i * 8192), 16, 0, 0); } while (0)
; #define PG8_LDA(dst, b, h) do { _Pragma("unroll") for (int m = 0; m < 4; ++m) _Pragma("unroll") for (int k = 0; k < 2; ++k) dst[m][k] = *(const PG8_LAS bf16x8*)(lds + PG8_SA(b, h) + aoff + m * 2048 + k * 1024); } while (0)
; template <class Epi, class Sched, bool ALIGN_EPI = false, bool SP2 = false>
; __device__ __forceinline__ void gemm_phase(PG8_LAS unsigned char* lds, const Gemm g, const Sched& S, const Epi& E) {
;     ...
;             PG8_LDA(At, 1, 1); PG8_STAGE(PG8_SB(1, 0), b3, voffB); PG8_STAGE(PG8_SB(1, 1), b3 + hstep, voffB); PG8_STAGE(PG8_SA(1, 0), a3, voffA);
	s_mov_b32 m0, s60
	ds_read_b128 v[176:179], v207 offset:49152
	ds_read_b128 v[184:187], v207 offset:50176
	ds_read_b128 v[190:193], v207 offset:51200
	ds_read_b128 v[210:213], v207 offset:52224
	ds_read_b128 v[214:217], v207 offset:53248
	ds_read_b128 v[218:221], v207 offset:54272
	ds_read_b128 v[222:225], v207 offset:55296
	ds_read_b128 v[226:229], v207 offset:56320
	global_load_lds_dwordx4 v250, s[96:97]
	s_add_i32 m0, s60, 0x2000
	s_add_u32 s12, s12, 0x80080

; #define PG8_STAGE(bufoff, gbase, voff) do { _Pragma("unroll") for (int _i = 0; _i < 2; ++_i) \
;         __builtin_amdgcn_global_load_lds((const unsigned*)((const char*)(gbase) + (voff)[_i]), (PG8_LAS unsigned*)(lds + (bufoff) + ldsw + _i * 8192), 16, 0, 0); } while (0)
; #define PG8_LDA(dst, b, h) do { _Pragma("unroll") for (int m = 0; m < 4; ++m) _Pragma("unroll") for (int k = 0; k < 2; ++k) dst[m][k] = *(const PG8_LAS bf16x8*)(lds + PG8_SA(b, h) + aoff + m * 2048 + k * 1024); } while (0)
; template <class Epi, class Sched, bool ALIGN_EPI = false, bool SP2 = false>
; __device__ __forceinline__ void gemm_phase(PG8_LAS unsigned char* lds, const Gemm g, const Sched& S, const Epi& E) {
;     ...
;             PG8_LDA(At, 1, 1); PG8_STAGE(PG8_SB(1, 0), b3, voffB); PG8_STAGE(PG8_SB(1, 1), b3 + hstep, voffB); PG8_STAGE(PG8_SA(1, 0), a3, voffA);
	s_addc_u32 s13, s13, 0
	s_add_i32 s60, s87, s64
	global_load_lds_dwordx4 v251, s[96:97]

; #define PG8_STAGE(bufoff, gbase, voff) do { _Pragma("unroll") for (int _i = 0; _i < 2; ++_i) \
;         __builtin_amdgcn_global_load_lds((const unsigned*)((const char*)(gbase) + (voff)[_i]), (PG8_LAS unsigned*)(lds + (bufoff) + ldsw + _i * 8192), 16, 0, 0); } while (0)
; #define PG8_LDA(dst, b, h) do { _Pragma("unroll") for (int m = 0; m < 4; ++m) _Pragma("unroll") for (int k = 0; k < 2; ++k) dst[m][k] = *(const PG8_LAS bf16x8*)(lds + PG8_SA(b, h) + aoff + m * 2048 + k * 1024); } while (0)
; template <class Epi, class Sched, bool ALIGN_EPI = false, bool SP2 = false>
; __device__ __forceinline__ void gemm_phase(PG8_LAS unsigned char* lds, const Gemm g, const Sched& S, const Epi& E) {
;     ...
;             PG8_LDA(At, 1, 1); PG8_STAGE(PG8_SB(1, 0), b3, voffB); PG8_STAGE(PG8_SB(1, 1), b3 + hstep, voffB); PG8_STAGE(PG8_SA(1, 0), a3, voffA);
	s_mov_b32 m0, s60
	s_nop 0
	global_load_lds_dwordx4 v162, s[12:13]

; #define PG8_STAGE(bufoff, gbase, voff) do { _Pragma("unroll") for (int _i = 0; _i < 2; ++_i) \
;         __builtin_amdgcn_global_load_lds((const unsigned*)((const char*)(gbase) + (voff)[_i]), (PG8_LAS unsigned*)(lds + (bufoff) + ldsw + _i * 8192), 16, 0, 0); } while (0)
; #define PG8_LDA(dst, b, h) do { _Pragma("unroll") for (int m = 0; m < 4; ++m) _Pragma("unroll") for (int k = 0; k < 2; ++k) dst[m][k] = *(const PG8_LAS bf16x8*)(lds + PG8_SA(b, h) + aoff + m * 2048 + k * 1024); } while (0)
; template <class Epi, class Sched, bool ALIGN_EPI = false, bool SP2 = false>
; __device__ __forceinline__ void gemm_phase(PG8_LAS unsigned char* lds, const Gemm g, const Sched& S, const Epi& E) {
;     ...
;             PG8_LDA(At, 1, 1); PG8_STAGE(PG8_SB(1, 0), b3, voffB); PG8_STAGE(PG8_SB(1, 1), b3 + hstep, voffB); PG8_STAGE(PG8_SA(1, 0), a3, voffA);
	s_add_i32 m0, s60, 0x2000
	s_nop 0
	global_load_lds_dwordx4 v166, s[12:13]

; #define PG8_STAGE(bufoff, gbase, voff) do { _Pragma("unroll") for (int _i = 0; _i < 2; ++_i) \
;         __builtin_amdgcn_global_load_lds((const unsigned*)((const char*)(gbase) + (voff)[_i]), (PG8_LAS unsigned*)(lds + (bufoff) + ldsw + _i * 8192), 16, 0, 0); } while (0)
; #define PG8_LDA(dst, b, h) do { _Pragma("unroll") for (int m = 0; m < 4; ++m) _Pragma("unroll") for (int k = 0; k < 2; ++k) dst[m][k] = *(const PG8_LAS bf16x8*)(lds + PG8_SA(b, h) + aoff + m * 2048 + k * 1024); } while (0)
; template <class Epi, class Sched, bool ALIGN_EPI = false, bool SP2 = false>
; __device__ __forceinline__ void gemm_phase(PG8_LAS unsigned char* lds, const Gemm g, const Sched& S, const Epi& E) {
;     ...
;             PG8_LDA(At, 1, 1); PG8_STAGE(PG8_SB(1, 0), b3, voffB); PG8_STAGE(PG8_SB(1, 1), b3 + hstep, voffB); PG8_STAGE(PG8_SA(1, 0), a3, voffA);
	s_mov_b32 m0, s71
	s_nop 0
	global_load_lds_dwordx4 v252, s[98:99]

; #define PG8_STAGE(bufoff, gbase, voff) do { _Pragma("unroll") for (int _i = 0; _i < 2; ++_i) \
;         __builtin_amdgcn_global_load_lds((const unsigned*)((const char*)(gbase) + (voff)[_i]), (PG8_LAS unsigned*)(lds + (bufoff) + ldsw + _i * 8192), 16, 0, 0); } while (0)
; #define PG8_LDA(dst, b, h) do { _Pragma("unroll") for (int m = 0; m < 4; ++m) _Pragma("unroll") for (int k = 0; k < 2; ++k) dst[m][k] = *(const PG8_LAS bf16x8*)(lds + PG8_SA(b, h) + aoff + m * 2048 + k * 1024); } while (0)
; #define PG8_MMA(ai, bj, At, Bt) do { __builtin_amdgcn_s_setprio(1); _Pragma("unroll") for (int m = 0; m < 4; ++m) _Pragma("unroll") for (int n = 0; n < 2; ++n) _Pragma("unroll") for (int k = 0; k < 2; ++k) \
;         acc[ai][bj][m][n] = __builtin_amdgcn_mfma_f32_16x16x32_bf16(Bt[n][k], At[m][k], acc[ai][bj][m][n], 0, 0, 0); __builtin_amdgcn_s_setprio(0); } while (0)
; #define PG8_WAIT_V(n) asm volatile("s_waitcnt vmcnt(" #n ")" ::: "memory")
; #define PG8_WAIT_L(n) asm volatile("s_waitcnt lgkmcnt(" #n ")" ::: "memory")
; #define PG8_BAR __builtin_amdgcn_s_barrier()
; #define PG8_SCHED __builtin_amdgcn_sched_barrier(0)
; template <class Epi, class Sched, bool ALIGN_EPI = false, bool SP2 = false>
; __device__ __forceinline__ void gemm_phase(PG8_LAS unsigned char* lds, const Gemm g, const Sched& S, const Epi& E) {
;     ...
;             PG8_LDA(At, 1, 1); PG8_STAGE(PG8_SB(1, 0), b3, voffB); PG8_STAGE(PG8_SB(1, 1), b3 + hstep, voffB); PG8_STAGE(PG8_SA(1, 0), a3, voffA);
;             PG8_WAIT_V(8); PG8_WAIT_L(0); PG8_BAR; PG8_MMA(1, 0, At, B0); PG8_MMA(1, 1, At, B1); PG8_BAR; PG8_SCHED;
	s_mov_b32 m0, s72
	s_nop 0
	global_load_lds_dwordx4 v253, s[98:99]
	s_waitcnt vmcnt(8)
	s_waitcnt lgkmcnt(0)
	s_setprio 1
	s_barrier

; #define PG8_MMA(ai, bj, At, Bt) do { __builtin_amdgcn_s_setprio(1); _Pragma("unroll") for (int m = 0; m < 4; ++m) _Pragma("unroll") for (int n = 0; n < 2; ++n) _Pragma("unroll") for (int k = 0; k < 2; ++k) \
;         acc[ai][bj][m][n] = __builtin_amdgcn_mfma_f32_16x16x32_bf16(Bt[n][k], At[m][k], acc[ai][bj][m][n], 0, 0, 0); __builtin_amdgcn_s_setprio(0); } while (0)
; #define PG8_WAIT_V(n) asm volatile("s_waitcnt vmcnt(" #n ")" ::: "memory")
; #define PG8_WAIT_L(n) asm volatile("s_waitcnt lgkmcnt(" #n ")" ::: "memory")
; #define PG8_BAR __builtin_amdgcn_s_barrier()
; #define PG8_SCHED __builtin_amdgcn_sched_barrier(0)
; template <class Epi, class Sched, bool ALIGN_EPI = false, bool SP2 = false>
; __device__ __forceinline__ void gemm_phase(PG8_LAS unsigned char* lds, const Gemm g, const Sched& S, const Epi& E) {
;     ...
;             PG8_WAIT_V(8); PG8_WAIT_L(0); PG8_BAR; PG8_MMA(1, 0, At, B0); PG8_MMA(1, 1, At, B1); PG8_BAR; PG8_SCHED;
	v_mfma_f32_16x16x32_bf16 v[60:63], v[128:131], v[176:179], v[60:63]
	v_mfma_f32_16x16x32_bf16 v[56:59], v[136:139], v[176:179], v[56:59]
	v_mfma_f32_16x16x32_bf16 v[44:47], v[128:131], v[190:193], v[44:47]
	v_mfma_f32_16x16x32_bf16 v[40:43], v[136:139], v[190:193], v[40:43]
	v_mfma_f32_16x16x32_bf16 v[28:31], v[128:131], v[214:217], v[28:31]
	v_mfma_f32_16x16x32_bf16 v[24:27], v[136:139], v[214:217], v[24:27]
	v_mfma_f32_16x16x32_bf16 v[12:15], v[128:131], v[222:225], v[12:15]
	v_mfma_f32_16x16x32_bf16 v[8:11], v[136:139], v[222:225], v[8:11]
	v_mfma_f32_16x16x32_bf16 v[60:63], v[132:135], v[184:187], v[60:63]
	v_mfma_f32_16x16x32_bf16 v[56:59], v[140:143], v[184:187], v[56:59]
	v_mfma_f32_16x16x32_bf16 v[44:47], v[132:135], v[210:213], v[44:47]
	v_mfma_f32_16x16x32_bf16 v[40:43], v[140:143], v[210:213], v[40:43]
	v_mfma_f32_16x16x32_bf16 v[28:31], v[132:135], v[218:221], v[28:31]
	v_mfma_f32_16x16x32_bf16 v[24:27], v[140:143], v[218:221], v[24:27]
	v_mfma_f32_16x16x32_bf16 v[12:15], v[132:135], v[226:229], v[12:15]
	v_mfma_f32_16x16x32_bf16 v[8:11], v[140:143], v[226:229], v[8:11]


; #define PG8_MMA(ai, bj, At, Bt) do { __builtin_amdgcn_s_setprio(1); _Pragma("unroll") for (int m = 0; m < 4; ++m) _Pragma("unroll") for (int n = 0; n < 2; ++n) _Pragma("unroll") for (int k = 0; k < 2; ++k) \
;         acc[ai][bj][m][n] = __builtin_amdgcn_mfma_f32_16x16x32_bf16(Bt[n][k], At[m][k], acc[ai][bj][m][n], 0, 0, 0); __builtin_amdgcn_s_setprio(0); } while (0)
; #define PG8_WAIT_V(n) asm volatile("s_waitcnt vmcnt(" #n ")" ::: "memory")
; #define PG8_WAIT_L(n) asm volatile("s_waitcnt lgkmcnt(" #n ")" ::: "memory")
; #define PG8_BAR __builtin_amdgcn_s_barrier()
; #define PG8_SCHED __builtin_amdgcn_sched_barrier(0)
; template <class Epi, class Sched, bool ALIGN_EPI = false, bool SP2 = false>
; __device__ __forceinline__ void gemm_phase(PG8_LAS unsigned char* lds, const Gemm g, const Sched& S, const Epi& E) {
;     ...
;         for (int t = 0; t < nt; t += 2) {
;     ...
;             PG8_WAIT_V(8); PG8_WAIT_L(0); PG8_BAR; PG8_MMA(1, 0, At, B0); PG8_MMA(1, 1, At, B1); PG8_BAR; PG8_SCHED;
	v_mfma_f32_16x16x32_bf16 v[52:55], v[144:147], v[176:179], v[52:55]
	v_mfma_f32_16x16x32_bf16 v[48:51], v[152:155], v[176:179], v[48:51]
	v_mfma_f32_16x16x32_bf16 v[36:39], v[144:147], v[190:193], v[36:39]
	v_mfma_f32_16x16x32_bf16 v[32:35], v[152:155], v[190:193], v[32:35]
	v_mfma_f32_16x16x32_bf16 v[20:23], v[144:147], v[214:217], v[20:23]
	v_mfma_f32_16x16x32_bf16 v[16:19], v[152:155], v[214:217], v[16:19]
	v_mfma_f32_16x16x32_bf16 v[4:7], v[144:147], v[222:225], v[4:7]
	v_mfma_f32_16x16x32_bf16 v[0:3], v[152:155], v[222:225], v[0:3]
	v_mfma_f32_16x16x32_bf16 v[52:55], v[148:151], v[184:187], v[52:55]
	v_mfma_f32_16x16x32_bf16 v[48:51], v[156:159], v[184:187], v[48:51]
	v_mfma_f32_16x16x32_bf16 v[36:39], v[148:151], v[210:213], v[36:39]
	v_mfma_f32_16x16x32_bf16 v[32:35], v[156:159], v[210:213], v[32:35]
	v_mfma_f32_16x16x32_bf16 v[20:23], v[148:151], v[218:221], v[20:23]
	v_mfma_f32_16x16x32_bf16 v[16:19], v[156:159], v[218:221], v[16:19]
	v_mfma_f32_16x16x32_bf16 v[4:7], v[148:151], v[226:229], v[4:7]
	v_mfma_f32_16x16x32_bf16 v[0:3], v[156:159], v[226:229], v[0:3]
	s_setprio 0
	s_add_i32 s85, s85, 2
	s_add_u32 s10, s10, 0x100
	s_addc_u32 s11, s11, 0
	s_add_u32 s83, s83, 0x100
	s_addc_u32 s84, s84, 0
	s_cmp_gt_u32 s85, 29
	s_barrier


; #define PG8_BAR __builtin_amdgcn_s_barrier()
; template <class Epi, class Sched, bool ALIGN_EPI = false, bool SP2 = false>
; __device__ __forceinline__ void gemm_phase(PG8_LAS unsigned char* lds, const Gemm g, const Sched& S, const Epi& E) {
;     ...
;         for (int t = 0; t < nt; t += 2) {
;     ...
;         if constexpr (ALIGN_EPI) { if (wr == 0) PG8_BAR; }
	s_cbranch_scc0 .LBB0_428
	s_and_b64 vcc, exec, s[42:43]
	s_cbranch_vccz .LBB0_431
	s_barrier

; #define PG8_STAGE(bufoff, gbase, voff) do { _Pragma("unroll") for (int _i = 0; _i < 2; ++_i) \
;         __builtin_amdgcn_global_load_lds((const unsigned*)((const char*)(gbase) + (voff)[_i]), (PG8_LAS unsigned*)(lds + (bufoff) + ldsw + _i * 8192), 16, 0, 0); } while (0)
; #define PG8_LDA(dst, b, h) do { _Pragma("unroll") for (int m = 0; m < 4; ++m) _Pragma("unroll") for (int k = 0; k < 2; ++k) dst[m][k] = *(const PG8_LAS bf16x8*)(lds + PG8_SA(b, h) + aoff + m * 2048 + k * 1024); } while (0)
; #define PG8_LDB(dst, b, h) do { _Pragma("unroll") for (int n = 0; n < 2; ++n) _Pragma("unroll") for (int k = 0; k < 2; ++k) dst[n][k] = *(const PG8_LAS bf16x8*)(lds + PG8_SB(b, h) + boff + n * 2048 + k * 1024); } while (0)
; #define PG8_SCHED __builtin_amdgcn_sched_barrier(0)
; template <class Epi, class Sched, bool ALIGN_EPI = false, bool SP2 = false>
; __device__ __forceinline__ void gemm_phase(PG8_LAS unsigned char* lds, const Gemm g, const Sched& S, const Epi& E) {
;     ...
;             const bool last = (t == nt - 2);
;             const char* a1 = cA + (size_t)(t + 1) * kstep;
;             const char* a2 = last ? nA : cA + (size_t)(t + 2) * kstep; const char* b2 = last ? nB : cB + (size_t)(t + 2) * kstep;
;             const char* a3 = a2 + kstep; const char* b3 = b2 + kstep;
;             if (last && has_next) S.a_ready(nxt);
;             if constexpr (SP2) {
;             PG8_LDB(B0, 0, 0); PG8_LDB(B1, 0, 1); PG8_SCHED; PG8_LDA(At, 0, 0); PG8_STAGE(PG8_SA(1, 1), a1 + hstep, voffA);
.LBB0_509:
	ds_read_b128 v[64:67], v213
	ds_read_b128 v[68:71], v213 offset:1024
	ds_read_b128 v[72:75], v213 offset:2048
	ds_read_b128 v[76:79], v213 offset:3072
	ds_read_b128 v[144:147], v214
	ds_read_b128 v[148:151], v214 offset:1024
	ds_read_b128 v[152:155], v214 offset:2048
	ds_read_b128 v[156:159], v214 offset:3072
	s_add_u32 s60, s58, 0xffe00080
	s_addc_u32 s61, s59, -1
	s_cmpk_eq_i32 s81, 0x7c
	s_cselect_b32 s63, s11, s61
	s_cselect_b32 s62, s51, s60
	s_cselect_b32 s61, s49, s80
	s_cselect_b32 s60, s78, s79

; #define PG8_STAGE(bufoff, gbase, voff) do { _Pragma("unroll") for (int _i = 0; _i < 2; ++_i) \
;         __builtin_amdgcn_global_load_lds((const unsigned*)((const char*)(gbase) + (voff)[_i]), (PG8_LAS unsigned*)(lds + (bufoff) + ldsw + _i * 8192), 16, 0, 0); } while (0)
; #define PG8_LDA(dst, b, h) do { _Pragma("unroll") for (int m = 0; m < 4; ++m) _Pragma("unroll") for (int k = 0; k < 2; ++k) dst[m][k] = *(const PG8_LAS bf16x8*)(lds + PG8_SA(b, h) + aoff + m * 2048 + k * 1024); } while (0)
; #define PG8_LDB(dst, b, h) do { _Pragma("unroll") for (int n = 0; n < 2; ++n) _Pragma("unroll") for (int k = 0; k < 2; ++k) dst[n][k] = *(const PG8_LAS bf16x8*)(lds + PG8_SB(b, h) + boff + n * 2048 + k * 1024); } while (0)
; #define PG8_SCHED __builtin_amdgcn_sched_barrier(0)
; template <class Epi, class Sched, bool ALIGN_EPI = false, bool SP2 = false>
; __device__ __forceinline__ void gemm_phase(PG8_LAS unsigned char* lds, const Gemm g, const Sched& S, const Epi& E) {
;     ...
;             PG8_LDB(B0, 0, 0); PG8_LDB(B1, 0, 1); PG8_SCHED; PG8_LDA(At, 0, 0); PG8_STAGE(PG8_SA(1, 1), a1 + hstep, voffA);
	s_add_i32 m0, s57, 0xc000
	ds_read_b128 v[176:179], v215
	ds_read_b128 v[180:183], v215 offset:1024
	ds_read_b128 v[184:187], v215 offset:2048
	ds_read_b128 v[188:191], v215 offset:3072
	ds_read_b128 v[192:195], v215 offset:4096
	ds_read_b128 v[196:199], v215 offset:5120
	ds_read_b128 v[200:203], v215 offset:6144
	ds_read_b128 v[204:207], v215 offset:7168
	global_load_lds_dwordx4 v168, s[58:59]

; #define PG8_STAGE(bufoff, gbase, voff) do { _Pragma("unroll") for (int _i = 0; _i < 2; ++_i) \
;         __builtin_amdgcn_global_load_lds((const unsigned*)((const char*)(gbase) + (voff)[_i]), (PG8_LAS unsigned*)(lds + (bufoff) + ldsw + _i * 8192), 16, 0, 0); } while (0)
; #define PG8_LDA(dst, b, h) do { _Pragma("unroll") for (int m = 0; m < 4; ++m) _Pragma("unroll") for (int k = 0; k < 2; ++k) dst[m][k] = *(const PG8_LAS bf16x8*)(lds + PG8_SA(b, h) + aoff + m * 2048 + k * 1024); } while (0)
; #define PG8_LDB(dst, b, h) do { _Pragma("unroll") for (int n = 0; n < 2; ++n) _Pragma("unroll") for (int k = 0; k < 2; ++k) dst[n][k] = *(const PG8_LAS bf16x8*)(lds + PG8_SB(b, h) + boff + n * 2048 + k * 1024); } while (0)
; #define PG8_MMA(ai, bj, At, Bt) do { __builtin_amdgcn_s_setprio(1); _Pragma("unroll") for (int m = 0; m < 4; ++m) _Pragma("unroll") for (int n = 0; n < 2; ++n) _Pragma("unroll") for (int k = 0; k < 2; ++k) \
;         acc[ai][bj][m][n] = __builtin_amdgcn_mfma_f32_16x16x32_bf16(Bt[n][k], At[m][k], acc[ai][bj][m][n], 0, 0, 0); __builtin_amdgcn_s_setprio(0); } while (0)
; #define PG8_WAIT_V(n) asm volatile("s_waitcnt vmcnt(" #n ")" ::: "memory")
; #define PG8_WAIT_L(n) asm volatile("s_waitcnt lgkmcnt(" #n ")" ::: "memory")
; #define PG8_BAR __builtin_amdgcn_s_barrier()
; #define PG8_SCHED __builtin_amdgcn_sched_barrier(0)
; template <class Epi, class Sched, bool ALIGN_EPI = false, bool SP2 = false>
; __device__ __forceinline__ void gemm_phase(PG8_LAS unsigned char* lds, const Gemm g, const Sched& S, const Epi& E) {
;     ...
;             PG8_LDB(B0, 0, 0); PG8_LDB(B1, 0, 1); PG8_SCHED; PG8_LDA(At, 0, 0); PG8_STAGE(PG8_SA(1, 1), a1 + hstep, voffA);
;             PG8_WAIT_V(8); PG8_WAIT_L(0); PG8_BAR; PG8_MMA(0, 0, At, B0); PG8_MMA(0, 1, At, B1); PG8_BAR; PG8_SCHED;
	s_add_i32 m0, s57, 0xe000
	s_nop 0
	global_load_lds_dwordx4 v170, s[58:59]
	s_waitcnt vmcnt(8)
	s_waitcnt lgkmcnt(0)
	s_setprio 1
	s_barrier

; #define PG8_MMA(ai, bj, At, Bt) do { __builtin_amdgcn_s_setprio(1); _Pragma("unroll") for (int m = 0; m < 4; ++m) _Pragma("unroll") for (int n = 0; n < 2; ++n) _Pragma("unroll") for (int k = 0; k < 2; ++k) \
;         acc[ai][bj][m][n] = __builtin_amdgcn_mfma_f32_16x16x32_bf16(Bt[n][k], At[m][k], acc[ai][bj][m][n], 0, 0, 0); __builtin_amdgcn_s_setprio(0); } while (0)
; #define PG8_WAIT_V(n) asm volatile("s_waitcnt vmcnt(" #n ")" ::: "memory")
; #define PG8_WAIT_L(n) asm volatile("s_waitcnt lgkmcnt(" #n ")" ::: "memory")
; #define PG8_BAR __builtin_amdgcn_s_barrier()
; #define PG8_SCHED __builtin_amdgcn_sched_barrier(0)
; template <class Epi, class Sched, bool ALIGN_EPI = false, bool SP2 = false>
; __device__ __forceinline__ void gemm_phase(PG8_LAS unsigned char* lds, const Gemm g, const Sched& S, const Epi& E) {
;     ...
;             PG8_WAIT_V(8); PG8_WAIT_L(0); PG8_BAR; PG8_MMA(0, 0, At, B0); PG8_MMA(0, 1, At, B1); PG8_BAR; PG8_SCHED;
	v_mfma_f32_16x16x32_bf16 v[140:143], v[64:67], v[176:179], v[140:143]
	v_mfma_f32_16x16x32_bf16 v[136:139], v[72:75], v[176:179], v[136:139]
	v_mfma_f32_16x16x32_bf16 v[124:127], v[64:67], v[184:187], v[124:127]
	v_mfma_f32_16x16x32_bf16 v[120:123], v[72:75], v[184:187], v[120:123]
	v_mfma_f32_16x16x32_bf16 v[108:111], v[64:67], v[192:195], v[108:111]
	v_mfma_f32_16x16x32_bf16 v[104:107], v[72:75], v[192:195], v[104:107]
	v_mfma_f32_16x16x32_bf16 v[92:95], v[64:67], v[200:203], v[92:95]
	v_mfma_f32_16x16x32_bf16 v[88:91], v[72:75], v[200:203], v[88:91]
	v_mfma_f32_16x16x32_bf16 v[140:143], v[68:71], v[180:183], v[140:143]
	v_mfma_f32_16x16x32_bf16 v[136:139], v[76:79], v[180:183], v[136:139]
	v_mfma_f32_16x16x32_bf16 v[124:127], v[68:71], v[188:191], v[124:127]
	v_mfma_f32_16x16x32_bf16 v[120:123], v[76:79], v[188:191], v[120:123]
	v_mfma_f32_16x16x32_bf16 v[108:111], v[68:71], v[196:199], v[108:111]
	v_mfma_f32_16x16x32_bf16 v[104:107], v[76:79], v[196:199], v[104:107]
	v_mfma_f32_16x16x32_bf16 v[92:95], v[68:71], v[204:207], v[92:95]
	v_mfma_f32_16x16x32_bf16 v[88:91], v[76:79], v[204:207], v[88:91]


; #define PG8_MMA(ai, bj, At, Bt) do { __builtin_amdgcn_s_setprio(1); _Pragma("unroll") for (int m = 0; m < 4; ++m) _Pragma("unroll") for (int n = 0; n < 2; ++n) _Pragma("unroll") for (int k = 0; k < 2; ++k) \
;         acc[ai][bj][m][n] = __builtin_amdgcn_mfma_f32_16x16x32_bf16(Bt[n][k], At[m][k], acc[ai][bj][m][n], 0, 0, 0); __builtin_amdgcn_s_setprio(0); } while (0)
; #define PG8_WAIT_V(n) asm volatile("s_waitcnt vmcnt(" #n ")" ::: "memory")
; #define PG8_WAIT_L(n) asm volatile("s_waitcnt lgkmcnt(" #n ")" ::: "memory")
; #define PG8_BAR __builtin_amdgcn_s_barrier()
; #define PG8_SCHED __builtin_amdgcn_sched_barrier(0)
; template <class Epi, class Sched, bool ALIGN_EPI = false, bool SP2 = false>
; __device__ __forceinline__ void gemm_phase(PG8_LAS unsigned char* lds, const Gemm g, const Sched& S, const Epi& E) {
;     ...
;             PG8_WAIT_V(8); PG8_WAIT_L(0); PG8_BAR; PG8_MMA(0, 0, At, B0); PG8_MMA(0, 1, At, B1); PG8_BAR; PG8_SCHED;
	v_mfma_f32_16x16x32_bf16 v[132:135], v[144:147], v[176:179], v[132:135]
	v_mfma_f32_16x16x32_bf16 v[128:131], v[152:155], v[176:179], v[128:131]
	v_mfma_f32_16x16x32_bf16 v[116:119], v[144:147], v[184:187], v[116:119]
	v_mfma_f32_16x16x32_bf16 v[112:115], v[152:155], v[184:187], v[112:115]
	v_mfma_f32_16x16x32_bf16 v[100:103], v[144:147], v[192:195], v[100:103]
	v_mfma_f32_16x16x32_bf16 v[96:99], v[152:155], v[192:195], v[96:99]
	v_mfma_f32_16x16x32_bf16 v[84:87], v[144:147], v[200:203], v[84:87]
	v_mfma_f32_16x16x32_bf16 v[80:83], v[152:155], v[200:203], v[80:83]
	v_mfma_f32_16x16x32_bf16 v[132:135], v[148:151], v[180:183], v[132:135]
	v_mfma_f32_16x16x32_bf16 v[128:131], v[156:159], v[180:183], v[128:131]
	v_mfma_f32_16x16x32_bf16 v[116:119], v[148:151], v[188:191], v[116:119]
	v_mfma_f32_16x16x32_bf16 v[112:115], v[156:159], v[188:191], v[112:115]
	v_mfma_f32_16x16x32_bf16 v[100:103], v[148:151], v[196:199], v[100:103]
	v_mfma_f32_16x16x32_bf16 v[96:99], v[156:159], v[196:199], v[96:99]
	v_mfma_f32_16x16x32_bf16 v[84:87], v[148:151], v[204:207], v[84:87]
	v_mfma_f32_16x16x32_bf16 v[80:83], v[156:159], v[204:207], v[80:83]
	s_setprio 0
	s_barrier
	s_add_i32 s82, s75, s64
	s_mov_b64 s[96:97], s[60:61]

; #define PG8_STAGE(bufoff, gbase, voff) do { _Pragma("unroll") for (int _i = 0; _i < 2; ++_i) \
;         __builtin_amdgcn_global_load_lds((const unsigned*)((const char*)(gbase) + (voff)[_i]), (PG8_LAS unsigned*)(lds + (bufoff) + ldsw + _i * 8192), 16, 0, 0); } while (0)
; #define PG8_LDA(dst, b, h) do { _Pragma("unroll") for (int m = 0; m < 4; ++m) _Pragma("unroll") for (int k = 0; k < 2; ++k) dst[m][k] = *(const PG8_LAS bf16x8*)(lds + PG8_SA(b, h) + aoff + m * 2048 + k * 1024); } while (0)
; template <class Epi, class Sched, bool ALIGN_EPI = false, bool SP2 = false>
; __device__ __forceinline__ void gemm_phase(PG8_LAS unsigned char* lds, const Gemm g, const Sched& S, const Epi& E) {
;     ...
;             PG8_LDA(At, 0, 1); PG8_STAGE(PG8_SB(0, 0), b2, voffB); PG8_STAGE(PG8_SB(0, 1), b2 + hstep, voffB); PG8_STAGE(PG8_SA(0, 0), a2, voffA);
	s_mov_b32 m0, s82
	ds_read_b128 v[176:179], v215 offset:16384
	ds_read_b128 v[180:183], v215 offset:17408
	ds_read_b128 v[184:187], v215 offset:18432
	ds_read_b128 v[188:191], v215 offset:19456
	ds_read_b128 v[192:195], v215 offset:20480
	ds_read_b128 v[196:199], v215 offset:21504
	ds_read_b128 v[200:203], v215 offset:22528
	ds_read_b128 v[204:207], v215 offset:23552
	global_load_lds_dwordx4 v162, s[60:61]
	s_add_i32 m0, s82, 0x2000
	s_add_u32 s82, s60, 0x200000

; #define PG8_STAGE(bufoff, gbase, voff) do { _Pragma("unroll") for (int _i = 0; _i < 2; ++_i) \
;         __builtin_amdgcn_global_load_lds((const unsigned*)((const char*)(gbase) + (voff)[_i]), (PG8_LAS unsigned*)(lds + (bufoff) + ldsw + _i * 8192), 16, 0, 0); } while (0)
; #define PG8_LDA(dst, b, h) do { _Pragma("unroll") for (int m = 0; m < 4; ++m) _Pragma("unroll") for (int k = 0; k < 2; ++k) dst[m][k] = *(const PG8_LAS bf16x8*)(lds + PG8_SA(b, h) + aoff + m * 2048 + k * 1024); } while (0)
; template <class Epi, class Sched, bool ALIGN_EPI = false, bool SP2 = false>
; __device__ __forceinline__ void gemm_phase(PG8_LAS unsigned char* lds, const Gemm g, const Sched& S, const Epi& E) {
;     ...
;             PG8_LDA(At, 0, 1); PG8_STAGE(PG8_SB(0, 0), b2, voffB); PG8_STAGE(PG8_SB(0, 1), b2 + hstep, voffB); PG8_STAGE(PG8_SA(0, 0), a2, voffA);
	s_addc_u32 s83, s61, 0
	s_add_i32 s84, s76, s64
	global_load_lds_dwordx4 v166, s[60:61]

; #define PG8_STAGE(bufoff, gbase, voff) do { _Pragma("unroll") for (int _i = 0; _i < 2; ++_i) \
;         __builtin_amdgcn_global_load_lds((const unsigned*)((const char*)(gbase) + (voff)[_i]), (PG8_LAS unsigned*)(lds + (bufoff) + ldsw + _i * 8192), 16, 0, 0); } while (0)
; #define PG8_LDA(dst, b, h) do { _Pragma("unroll") for (int m = 0; m < 4; ++m) _Pragma("unroll") for (int k = 0; k < 2; ++k) dst[m][k] = *(const PG8_LAS bf16x8*)(lds + PG8_SA(b, h) + aoff + m * 2048 + k * 1024); } while (0)
; template <class Epi, class Sched, bool ALIGN_EPI = false, bool SP2 = false>
; __device__ __forceinline__ void gemm_phase(PG8_LAS unsigned char* lds, const Gemm g, const Sched& S, const Epi& E) {
;     ...
;             PG8_LDA(At, 0, 1); PG8_STAGE(PG8_SB(0, 0), b2, voffB); PG8_STAGE(PG8_SB(0, 1), b2 + hstep, voffB); PG8_STAGE(PG8_SA(0, 0), a2, voffA);
	s_mov_b32 m0, s84
	s_nop 0
	global_load_lds_dwordx4 v162, s[82:83]

; #define PG8_STAGE(bufoff, gbase, voff) do { _Pragma("unroll") for (int _i = 0; _i < 2; ++_i) \
;         __builtin_amdgcn_global_load_lds((const unsigned*)((const char*)(gbase) + (voff)[_i]), (PG8_LAS unsigned*)(lds + (bufoff) + ldsw + _i * 8192), 16, 0, 0); } while (0)
; #define PG8_LDA(dst, b, h) do { _Pragma("unroll") for (int m = 0; m < 4; ++m) _Pragma("unroll") for (int k = 0; k < 2; ++k) dst[m][k] = *(const PG8_LAS bf16x8*)(lds + PG8_SA(b, h) + aoff + m * 2048 + k * 1024); } while (0)
; template <class Epi, class Sched, bool ALIGN_EPI = false, bool SP2 = false>
; __device__ __forceinline__ void gemm_phase(PG8_LAS unsigned char* lds, const Gemm g, const Sched& S, const Epi& E) {
;     ...
;             PG8_LDA(At, 0, 1); PG8_STAGE(PG8_SB(0, 0), b2, voffB); PG8_STAGE(PG8_SB(0, 1), b2 + hstep, voffB); PG8_STAGE(PG8_SA(0, 0), a2, voffA);
	s_add_i32 m0, s84, 0x2000
	s_nop 0
	global_load_lds_dwordx4 v166, s[82:83]
	s_mov_b64 s[98:99], s[62:63]

; #define PG8_STAGE(bufoff, gbase, voff) do { _Pragma("unroll") for (int _i = 0; _i < 2; ++_i) \
;         __builtin_amdgcn_global_load_lds((const unsigned*)((const char*)(gbase) + (voff)[_i]), (PG8_LAS unsigned*)(lds + (bufoff) + ldsw + _i * 8192), 16, 0, 0); } while (0)
; #define PG8_LDA(dst, b, h) do { _Pragma("unroll") for (int m = 0; m < 4; ++m) _Pragma("unroll") for (int k = 0; k < 2; ++k) dst[m][k] = *(const PG8_LAS bf16x8*)(lds + PG8_SA(b, h) + aoff + m * 2048 + k * 1024); } while (0)
; #define PG8_MMA(ai, bj, At, Bt) do { __builtin_amdgcn_s_setprio(1); _Pragma("unroll") for (int m = 0; m < 4; ++m) _Pragma("unroll") for (int n = 0; n < 2; ++n) _Pragma("unroll") for (int k = 0; k < 2; ++k) \
;         acc[ai][bj][m][n] = __builtin_amdgcn_mfma_f32_16x16x32_bf16(Bt[n][k], At[m][k], acc[ai][bj][m][n], 0, 0, 0); __builtin_amdgcn_s_setprio(0); } while (0)
; #define PG8_WAIT_V(n) asm volatile("s_waitcnt vmcnt(" #n ")" ::: "memory")
; #define PG8_WAIT_L(n) asm volatile("s_waitcnt lgkmcnt(" #n ")" ::: "memory")
; #define PG8_BAR __builtin_amdgcn_s_barrier()
; #define PG8_SCHED __builtin_amdgcn_sched_barrier(0)
; template <class Epi, class Sched, bool ALIGN_EPI = false, bool SP2 = false>
; __device__ __forceinline__ void gemm_phase(PG8_LAS unsigned char* lds, const Gemm g, const Sched& S, const Epi& E) {
;     ...
;             PG8_LDA(At, 0, 1); PG8_STAGE(PG8_SB(0, 0), b2, voffB); PG8_STAGE(PG8_SB(0, 1), b2 + hstep, voffB); PG8_STAGE(PG8_SA(0, 0), a2, voffA);
;             PG8_WAIT_V(8); PG8_WAIT_L(0); PG8_BAR; PG8_MMA(1, 0, At, B0); PG8_MMA(1, 1, At, B1); PG8_BAR; PG8_SCHED;
	s_mov_b32 m0, s57
	s_nop 0
	global_load_lds_dwordx4 v160, s[62:63]
	s_mov_b32 m0, s65
	s_nop 0
	global_load_lds_dwordx4 v164, s[62:63]
	s_waitcnt vmcnt(8)
	s_waitcnt lgkmcnt(0)
	s_setprio 1
	s_barrier

; #define PG8_MMA(ai, bj, At, Bt) do { __builtin_amdgcn_s_setprio(1); _Pragma("unroll") for (int m = 0; m < 4; ++m) _Pragma("unroll") for (int n = 0; n < 2; ++n) _Pragma("unroll") for (int k = 0; k < 2; ++k) \
;         acc[ai][bj][m][n] = __builtin_amdgcn_mfma_f32_16x16x32_bf16(Bt[n][k], At[m][k], acc[ai][bj][m][n], 0, 0, 0); __builtin_amdgcn_s_setprio(0); } while (0)
; #define PG8_WAIT_V(n) asm volatile("s_waitcnt vmcnt(" #n ")" ::: "memory")
; #define PG8_WAIT_L(n) asm volatile("s_waitcnt lgkmcnt(" #n ")" ::: "memory")
; #define PG8_BAR __builtin_amdgcn_s_barrier()
; #define PG8_SCHED __builtin_amdgcn_sched_barrier(0)
; template <class Epi, class Sched, bool ALIGN_EPI = false, bool SP2 = false>
; __device__ __forceinline__ void gemm_phase(PG8_LAS unsigned char* lds, const Gemm g, const Sched& S, const Epi& E) {
;     ...
;             PG8_WAIT_V(8); PG8_WAIT_L(0); PG8_BAR; PG8_MMA(1, 0, At, B0); PG8_MMA(1, 1, At, B1); PG8_BAR; PG8_SCHED;
	v_mfma_f32_16x16x32_bf16 v[60:63], v[64:67], v[176:179], v[60:63]
	v_mfma_f32_16x16x32_bf16 v[56:59], v[72:75], v[176:179], v[56:59]
	v_mfma_f32_16x16x32_bf16 v[44:47], v[64:67], v[184:187], v[44:47]
	v_mfma_f32_16x16x32_bf16 v[40:43], v[72:75], v[184:187], v[40:43]
	v_mfma_f32_16x16x32_bf16 v[28:31], v[64:67], v[192:195], v[28:31]
	v_mfma_f32_16x16x32_bf16 v[24:27], v[72:75], v[192:195], v[24:27]
	v_mfma_f32_16x16x32_bf16 v[12:15], v[64:67], v[200:203], v[12:15]
	v_mfma_f32_16x16x32_bf16 v[8:11], v[72:75], v[200:203], v[8:11]
	v_mfma_f32_16x16x32_bf16 v[60:63], v[68:71], v[180:183], v[60:63]
	v_mfma_f32_16x16x32_bf16 v[56:59], v[76:79], v[180:183], v[56:59]
	v_mfma_f32_16x16x32_bf16 v[44:47], v[68:71], v[188:191], v[44:47]
	v_mfma_f32_16x16x32_bf16 v[40:43], v[76:79], v[188:191], v[40:43]
	v_mfma_f32_16x16x32_bf16 v[28:31], v[68:71], v[196:199], v[28:31]
	v_mfma_f32_16x16x32_bf16 v[24:27], v[76:79], v[196:199], v[24:27]
	v_mfma_f32_16x16x32_bf16 v[12:15], v[68:71], v[204:207], v[12:15]
	v_mfma_f32_16x16x32_bf16 v[8:11], v[76:79], v[204:207], v[8:11]


; #define PG8_MMA(ai, bj, At, Bt) do { __builtin_amdgcn_s_setprio(1); _Pragma("unroll") for (int m = 0; m < 4; ++m) _Pragma("unroll") for (int n = 0; n < 2; ++n) _Pragma("unroll") for (int k = 0; k < 2; ++k) \
;         acc[ai][bj][m][n] = __builtin_amdgcn_mfma_f32_16x16x32_bf16(Bt[n][k], At[m][k], acc[ai][bj][m][n], 0, 0, 0); __builtin_amdgcn_s_setprio(0); } while (0)
; #define PG8_WAIT_V(n) asm volatile("s_waitcnt vmcnt(" #n ")" ::: "memory")
; #define PG8_WAIT_L(n) asm volatile("s_waitcnt lgkmcnt(" #n ")" ::: "memory")
; #define PG8_BAR __builtin_amdgcn_s_barrier()
; #define PG8_SCHED __builtin_amdgcn_sched_barrier(0)
; template <class Epi, class Sched, bool ALIGN_EPI = false, bool SP2 = false>
; __device__ __forceinline__ void gemm_phase(PG8_LAS unsigned char* lds, const Gemm g, const Sched& S, const Epi& E) {
;     ...
;             PG8_WAIT_V(8); PG8_WAIT_L(0); PG8_BAR; PG8_MMA(1, 0, At, B0); PG8_MMA(1, 1, At, B1); PG8_BAR; PG8_SCHED;
	v_mfma_f32_16x16x32_bf16 v[52:55], v[144:147], v[176:179], v[52:55]
	v_mfma_f32_16x16x32_bf16 v[48:51], v[152:155], v[176:179], v[48:51]
	v_mfma_f32_16x16x32_bf16 v[36:39], v[144:147], v[184:187], v[36:39]
	v_mfma_f32_16x16x32_bf16 v[32:35], v[152:155], v[184:187], v[32:35]
	v_mfma_f32_16x16x32_bf16 v[20:23], v[144:147], v[192:195], v[20:23]
	v_mfma_f32_16x16x32_bf16 v[16:19], v[152:155], v[192:195], v[16:19]
	v_mfma_f32_16x16x32_bf16 v[4:7], v[144:147], v[200:203], v[4:7]
	v_mfma_f32_16x16x32_bf16 v[0:3], v[152:155], v[200:203], v[0:3]
	v_mfma_f32_16x16x32_bf16 v[52:55], v[148:151], v[180:183], v[52:55]
	v_mfma_f32_16x16x32_bf16 v[48:51], v[156:159], v[180:183], v[48:51]
	v_mfma_f32_16x16x32_bf16 v[36:39], v[148:151], v[188:191], v[36:39]
	v_mfma_f32_16x16x32_bf16 v[32:35], v[156:159], v[188:191], v[32:35]
	v_mfma_f32_16x16x32_bf16 v[20:23], v[148:151], v[196:199], v[20:23]
	v_mfma_f32_16x16x32_bf16 v[16:19], v[156:159], v[196:199], v[16:19]
	v_mfma_f32_16x16x32_bf16 v[4:7], v[148:151], v[204:207], v[4:7]
	v_mfma_f32_16x16x32_bf16 v[0:3], v[156:159], v[204:207], v[0:3]
	s_setprio 0
	s_barrier
	s_add_i32 s82, 0, 0x18000
	s_add_i32 s83, 0, 0x1c000


; #define PG8_STAGE(bufoff, gbase, voff) do { _Pragma("unroll") for (int _i = 0; _i < 2; ++_i) \
;         __builtin_amdgcn_global_load_lds((const unsigned*)((const char*)(gbase) + (voff)[_i]), (PG8_LAS unsigned*)(lds + (bufoff) + ldsw + _i * 8192), 16, 0, 0); } while (0)
; #define PG8_LDA(dst, b, h) do { _Pragma("unroll") for (int m = 0; m < 4; ++m) _Pragma("unroll") for (int k = 0; k < 2; ++k) dst[m][k] = *(const PG8_LAS bf16x8*)(lds + PG8_SA(b, h) + aoff + m * 2048 + k * 1024); } while (0)
; #define PG8_LDB(dst, b, h) do { _Pragma("unroll") for (int n = 0; n < 2; ++n) _Pragma("unroll") for (int k = 0; k < 2; ++k) dst[n][k] = *(const PG8_LAS bf16x8*)(lds + PG8_SB(b, h) + boff + n * 2048 + k * 1024); } while (0)
; #define PG8_SCHED __builtin_amdgcn_sched_barrier(0)
; template <class Epi, class Sched, bool ALIGN_EPI = false, bool SP2 = false>
; __device__ __forceinline__ void gemm_phase(PG8_LAS unsigned char* lds, const Gemm g, const Sched& S, const Epi& E) {
;     ...
;             PG8_LDB(B0, 1, 0); PG8_LDB(B1, 1, 1); PG8_SCHED; PG8_LDA(At, 1, 0); PG8_STAGE(PG8_SA(0, 1), a2 + hstep, voffA);
	ds_read_b128 v[64:67], v254
	ds_read_b128 v[68:71], v254 offset:1024
	ds_read_b128 v[72:75], v254 offset:2048
	ds_read_b128 v[76:79], v254 offset:3072
	ds_read_b128 v[144:147], v255
	ds_read_b128 v[148:151], v255 offset:1024
	ds_read_b128 v[152:155], v255 offset:2048
	ds_read_b128 v[156:159], v255 offset:3072
	s_add_u32 s62, s62, 0x200000
	s_addc_u32 s63, s63, 0
	s_mov_b32 m0, s67

; #define PG8_STAGE(bufoff, gbase, voff) do { _Pragma("unroll") for (int _i = 0; _i < 2; ++_i) \
;         __builtin_amdgcn_global_load_lds((const unsigned*)((const char*)(gbase) + (voff)[_i]), (PG8_LAS unsigned*)(lds + (bufoff) + ldsw + _i * 8192), 16, 0, 0); } while (0)
; #define PG8_LDA(dst, b, h) do { _Pragma("unroll") for (int m = 0; m < 4; ++m) _Pragma("unroll") for (int k = 0; k < 2; ++k) dst[m][k] = *(const PG8_LAS bf16x8*)(lds + PG8_SA(b, h) + aoff + m * 2048 + k * 1024); } while (0)
; #define PG8_LDB(dst, b, h) do { _Pragma("unroll") for (int n = 0; n < 2; ++n) _Pragma("unroll") for (int k = 0; k < 2; ++k) dst[n][k] = *(const PG8_LAS bf16x8*)(lds + PG8_SB(b, h) + boff + n * 2048 + k * 1024); } while (0)
; #define PG8_SCHED __builtin_amdgcn_sched_barrier(0)
; template <class Epi, class Sched, bool ALIGN_EPI = false, bool SP2 = false>
; __device__ __forceinline__ void gemm_phase(PG8_LAS unsigned char* lds, const Gemm g, const Sched& S, const Epi& E) {
;     ...
;             PG8_LDB(B0, 1, 0); PG8_LDB(B1, 1, 1); PG8_SCHED; PG8_LDA(At, 1, 0); PG8_STAGE(PG8_SA(0, 1), a2 + hstep, voffA);
	ds_read_b128 v[176:179], v215 offset:32768
	ds_read_b128 v[180:183], v215 offset:33792
	ds_read_b128 v[184:187], v215 offset:34816
	ds_read_b128 v[188:191], v215 offset:35840
	ds_read_b128 v[192:195], v215 offset:36864
	ds_read_b128 v[196:199], v215 offset:37888
	ds_read_b128 v[200:203], v215 offset:38912
	ds_read_b128 v[204:207], v215 offset:39936
	global_load_lds_dwordx4 v160, s[62:63]

; #define PG8_MMA(ai, bj, At, Bt) do { __builtin_amdgcn_s_setprio(1); _Pragma("unroll") for (int m = 0; m < 4; ++m) _Pragma("unroll") for (int n = 0; n < 2; ++n) _Pragma("unroll") for (int k = 0; k < 2; ++k) \
;         acc[ai][bj][m][n] = __builtin_amdgcn_mfma_f32_16x16x32_bf16(Bt[n][k], At[m][k], acc[ai][bj][m][n], 0, 0, 0); __builtin_amdgcn_s_setprio(0); } while (0)
; #define PG8_WAIT_V(n) asm volatile("s_waitcnt vmcnt(" #n ")" ::: "memory")
; #define PG8_WAIT_L(n) asm volatile("s_waitcnt lgkmcnt(" #n ")" ::: "memory")
; #define PG8_BAR __builtin_amdgcn_s_barrier()
; #define PG8_SCHED __builtin_amdgcn_sched_barrier(0)
; template <class Epi, class Sched, bool ALIGN_EPI = false, bool SP2 = false>
; __device__ __forceinline__ void gemm_phase(PG8_LAS unsigned char* lds, const Gemm g, const Sched& S, const Epi& E) {
;     ...
;             PG8_WAIT_V(8); PG8_WAIT_L(0); PG8_BAR; PG8_MMA(0, 0, At, B0); PG8_MMA(0, 1, At, B1); PG8_BAR; PG8_SCHED;
	s_mov_b32 m0, s68
	s_nop 0
	global_load_lds_dwordx4 v164, s[62:63]
	s_waitcnt vmcnt(8)
	s_waitcnt lgkmcnt(0)
	s_setprio 1
	s_barrier

; #define PG8_MMA(ai, bj, At, Bt) do { __builtin_amdgcn_s_setprio(1); _Pragma("unroll") for (int m = 0; m < 4; ++m) _Pragma("unroll") for (int n = 0; n < 2; ++n) _Pragma("unroll") for (int k = 0; k < 2; ++k) \
;         acc[ai][bj][m][n] = __builtin_amdgcn_mfma_f32_16x16x32_bf16(Bt[n][k], At[m][k], acc[ai][bj][m][n], 0, 0, 0); __builtin_amdgcn_s_setprio(0); } while (0)
; #define PG8_WAIT_V(n) asm volatile("s_waitcnt vmcnt(" #n ")" ::: "memory")
; #define PG8_WAIT_L(n) asm volatile("s_waitcnt lgkmcnt(" #n ")" ::: "memory")
; #define PG8_BAR __builtin_amdgcn_s_barrier()
; #define PG8_SCHED __builtin_amdgcn_sched_barrier(0)
; template <class Epi, class Sched, bool ALIGN_EPI = false, bool SP2 = false>
; __device__ __forceinline__ void gemm_phase(PG8_LAS unsigned char* lds, const Gemm g, const Sched& S, const Epi& E) {
;     ...
;             PG8_WAIT_V(8); PG8_WAIT_L(0); PG8_BAR; PG8_MMA(0, 0, At, B0); PG8_MMA(0, 1, At, B1); PG8_BAR; PG8_SCHED;
	v_mfma_f32_16x16x32_bf16 v[140:143], v[64:67], v[176:179], v[140:143]
	v_mfma_f32_16x16x32_bf16 v[136:139], v[72:75], v[176:179], v[136:139]
	v_mfma_f32_16x16x32_bf16 v[124:127], v[64:67], v[184:187], v[124:127]
	v_mfma_f32_16x16x32_bf16 v[120:123], v[72:75], v[184:187], v[120:123]
	v_mfma_f32_16x16x32_bf16 v[108:111], v[64:67], v[192:195], v[108:111]
	v_mfma_f32_16x16x32_bf16 v[104:107], v[72:75], v[192:195], v[104:107]
	v_mfma_f32_16x16x32_bf16 v[92:95], v[64:67], v[200:203], v[92:95]
	v_mfma_f32_16x16x32_bf16 v[88:91], v[72:75], v[200:203], v[88:91]
	v_mfma_f32_16x16x32_bf16 v[140:143], v[68:71], v[180:183], v[140:143]
	v_mfma_f32_16x16x32_bf16 v[136:139], v[76:79], v[180:183], v[136:139]
	v_mfma_f32_16x16x32_bf16 v[124:127], v[68:71], v[188:191], v[124:127]
	v_mfma_f32_16x16x32_bf16 v[120:123], v[76:79], v[188:191], v[120:123]
	v_mfma_f32_16x16x32_bf16 v[108:111], v[68:71], v[196:199], v[108:111]
	v_mfma_f32_16x16x32_bf16 v[104:107], v[76:79], v[196:199], v[104:107]
	v_mfma_f32_16x16x32_bf16 v[92:95], v[68:71], v[204:207], v[92:95]
	v_mfma_f32_16x16x32_bf16 v[88:91], v[76:79], v[204:207], v[88:91]


; #define PG8_STAGE(bufoff, gbase, voff) do { _Pragma("unroll") for (int _i = 0; _i < 2; ++_i) \
;         __builtin_amdgcn_global_load_lds((const unsigned*)((const char*)(gbase) + (voff)[_i]), (PG8_LAS unsigned*)(lds + (bufoff) + ldsw + _i * 8192), 16, 0, 0); } while (0)
; #define PG8_LDA(dst, b, h) do { _Pragma("unroll") for (int m = 0; m < 4; ++m) _Pragma("unroll") for (int k = 0; k < 2; ++k) dst[m][k] = *(const PG8_LAS bf16x8*)(lds + PG8_SA(b, h) + aoff + m * 2048 + k * 1024); } while (0)
; #define PG8_MMA(ai, bj, At, Bt) do { __builtin_amdgcn_s_setprio(1); _Pragma("unroll") for (int m = 0; m < 4; ++m) _Pragma("unroll") for (int n = 0; n < 2; ++n) _Pragma("unroll") for (int k = 0; k < 2; ++k) \
;         acc[ai][bj][m][n] = __builtin_amdgcn_mfma_f32_16x16x32_bf16(Bt[n][k], At[m][k], acc[ai][bj][m][n], 0, 0, 0); __builtin_amdgcn_s_setprio(0); } while (0)
; #define PG8_WAIT_V(n) asm volatile("s_waitcnt vmcnt(" #n ")" ::: "memory")
; #define PG8_WAIT_L(n) asm volatile("s_waitcnt lgkmcnt(" #n ")" ::: "memory")
; #define PG8_BAR __builtin_amdgcn_s_barrier()
; #define PG8_SCHED __builtin_amdgcn_sched_barrier(0)
; template <class Epi, class Sched, bool ALIGN_EPI = false, bool SP2 = false>
; __device__ __forceinline__ void gemm_phase(PG8_LAS unsigned char* lds, const Gemm g, const Sched& S, const Epi& E) {
;     ...
;             PG8_WAIT_V(8); PG8_WAIT_L(0); PG8_BAR; PG8_MMA(0, 0, At, B0); PG8_MMA(0, 1, At, B1); PG8_BAR; PG8_SCHED;
;             PG8_LDA(At, 1, 1); PG8_STAGE(PG8_SB(1, 0), b3, voffB); PG8_STAGE(PG8_SB(1, 1), b3 + hstep, voffB); PG8_STAGE(PG8_SA(1, 0), a3, voffA);
	v_mfma_f32_16x16x32_bf16 v[132:135], v[144:147], v[176:179], v[132:135]
	v_mfma_f32_16x16x32_bf16 v[128:131], v[152:155], v[176:179], v[128:131]
	v_mfma_f32_16x16x32_bf16 v[116:119], v[144:147], v[184:187], v[116:119]
	v_mfma_f32_16x16x32_bf16 v[112:115], v[152:155], v[184:187], v[112:115]
	v_mfma_f32_16x16x32_bf16 v[100:103], v[144:147], v[192:195], v[100:103]
	v_mfma_f32_16x16x32_bf16 v[96:99], v[152:155], v[192:195], v[96:99]
	v_mfma_f32_16x16x32_bf16 v[84:87], v[144:147], v[200:203], v[84:87]
	v_mfma_f32_16x16x32_bf16 v[80:83], v[152:155], v[200:203], v[80:83]
	v_mfma_f32_16x16x32_bf16 v[132:135], v[148:151], v[180:183], v[132:135]
	v_mfma_f32_16x16x32_bf16 v[128:131], v[156:159], v[180:183], v[128:131]
	v_mfma_f32_16x16x32_bf16 v[116:119], v[148:151], v[188:191], v[116:119]
	v_mfma_f32_16x16x32_bf16 v[112:115], v[156:159], v[188:191], v[112:115]
	v_mfma_f32_16x16x32_bf16 v[100:103], v[148:151], v[196:199], v[100:103]
	v_mfma_f32_16x16x32_bf16 v[96:99], v[156:159], v[196:199], v[96:99]
	v_mfma_f32_16x16x32_bf16 v[84:87], v[148:151], v[204:207], v[84:87]
	v_mfma_f32_16x16x32_bf16 v[80:83], v[156:159], v[204:207], v[80:83]
	s_setprio 0
	s_barrier
	s_add_i32 s62, s82, s64

; #define PG8_STAGE(bufoff, gbase, voff) do { _Pragma("unroll") for (int _i = 0; _i < 2; ++_i) \
;         __builtin_amdgcn_global_load_lds((const unsigned*)((const char*)(gbase) + (voff)[_i]), (PG8_LAS unsigned*)(lds + (bufoff) + ldsw + _i * 8192), 16, 0, 0); } while (0)
; #define PG8_LDA(dst, b, h) do { _Pragma("unroll") for (int m = 0; m < 4; ++m) _Pragma("unroll") for (int k = 0; k < 2; ++k) dst[m][k] = *(const PG8_LAS bf16x8*)(lds + PG8_SA(b, h) + aoff + m * 2048 + k * 1024); } while (0)
; template <class Epi, class Sched, bool ALIGN_EPI = false, bool SP2 = false>
; __device__ __forceinline__ void gemm_phase(PG8_LAS unsigned char* lds, const Gemm g, const Sched& S, const Epi& E) {
;     ...
;             PG8_LDA(At, 1, 1); PG8_STAGE(PG8_SB(1, 0), b3, voffB); PG8_STAGE(PG8_SB(1, 1), b3 + hstep, voffB); PG8_STAGE(PG8_SA(1, 0), a3, voffA);
	s_mov_b32 m0, s62
	ds_read_b128 v[176:179], v215 offset:49152
	ds_read_b128 v[180:183], v215 offset:50176
	ds_read_b128 v[184:187], v215 offset:51200
	ds_read_b128 v[188:191], v215 offset:52224
	ds_read_b128 v[192:195], v215 offset:53248
	ds_read_b128 v[196:199], v215 offset:54272
	ds_read_b128 v[200:203], v215 offset:55296
	ds_read_b128 v[204:207], v215 offset:56320
	global_load_lds_dwordx4 v250, s[96:97]
	s_add_i32 m0, s62, 0x2000
	s_add_u32 s60, s60, 0x200080

; #define PG8_STAGE(bufoff, gbase, voff) do { _Pragma("unroll") for (int _i = 0; _i < 2; ++_i) \
;         __builtin_amdgcn_global_load_lds((const unsigned*)((const char*)(gbase) + (voff)[_i]), (PG8_LAS unsigned*)(lds + (bufoff) + ldsw + _i * 8192), 16, 0, 0); } while (0)
; #define PG8_LDA(dst, b, h) do { _Pragma("unroll") for (int m = 0; m < 4; ++m) _Pragma("unroll") for (int k = 0; k < 2; ++k) dst[m][k] = *(const PG8_LAS bf16x8*)(lds + PG8_SA(b, h) + aoff + m * 2048 + k * 1024); } while (0)
; template <class Epi, class Sched, bool ALIGN_EPI = false, bool SP2 = false>
; __device__ __forceinline__ void gemm_phase(PG8_LAS unsigned char* lds, const Gemm g, const Sched& S, const Epi& E) {
;     ...
;             PG8_LDA(At, 1, 1); PG8_STAGE(PG8_SB(1, 0), b3, voffB); PG8_STAGE(PG8_SB(1, 1), b3 + hstep, voffB); PG8_STAGE(PG8_SA(1, 0), a3, voffA);
	s_addc_u32 s61, s61, 0
	s_add_i32 s62, s83, s64
	global_load_lds_dwordx4 v251, s[96:97]

; #define PG8_STAGE(bufoff, gbase, voff) do { _Pragma("unroll") for (int _i = 0; _i < 2; ++_i) \
;         __builtin_amdgcn_global_load_lds((const unsigned*)((const char*)(gbase) + (voff)[_i]), (PG8_LAS unsigned*)(lds + (bufoff) + ldsw + _i * 8192), 16, 0, 0); } while (0)
; #define PG8_LDA(dst, b, h) do { _Pragma("unroll") for (int m = 0; m < 4; ++m) _Pragma("unroll") for (int k = 0; k < 2; ++k) dst[m][k] = *(const PG8_LAS bf16x8*)(lds + PG8_SA(b, h) + aoff + m * 2048 + k * 1024); } while (0)
; template <class Epi, class Sched, bool ALIGN_EPI = false, bool SP2 = false>
; __device__ __forceinline__ void gemm_phase(PG8_LAS unsigned char* lds, const Gemm g, const Sched& S, const Epi& E) {
;     ...
;             PG8_LDA(At, 1, 1); PG8_STAGE(PG8_SB(1, 0), b3, voffB); PG8_STAGE(PG8_SB(1, 1), b3 + hstep, voffB); PG8_STAGE(PG8_SA(1, 0), a3, voffA);
	s_mov_b32 m0, s62
	s_nop 0
	global_load_lds_dwordx4 v162, s[60:61]

; #define PG8_STAGE(bufoff, gbase, voff) do { _Pragma("unroll") for (int _i = 0; _i < 2; ++_i) \
;         __builtin_amdgcn_global_load_lds((const unsigned*)((const char*)(gbase) + (voff)[_i]), (PG8_LAS unsigned*)(lds + (bufoff) + ldsw + _i * 8192), 16, 0, 0); } while (0)
; #define PG8_LDA(dst, b, h) do { _Pragma("unroll") for (int m = 0; m < 4; ++m) _Pragma("unroll") for (int k = 0; k < 2; ++k) dst[m][k] = *(const PG8_LAS bf16x8*)(lds + PG8_SA(b, h) + aoff + m * 2048 + k * 1024); } while (0)
; template <class Epi, class Sched, bool ALIGN_EPI = false, bool SP2 = false>
; __device__ __forceinline__ void gemm_phase(PG8_LAS unsigned char* lds, const Gemm g, const Sched& S, const Epi& E) {
;     ...
;             PG8_LDA(At, 1, 1); PG8_STAGE(PG8_SB(1, 0), b3, voffB); PG8_STAGE(PG8_SB(1, 1), b3 + hstep, voffB); PG8_STAGE(PG8_SA(1, 0), a3, voffA);
	s_add_i32 m0, s62, 0x2000
	s_nop 0
	global_load_lds_dwordx4 v166, s[60:61]

; #define PG8_STAGE(bufoff, gbase, voff) do { _Pragma("unroll") for (int _i = 0; _i < 2; ++_i) \
;         __builtin_amdgcn_global_load_lds((const unsigned*)((const char*)(gbase) + (voff)[_i]), (PG8_LAS unsigned*)(lds + (bufoff) + ldsw + _i * 8192), 16, 0, 0); } while (0)
; #define PG8_LDA(dst, b, h) do { _Pragma("unroll") for (int m = 0; m < 4; ++m) _Pragma("unroll") for (int k = 0; k < 2; ++k) dst[m][k] = *(const PG8_LAS bf16x8*)(lds + PG8_SA(b, h) + aoff + m * 2048 + k * 1024); } while (0)
; template <class Epi, class Sched, bool ALIGN_EPI = false, bool SP2 = false>
; __device__ __forceinline__ void gemm_phase(PG8_LAS unsigned char* lds, const Gemm g, const Sched& S, const Epi& E) {
;     ...
;             PG8_LDA(At, 1, 1); PG8_STAGE(PG8_SB(1, 0), b3, voffB); PG8_STAGE(PG8_SB(1, 1), b3 + hstep, voffB); PG8_STAGE(PG8_SA(1, 0), a3, voffA);
	s_mov_b32 m0, s70
	s_nop 0
	global_load_lds_dwordx4 v252, s[98:99]

; #define PG8_MMA(ai, bj, At, Bt) do { __builtin_amdgcn_s_setprio(1); _Pragma("unroll") for (int m = 0; m < 4; ++m) _Pragma("unroll") for (int n = 0; n < 2; ++n) _Pragma("unroll") for (int k = 0; k < 2; ++k) \
;         acc[ai][bj][m][n] = __builtin_amdgcn_mfma_f32_16x16x32_bf16(Bt[n][k], At[m][k], acc[ai][bj][m][n], 0, 0, 0); __builtin_amdgcn_s_setprio(0); } while (0)
; #define PG8_WAIT_V(n) asm volatile("s_waitcnt vmcnt(" #n ")" ::: "memory")
; #define PG8_WAIT_L(n) asm volatile("s_waitcnt lgkmcnt(" #n ")" ::: "memory")
; #define PG8_BAR __builtin_amdgcn_s_barrier()
; #define PG8_SCHED __builtin_amdgcn_sched_barrier(0)
; template <class Epi, class Sched, bool ALIGN_EPI = false, bool SP2 = false>
; __device__ __forceinline__ void gemm_phase(PG8_LAS unsigned char* lds, const Gemm g, const Sched& S, const Epi& E) {
;     ...
;             PG8_WAIT_V(8); PG8_WAIT_L(0); PG8_BAR; PG8_MMA(1, 0, At, B0); PG8_MMA(1, 1, At, B1); PG8_BAR; PG8_SCHED;
	s_mov_b32 m0, s71
	s_nop 0
	global_load_lds_dwordx4 v253, s[98:99]
	s_waitcnt vmcnt(8)
	s_waitcnt lgkmcnt(0)
	s_setprio 1
	s_barrier

; #define PG8_MMA(ai, bj, At, Bt) do { __builtin_amdgcn_s_setprio(1); _Pragma("unroll") for (int m = 0; m < 4; ++m) _Pragma("unroll") for (int n = 0; n < 2; ++n) _Pragma("unroll") for (int k = 0; k < 2; ++k) \
;         acc[ai][bj][m][n] = __builtin_amdgcn_mfma_f32_16x16x32_bf16(Bt[n][k], At[m][k], acc[ai][bj][m][n], 0, 0, 0); __builtin_amdgcn_s_setprio(0); } while (0)
; #define PG8_WAIT_V(n) asm volatile("s_waitcnt vmcnt(" #n ")" ::: "memory")
; #define PG8_WAIT_L(n) asm volatile("s_waitcnt lgkmcnt(" #n ")" ::: "memory")
; #define PG8_BAR __builtin_amdgcn_s_barrier()
; #define PG8_SCHED __builtin_amdgcn_sched_barrier(0)
; template <class Epi, class Sched, bool ALIGN_EPI = false, bool SP2 = false>
; __device__ __forceinline__ void gemm_phase(PG8_LAS unsigned char* lds, const Gemm g, const Sched& S, const Epi& E) {
;     ...
;             PG8_WAIT_V(8); PG8_WAIT_L(0); PG8_BAR; PG8_MMA(1, 0, At, B0); PG8_MMA(1, 1, At, B1); PG8_BAR; PG8_SCHED;
	v_mfma_f32_16x16x32_bf16 v[60:63], v[64:67], v[176:179], v[60:63]
	v_mfma_f32_16x16x32_bf16 v[56:59], v[72:75], v[176:179], v[56:59]
	v_mfma_f32_16x16x32_bf16 v[44:47], v[64:67], v[184:187], v[44:47]
	v_mfma_f32_16x16x32_bf16 v[40:43], v[72:75], v[184:187], v[40:43]
	v_mfma_f32_16x16x32_bf16 v[28:31], v[64:67], v[192:195], v[28:31]
	v_mfma_f32_16x16x32_bf16 v[24:27], v[72:75], v[192:195], v[24:27]
	v_mfma_f32_16x16x32_bf16 v[12:15], v[64:67], v[200:203], v[12:15]
	v_mfma_f32_16x16x32_bf16 v[8:11], v[72:75], v[200:203], v[8:11]
	v_mfma_f32_16x16x32_bf16 v[60:63], v[68:71], v[180:183], v[60:63]
	v_mfma_f32_16x16x32_bf16 v[56:59], v[76:79], v[180:183], v[56:59]
	v_mfma_f32_16x16x32_bf16 v[44:47], v[68:71], v[188:191], v[44:47]
	v_mfma_f32_16x16x32_bf16 v[40:43], v[76:79], v[188:191], v[40:43]
	v_mfma_f32_16x16x32_bf16 v[28:31], v[68:71], v[196:199], v[28:31]
	v_mfma_f32_16x16x32_bf16 v[24:27], v[76:79], v[196:199], v[24:27]
	v_mfma_f32_16x16x32_bf16 v[12:15], v[68:71], v[204:207], v[12:15]
	v_mfma_f32_16x16x32_bf16 v[8:11], v[76:79], v[204:207], v[8:11]


; #define PG8_MMA(ai, bj, At, Bt) do { __builtin_amdgcn_s_setprio(1); _Pragma("unroll") for (int m = 0; m < 4; ++m) _Pragma("unroll") for (int n = 0; n < 2; ++n) _Pragma("unroll") for (int k = 0; k < 2; ++k) \
;         acc[ai][bj][m][n] = __builtin_amdgcn_mfma_f32_16x16x32_bf16(Bt[n][k], At[m][k], acc[ai][bj][m][n], 0, 0, 0); __builtin_amdgcn_s_setprio(0); } while (0)
; #define PG8_WAIT_V(n) asm volatile("s_waitcnt vmcnt(" #n ")" ::: "memory")
; #define PG8_WAIT_L(n) asm volatile("s_waitcnt lgkmcnt(" #n ")" ::: "memory")
; #define PG8_BAR __builtin_amdgcn_s_barrier()
; #define PG8_SCHED __builtin_amdgcn_sched_barrier(0)
; template <class Epi, class Sched, bool ALIGN_EPI = false, bool SP2 = false>
; __device__ __forceinline__ void gemm_phase(PG8_LAS unsigned char* lds, const Gemm g, const Sched& S, const Epi& E) {
;     ...
;         for (int t = 0; t < nt; t += 2) {
;     ...
;             PG8_WAIT_V(8); PG8_WAIT_L(0); PG8_BAR; PG8_MMA(1, 0, At, B0); PG8_MMA(1, 1, At, B1); PG8_BAR; PG8_SCHED;
	v_mfma_f32_16x16x32_bf16 v[52:55], v[144:147], v[176:179], v[52:55]
	v_mfma_f32_16x16x32_bf16 v[48:51], v[152:155], v[176:179], v[48:51]
	v_mfma_f32_16x16x32_bf16 v[36:39], v[144:147], v[184:187], v[36:39]
	v_mfma_f32_16x16x32_bf16 v[32:35], v[152:155], v[184:187], v[32:35]
	v_mfma_f32_16x16x32_bf16 v[20:23], v[144:147], v[192:195], v[20:23]
	v_mfma_f32_16x16x32_bf16 v[16:19], v[152:155], v[192:195], v[16:19]
	v_mfma_f32_16x16x32_bf16 v[4:7], v[144:147], v[200:203], v[4:7]
	v_mfma_f32_16x16x32_bf16 v[0:3], v[152:155], v[200:203], v[0:3]
	v_mfma_f32_16x16x32_bf16 v[52:55], v[148:151], v[180:183], v[52:55]
	v_mfma_f32_16x16x32_bf16 v[48:51], v[156:159], v[180:183], v[48:51]
	v_mfma_f32_16x16x32_bf16 v[36:39], v[148:151], v[188:191], v[36:39]
	v_mfma_f32_16x16x32_bf16 v[32:35], v[156:159], v[188:191], v[32:35]
	v_mfma_f32_16x16x32_bf16 v[20:23], v[148:151], v[196:199], v[20:23]
	v_mfma_f32_16x16x32_bf16 v[16:19], v[156:159], v[196:199], v[16:19]
	v_mfma_f32_16x16x32_bf16 v[4:7], v[148:151], v[204:207], v[4:7]
	v_mfma_f32_16x16x32_bf16 v[0:3], v[156:159], v[204:207], v[0:3]
	s_setprio 0
	s_add_i32 s81, s81, 2
	s_add_u32 s58, s58, 0x100
	s_addc_u32 s59, s59, 0
	s_add_u32 s79, s79, 0x100
	s_addc_u32 s80, s80, 0
	s_cmpk_gt_u32 s81, 0x7d
	s_barrier


; #define PG8_BAR __builtin_amdgcn_s_barrier()
; template <class Epi, class Sched, bool ALIGN_EPI = false, bool SP2 = false>
; __device__ __forceinline__ void gemm_phase(PG8_LAS unsigned char* lds, const Gemm g, const Sched& S, const Epi& E) {
;     ...
;         for (int t = 0; t < nt; t += 2) {
;     ...
;         if constexpr (ALIGN_EPI) { if (wr == 0) PG8_BAR; }
	s_cbranch_scc0 .LBB0_509
	s_and_b64 vcc, exec, s[42:43]
	s_cbranch_vccz .LBB0_512
	s_barrier

; #define PG8_STAGE(bufoff, gbase, voff) do { _Pragma("unroll") for (int _i = 0; _i < 2; ++_i) \
;         __builtin_amdgcn_global_load_lds((const unsigned*)((const char*)(gbase) + (voff)[_i]), (PG8_LAS unsigned*)(lds + (bufoff) + ldsw + _i * 8192), 16, 0, 0); } while (0)
; #define PG8_LDA(dst, b, h) do { _Pragma("unroll") for (int m = 0; m < 4; ++m) _Pragma("unroll") for (int k = 0; k < 2; ++k) dst[m][k] = *(const PG8_LAS bf16x8*)(lds + PG8_SA(b, h) + aoff + m * 2048 + k * 1024); } while (0)
; #define PG8_LDB(dst, b, h) do { _Pragma("unroll") for (int n = 0; n < 2; ++n) _Pragma("unroll") for (int k = 0; k < 2; ++k) dst[n][k] = *(const PG8_LAS bf16x8*)(lds + PG8_SB(b, h) + boff + n * 2048 + k * 1024); } while (0)
; #define PG8_SCHED __builtin_amdgcn_sched_barrier(0)
; template <class Epi, class Sched, bool ALIGN_EPI = false, bool SP2 = false>
; __device__ __forceinline__ void gemm_phase(PG8_LAS unsigned char* lds, const Gemm g, const Sched& S, const Epi& E) {
;     ...
;             const bool last = (t == nt - 2);
;             const char* a1 = cA + (size_t)(t + 1) * kstep;
;             const char* a2 = last ? nA : cA + (size_t)(t + 2) * kstep; const char* b2 = last ? nB : cB + (size_t)(t + 2) * kstep;
;             const char* a3 = a2 + kstep; const char* b3 = b2 + kstep;
;     ...
;             PG8_LDB(B0, 0, 0); PG8_LDB(B1, 0, 1); PG8_SCHED; PG8_LDA(At, 0, 0); PG8_STAGE(PG8_SA(1, 1), a1 + hstep, voffA);
.LBB0_679:
	ds_read_b128 v[128:131], v203
	ds_read_b128 v[132:135], v203 offset:1024
	ds_read_b128 v[136:139], v203 offset:2048
	ds_read_b128 v[140:143], v203 offset:3072
	ds_read_b128 v[144:147], v205
	ds_read_b128 v[148:151], v205 offset:1024
	ds_read_b128 v[152:155], v205 offset:2048
	ds_read_b128 v[156:159], v205 offset:3072
	s_add_u32 s12, s10, 0xfff80080
	s_addc_u32 s13, s11, -1
	s_cmp_eq_u32 s78, 28
	s_cselect_b32 s55, s49, s13
	s_cselect_b32 s54, s74, s12
	s_cselect_b32 s13, s47, s77
	s_cselect_b32 s12, s75, s76

; #define PG8_STAGE(bufoff, gbase, voff) do { _Pragma("unroll") for (int _i = 0; _i < 2; ++_i) \
;         __builtin_amdgcn_global_load_lds((const unsigned*)((const char*)(gbase) + (voff)[_i]), (PG8_LAS unsigned*)(lds + (bufoff) + ldsw + _i * 8192), 16, 0, 0); } while (0)
; #define PG8_LDA(dst, b, h) do { _Pragma("unroll") for (int m = 0; m < 4; ++m) _Pragma("unroll") for (int k = 0; k < 2; ++k) dst[m][k] = *(const PG8_LAS bf16x8*)(lds + PG8_SA(b, h) + aoff + m * 2048 + k * 1024); } while (0)
; #define PG8_LDB(dst, b, h) do { _Pragma("unroll") for (int n = 0; n < 2; ++n) _Pragma("unroll") for (int k = 0; k < 2; ++k) dst[n][k] = *(const PG8_LAS bf16x8*)(lds + PG8_SB(b, h) + boff + n * 2048 + k * 1024); } while (0)
; #define PG8_SCHED __builtin_amdgcn_sched_barrier(0)
; template <class Epi, class Sched, bool ALIGN_EPI = false, bool SP2 = false>
; __device__ __forceinline__ void gemm_phase(PG8_LAS unsigned char* lds, const Gemm g, const Sched& S, const Epi& E) {
;     ...
;             PG8_LDB(B0, 0, 0); PG8_LDB(B1, 0, 1); PG8_SCHED; PG8_LDA(At, 0, 0); PG8_STAGE(PG8_SA(1, 1), a1 + hstep, voffA);
	s_add_i32 m0, s60, 0xc000
	ds_read_b128 v[176:179], v207
	ds_read_b128 v[180:183], v207 offset:1024
	ds_read_b128 v[184:187], v207 offset:2048
	ds_read_b128 v[192:195], v207 offset:3072
	ds_read_b128 v[210:213], v207 offset:4096
	ds_read_b128 v[214:217], v207 offset:5120
	ds_read_b128 v[218:221], v207 offset:6144
	ds_read_b128 v[222:225], v207 offset:7168
	global_load_lds_dwordx4 v168, s[10:11]

; #define PG8_MMA(ai, bj, At, Bt) do { __builtin_amdgcn_s_setprio(1); _Pragma("unroll") for (int m = 0; m < 4; ++m) _Pragma("unroll") for (int n = 0; n < 2; ++n) _Pragma("unroll") for (int k = 0; k < 2; ++k) \
;         acc[ai][bj][m][n] = __builtin_amdgcn_mfma_f32_16x16x32_bf16(Bt[n][k], At[m][k], acc[ai][bj][m][n], 0, 0, 0); __builtin_amdgcn_s_setprio(0); } while (0)
; #define PG8_WAIT_V(n) asm volatile("s_waitcnt vmcnt(" #n ")" ::: "memory")
; #define PG8_WAIT_L(n) asm volatile("s_waitcnt lgkmcnt(" #n ")" ::: "memory")
; #define PG8_BAR __builtin_amdgcn_s_barrier()
; #define PG8_SCHED __builtin_amdgcn_sched_barrier(0)
; template <class Epi, class Sched, bool ALIGN_EPI = false, bool SP2 = false>
; __device__ __forceinline__ void gemm_phase(PG8_LAS unsigned char* lds, const Gemm g, const Sched& S, const Epi& E) {
;     ...
;             PG8_WAIT_V(8); PG8_WAIT_L(0); PG8_BAR; PG8_MMA(0, 0, At, B0); PG8_MMA(0, 1, At, B1); PG8_BAR; PG8_SCHED;
	s_add_i32 m0, s60, 0xe000
	s_nop 0
	global_load_lds_dwordx4 v170, s[10:11]
	s_waitcnt vmcnt(8)
	s_waitcnt lgkmcnt(0)
	s_setprio 1
	s_barrier

; #define PG8_MMA(ai, bj, At, Bt) do { __builtin_amdgcn_s_setprio(1); _Pragma("unroll") for (int m = 0; m < 4; ++m) _Pragma("unroll") for (int n = 0; n < 2; ++n) _Pragma("unroll") for (int k = 0; k < 2; ++k) \
;         acc[ai][bj][m][n] = __builtin_amdgcn_mfma_f32_16x16x32_bf16(Bt[n][k], At[m][k], acc[ai][bj][m][n], 0, 0, 0); __builtin_amdgcn_s_setprio(0); } while (0)
; #define PG8_WAIT_V(n) asm volatile("s_waitcnt vmcnt(" #n ")" ::: "memory")
; #define PG8_WAIT_L(n) asm volatile("s_waitcnt lgkmcnt(" #n ")" ::: "memory")
; #define PG8_BAR __builtin_amdgcn_s_barrier()
; #define PG8_SCHED __builtin_amdgcn_sched_barrier(0)
; template <class Epi, class Sched, bool ALIGN_EPI = false, bool SP2 = false>
; __device__ __forceinline__ void gemm_phase(PG8_LAS unsigned char* lds, const Gemm g, const Sched& S, const Epi& E) {
;     ...
;             PG8_WAIT_V(8); PG8_WAIT_L(0); PG8_BAR; PG8_MMA(0, 0, At, B0); PG8_MMA(0, 1, At, B1); PG8_BAR; PG8_SCHED;
	v_mfma_f32_16x16x32_bf16 v[124:127], v[128:131], v[176:179], v[124:127]
	v_mfma_f32_16x16x32_bf16 v[120:123], v[136:139], v[176:179], v[120:123]
	v_mfma_f32_16x16x32_bf16 v[112:115], v[128:131], v[184:187], v[112:115]
	v_mfma_f32_16x16x32_bf16 v[104:107], v[136:139], v[184:187], v[104:107]
	v_mfma_f32_16x16x32_bf16 v[100:103], v[128:131], v[210:213], v[100:103]
	v_mfma_f32_16x16x32_bf16 v[88:91], v[136:139], v[210:213], v[88:91]
	v_mfma_f32_16x16x32_bf16 v[84:87], v[128:131], v[218:221], v[84:87]
	v_mfma_f32_16x16x32_bf16 v[72:75], v[136:139], v[218:221], v[72:75]
	v_mfma_f32_16x16x32_bf16 v[124:127], v[132:135], v[180:183], v[124:127]
	v_mfma_f32_16x16x32_bf16 v[120:123], v[140:143], v[180:183], v[120:123]
	v_mfma_f32_16x16x32_bf16 v[112:115], v[132:135], v[192:195], v[112:115]
	v_mfma_f32_16x16x32_bf16 v[104:107], v[140:143], v[192:195], v[104:107]
	v_mfma_f32_16x16x32_bf16 v[100:103], v[132:135], v[214:217], v[100:103]
	v_mfma_f32_16x16x32_bf16 v[88:91], v[140:143], v[214:217], v[88:91]
	v_mfma_f32_16x16x32_bf16 v[84:87], v[132:135], v[222:225], v[84:87]
	v_mfma_f32_16x16x32_bf16 v[72:75], v[140:143], v[222:225], v[72:75]


; #define PG8_STAGE(bufoff, gbase, voff) do { _Pragma("unroll") for (int _i = 0; _i < 2; ++_i) \
;         __builtin_amdgcn_global_load_lds((const unsigned*)((const char*)(gbase) + (voff)[_i]), (PG8_LAS unsigned*)(lds + (bufoff) + ldsw + _i * 8192), 16, 0, 0); } while (0)
; #define PG8_LDA(dst, b, h) do { _Pragma("unroll") for (int m = 0; m < 4; ++m) _Pragma("unroll") for (int k = 0; k < 2; ++k) dst[m][k] = *(const PG8_LAS bf16x8*)(lds + PG8_SA(b, h) + aoff + m * 2048 + k * 1024); } while (0)
; #define PG8_MMA(ai, bj, At, Bt) do { __builtin_amdgcn_s_setprio(1); _Pragma("unroll") for (int m = 0; m < 4; ++m) _Pragma("unroll") for (int n = 0; n < 2; ++n) _Pragma("unroll") for (int k = 0; k < 2; ++k) \
;         acc[ai][bj][m][n] = __builtin_amdgcn_mfma_f32_16x16x32_bf16(Bt[n][k], At[m][k], acc[ai][bj][m][n], 0, 0, 0); __builtin_amdgcn_s_setprio(0); } while (0)
; #define PG8_WAIT_V(n) asm volatile("s_waitcnt vmcnt(" #n ")" ::: "memory")
; #define PG8_WAIT_L(n) asm volatile("s_waitcnt lgkmcnt(" #n ")" ::: "memory")
; #define PG8_BAR __builtin_amdgcn_s_barrier()
; #define PG8_SCHED __builtin_amdgcn_sched_barrier(0)
; template <class Epi, class Sched, bool ALIGN_EPI = false, bool SP2 = false>
; __device__ __forceinline__ void gemm_phase(PG8_LAS unsigned char* lds, const Gemm g, const Sched& S, const Epi& E) {
;     ...
;             PG8_WAIT_V(8); PG8_WAIT_L(0); PG8_BAR; PG8_MMA(0, 0, At, B0); PG8_MMA(0, 1, At, B1); PG8_BAR; PG8_SCHED;
;             PG8_LDA(At, 0, 1); PG8_STAGE(PG8_SB(0, 0), b2, voffB); PG8_STAGE(PG8_SB(0, 1), b2 + hstep, voffB); PG8_STAGE(PG8_SA(0, 0), a2, voffA);
	v_mfma_f32_16x16x32_bf16 v[116:119], v[144:147], v[176:179], v[116:119]
	v_mfma_f32_16x16x32_bf16 v[108:111], v[152:155], v[176:179], v[108:111]
	v_mfma_f32_16x16x32_bf16 v[96:99], v[144:147], v[184:187], v[96:99]
	v_mfma_f32_16x16x32_bf16 v[92:95], v[152:155], v[184:187], v[92:95]
	v_mfma_f32_16x16x32_bf16 v[80:83], v[144:147], v[210:213], v[80:83]
	v_mfma_f32_16x16x32_bf16 v[76:79], v[152:155], v[210:213], v[76:79]
	v_mfma_f32_16x16x32_bf16 v[68:71], v[144:147], v[218:221], v[68:71]
	v_mfma_f32_16x16x32_bf16 v[64:67], v[152:155], v[218:221], v[64:67]
	v_mfma_f32_16x16x32_bf16 v[116:119], v[148:151], v[180:183], v[116:119]
	v_mfma_f32_16x16x32_bf16 v[108:111], v[156:159], v[180:183], v[108:111]
	v_mfma_f32_16x16x32_bf16 v[96:99], v[148:151], v[192:195], v[96:99]
	v_mfma_f32_16x16x32_bf16 v[92:95], v[156:159], v[192:195], v[92:95]
	v_mfma_f32_16x16x32_bf16 v[80:83], v[148:151], v[214:217], v[80:83]
	v_mfma_f32_16x16x32_bf16 v[76:79], v[156:159], v[214:217], v[76:79]
	v_mfma_f32_16x16x32_bf16 v[68:71], v[148:151], v[222:225], v[68:71]
	v_mfma_f32_16x16x32_bf16 v[64:67], v[156:159], v[222:225], v[64:67]
	s_setprio 0
	s_barrier
	s_add_i32 s79, s70, s57
	s_mov_b64 s[96:97], s[12:13]

; #define PG8_STAGE(bufoff, gbase, voff) do { _Pragma("unroll") for (int _i = 0; _i < 2; ++_i) \
;         __builtin_amdgcn_global_load_lds((const unsigned*)((const char*)(gbase) + (voff)[_i]), (PG8_LAS unsigned*)(lds + (bufoff) + ldsw + _i * 8192), 16, 0, 0); } while (0)
; #define PG8_LDA(dst, b, h) do { _Pragma("unroll") for (int m = 0; m < 4; ++m) _Pragma("unroll") for (int k = 0; k < 2; ++k) dst[m][k] = *(const PG8_LAS bf16x8*)(lds + PG8_SA(b, h) + aoff + m * 2048 + k * 1024); } while (0)
; template <class Epi, class Sched, bool ALIGN_EPI = false, bool SP2 = false>
; __device__ __forceinline__ void gemm_phase(PG8_LAS unsigned char* lds, const Gemm g, const Sched& S, const Epi& E) {
;     ...
;             PG8_LDA(At, 0, 1); PG8_STAGE(PG8_SB(0, 0), b2, voffB); PG8_STAGE(PG8_SB(0, 1), b2 + hstep, voffB); PG8_STAGE(PG8_SA(0, 0), a2, voffA);
	s_mov_b32 m0, s79
	ds_read_b128 v[176:179], v207 offset:16384
	ds_read_b128 v[180:183], v207 offset:17408
	ds_read_b128 v[184:187], v207 offset:18432
	ds_read_b128 v[192:195], v207 offset:19456
	ds_read_b128 v[210:213], v207 offset:20480
	ds_read_b128 v[214:217], v207 offset:21504
	ds_read_b128 v[218:221], v207 offset:22528
	ds_read_b128 v[222:225], v207 offset:23552
	global_load_lds_dwordx4 v164, s[12:13]
	s_add_i32 m0, s79, 0x2000
	s_add_u32 s80, s12, 0x80000

; #define PG8_STAGE(bufoff, gbase, voff) do { _Pragma("unroll") for (int _i = 0; _i < 2; ++_i) \
;         __builtin_amdgcn_global_load_lds((const unsigned*)((const char*)(gbase) + (voff)[_i]), (PG8_LAS unsigned*)(lds + (bufoff) + ldsw + _i * 8192), 16, 0, 0); } while (0)
; #define PG8_LDA(dst, b, h) do { _Pragma("unroll") for (int m = 0; m < 4; ++m) _Pragma("unroll") for (int k = 0; k < 2; ++k) dst[m][k] = *(const PG8_LAS bf16x8*)(lds + PG8_SA(b, h) + aoff + m * 2048 + k * 1024); } while (0)
; template <class Epi, class Sched, bool ALIGN_EPI = false, bool SP2 = false>
; __device__ __forceinline__ void gemm_phase(PG8_LAS unsigned char* lds, const Gemm g, const Sched& S, const Epi& E) {
;     ...
;             PG8_LDA(At, 0, 1); PG8_STAGE(PG8_SB(0, 0), b2, voffB); PG8_STAGE(PG8_SB(0, 1), b2 + hstep, voffB); PG8_STAGE(PG8_SA(0, 0), a2, voffA);
	s_addc_u32 s81, s13, 0
	s_add_i32 s79, s71, s57
	global_load_lds_dwordx4 v160, s[12:13]

; #define PG8_STAGE(bufoff, gbase, voff) do { _Pragma("unroll") for (int _i = 0; _i < 2; ++_i) \
;         __builtin_amdgcn_global_load_lds((const unsigned*)((const char*)(gbase) + (voff)[_i]), (PG8_LAS unsigned*)(lds + (bufoff) + ldsw + _i * 8192), 16, 0, 0); } while (0)
; #define PG8_LDA(dst, b, h) do { _Pragma("unroll") for (int m = 0; m < 4; ++m) _Pragma("unroll") for (int k = 0; k < 2; ++k) dst[m][k] = *(const PG8_LAS bf16x8*)(lds + PG8_SA(b, h) + aoff + m * 2048 + k * 1024); } while (0)
; template <class Epi, class Sched, bool ALIGN_EPI = false, bool SP2 = false>
; __device__ __forceinline__ void gemm_phase(PG8_LAS unsigned char* lds, const Gemm g, const Sched& S, const Epi& E) {
;     ...
;             PG8_LDA(At, 0, 1); PG8_STAGE(PG8_SB(0, 0), b2, voffB); PG8_STAGE(PG8_SB(0, 1), b2 + hstep, voffB); PG8_STAGE(PG8_SA(0, 0), a2, voffA);
	s_mov_b32 m0, s79
	s_nop 0
	global_load_lds_dwordx4 v164, s[80:81]

; #define PG8_STAGE(bufoff, gbase, voff) do { _Pragma("unroll") for (int _i = 0; _i < 2; ++_i) \
;         __builtin_amdgcn_global_load_lds((const unsigned*)((const char*)(gbase) + (voff)[_i]), (PG8_LAS unsigned*)(lds + (bufoff) + ldsw + _i * 8192), 16, 0, 0); } while (0)
; #define PG8_LDA(dst, b, h) do { _Pragma("unroll") for (int m = 0; m < 4; ++m) _Pragma("unroll") for (int k = 0; k < 2; ++k) dst[m][k] = *(const PG8_LAS bf16x8*)(lds + PG8_SA(b, h) + aoff + m * 2048 + k * 1024); } while (0)
; template <class Epi, class Sched, bool ALIGN_EPI = false, bool SP2 = false>
; __device__ __forceinline__ void gemm_phase(PG8_LAS unsigned char* lds, const Gemm g, const Sched& S, const Epi& E) {
;     ...
;             PG8_LDA(At, 0, 1); PG8_STAGE(PG8_SB(0, 0), b2, voffB); PG8_STAGE(PG8_SB(0, 1), b2 + hstep, voffB); PG8_STAGE(PG8_SA(0, 0), a2, voffA);
	s_add_i32 m0, s79, 0x2000
	s_nop 0
	global_load_lds_dwordx4 v160, s[80:81]
	s_mov_b64 s[98:99], s[54:55]

; #define PG8_STAGE(bufoff, gbase, voff) do { _Pragma("unroll") for (int _i = 0; _i < 2; ++_i) \
;         __builtin_amdgcn_global_load_lds((const unsigned*)((const char*)(gbase) + (voff)[_i]), (PG8_LAS unsigned*)(lds + (bufoff) + ldsw + _i * 8192), 16, 0, 0); } while (0)
; #define PG8_LDA(dst, b, h) do { _Pragma("unroll") for (int m = 0; m < 4; ++m) _Pragma("unroll") for (int k = 0; k < 2; ++k) dst[m][k] = *(const PG8_LAS bf16x8*)(lds + PG8_SA(b, h) + aoff + m * 2048 + k * 1024); } while (0)
; #define PG8_MMA(ai, bj, At, Bt) do { __builtin_amdgcn_s_setprio(1); _Pragma("unroll") for (int m = 0; m < 4; ++m) _Pragma("unroll") for (int n = 0; n < 2; ++n) _Pragma("unroll") for (int k = 0; k < 2; ++k) \
;         acc[ai][bj][m][n] = __builtin_amdgcn_mfma_f32_16x16x32_bf16(Bt[n][k], At[m][k], acc[ai][bj][m][n], 0, 0, 0); __builtin_amdgcn_s_setprio(0); } while (0)
; #define PG8_WAIT_V(n) asm volatile("s_waitcnt vmcnt(" #n ")" ::: "memory")
; #define PG8_WAIT_L(n) asm volatile("s_waitcnt lgkmcnt(" #n ")" ::: "memory")
; #define PG8_BAR __builtin_amdgcn_s_barrier()
; #define PG8_SCHED __builtin_amdgcn_sched_barrier(0)
; template <class Epi, class Sched, bool ALIGN_EPI = false, bool SP2 = false>
; __device__ __forceinline__ void gemm_phase(PG8_LAS unsigned char* lds, const Gemm g, const Sched& S, const Epi& E) {
;     ...
;             PG8_LDA(At, 0, 1); PG8_STAGE(PG8_SB(0, 0), b2, voffB); PG8_STAGE(PG8_SB(0, 1), b2 + hstep, voffB); PG8_STAGE(PG8_SA(0, 0), a2, voffA);
;             PG8_WAIT_V(8); PG8_WAIT_L(0); PG8_BAR; PG8_MMA(1, 0, At, B0); PG8_MMA(1, 1, At, B1); PG8_BAR; PG8_SCHED;
	s_mov_b32 m0, s60
	s_nop 0
	global_load_lds_dwordx4 v166, s[54:55]
	s_mov_b32 m0, s61
	s_nop 0
	global_load_lds_dwordx4 v162, s[54:55]
	s_waitcnt vmcnt(8)
	s_waitcnt lgkmcnt(0)
	s_setprio 1
	s_barrier

; #define PG8_MMA(ai, bj, At, Bt) do { __builtin_amdgcn_s_setprio(1); _Pragma("unroll") for (int m = 0; m < 4; ++m) _Pragma("unroll") for (int n = 0; n < 2; ++n) _Pragma("unroll") for (int k = 0; k < 2; ++k) \
;         acc[ai][bj][m][n] = __builtin_amdgcn_mfma_f32_16x16x32_bf16(Bt[n][k], At[m][k], acc[ai][bj][m][n], 0, 0, 0); __builtin_amdgcn_s_setprio(0); } while (0)
; #define PG8_WAIT_V(n) asm volatile("s_waitcnt vmcnt(" #n ")" ::: "memory")
; #define PG8_WAIT_L(n) asm volatile("s_waitcnt lgkmcnt(" #n ")" ::: "memory")
; #define PG8_BAR __builtin_amdgcn_s_barrier()
; #define PG8_SCHED __builtin_amdgcn_sched_barrier(0)
; template <class Epi, class Sched, bool ALIGN_EPI = false, bool SP2 = false>
; __device__ __forceinline__ void gemm_phase(PG8_LAS unsigned char* lds, const Gemm g, const Sched& S, const Epi& E) {
;     ...
;             PG8_WAIT_V(8); PG8_WAIT_L(0); PG8_BAR; PG8_MMA(1, 0, At, B0); PG8_MMA(1, 1, At, B1); PG8_BAR; PG8_SCHED;
	v_mfma_f32_16x16x32_bf16 v[60:63], v[128:131], v[176:179], v[60:63]
	v_mfma_f32_16x16x32_bf16 v[56:59], v[136:139], v[176:179], v[56:59]
	v_mfma_f32_16x16x32_bf16 v[52:55], v[128:131], v[184:187], v[52:55]
	v_mfma_f32_16x16x32_bf16 v[40:43], v[136:139], v[184:187], v[40:43]
	v_mfma_f32_16x16x32_bf16 v[36:39], v[128:131], v[210:213], v[36:39]
	v_mfma_f32_16x16x32_bf16 v[24:27], v[136:139], v[210:213], v[24:27]
	v_mfma_f32_16x16x32_bf16 v[20:23], v[128:131], v[218:221], v[20:23]
	v_mfma_f32_16x16x32_bf16 v[8:11], v[136:139], v[218:221], v[8:11]
	v_mfma_f32_16x16x32_bf16 v[60:63], v[132:135], v[180:183], v[60:63]
	v_mfma_f32_16x16x32_bf16 v[56:59], v[140:143], v[180:183], v[56:59]
	v_mfma_f32_16x16x32_bf16 v[52:55], v[132:135], v[192:195], v[52:55]
	v_mfma_f32_16x16x32_bf16 v[40:43], v[140:143], v[192:195], v[40:43]
	v_mfma_f32_16x16x32_bf16 v[36:39], v[132:135], v[214:217], v[36:39]
	v_mfma_f32_16x16x32_bf16 v[24:27], v[140:143], v[214:217], v[24:27]
	v_mfma_f32_16x16x32_bf16 v[20:23], v[132:135], v[222:225], v[20:23]
	v_mfma_f32_16x16x32_bf16 v[8:11], v[140:143], v[222:225], v[8:11]


; #define PG8_MMA(ai, bj, At, Bt) do { __builtin_amdgcn_s_setprio(1); _Pragma("unroll") for (int m = 0; m < 4; ++m) _Pragma("unroll") for (int n = 0; n < 2; ++n) _Pragma("unroll") for (int k = 0; k < 2; ++k) \
;         acc[ai][bj][m][n] = __builtin_amdgcn_mfma_f32_16x16x32_bf16(Bt[n][k], At[m][k], acc[ai][bj][m][n], 0, 0, 0); __builtin_amdgcn_s_setprio(0); } while (0)
; #define PG8_WAIT_V(n) asm volatile("s_waitcnt vmcnt(" #n ")" ::: "memory")
; #define PG8_WAIT_L(n) asm volatile("s_waitcnt lgkmcnt(" #n ")" ::: "memory")
; #define PG8_BAR __builtin_amdgcn_s_barrier()
; #define PG8_SCHED __builtin_amdgcn_sched_barrier(0)
; template <class Epi, class Sched, bool ALIGN_EPI = false, bool SP2 = false>
; __device__ __forceinline__ void gemm_phase(PG8_LAS unsigned char* lds, const Gemm g, const Sched& S, const Epi& E) {
;     ...
;             PG8_WAIT_V(8); PG8_WAIT_L(0); PG8_BAR; PG8_MMA(1, 0, At, B0); PG8_MMA(1, 1, At, B1); PG8_BAR; PG8_SCHED;
	v_mfma_f32_16x16x32_bf16 v[48:51], v[144:147], v[176:179], v[48:51]
	v_mfma_f32_16x16x32_bf16 v[44:47], v[152:155], v[176:179], v[44:47]
	v_mfma_f32_16x16x32_bf16 v[32:35], v[144:147], v[184:187], v[32:35]
	v_mfma_f32_16x16x32_bf16 v[28:31], v[152:155], v[184:187], v[28:31]
	v_mfma_f32_16x16x32_bf16 v[16:19], v[144:147], v[210:213], v[16:19]
	v_mfma_f32_16x16x32_bf16 v[12:15], v[152:155], v[210:213], v[12:15]
	v_mfma_f32_16x16x32_bf16 v[4:7], v[144:147], v[218:221], v[4:7]
	v_mfma_f32_16x16x32_bf16 v[0:3], v[152:155], v[218:221], v[0:3]
	v_mfma_f32_16x16x32_bf16 v[48:51], v[148:151], v[180:183], v[48:51]
	v_mfma_f32_16x16x32_bf16 v[44:47], v[156:159], v[180:183], v[44:47]
	v_mfma_f32_16x16x32_bf16 v[32:35], v[148:151], v[192:195], v[32:35]
	v_mfma_f32_16x16x32_bf16 v[28:31], v[156:159], v[192:195], v[28:31]
	v_mfma_f32_16x16x32_bf16 v[16:19], v[148:151], v[214:217], v[16:19]
	v_mfma_f32_16x16x32_bf16 v[12:15], v[156:159], v[214:217], v[12:15]
	v_mfma_f32_16x16x32_bf16 v[4:7], v[148:151], v[222:225], v[4:7]
	v_mfma_f32_16x16x32_bf16 v[0:3], v[156:159], v[222:225], v[0:3]
	s_setprio 0
	s_barrier
	s_add_i32 s79, 0, 0x18000
	s_add_i32 s80, 0, 0x1c000


; #define PG8_STAGE(bufoff, gbase, voff) do { _Pragma("unroll") for (int _i = 0; _i < 2; ++_i) \
;         __builtin_amdgcn_global_load_lds((const unsigned*)((const char*)(gbase) + (voff)[_i]), (PG8_LAS unsigned*)(lds + (bufoff) + ldsw + _i * 8192), 16, 0, 0); } while (0)
; #define PG8_LDA(dst, b, h) do { _Pragma("unroll") for (int m = 0; m < 4; ++m) _Pragma("unroll") for (int k = 0; k < 2; ++k) dst[m][k] = *(const PG8_LAS bf16x8*)(lds + PG8_SA(b, h) + aoff + m * 2048 + k * 1024); } while (0)
; #define PG8_LDB(dst, b, h) do { _Pragma("unroll") for (int n = 0; n < 2; ++n) _Pragma("unroll") for (int k = 0; k < 2; ++k) dst[n][k] = *(const PG8_LAS bf16x8*)(lds + PG8_SB(b, h) + boff + n * 2048 + k * 1024); } while (0)
; #define PG8_SCHED __builtin_amdgcn_sched_barrier(0)
; template <class Epi, class Sched, bool ALIGN_EPI = false, bool SP2 = false>
; __device__ __forceinline__ void gemm_phase(PG8_LAS unsigned char* lds, const Gemm g, const Sched& S, const Epi& E) {
;     ...
;             PG8_LDB(B0, 1, 0); PG8_LDB(B1, 1, 1); PG8_SCHED; PG8_LDA(At, 1, 0); PG8_STAGE(PG8_SA(0, 1), a2 + hstep, voffA);
	ds_read_b128 v[128:131], v254
	ds_read_b128 v[132:135], v254 offset:1024
	ds_read_b128 v[136:139], v254 offset:2048
	ds_read_b128 v[140:143], v254 offset:3072
	ds_read_b128 v[144:147], v255
	ds_read_b128 v[148:151], v255 offset:1024
	ds_read_b128 v[152:155], v255 offset:2048
	ds_read_b128 v[156:159], v255 offset:3072
	s_add_u32 s54, s54, 0x80000
	s_addc_u32 s55, s55, 0
	s_mov_b32 m0, s62

; #define PG8_STAGE(bufoff, gbase, voff) do { _Pragma("unroll") for (int _i = 0; _i < 2; ++_i) \
;         __builtin_amdgcn_global_load_lds((const unsigned*)((const char*)(gbase) + (voff)[_i]), (PG8_LAS unsigned*)(lds + (bufoff) + ldsw + _i * 8192), 16, 0, 0); } while (0)
; #define PG8_LDA(dst, b, h) do { _Pragma("unroll") for (int m = 0; m < 4; ++m) _Pragma("unroll") for (int k = 0; k < 2; ++k) dst[m][k] = *(const PG8_LAS bf16x8*)(lds + PG8_SA(b, h) + aoff + m * 2048 + k * 1024); } while (0)
; #define PG8_LDB(dst, b, h) do { _Pragma("unroll") for (int n = 0; n < 2; ++n) _Pragma("unroll") for (int k = 0; k < 2; ++k) dst[n][k] = *(const PG8_LAS bf16x8*)(lds + PG8_SB(b, h) + boff + n * 2048 + k * 1024); } while (0)
; #define PG8_SCHED __builtin_amdgcn_sched_barrier(0)
; template <class Epi, class Sched, bool ALIGN_EPI = false, bool SP2 = false>
; __device__ __forceinline__ void gemm_phase(PG8_LAS unsigned char* lds, const Gemm g, const Sched& S, const Epi& E) {
;     ...
;             PG8_LDB(B0, 1, 0); PG8_LDB(B1, 1, 1); PG8_SCHED; PG8_LDA(At, 1, 0); PG8_STAGE(PG8_SA(0, 1), a2 + hstep, voffA);
	ds_read_b128 v[176:179], v207 offset:32768
	ds_read_b128 v[180:183], v207 offset:33792
	ds_read_b128 v[184:187], v207 offset:34816
	ds_read_b128 v[192:195], v207 offset:35840
	ds_read_b128 v[210:213], v207 offset:36864
	ds_read_b128 v[214:217], v207 offset:37888
	ds_read_b128 v[218:221], v207 offset:38912
	ds_read_b128 v[222:225], v207 offset:39936
	global_load_lds_dwordx4 v166, s[54:55]

; #define PG8_MMA(ai, bj, At, Bt) do { __builtin_amdgcn_s_setprio(1); _Pragma("unroll") for (int m = 0; m < 4; ++m) _Pragma("unroll") for (int n = 0; n < 2; ++n) _Pragma("unroll") for (int k = 0; k < 2; ++k) \
;         acc[ai][bj][m][n] = __builtin_amdgcn_mfma_f32_16x16x32_bf16(Bt[n][k], At[m][k], acc[ai][bj][m][n], 0, 0, 0); __builtin_amdgcn_s_setprio(0); } while (0)
; #define PG8_WAIT_V(n) asm volatile("s_waitcnt vmcnt(" #n ")" ::: "memory")
; #define PG8_WAIT_L(n) asm volatile("s_waitcnt lgkmcnt(" #n ")" ::: "memory")
; #define PG8_BAR __builtin_amdgcn_s_barrier()
; #define PG8_SCHED __builtin_amdgcn_sched_barrier(0)
; template <class Epi, class Sched, bool ALIGN_EPI = false, bool SP2 = false>
; __device__ __forceinline__ void gemm_phase(PG8_LAS unsigned char* lds, const Gemm g, const Sched& S, const Epi& E) {
;     ...
;             PG8_WAIT_V(8); PG8_WAIT_L(0); PG8_BAR; PG8_MMA(0, 0, At, B0); PG8_MMA(0, 1, At, B1); PG8_BAR; PG8_SCHED;
	s_mov_b32 m0, s63
	s_nop 0
	global_load_lds_dwordx4 v162, s[54:55]
	s_waitcnt vmcnt(8)
	s_waitcnt lgkmcnt(0)
	s_setprio 1
	s_barrier

; #define PG8_MMA(ai, bj, At, Bt) do { __builtin_amdgcn_s_setprio(1); _Pragma("unroll") for (int m = 0; m < 4; ++m) _Pragma("unroll") for (int n = 0; n < 2; ++n) _Pragma("unroll") for (int k = 0; k < 2; ++k) \
;         acc[ai][bj][m][n] = __builtin_amdgcn_mfma_f32_16x16x32_bf16(Bt[n][k], At[m][k], acc[ai][bj][m][n], 0, 0, 0); __builtin_amdgcn_s_setprio(0); } while (0)
; #define PG8_WAIT_V(n) asm volatile("s_waitcnt vmcnt(" #n ")" ::: "memory")
; #define PG8_WAIT_L(n) asm volatile("s_waitcnt lgkmcnt(" #n ")" ::: "memory")
; #define PG8_BAR __builtin_amdgcn_s_barrier()
; #define PG8_SCHED __builtin_amdgcn_sched_barrier(0)
; template <class Epi, class Sched, bool ALIGN_EPI = false, bool SP2 = false>
; __device__ __forceinline__ void gemm_phase(PG8_LAS unsigned char* lds, const Gemm g, const Sched& S, const Epi& E) {
;     ...
;             PG8_WAIT_V(8); PG8_WAIT_L(0); PG8_BAR; PG8_MMA(0, 0, At, B0); PG8_MMA(0, 1, At, B1); PG8_BAR; PG8_SCHED;
	v_mfma_f32_16x16x32_bf16 v[124:127], v[128:131], v[176:179], v[124:127]
	v_mfma_f32_16x16x32_bf16 v[120:123], v[136:139], v[176:179], v[120:123]
	v_mfma_f32_16x16x32_bf16 v[112:115], v[128:131], v[184:187], v[112:115]
	v_mfma_f32_16x16x32_bf16 v[104:107], v[136:139], v[184:187], v[104:107]
	v_mfma_f32_16x16x32_bf16 v[100:103], v[128:131], v[210:213], v[100:103]
	v_mfma_f32_16x16x32_bf16 v[88:91], v[136:139], v[210:213], v[88:91]
	v_mfma_f32_16x16x32_bf16 v[84:87], v[128:131], v[218:221], v[84:87]
	v_mfma_f32_16x16x32_bf16 v[72:75], v[136:139], v[218:221], v[72:75]
	v_mfma_f32_16x16x32_bf16 v[124:127], v[132:135], v[180:183], v[124:127]
	v_mfma_f32_16x16x32_bf16 v[120:123], v[140:143], v[180:183], v[120:123]
	v_mfma_f32_16x16x32_bf16 v[112:115], v[132:135], v[192:195], v[112:115]
	v_mfma_f32_16x16x32_bf16 v[104:107], v[140:143], v[192:195], v[104:107]
	v_mfma_f32_16x16x32_bf16 v[100:103], v[132:135], v[214:217], v[100:103]
	v_mfma_f32_16x16x32_bf16 v[88:91], v[140:143], v[214:217], v[88:91]
	v_mfma_f32_16x16x32_bf16 v[84:87], v[132:135], v[222:225], v[84:87]
	v_mfma_f32_16x16x32_bf16 v[72:75], v[140:143], v[222:225], v[72:75]


; #define PG8_STAGE(bufoff, gbase, voff) do { _Pragma("unroll") for (int _i = 0; _i < 2; ++_i) \
;         __builtin_amdgcn_global_load_lds((const unsigned*)((const char*)(gbase) + (voff)[_i]), (PG8_LAS unsigned*)(lds + (bufoff) + ldsw + _i * 8192), 16, 0, 0); } while (0)
; #define PG8_LDA(dst, b, h) do { _Pragma("unroll") for (int m = 0; m < 4; ++m) _Pragma("unroll") for (int k = 0; k < 2; ++k) dst[m][k] = *(const PG8_LAS bf16x8*)(lds + PG8_SA(b, h) + aoff + m * 2048 + k * 1024); } while (0)
; #define PG8_MMA(ai, bj, At, Bt) do { __builtin_amdgcn_s_setprio(1); _Pragma("unroll") for (int m = 0; m < 4; ++m) _Pragma("unroll") for (int n = 0; n < 2; ++n) _Pragma("unroll") for (int k = 0; k < 2; ++k) \
;         acc[ai][bj][m][n] = __builtin_amdgcn_mfma_f32_16x16x32_bf16(Bt[n][k], At[m][k], acc[ai][bj][m][n], 0, 0, 0); __builtin_amdgcn_s_setprio(0); } while (0)
; #define PG8_WAIT_V(n) asm volatile("s_waitcnt vmcnt(" #n ")" ::: "memory")
; #define PG8_WAIT_L(n) asm volatile("s_waitcnt lgkmcnt(" #n ")" ::: "memory")
; #define PG8_BAR __builtin_amdgcn_s_barrier()
; #define PG8_SCHED __builtin_amdgcn_sched_barrier(0)
; template <class Epi, class Sched, bool ALIGN_EPI = false, bool SP2 = false>
; __device__ __forceinline__ void gemm_phase(PG8_LAS unsigned char* lds, const Gemm g, const Sched& S, const Epi& E) {
;     ...
;             PG8_WAIT_V(8); PG8_WAIT_L(0); PG8_BAR; PG8_MMA(0, 0, At, B0); PG8_MMA(0, 1, At, B1); PG8_BAR; PG8_SCHED;
;             PG8_LDA(At, 1, 1); PG8_STAGE(PG8_SB(1, 0), b3, voffB); PG8_STAGE(PG8_SB(1, 1), b3 + hstep, voffB); PG8_STAGE(PG8_SA(1, 0), a3, voffA);
	v_mfma_f32_16x16x32_bf16 v[116:119], v[144:147], v[176:179], v[116:119]
	v_mfma_f32_16x16x32_bf16 v[108:111], v[152:155], v[176:179], v[108:111]
	v_mfma_f32_16x16x32_bf16 v[96:99], v[144:147], v[184:187], v[96:99]
	v_mfma_f32_16x16x32_bf16 v[92:95], v[152:155], v[184:187], v[92:95]
	v_mfma_f32_16x16x32_bf16 v[80:83], v[144:147], v[210:213], v[80:83]
	v_mfma_f32_16x16x32_bf16 v[76:79], v[152:155], v[210:213], v[76:79]
	v_mfma_f32_16x16x32_bf16 v[68:71], v[144:147], v[218:221], v[68:71]
	v_mfma_f32_16x16x32_bf16 v[64:67], v[152:155], v[218:221], v[64:67]
	v_mfma_f32_16x16x32_bf16 v[116:119], v[148:151], v[180:183], v[116:119]
	v_mfma_f32_16x16x32_bf16 v[108:111], v[156:159], v[180:183], v[108:111]
	v_mfma_f32_16x16x32_bf16 v[96:99], v[148:151], v[192:195], v[96:99]
	v_mfma_f32_16x16x32_bf16 v[92:95], v[156:159], v[192:195], v[92:95]
	v_mfma_f32_16x16x32_bf16 v[80:83], v[148:151], v[214:217], v[80:83]
	v_mfma_f32_16x16x32_bf16 v[76:79], v[156:159], v[214:217], v[76:79]
	v_mfma_f32_16x16x32_bf16 v[68:71], v[148:151], v[222:225], v[68:71]
	v_mfma_f32_16x16x32_bf16 v[64:67], v[156:159], v[222:225], v[64:67]
	s_setprio 0
	s_barrier
	s_add_i32 s54, s79, s57

; #define PG8_STAGE(bufoff, gbase, voff) do { _Pragma("unroll") for (int _i = 0; _i < 2; ++_i) \
;         __builtin_amdgcn_global_load_lds((const unsigned*)((const char*)(gbase) + (voff)[_i]), (PG8_LAS unsigned*)(lds + (bufoff) + ldsw + _i * 8192), 16, 0, 0); } while (0)
; #define PG8_LDA(dst, b, h) do { _Pragma("unroll") for (int m = 0; m < 4; ++m) _Pragma("unroll") for (int k = 0; k < 2; ++k) dst[m][k] = *(const PG8_LAS bf16x8*)(lds + PG8_SA(b, h) + aoff + m * 2048 + k * 1024); } while (0)
; template <class Epi, class Sched, bool ALIGN_EPI = false, bool SP2 = false>
; __device__ __forceinline__ void gemm_phase(PG8_LAS unsigned char* lds, const Gemm g, const Sched& S, const Epi& E) {
;     ...
;             PG8_LDA(At, 1, 1); PG8_STAGE(PG8_SB(1, 0), b3, voffB); PG8_STAGE(PG8_SB(1, 1), b3 + hstep, voffB); PG8_STAGE(PG8_SA(1, 0), a3, voffA);
	s_mov_b32 m0, s54
	ds_read_b128 v[176:179], v207 offset:49152
	ds_read_b128 v[180:183], v207 offset:50176
	ds_read_b128 v[184:187], v207 offset:51200
	ds_read_b128 v[192:195], v207 offset:52224
	ds_read_b128 v[210:213], v207 offset:53248
	ds_read_b128 v[214:217], v207 offset:54272
	ds_read_b128 v[218:221], v207 offset:55296
	ds_read_b128 v[222:225], v207 offset:56320
	global_load_lds_dwordx4 v250, s[96:97]
	s_add_i32 m0, s54, 0x2000
	s_add_u32 s12, s12, 0x80080

; #define PG8_STAGE(bufoff, gbase, voff) do { _Pragma("unroll") for (int _i = 0; _i < 2; ++_i) \
;         __builtin_amdgcn_global_load_lds((const unsigned*)((const char*)(gbase) + (voff)[_i]), (PG8_LAS unsigned*)(lds + (bufoff) + ldsw + _i * 8192), 16, 0, 0); } while (0)
; #define PG8_LDA(dst, b, h) do { _Pragma("unroll") for (int m = 0; m < 4; ++m) _Pragma("unroll") for (int k = 0; k < 2; ++k) dst[m][k] = *(const PG8_LAS bf16x8*)(lds + PG8_SA(b, h) + aoff + m * 2048 + k * 1024); } while (0)
; template <class Epi, class Sched, bool ALIGN_EPI = false, bool SP2 = false>
; __device__ __forceinline__ void gemm_phase(PG8_LAS unsigned char* lds, const Gemm g, const Sched& S, const Epi& E) {
;     ...
;             PG8_LDA(At, 1, 1); PG8_STAGE(PG8_SB(1, 0), b3, voffB); PG8_STAGE(PG8_SB(1, 1), b3 + hstep, voffB); PG8_STAGE(PG8_SA(1, 0), a3, voffA);
	s_addc_u32 s13, s13, 0
	s_add_i32 s54, s80, s57
	global_load_lds_dwordx4 v251, s[96:97]

; #define PG8_STAGE(bufoff, gbase, voff) do { _Pragma("unroll") for (int _i = 0; _i < 2; ++_i) \
;         __builtin_amdgcn_global_load_lds((const unsigned*)((const char*)(gbase) + (voff)[_i]), (PG8_LAS unsigned*)(lds + (bufoff) + ldsw + _i * 8192), 16, 0, 0); } while (0)
; #define PG8_LDA(dst, b, h) do { _Pragma("unroll") for (int m = 0; m < 4; ++m) _Pragma("unroll") for (int k = 0; k < 2; ++k) dst[m][k] = *(const PG8_LAS bf16x8*)(lds + PG8_SA(b, h) + aoff + m * 2048 + k * 1024); } while (0)
; template <class Epi, class Sched, bool ALIGN_EPI = false, bool SP2 = false>
; __device__ __forceinline__ void gemm_phase(PG8_LAS unsigned char* lds, const Gemm g, const Sched& S, const Epi& E) {
;     ...
;             PG8_LDA(At, 1, 1); PG8_STAGE(PG8_SB(1, 0), b3, voffB); PG8_STAGE(PG8_SB(1, 1), b3 + hstep, voffB); PG8_STAGE(PG8_SA(1, 0), a3, voffA);
	s_mov_b32 m0, s54
	s_nop 0
	global_load_lds_dwordx4 v164, s[12:13]

; #define PG8_STAGE(bufoff, gbase, voff) do { _Pragma("unroll") for (int _i = 0; _i < 2; ++_i) \
;         __builtin_amdgcn_global_load_lds((const unsigned*)((const char*)(gbase) + (voff)[_i]), (PG8_LAS unsigned*)(lds + (bufoff) + ldsw + _i * 8192), 16, 0, 0); } while (0)
; #define PG8_LDA(dst, b, h) do { _Pragma("unroll") for (int m = 0; m < 4; ++m) _Pragma("unroll") for (int k = 0; k < 2; ++k) dst[m][k] = *(const PG8_LAS bf16x8*)(lds + PG8_SA(b, h) + aoff + m * 2048 + k * 1024); } while (0)
; template <class Epi, class Sched, bool ALIGN_EPI = false, bool SP2 = false>
; __device__ __forceinline__ void gemm_phase(PG8_LAS unsigned char* lds, const Gemm g, const Sched& S, const Epi& E) {
;     ...
;             PG8_LDA(At, 1, 1); PG8_STAGE(PG8_SB(1, 0), b3, voffB); PG8_STAGE(PG8_SB(1, 1), b3 + hstep, voffB); PG8_STAGE(PG8_SA(1, 0), a3, voffA);
	s_add_i32 m0, s54, 0x2000
	s_nop 0
	global_load_lds_dwordx4 v160, s[12:13]

; #define PG8_STAGE(bufoff, gbase, voff) do { _Pragma("unroll") for (int _i = 0; _i < 2; ++_i) \
;         __builtin_amdgcn_global_load_lds((const unsigned*)((const char*)(gbase) + (voff)[_i]), (PG8_LAS unsigned*)(lds + (bufoff) + ldsw + _i * 8192), 16, 0, 0); } while (0)
; #define PG8_LDA(dst, b, h) do { _Pragma("unroll") for (int m = 0; m < 4; ++m) _Pragma("unroll") for (int k = 0; k < 2; ++k) dst[m][k] = *(const PG8_LAS bf16x8*)(lds + PG8_SA(b, h) + aoff + m * 2048 + k * 1024); } while (0)
; template <class Epi, class Sched, bool ALIGN_EPI = false, bool SP2 = false>
; __device__ __forceinline__ void gemm_phase(PG8_LAS unsigned char* lds, const Gemm g, const Sched& S, const Epi& E) {
;     ...
;             PG8_LDA(At, 1, 1); PG8_STAGE(PG8_SB(1, 0), b3, voffB); PG8_STAGE(PG8_SB(1, 1), b3 + hstep, voffB); PG8_STAGE(PG8_SA(1, 0), a3, voffA);
	s_mov_b32 m0, s65
	s_nop 0
	global_load_lds_dwordx4 v252, s[98:99]

; #define PG8_MMA(ai, bj, At, Bt) do { __builtin_amdgcn_s_setprio(1); _Pragma("unroll") for (int m = 0; m < 4; ++m) _Pragma("unroll") for (int n = 0; n < 2; ++n) _Pragma("unroll") for (int k = 0; k < 2; ++k) \
;         acc[ai][bj][m][n] = __builtin_amdgcn_mfma_f32_16x16x32_bf16(Bt[n][k], At[m][k], acc[ai][bj][m][n], 0, 0, 0); __builtin_amdgcn_s_setprio(0); } while (0)
; #define PG8_WAIT_V(n) asm volatile("s_waitcnt vmcnt(" #n ")" ::: "memory")
; #define PG8_WAIT_L(n) asm volatile("s_waitcnt lgkmcnt(" #n ")" ::: "memory")
; #define PG8_BAR __builtin_amdgcn_s_barrier()
; #define PG8_SCHED __builtin_amdgcn_sched_barrier(0)
; template <class Epi, class Sched, bool ALIGN_EPI = false, bool SP2 = false>
; __device__ __forceinline__ void gemm_phase(PG8_LAS unsigned char* lds, const Gemm g, const Sched& S, const Epi& E) {
;     ...
;             PG8_WAIT_V(8); PG8_WAIT_L(0); PG8_BAR; PG8_MMA(1, 0, At, B0); PG8_MMA(1, 1, At, B1); PG8_BAR; PG8_SCHED;
	s_mov_b32 m0, s67
	s_nop 0
	global_load_lds_dwordx4 v253, s[98:99]
	s_waitcnt vmcnt(8)
	s_waitcnt lgkmcnt(0)
	s_setprio 1
	s_barrier

; #define PG8_MMA(ai, bj, At, Bt) do { __builtin_amdgcn_s_setprio(1); _Pragma("unroll") for (int m = 0; m < 4; ++m) _Pragma("unroll") for (int n = 0; n < 2; ++n) _Pragma("unroll") for (int k = 0; k < 2; ++k) \
;         acc[ai][bj][m][n] = __builtin_amdgcn_mfma_f32_16x16x32_bf16(Bt[n][k], At[m][k], acc[ai][bj][m][n], 0, 0, 0); __builtin_amdgcn_s_setprio(0); } while (0)
; #define PG8_WAIT_V(n) asm volatile("s_waitcnt vmcnt(" #n ")" ::: "memory")
; #define PG8_WAIT_L(n) asm volatile("s_waitcnt lgkmcnt(" #n ")" ::: "memory")
; #define PG8_BAR __builtin_amdgcn_s_barrier()
; #define PG8_SCHED __builtin_amdgcn_sched_barrier(0)
; template <class Epi, class Sched, bool ALIGN_EPI = false, bool SP2 = false>
; __device__ __forceinline__ void gemm_phase(PG8_LAS unsigned char* lds, const Gemm g, const Sched& S, const Epi& E) {
;     ...
;             PG8_WAIT_V(8); PG8_WAIT_L(0); PG8_BAR; PG8_MMA(1, 0, At, B0); PG8_MMA(1, 1, At, B1); PG8_BAR; PG8_SCHED;
	v_mfma_f32_16x16x32_bf16 v[60:63], v[128:131], v[176:179], v[60:63]
	v_mfma_f32_16x16x32_bf16 v[56:59], v[136:139], v[176:179], v[56:59]
	v_mfma_f32_16x16x32_bf16 v[52:55], v[128:131], v[184:187], v[52:55]
	v_mfma_f32_16x16x32_bf16 v[40:43], v[136:139], v[184:187], v[40:43]
	v_mfma_f32_16x16x32_bf16 v[36:39], v[128:131], v[210:213], v[36:39]
	v_mfma_f32_16x16x32_bf16 v[24:27], v[136:139], v[210:213], v[24:27]
	v_mfma_f32_16x16x32_bf16 v[20:23], v[128:131], v[218:221], v[20:23]
	v_mfma_f32_16x16x32_bf16 v[8:11], v[136:139], v[218:221], v[8:11]
	v_mfma_f32_16x16x32_bf16 v[60:63], v[132:135], v[180:183], v[60:63]
	v_mfma_f32_16x16x32_bf16 v[56:59], v[140:143], v[180:183], v[56:59]
	v_mfma_f32_16x16x32_bf16 v[52:55], v[132:135], v[192:195], v[52:55]
	v_mfma_f32_16x16x32_bf16 v[40:43], v[140:143], v[192:195], v[40:43]
	v_mfma_f32_16x16x32_bf16 v[36:39], v[132:135], v[214:217], v[36:39]
	v_mfma_f32_16x16x32_bf16 v[24:27], v[140:143], v[214:217], v[24:27]
	v_mfma_f32_16x16x32_bf16 v[20:23], v[132:135], v[222:225], v[20:23]
	v_mfma_f32_16x16x32_bf16 v[8:11], v[140:143], v[222:225], v[8:11]


; #define PG8_MMA(ai, bj, At, Bt) do { __builtin_amdgcn_s_setprio(1); _Pragma("unroll") for (int m = 0; m < 4; ++m) _Pragma("unroll") for (int n = 0; n < 2; ++n) _Pragma("unroll") for (int k = 0; k < 2; ++k) \
;         acc[ai][bj][m][n] = __builtin_amdgcn_mfma_f32_16x16x32_bf16(Bt[n][k], At[m][k], acc[ai][bj][m][n], 0, 0, 0); __builtin_amdgcn_s_setprio(0); } while (0)
; #define PG8_WAIT_V(n) asm volatile("s_waitcnt vmcnt(" #n ")" ::: "memory")
; #define PG8_WAIT_L(n) asm volatile("s_waitcnt lgkmcnt(" #n ")" ::: "memory")
; #define PG8_BAR __builtin_amdgcn_s_barrier()
; #define PG8_SCHED __builtin_amdgcn_sched_barrier(0)
; template <class Epi, class Sched, bool ALIGN_EPI = false, bool SP2 = false>
; __device__ __forceinline__ void gemm_phase(PG8_LAS unsigned char* lds, const Gemm g, const Sched& S, const Epi& E) {
;     ...
;         for (int t = 0; t < nt; t += 2) {
;     ...
;             PG8_WAIT_V(8); PG8_WAIT_L(0); PG8_BAR; PG8_MMA(1, 0, At, B0); PG8_MMA(1, 1, At, B1); PG8_BAR; PG8_SCHED;
	v_mfma_f32_16x16x32_bf16 v[48:51], v[144:147], v[176:179], v[48:51]
	v_mfma_f32_16x16x32_bf16 v[44:47], v[152:155], v[176:179], v[44:47]
	v_mfma_f32_16x16x32_bf16 v[32:35], v[144:147], v[184:187], v[32:35]
	v_mfma_f32_16x16x32_bf16 v[28:31], v[152:155], v[184:187], v[28:31]
	v_mfma_f32_16x16x32_bf16 v[16:19], v[144:147], v[210:213], v[16:19]
	v_mfma_f32_16x16x32_bf16 v[12:15], v[152:155], v[210:213], v[12:15]
	v_mfma_f32_16x16x32_bf16 v[4:7], v[144:147], v[218:221], v[4:7]
	v_mfma_f32_16x16x32_bf16 v[0:3], v[152:155], v[218:221], v[0:3]
	v_mfma_f32_16x16x32_bf16 v[48:51], v[148:151], v[180:183], v[48:51]
	v_mfma_f32_16x16x32_bf16 v[44:47], v[156:159], v[180:183], v[44:47]
	v_mfma_f32_16x16x32_bf16 v[32:35], v[148:151], v[192:195], v[32:35]
	v_mfma_f32_16x16x32_bf16 v[28:31], v[156:159], v[192:195], v[28:31]
	v_mfma_f32_16x16x32_bf16 v[16:19], v[148:151], v[214:217], v[16:19]
	v_mfma_f32_16x16x32_bf16 v[12:15], v[156:159], v[214:217], v[12:15]
	v_mfma_f32_16x16x32_bf16 v[4:7], v[148:151], v[222:225], v[4:7]
	v_mfma_f32_16x16x32_bf16 v[0:3], v[156:159], v[222:225], v[0:3]
	s_setprio 0
	s_add_i32 s78, s78, 2
	s_add_u32 s10, s10, 0x100
	s_addc_u32 s11, s11, 0
	s_add_u32 s76, s76, 0x100
	s_addc_u32 s77, s77, 0
	s_cmp_gt_u32 s78, 29
	s_barrier


; #define PG8_BAR __builtin_amdgcn_s_barrier()
; template <class Epi, class Sched, bool ALIGN_EPI = false, bool SP2 = false>
; __device__ __forceinline__ void gemm_phase(PG8_LAS unsigned char* lds, const Gemm g, const Sched& S, const Epi& E) {
;     ...
;         for (int t = 0; t < nt; t += 2) {
;     ...
;         if constexpr (ALIGN_EPI) { if (wr == 0) PG8_BAR; }
	s_cbranch_scc0 .LBB0_679
	s_and_b64 vcc, exec, s[42:43]
	s_cbranch_vccz .LBB0_682
	s_barrier

; #define PG8_STAGE(bufoff, gbase, voff) do { _Pragma("unroll") for (int _i = 0; _i < 2; ++_i) \
;         __builtin_amdgcn_global_load_lds((const unsigned*)((const char*)(gbase) + (voff)[_i]), (PG8_LAS unsigned*)(lds + (bufoff) + ldsw + _i * 8192), 16, 0, 0); } while (0)
; #define PG8_LDA(dst, b, h) do { _Pragma("unroll") for (int m = 0; m < 4; ++m) _Pragma("unroll") for (int k = 0; k < 2; ++k) dst[m][k] = *(const PG8_LAS bf16x8*)(lds + PG8_SA(b, h) + aoff + m * 2048 + k * 1024); } while (0)
; #define PG8_LDB(dst, b, h) do { _Pragma("unroll") for (int n = 0; n < 2; ++n) _Pragma("unroll") for (int k = 0; k < 2; ++k) dst[n][k] = *(const PG8_LAS bf16x8*)(lds + PG8_SB(b, h) + boff + n * 2048 + k * 1024); } while (0)
; #define PG8_SCHED __builtin_amdgcn_sched_barrier(0)
; template <class Epi, class Sched, bool ALIGN_EPI = false, bool SP2 = false>
; __device__ __forceinline__ void gemm_phase(PG8_LAS unsigned char* lds, const Gemm g, const Sched& S, const Epi& E) {
;     ...
;             const bool last = (t == nt - 2);
;             const char* a1 = cA + (size_t)(t + 1) * kstep;
;             const char* a2 = last ? nA : cA + (size_t)(t + 2) * kstep; const char* b2 = last ? nB : cB + (size_t)(t + 2) * kstep;
;             const char* a3 = a2 + kstep; const char* b3 = b2 + kstep;
;     ...
;             PG8_LDB(B0, 0, 0); PG8_LDB(B1, 0, 1); PG8_SCHED; PG8_LDA(At, 0, 0); PG8_STAGE(PG8_SA(1, 1), a1 + hstep, voffA);
.LBB0_939:
	ds_read_b128 v[64:67], v213
	ds_read_b128 v[68:71], v213 offset:1024
	ds_read_b128 v[72:75], v213 offset:2048
	ds_read_b128 v[76:79], v213 offset:3072
	ds_read_b128 v[144:147], v214
	ds_read_b128 v[148:151], v214 offset:1024
	ds_read_b128 v[152:155], v214 offset:2048
	ds_read_b128 v[156:159], v214 offset:3072
	s_add_u32 s60, s58, 0xfff80080
	s_addc_u32 s61, s59, -1
	s_cmp_eq_u32 s81, 28
	s_cselect_b32 s63, s11, s61
	s_cselect_b32 s62, s51, s60
	s_cselect_b32 s61, s49, s80
	s_cselect_b32 s60, s78, s79

; #define PG8_STAGE(bufoff, gbase, voff) do { _Pragma("unroll") for (int _i = 0; _i < 2; ++_i) \
;         __builtin_amdgcn_global_load_lds((const unsigned*)((const char*)(gbase) + (voff)[_i]), (PG8_LAS unsigned*)(lds + (bufoff) + ldsw + _i * 8192), 16, 0, 0); } while (0)
; #define PG8_LDA(dst, b, h) do { _Pragma("unroll") for (int m = 0; m < 4; ++m) _Pragma("unroll") for (int k = 0; k < 2; ++k) dst[m][k] = *(const PG8_LAS bf16x8*)(lds + PG8_SA(b, h) + aoff + m * 2048 + k * 1024); } while (0)
; #define PG8_LDB(dst, b, h) do { _Pragma("unroll") for (int n = 0; n < 2; ++n) _Pragma("unroll") for (int k = 0; k < 2; ++k) dst[n][k] = *(const PG8_LAS bf16x8*)(lds + PG8_SB(b, h) + boff + n * 2048 + k * 1024); } while (0)
; #define PG8_SCHED __builtin_amdgcn_sched_barrier(0)
; template <class Epi, class Sched, bool ALIGN_EPI = false, bool SP2 = false>
; __device__ __forceinline__ void gemm_phase(PG8_LAS unsigned char* lds, const Gemm g, const Sched& S, const Epi& E) {
;     ...
;             PG8_LDB(B0, 0, 0); PG8_LDB(B1, 0, 1); PG8_SCHED; PG8_LDA(At, 0, 0); PG8_STAGE(PG8_SA(1, 1), a1 + hstep, voffA);
	s_add_i32 m0, s57, 0xc000
	ds_read_b128 v[176:179], v215
	ds_read_b128 v[180:183], v215 offset:1024
	ds_read_b128 v[184:187], v215 offset:2048
	ds_read_b128 v[188:191], v215 offset:3072
	ds_read_b128 v[192:195], v215 offset:4096
	ds_read_b128 v[196:199], v215 offset:5120
	ds_read_b128 v[200:203], v215 offset:6144
	ds_read_b128 v[204:207], v215 offset:7168
	global_load_lds_dwordx4 v168, s[58:59]

; #define PG8_MMA(ai, bj, At, Bt) do { __builtin_amdgcn_s_setprio(1); _Pragma("unroll") for (int m = 0; m < 4; ++m) _Pragma("unroll") for (int n = 0; n < 2; ++n) _Pragma("unroll") for (int k = 0; k < 2; ++k) \
;         acc[ai][bj][m][n] = __builtin_amdgcn_mfma_f32_16x16x32_bf16(Bt[n][k], At[m][k], acc[ai][bj][m][n], 0, 0, 0); __builtin_amdgcn_s_setprio(0); } while (0)
; #define PG8_WAIT_V(n) asm volatile("s_waitcnt vmcnt(" #n ")" ::: "memory")
; #define PG8_WAIT_L(n) asm volatile("s_waitcnt lgkmcnt(" #n ")" ::: "memory")
; #define PG8_BAR __builtin_amdgcn_s_barrier()
; #define PG8_SCHED __builtin_amdgcn_sched_barrier(0)
; template <class Epi, class Sched, bool ALIGN_EPI = false, bool SP2 = false>
; __device__ __forceinline__ void gemm_phase(PG8_LAS unsigned char* lds, const Gemm g, const Sched& S, const Epi& E) {
;     ...
;             PG8_WAIT_V(8); PG8_WAIT_L(0); PG8_BAR; PG8_MMA(0, 0, At, B0); PG8_MMA(0, 1, At, B1); PG8_BAR; PG8_SCHED;
	s_add_i32 m0, s57, 0xe000
	s_nop 0
	global_load_lds_dwordx4 v170, s[58:59]
	s_waitcnt vmcnt(8)
	s_waitcnt lgkmcnt(0)
	s_setprio 1
	s_barrier

; #define PG8_MMA(ai, bj, At, Bt) do { __builtin_amdgcn_s_setprio(1); _Pragma("unroll") for (int m = 0; m < 4; ++m) _Pragma("unroll") for (int n = 0; n < 2; ++n) _Pragma("unroll") for (int k = 0; k < 2; ++k) \
;         acc[ai][bj][m][n] = __builtin_amdgcn_mfma_f32_16x16x32_bf16(Bt[n][k], At[m][k], acc[ai][bj][m][n], 0, 0, 0); __builtin_amdgcn_s_setprio(0); } while (0)
; #define PG8_WAIT_V(n) asm volatile("s_waitcnt vmcnt(" #n ")" ::: "memory")
; #define PG8_WAIT_L(n) asm volatile("s_waitcnt lgkmcnt(" #n ")" ::: "memory")
; #define PG8_BAR __builtin_amdgcn_s_barrier()
; #define PG8_SCHED __builtin_amdgcn_sched_barrier(0)
; template <class Epi, class Sched, bool ALIGN_EPI = false, bool SP2 = false>
; __device__ __forceinline__ void gemm_phase(PG8_LAS unsigned char* lds, const Gemm g, const Sched& S, const Epi& E) {
;     ...
;             PG8_WAIT_V(8); PG8_WAIT_L(0); PG8_BAR; PG8_MMA(0, 0, At, B0); PG8_MMA(0, 1, At, B1); PG8_BAR; PG8_SCHED;
	v_mfma_f32_16x16x32_bf16 v[140:143], v[64:67], v[176:179], v[140:143]
	v_mfma_f32_16x16x32_bf16 v[136:139], v[72:75], v[176:179], v[136:139]
	v_mfma_f32_16x16x32_bf16 v[124:127], v[64:67], v[184:187], v[124:127]
	v_mfma_f32_16x16x32_bf16 v[120:123], v[72:75], v[184:187], v[120:123]
	v_mfma_f32_16x16x32_bf16 v[108:111], v[64:67], v[192:195], v[108:111]
	v_mfma_f32_16x16x32_bf16 v[104:107], v[72:75], v[192:195], v[104:107]
	v_mfma_f32_16x16x32_bf16 v[92:95], v[64:67], v[200:203], v[92:95]
	v_mfma_f32_16x16x32_bf16 v[88:91], v[72:75], v[200:203], v[88:91]
	v_mfma_f32_16x16x32_bf16 v[140:143], v[68:71], v[180:183], v[140:143]
	v_mfma_f32_16x16x32_bf16 v[136:139], v[76:79], v[180:183], v[136:139]
	v_mfma_f32_16x16x32_bf16 v[124:127], v[68:71], v[188:191], v[124:127]
	v_mfma_f32_16x16x32_bf16 v[120:123], v[76:79], v[188:191], v[120:123]
	v_mfma_f32_16x16x32_bf16 v[108:111], v[68:71], v[196:199], v[108:111]
	v_mfma_f32_16x16x32_bf16 v[104:107], v[76:79], v[196:199], v[104:107]
	v_mfma_f32_16x16x32_bf16 v[92:95], v[68:71], v[204:207], v[92:95]
	v_mfma_f32_16x16x32_bf16 v[88:91], v[76:79], v[204:207], v[88:91]


; #define PG8_STAGE(bufoff, gbase, voff) do { _Pragma("unroll") for (int _i = 0; _i < 2; ++_i) \
;         __builtin_amdgcn_global_load_lds((const unsigned*)((const char*)(gbase) + (voff)[_i]), (PG8_LAS unsigned*)(lds + (bufoff) + ldsw + _i * 8192), 16, 0, 0); } while (0)
; #define PG8_LDA(dst, b, h) do { _Pragma("unroll") for (int m = 0; m < 4; ++m) _Pragma("unroll") for (int k = 0; k < 2; ++k) dst[m][k] = *(const PG8_LAS bf16x8*)(lds + PG8_SA(b, h) + aoff + m * 2048 + k * 1024); } while (0)
; #define PG8_MMA(ai, bj, At, Bt) do { __builtin_amdgcn_s_setprio(1); _Pragma("unroll") for (int m = 0; m < 4; ++m) _Pragma("unroll") for (int n = 0; n < 2; ++n) _Pragma("unroll") for (int k = 0; k < 2; ++k) \
;         acc[ai][bj][m][n] = __builtin_amdgcn_mfma_f32_16x16x32_bf16(Bt[n][k], At[m][k], acc[ai][bj][m][n], 0, 0, 0); __builtin_amdgcn_s_setprio(0); } while (0)
; #define PG8_WAIT_V(n) asm volatile("s_waitcnt vmcnt(" #n ")" ::: "memory")
; #define PG8_WAIT_L(n) asm volatile("s_waitcnt lgkmcnt(" #n ")" ::: "memory")
; #define PG8_BAR __builtin_amdgcn_s_barrier()
; #define PG8_SCHED __builtin_amdgcn_sched_barrier(0)
; template <class Epi, class Sched, bool ALIGN_EPI = false, bool SP2 = false>
; __device__ __forceinline__ void gemm_phase(PG8_LAS unsigned char* lds, const Gemm g, const Sched& S, const Epi& E) {
;     ...
;             PG8_WAIT_V(8); PG8_WAIT_L(0); PG8_BAR; PG8_MMA(0, 0, At, B0); PG8_MMA(0, 1, At, B1); PG8_BAR; PG8_SCHED;
;             PG8_LDA(At, 0, 1); PG8_STAGE(PG8_SB(0, 0), b2, voffB); PG8_STAGE(PG8_SB(0, 1), b2 + hstep, voffB); PG8_STAGE(PG8_SA(0, 0), a2, voffA);
	v_mfma_f32_16x16x32_bf16 v[132:135], v[144:147], v[176:179], v[132:135]
	v_mfma_f32_16x16x32_bf16 v[128:131], v[152:155], v[176:179], v[128:131]
	v_mfma_f32_16x16x32_bf16 v[116:119], v[144:147], v[184:187], v[116:119]
	v_mfma_f32_16x16x32_bf16 v[112:115], v[152:155], v[184:187], v[112:115]
	v_mfma_f32_16x16x32_bf16 v[100:103], v[144:147], v[192:195], v[100:103]
	v_mfma_f32_16x16x32_bf16 v[96:99], v[152:155], v[192:195], v[96:99]
	v_mfma_f32_16x16x32_bf16 v[84:87], v[144:147], v[200:203], v[84:87]
	v_mfma_f32_16x16x32_bf16 v[80:83], v[152:155], v[200:203], v[80:83]
	v_mfma_f32_16x16x32_bf16 v[132:135], v[148:151], v[180:183], v[132:135]
	v_mfma_f32_16x16x32_bf16 v[128:131], v[156:159], v[180:183], v[128:131]
	v_mfma_f32_16x16x32_bf16 v[116:119], v[148:151], v[188:191], v[116:119]
	v_mfma_f32_16x16x32_bf16 v[112:115], v[156:159], v[188:191], v[112:115]
	v_mfma_f32_16x16x32_bf16 v[100:103], v[148:151], v[196:199], v[100:103]
	v_mfma_f32_16x16x32_bf16 v[96:99], v[156:159], v[196:199], v[96:99]
	v_mfma_f32_16x16x32_bf16 v[84:87], v[148:151], v[204:207], v[84:87]
	v_mfma_f32_16x16x32_bf16 v[80:83], v[156:159], v[204:207], v[80:83]
	s_setprio 0
	s_barrier
	s_add_i32 s82, s75, s64
	s_mov_b64 s[96:97], s[60:61]

; #define PG8_STAGE(bufoff, gbase, voff) do { _Pragma("unroll") for (int _i = 0; _i < 2; ++_i) \
;         __builtin_amdgcn_global_load_lds((const unsigned*)((const char*)(gbase) + (voff)[_i]), (PG8_LAS unsigned*)(lds + (bufoff) + ldsw + _i * 8192), 16, 0, 0); } while (0)
; #define PG8_LDA(dst, b, h) do { _Pragma("unroll") for (int m = 0; m < 4; ++m) _Pragma("unroll") for (int k = 0; k < 2; ++k) dst[m][k] = *(const PG8_LAS bf16x8*)(lds + PG8_SA(b, h) + aoff + m * 2048 + k * 1024); } while (0)
; template <class Epi, class Sched, bool ALIGN_EPI = false, bool SP2 = false>
; __device__ __forceinline__ void gemm_phase(PG8_LAS unsigned char* lds, const Gemm g, const Sched& S, const Epi& E) {
;     ...
;             PG8_LDA(At, 0, 1); PG8_STAGE(PG8_SB(0, 0), b2, voffB); PG8_STAGE(PG8_SB(0, 1), b2 + hstep, voffB); PG8_STAGE(PG8_SA(0, 0), a2, voffA);
	s_mov_b32 m0, s82
	ds_read_b128 v[176:179], v215 offset:16384
	ds_read_b128 v[180:183], v215 offset:17408
	ds_read_b128 v[184:187], v215 offset:18432
	ds_read_b128 v[188:191], v215 offset:19456
	ds_read_b128 v[192:195], v215 offset:20480
	ds_read_b128 v[196:199], v215 offset:21504
	ds_read_b128 v[200:203], v215 offset:22528
	ds_read_b128 v[204:207], v215 offset:23552
	global_load_lds_dwordx4 v162, s[60:61]
	s_add_i32 m0, s82, 0x2000
	s_add_u32 s82, s60, 0x80000

; #define PG8_STAGE(bufoff, gbase, voff) do { _Pragma("unroll") for (int _i = 0; _i < 2; ++_i) \
;         __builtin_amdgcn_global_load_lds((const unsigned*)((const char*)(gbase) + (voff)[_i]), (PG8_LAS unsigned*)(lds + (bufoff) + ldsw + _i * 8192), 16, 0, 0); } while (0)
; #define PG8_LDA(dst, b, h) do { _Pragma("unroll") for (int m = 0; m < 4; ++m) _Pragma("unroll") for (int k = 0; k < 2; ++k) dst[m][k] = *(const PG8_LAS bf16x8*)(lds + PG8_SA(b, h) + aoff + m * 2048 + k * 1024); } while (0)
; template <class Epi, class Sched, bool ALIGN_EPI = false, bool SP2 = false>
; __device__ __forceinline__ void gemm_phase(PG8_LAS unsigned char* lds, const Gemm g, const Sched& S, const Epi& E) {
;     ...
;             PG8_LDA(At, 0, 1); PG8_STAGE(PG8_SB(0, 0), b2, voffB); PG8_STAGE(PG8_SB(0, 1), b2 + hstep, voffB); PG8_STAGE(PG8_SA(0, 0), a2, voffA);
	s_addc_u32 s83, s61, 0
	s_add_i32 s84, s76, s64
	global_load_lds_dwordx4 v166, s[60:61]

; #define PG8_STAGE(bufoff, gbase, voff) do { _Pragma("unroll") for (int _i = 0; _i < 2; ++_i) \
;         __builtin_amdgcn_global_load_lds((const unsigned*)((const char*)(gbase) + (voff)[_i]), (PG8_LAS unsigned*)(lds + (bufoff) + ldsw + _i * 8192), 16, 0, 0); } while (0)
; #define PG8_LDA(dst, b, h) do { _Pragma("unroll") for (int m = 0; m < 4; ++m) _Pragma("unroll") for (int k = 0; k < 2; ++k) dst[m][k] = *(const PG8_LAS bf16x8*)(lds + PG8_SA(b, h) + aoff + m * 2048 + k * 1024); } while (0)
; template <class Epi, class Sched, bool ALIGN_EPI = false, bool SP2 = false>
; __device__ __forceinline__ void gemm_phase(PG8_LAS unsigned char* lds, const Gemm g, const Sched& S, const Epi& E) {
;     ...
;             PG8_LDA(At, 0, 1); PG8_STAGE(PG8_SB(0, 0), b2, voffB); PG8_STAGE(PG8_SB(0, 1), b2 + hstep, voffB); PG8_STAGE(PG8_SA(0, 0), a2, voffA);
	s_mov_b32 m0, s84
	s_nop 0
	global_load_lds_dwordx4 v162, s[82:83]

; #define PG8_STAGE(bufoff, gbase, voff) do { _Pragma("unroll") for (int _i = 0; _i < 2; ++_i) \
;         __builtin_amdgcn_global_load_lds((const unsigned*)((const char*)(gbase) + (voff)[_i]), (PG8_LAS unsigned*)(lds + (bufoff) + ldsw + _i * 8192), 16, 0, 0); } while (0)
; #define PG8_LDA(dst, b, h) do { _Pragma("unroll") for (int m = 0; m < 4; ++m) _Pragma("unroll") for (int k = 0; k < 2; ++k) dst[m][k] = *(const PG8_LAS bf16x8*)(lds + PG8_SA(b, h) + aoff + m * 2048 + k * 1024); } while (0)
; template <class Epi, class Sched, bool ALIGN_EPI = false, bool SP2 = false>
; __device__ __forceinline__ void gemm_phase(PG8_LAS unsigned char* lds, const Gemm g, const Sched& S, const Epi& E) {
;     ...
;             PG8_LDA(At, 0, 1); PG8_STAGE(PG8_SB(0, 0), b2, voffB); PG8_STAGE(PG8_SB(0, 1), b2 + hstep, voffB); PG8_STAGE(PG8_SA(0, 0), a2, voffA);
	s_add_i32 m0, s84, 0x2000
	s_nop 0
	global_load_lds_dwordx4 v166, s[82:83]
	s_mov_b64 s[98:99], s[62:63]

; #define PG8_STAGE(bufoff, gbase, voff) do { _Pragma("unroll") for (int _i = 0; _i < 2; ++_i) \
;         __builtin_amdgcn_global_load_lds((const unsigned*)((const char*)(gbase) + (voff)[_i]), (PG8_LAS unsigned*)(lds + (bufoff) + ldsw + _i * 8192), 16, 0, 0); } while (0)
; #define PG8_LDA(dst, b, h) do { _Pragma("unroll") for (int m = 0; m < 4; ++m) _Pragma("unroll") for (int k = 0; k < 2; ++k) dst[m][k] = *(const PG8_LAS bf16x8*)(lds + PG8_SA(b, h) + aoff + m * 2048 + k * 1024); } while (0)
; #define PG8_MMA(ai, bj, At, Bt) do { __builtin_amdgcn_s_setprio(1); _Pragma("unroll") for (int m = 0; m < 4; ++m) _Pragma("unroll") for (int n = 0; n < 2; ++n) _Pragma("unroll") for (int k = 0; k < 2; ++k) \
;         acc[ai][bj][m][n] = __builtin_amdgcn_mfma_f32_16x16x32_bf16(Bt[n][k], At[m][k], acc[ai][bj][m][n], 0, 0, 0); __builtin_amdgcn_s_setprio(0); } while (0)
; #define PG8_WAIT_V(n) asm volatile("s_waitcnt vmcnt(" #n ")" ::: "memory")
; #define PG8_WAIT_L(n) asm volatile("s_waitcnt lgkmcnt(" #n ")" ::: "memory")
; #define PG8_BAR __builtin_amdgcn_s_barrier()
; #define PG8_SCHED __builtin_amdgcn_sched_barrier(0)
; template <class Epi, class Sched, bool ALIGN_EPI = false, bool SP2 = false>
; __device__ __forceinline__ void gemm_phase(PG8_LAS unsigned char* lds, const Gemm g, const Sched& S, const Epi& E) {
;     ...
;             PG8_LDA(At, 0, 1); PG8_STAGE(PG8_SB(0, 0), b2, voffB); PG8_STAGE(PG8_SB(0, 1), b2 + hstep, voffB); PG8_STAGE(PG8_SA(0, 0), a2, voffA);
;             PG8_WAIT_V(8); PG8_WAIT_L(0); PG8_BAR; PG8_MMA(1, 0, At, B0); PG8_MMA(1, 1, At, B1); PG8_BAR; PG8_SCHED;
	s_mov_b32 m0, s57
	s_nop 0
	global_load_lds_dwordx4 v160, s[62:63]
	s_mov_b32 m0, s65
	s_nop 0
	global_load_lds_dwordx4 v164, s[62:63]
	s_waitcnt vmcnt(8)
	s_waitcnt lgkmcnt(0)
	s_setprio 1
	s_barrier

; #define PG8_MMA(ai, bj, At, Bt) do { __builtin_amdgcn_s_setprio(1); _Pragma("unroll") for (int m = 0; m < 4; ++m) _Pragma("unroll") for (int n = 0; n < 2; ++n) _Pragma("unroll") for (int k = 0; k < 2; ++k) \
;         acc[ai][bj][m][n] = __builtin_amdgcn_mfma_f32_16x16x32_bf16(Bt[n][k], At[m][k], acc[ai][bj][m][n], 0, 0, 0); __builtin_amdgcn_s_setprio(0); } while (0)
; #define PG8_WAIT_V(n) asm volatile("s_waitcnt vmcnt(" #n ")" ::: "memory")
; #define PG8_WAIT_L(n) asm volatile("s_waitcnt lgkmcnt(" #n ")" ::: "memory")
; #define PG8_BAR __builtin_amdgcn_s_barrier()
; #define PG8_SCHED __builtin_amdgcn_sched_barrier(0)
; template <class Epi, class Sched, bool ALIGN_EPI = false, bool SP2 = false>
; __device__ __forceinline__ void gemm_phase(PG8_LAS unsigned char* lds, const Gemm g, const Sched& S, const Epi& E) {
;     ...
;             PG8_WAIT_V(8); PG8_WAIT_L(0); PG8_BAR; PG8_MMA(1, 0, At, B0); PG8_MMA(1, 1, At, B1); PG8_BAR; PG8_SCHED;
	v_mfma_f32_16x16x32_bf16 v[60:63], v[64:67], v[176:179], v[60:63]
	v_mfma_f32_16x16x32_bf16 v[56:59], v[72:75], v[176:179], v[56:59]
	v_mfma_f32_16x16x32_bf16 v[44:47], v[64:67], v[184:187], v[44:47]
	v_mfma_f32_16x16x32_bf16 v[40:43], v[72:75], v[184:187], v[40:43]
	v_mfma_f32_16x16x32_bf16 v[28:31], v[64:67], v[192:195], v[28:31]
	v_mfma_f32_16x16x32_bf16 v[24:27], v[72:75], v[192:195], v[24:27]
	v_mfma_f32_16x16x32_bf16 v[12:15], v[64:67], v[200:203], v[12:15]
	v_mfma_f32_16x16x32_bf16 v[8:11], v[72:75], v[200:203], v[8:11]
	v_mfma_f32_16x16x32_bf16 v[60:63], v[68:71], v[180:183], v[60:63]
	v_mfma_f32_16x16x32_bf16 v[56:59], v[76:79], v[180:183], v[56:59]
	v_mfma_f32_16x16x32_bf16 v[44:47], v[68:71], v[188:191], v[44:47]
	v_mfma_f32_16x16x32_bf16 v[40:43], v[76:79], v[188:191], v[40:43]
	v_mfma_f32_16x16x32_bf16 v[28:31], v[68:71], v[196:199], v[28:31]
	v_mfma_f32_16x16x32_bf16 v[24:27], v[76:79], v[196:199], v[24:27]
	v_mfma_f32_16x16x32_bf16 v[12:15], v[68:71], v[204:207], v[12:15]
	v_mfma_f32_16x16x32_bf16 v[8:11], v[76:79], v[204:207], v[8:11]


; #define PG8_MMA(ai, bj, At, Bt) do { __builtin_amdgcn_s_setprio(1); _Pragma("unroll") for (int m = 0; m < 4; ++m) _Pragma("unroll") for (int n = 0; n < 2; ++n) _Pragma("unroll") for (int k = 0; k < 2; ++k) \
;         acc[ai][bj][m][n] = __builtin_amdgcn_mfma_f32_16x16x32_bf16(Bt[n][k], At[m][k], acc[ai][bj][m][n], 0, 0, 0); __builtin_amdgcn_s_setprio(0); } while (0)
; #define PG8_WAIT_V(n) asm volatile("s_waitcnt vmcnt(" #n ")" ::: "memory")
; #define PG8_WAIT_L(n) asm volatile("s_waitcnt lgkmcnt(" #n ")" ::: "memory")
; #define PG8_BAR __builtin_amdgcn_s_barrier()
; #define PG8_SCHED __builtin_amdgcn_sched_barrier(0)
; template <class Epi, class Sched, bool ALIGN_EPI = false, bool SP2 = false>
; __device__ __forceinline__ void gemm_phase(PG8_LAS unsigned char* lds, const Gemm g, const Sched& S, const Epi& E) {
;     ...
;             PG8_WAIT_V(8); PG8_WAIT_L(0); PG8_BAR; PG8_MMA(1, 0, At, B0); PG8_MMA(1, 1, At, B1); PG8_BAR; PG8_SCHED;
	v_mfma_f32_16x16x32_bf16 v[52:55], v[144:147], v[176:179], v[52:55]
	v_mfma_f32_16x16x32_bf16 v[48:51], v[152:155], v[176:179], v[48:51]
	v_mfma_f32_16x16x32_bf16 v[36:39], v[144:147], v[184:187], v[36:39]
	v_mfma_f32_16x16x32_bf16 v[32:35], v[152:155], v[184:187], v[32:35]
	v_mfma_f32_16x16x32_bf16 v[20:23], v[144:147], v[192:195], v[20:23]
	v_mfma_f32_16x16x32_bf16 v[16:19], v[152:155], v[192:195], v[16:19]
	v_mfma_f32_16x16x32_bf16 v[4:7], v[144:147], v[200:203], v[4:7]
	v_mfma_f32_16x16x32_bf16 v[0:3], v[152:155], v[200:203], v[0:3]
	v_mfma_f32_16x16x32_bf16 v[52:55], v[148:151], v[180:183], v[52:55]
	v_mfma_f32_16x16x32_bf16 v[48:51], v[156:159], v[180:183], v[48:51]
	v_mfma_f32_16x16x32_bf16 v[36:39], v[148:151], v[188:191], v[36:39]
	v_mfma_f32_16x16x32_bf16 v[32:35], v[156:159], v[188:191], v[32:35]
	v_mfma_f32_16x16x32_bf16 v[20:23], v[148:151], v[196:199], v[20:23]
	v_mfma_f32_16x16x32_bf16 v[16:19], v[156:159], v[196:199], v[16:19]
	v_mfma_f32_16x16x32_bf16 v[4:7], v[148:151], v[204:207], v[4:7]
	v_mfma_f32_16x16x32_bf16 v[0:3], v[156:159], v[204:207], v[0:3]
	s_setprio 0
	s_barrier
	s_add_i32 s82, 0, 0x18000
	s_add_i32 s83, 0, 0x1c000


; #define PG8_STAGE(bufoff, gbase, voff) do { _Pragma("unroll") for (int _i = 0; _i < 2; ++_i) \
;         __builtin_amdgcn_global_load_lds((const unsigned*)((const char*)(gbase) + (voff)[_i]), (PG8_LAS unsigned*)(lds + (bufoff) + ldsw + _i * 8192), 16, 0, 0); } while (0)
; #define PG8_LDA(dst, b, h) do { _Pragma("unroll") for (int m = 0; m < 4; ++m) _Pragma("unroll") for (int k = 0; k < 2; ++k) dst[m][k] = *(const PG8_LAS bf16x8*)(lds + PG8_SA(b, h) + aoff + m * 2048 + k * 1024); } while (0)
; #define PG8_LDB(dst, b, h) do { _Pragma("unroll") for (int n = 0; n < 2; ++n) _Pragma("unroll") for (int k = 0; k < 2; ++k) dst[n][k] = *(const PG8_LAS bf16x8*)(lds + PG8_SB(b, h) + boff + n * 2048 + k * 1024); } while (0)
; #define PG8_SCHED __builtin_amdgcn_sched_barrier(0)
; template <class Epi, class Sched, bool ALIGN_EPI = false, bool SP2 = false>
; __device__ __forceinline__ void gemm_phase(PG8_LAS unsigned char* lds, const Gemm g, const Sched& S, const Epi& E) {
;     ...
;             PG8_LDB(B0, 1, 0); PG8_LDB(B1, 1, 1); PG8_SCHED; PG8_LDA(At, 1, 0); PG8_STAGE(PG8_SA(0, 1), a2 + hstep, voffA);
	ds_read_b128 v[64:67], v254
	ds_read_b128 v[68:71], v254 offset:1024
	ds_read_b128 v[72:75], v254 offset:2048
	ds_read_b128 v[76:79], v254 offset:3072
	ds_read_b128 v[144:147], v255
	ds_read_b128 v[148:151], v255 offset:1024
	ds_read_b128 v[152:155], v255 offset:2048
	ds_read_b128 v[156:159], v255 offset:3072
	s_add_u32 s62, s62, 0x80000
	s_addc_u32 s63, s63, 0
	s_mov_b32 m0, s67

; #define PG8_STAGE(bufoff, gbase, voff) do { _Pragma("unroll") for (int _i = 0; _i < 2; ++_i) \
;         __builtin_amdgcn_global_load_lds((const unsigned*)((const char*)(gbase) + (voff)[_i]), (PG8_LAS unsigned*)(lds + (bufoff) + ldsw + _i * 8192), 16, 0, 0); } while (0)
; #define PG8_LDA(dst, b, h) do { _Pragma("unroll") for (int m = 0; m < 4; ++m) _Pragma("unroll") for (int k = 0; k < 2; ++k) dst[m][k] = *(const PG8_LAS bf16x8*)(lds + PG8_SA(b, h) + aoff + m * 2048 + k * 1024); } while (0)
; #define PG8_LDB(dst, b, h) do { _Pragma("unroll") for (int n = 0; n < 2; ++n) _Pragma("unroll") for (int k = 0; k < 2; ++k) dst[n][k] = *(const PG8_LAS bf16x8*)(lds + PG8_SB(b, h) + boff + n * 2048 + k * 1024); } while (0)
; #define PG8_SCHED __builtin_amdgcn_sched_barrier(0)
; template <class Epi, class Sched, bool ALIGN_EPI = false, bool SP2 = false>
; __device__ __forceinline__ void gemm_phase(PG8_LAS unsigned char* lds, const Gemm g, const Sched& S, const Epi& E) {
;     ...
;             PG8_LDB(B0, 1, 0); PG8_LDB(B1, 1, 1); PG8_SCHED; PG8_LDA(At, 1, 0); PG8_STAGE(PG8_SA(0, 1), a2 + hstep, voffA);
	ds_read_b128 v[176:179], v215 offset:32768
	ds_read_b128 v[180:183], v215 offset:33792
	ds_read_b128 v[184:187], v215 offset:34816
	ds_read_b128 v[188:191], v215 offset:35840
	ds_read_b128 v[192:195], v215 offset:36864
	ds_read_b128 v[196:199], v215 offset:37888
	ds_read_b128 v[200:203], v215 offset:38912
	ds_read_b128 v[204:207], v215 offset:39936
	global_load_lds_dwordx4 v160, s[62:63]

; #define PG8_MMA(ai, bj, At, Bt) do { __builtin_amdgcn_s_setprio(1); _Pragma("unroll") for (int m = 0; m < 4; ++m) _Pragma("unroll") for (int n = 0; n < 2; ++n) _Pragma("unroll") for (int k = 0; k < 2; ++k) \
;         acc[ai][bj][m][n] = __builtin_amdgcn_mfma_f32_16x16x32_bf16(Bt[n][k], At[m][k], acc[ai][bj][m][n], 0, 0, 0); __builtin_amdgcn_s_setprio(0); } while (0)
; #define PG8_WAIT_V(n) asm volatile("s_waitcnt vmcnt(" #n ")" ::: "memory")
; #define PG8_WAIT_L(n) asm volatile("s_waitcnt lgkmcnt(" #n ")" ::: "memory")
; #define PG8_BAR __builtin_amdgcn_s_barrier()
; #define PG8_SCHED __builtin_amdgcn_sched_barrier(0)
; template <class Epi, class Sched, bool ALIGN_EPI = false, bool SP2 = false>
; __device__ __forceinline__ void gemm_phase(PG8_LAS unsigned char* lds, const Gemm g, const Sched& S, const Epi& E) {
;     ...
;             PG8_WAIT_V(8); PG8_WAIT_L(0); PG8_BAR; PG8_MMA(0, 0, At, B0); PG8_MMA(0, 1, At, B1); PG8_BAR; PG8_SCHED;
	s_mov_b32 m0, s68
	s_nop 0
	global_load_lds_dwordx4 v164, s[62:63]
	s_waitcnt vmcnt(8)
	s_waitcnt lgkmcnt(0)
	s_setprio 1
	s_barrier

; #define PG8_MMA(ai, bj, At, Bt) do { __builtin_amdgcn_s_setprio(1); _Pragma("unroll") for (int m = 0; m < 4; ++m) _Pragma("unroll") for (int n = 0; n < 2; ++n) _Pragma("unroll") for (int k = 0; k < 2; ++k) \
;         acc[ai][bj][m][n] = __builtin_amdgcn_mfma_f32_16x16x32_bf16(Bt[n][k], At[m][k], acc[ai][bj][m][n], 0, 0, 0); __builtin_amdgcn_s_setprio(0); } while (0)
; #define PG8_WAIT_V(n) asm volatile("s_waitcnt vmcnt(" #n ")" ::: "memory")
; #define PG8_WAIT_L(n) asm volatile("s_waitcnt lgkmcnt(" #n ")" ::: "memory")
; #define PG8_BAR __builtin_amdgcn_s_barrier()
; #define PG8_SCHED __builtin_amdgcn_sched_barrier(0)
; template <class Epi, class Sched, bool ALIGN_EPI = false, bool SP2 = false>
; __device__ __forceinline__ void gemm_phase(PG8_LAS unsigned char* lds, const Gemm g, const Sched& S, const Epi& E) {
;     ...
;             PG8_WAIT_V(8); PG8_WAIT_L(0); PG8_BAR; PG8_MMA(0, 0, At, B0); PG8_MMA(0, 1, At, B1); PG8_BAR; PG8_SCHED;
	v_mfma_f32_16x16x32_bf16 v[140:143], v[64:67], v[176:179], v[140:143]
	v_mfma_f32_16x16x32_bf16 v[136:139], v[72:75], v[176:179], v[136:139]
	v_mfma_f32_16x16x32_bf16 v[124:127], v[64:67], v[184:187], v[124:127]
	v_mfma_f32_16x16x32_bf16 v[120:123], v[72:75], v[184:187], v[120:123]
	v_mfma_f32_16x16x32_bf16 v[108:111], v[64:67], v[192:195], v[108:111]
	v_mfma_f32_16x16x32_bf16 v[104:107], v[72:75], v[192:195], v[104:107]
	v_mfma_f32_16x16x32_bf16 v[92:95], v[64:67], v[200:203], v[92:95]
	v_mfma_f32_16x16x32_bf16 v[88:91], v[72:75], v[200:203], v[88:91]
	v_mfma_f32_16x16x32_bf16 v[140:143], v[68:71], v[180:183], v[140:143]
	v_mfma_f32_16x16x32_bf16 v[136:139], v[76:79], v[180:183], v[136:139]
	v_mfma_f32_16x16x32_bf16 v[124:127], v[68:71], v[188:191], v[124:127]
	v_mfma_f32_16x16x32_bf16 v[120:123], v[76:79], v[188:191], v[120:123]
	v_mfma_f32_16x16x32_bf16 v[108:111], v[68:71], v[196:199], v[108:111]
	v_mfma_f32_16x16x32_bf16 v[104:107], v[76:79], v[196:199], v[104:107]
	v_mfma_f32_16x16x32_bf16 v[92:95], v[68:71], v[204:207], v[92:95]
	v_mfma_f32_16x16x32_bf16 v[88:91], v[76:79], v[204:207], v[88:91]


; #define PG8_STAGE(bufoff, gbase, voff) do { _Pragma("unroll") for (int _i = 0; _i < 2; ++_i) \
;         __builtin_amdgcn_global_load_lds((const unsigned*)((const char*)(gbase) + (voff)[_i]), (PG8_LAS unsigned*)(lds + (bufoff) + ldsw + _i * 8192), 16, 0, 0); } while (0)
; #define PG8_LDA(dst, b, h) do { _Pragma("unroll") for (int m = 0; m < 4; ++m) _Pragma("unroll") for (int k = 0; k < 2; ++k) dst[m][k] = *(const PG8_LAS bf16x8*)(lds + PG8_SA(b, h) + aoff + m * 2048 + k * 1024); } while (0)
; #define PG8_MMA(ai, bj, At, Bt) do { __builtin_amdgcn_s_setprio(1); _Pragma("unroll") for (int m = 0; m < 4; ++m) _Pragma("unroll") for (int n = 0; n < 2; ++n) _Pragma("unroll") for (int k = 0; k < 2; ++k) \
;         acc[ai][bj][m][n] = __builtin_amdgcn_mfma_f32_16x16x32_bf16(Bt[n][k], At[m][k], acc[ai][bj][m][n], 0, 0, 0); __builtin_amdgcn_s_setprio(0); } while (0)
; #define PG8_WAIT_V(n) asm volatile("s_waitcnt vmcnt(" #n ")" ::: "memory")
; #define PG8_WAIT_L(n) asm volatile("s_waitcnt lgkmcnt(" #n ")" ::: "memory")
; #define PG8_BAR __builtin_amdgcn_s_barrier()
; #define PG8_SCHED __builtin_amdgcn_sched_barrier(0)
; template <class Epi, class Sched, bool ALIGN_EPI = false, bool SP2 = false>
; __device__ __forceinline__ void gemm_phase(PG8_LAS unsigned char* lds, const Gemm g, const Sched& S, const Epi& E) {
;     ...
;             PG8_WAIT_V(8); PG8_WAIT_L(0); PG8_BAR; PG8_MMA(0, 0, At, B0); PG8_MMA(0, 1, At, B1); PG8_BAR; PG8_SCHED;
;             PG8_LDA(At, 1, 1); PG8_STAGE(PG8_SB(1, 0), b3, voffB); PG8_STAGE(PG8_SB(1, 1), b3 + hstep, voffB); PG8_STAGE(PG8_SA(1, 0), a3, voffA);
	v_mfma_f32_16x16x32_bf16 v[132:135], v[144:147], v[176:179], v[132:135]
	v_mfma_f32_16x16x32_bf16 v[128:131], v[152:155], v[176:179], v[128:131]
	v_mfma_f32_16x16x32_bf16 v[116:119], v[144:147], v[184:187], v[116:119]
	v_mfma_f32_16x16x32_bf16 v[112:115], v[152:155], v[184:187], v[112:115]
	v_mfma_f32_16x16x32_bf16 v[100:103], v[144:147], v[192:195], v[100:103]
	v_mfma_f32_16x16x32_bf16 v[96:99], v[152:155], v[192:195], v[96:99]
	v_mfma_f32_16x16x32_bf16 v[84:87], v[144:147], v[200:203], v[84:87]
	v_mfma_f32_16x16x32_bf16 v[80:83], v[152:155], v[200:203], v[80:83]
	v_mfma_f32_16x16x32_bf16 v[132:135], v[148:151], v[180:183], v[132:135]
	v_mfma_f32_16x16x32_bf16 v[128:131], v[156:159], v[180:183], v[128:131]
	v_mfma_f32_16x16x32_bf16 v[116:119], v[148:151], v[188:191], v[116:119]
	v_mfma_f32_16x16x32_bf16 v[112:115], v[156:159], v[188:191], v[112:115]
	v_mfma_f32_16x16x32_bf16 v[100:103], v[148:151], v[196:199], v[100:103]
	v_mfma_f32_16x16x32_bf16 v[96:99], v[156:159], v[196:199], v[96:99]
	v_mfma_f32_16x16x32_bf16 v[84:87], v[148:151], v[204:207], v[84:87]
	v_mfma_f32_16x16x32_bf16 v[80:83], v[156:159], v[204:207], v[80:83]
	s_setprio 0
	s_barrier
	s_add_i32 s62, s82, s64

; #define PG8_STAGE(bufoff, gbase, voff) do { _Pragma("unroll") for (int _i = 0; _i < 2; ++_i) \
;         __builtin_amdgcn_global_load_lds((const unsigned*)((const char*)(gbase) + (voff)[_i]), (PG8_LAS unsigned*)(lds + (bufoff) + ldsw + _i * 8192), 16, 0, 0); } while (0)
; #define PG8_LDA(dst, b, h) do { _Pragma("unroll") for (int m = 0; m < 4; ++m) _Pragma("unroll") for (int k = 0; k < 2; ++k) dst[m][k] = *(const PG8_LAS bf16x8*)(lds + PG8_SA(b, h) + aoff + m * 2048 + k * 1024); } while (0)
; template <class Epi, class Sched, bool ALIGN_EPI = false, bool SP2 = false>
; __device__ __forceinline__ void gemm_phase(PG8_LAS unsigned char* lds, const Gemm g, const Sched& S, const Epi& E) {
;     ...
;             PG8_LDA(At, 1, 1); PG8_STAGE(PG8_SB(1, 0), b3, voffB); PG8_STAGE(PG8_SB(1, 1), b3 + hstep, voffB); PG8_STAGE(PG8_SA(1, 0), a3, voffA);
	s_mov_b32 m0, s62
	ds_read_b128 v[176:179], v215 offset:49152
	ds_read_b128 v[180:183], v215 offset:50176
	ds_read_b128 v[184:187], v215 offset:51200
	ds_read_b128 v[188:191], v215 offset:52224
	ds_read_b128 v[192:195], v215 offset:53248
	ds_read_b128 v[196:199], v215 offset:54272
	ds_read_b128 v[200:203], v215 offset:55296
	ds_read_b128 v[204:207], v215 offset:56320
	global_load_lds_dwordx4 v250, s[96:97]
	s_add_i32 m0, s62, 0x2000
	s_add_u32 s60, s60, 0x80080

; #define PG8_STAGE(bufoff, gbase, voff) do { _Pragma("unroll") for (int _i = 0; _i < 2; ++_i) \
;         __builtin_amdgcn_global_load_lds((const unsigned*)((const char*)(gbase) + (voff)[_i]), (PG8_LAS unsigned*)(lds + (bufoff) + ldsw + _i * 8192), 16, 0, 0); } while (0)
; #define PG8_LDA(dst, b, h) do { _Pragma("unroll") for (int m = 0; m < 4; ++m) _Pragma("unroll") for (int k = 0; k < 2; ++k) dst[m][k] = *(const PG8_LAS bf16x8*)(lds + PG8_SA(b, h) + aoff + m * 2048 + k * 1024); } while (0)
; template <class Epi, class Sched, bool ALIGN_EPI = false, bool SP2 = false>
; __device__ __forceinline__ void gemm_phase(PG8_LAS unsigned char* lds, const Gemm g, const Sched& S, const Epi& E) {
;     ...
;             PG8_LDA(At, 1, 1); PG8_STAGE(PG8_SB(1, 0), b3, voffB); PG8_STAGE(PG8_SB(1, 1), b3 + hstep, voffB); PG8_STAGE(PG8_SA(1, 0), a3, voffA);
	s_addc_u32 s61, s61, 0
	s_add_i32 s62, s83, s64
	global_load_lds_dwordx4 v251, s[96:97]

; #define PG8_STAGE(bufoff, gbase, voff) do { _Pragma("unroll") for (int _i = 0; _i < 2; ++_i) \
;         __builtin_amdgcn_global_load_lds((const unsigned*)((const char*)(gbase) + (voff)[_i]), (PG8_LAS unsigned*)(lds + (bufoff) + ldsw + _i * 8192), 16, 0, 0); } while (0)
; #define PG8_LDA(dst, b, h) do { _Pragma("unroll") for (int m = 0; m < 4; ++m) _Pragma("unroll") for (int k = 0; k < 2; ++k) dst[m][k] = *(const PG8_LAS bf16x8*)(lds + PG8_SA(b, h) + aoff + m * 2048 + k * 1024); } while (0)
; template <class Epi, class Sched, bool ALIGN_EPI = false, bool SP2 = false>
; __device__ __forceinline__ void gemm_phase(PG8_LAS unsigned char* lds, const Gemm g, const Sched& S, const Epi& E) {
;     ...
;             PG8_LDA(At, 1, 1); PG8_STAGE(PG8_SB(1, 0), b3, voffB); PG8_STAGE(PG8_SB(1, 1), b3 + hstep, voffB); PG8_STAGE(PG8_SA(1, 0), a3, voffA);
	s_mov_b32 m0, s62
	s_nop 0
	global_load_lds_dwordx4 v162, s[60:61]

; #define PG8_STAGE(bufoff, gbase, voff) do { _Pragma("unroll") for (int _i = 0; _i < 2; ++_i) \
;         __builtin_amdgcn_global_load_lds((const unsigned*)((const char*)(gbase) + (voff)[_i]), (PG8_LAS unsigned*)(lds + (bufoff) + ldsw + _i * 8192), 16, 0, 0); } while (0)
; #define PG8_LDA(dst, b, h) do { _Pragma("unroll") for (int m = 0; m < 4; ++m) _Pragma("unroll") for (int k = 0; k < 2; ++k) dst[m][k] = *(const PG8_LAS bf16x8*)(lds + PG8_SA(b, h) + aoff + m * 2048 + k * 1024); } while (0)
; template <class Epi, class Sched, bool ALIGN_EPI = false, bool SP2 = false>
; __device__ __forceinline__ void gemm_phase(PG8_LAS unsigned char* lds, const Gemm g, const Sched& S, const Epi& E) {
;     ...
;             PG8_LDA(At, 1, 1); PG8_STAGE(PG8_SB(1, 0), b3, voffB); PG8_STAGE(PG8_SB(1, 1), b3 + hstep, voffB); PG8_STAGE(PG8_SA(1, 0), a3, voffA);
	s_add_i32 m0, s62, 0x2000
	s_nop 0
	global_load_lds_dwordx4 v166, s[60:61]

; #define PG8_STAGE(bufoff, gbase, voff) do { _Pragma("unroll") for (int _i = 0; _i < 2; ++_i) \
;         __builtin_amdgcn_global_load_lds((const unsigned*)((const char*)(gbase) + (voff)[_i]), (PG8_LAS unsigned*)(lds + (bufoff) + ldsw + _i * 8192), 16, 0, 0); } while (0)
; #define PG8_LDA(dst, b, h) do { _Pragma("unroll") for (int m = 0; m < 4; ++m) _Pragma("unroll") for (int k = 0; k < 2; ++k) dst[m][k] = *(const PG8_LAS bf16x8*)(lds + PG8_SA(b, h) + aoff + m * 2048 + k * 1024); } while (0)
; template <class Epi, class Sched, bool ALIGN_EPI = false, bool SP2 = false>
; __device__ __forceinline__ void gemm_phase(PG8_LAS unsigned char* lds, const Gemm g, const Sched& S, const Epi& E) {
;     ...
;             PG8_LDA(At, 1, 1); PG8_STAGE(PG8_SB(1, 0), b3, voffB); PG8_STAGE(PG8_SB(1, 1), b3 + hstep, voffB); PG8_STAGE(PG8_SA(1, 0), a3, voffA);
	s_mov_b32 m0, s70
	s_nop 0
	global_load_lds_dwordx4 v252, s[98:99]

; #define PG8_STAGE(bufoff, gbase, voff) do { _Pragma("unroll") for (int _i = 0; _i < 2; ++_i) \
;         __builtin_amdgcn_global_load_lds((const unsigned*)((const char*)(gbase) + (voff)[_i]), (PG8_LAS unsigned*)(lds + (bufoff) + ldsw + _i * 8192), 16, 0, 0); } while (0)
; #define PG8_LDA(dst, b, h) do { _Pragma("unroll") for (int m = 0; m < 4; ++m) _Pragma("unroll") for (int k = 0; k < 2; ++k) dst[m][k] = *(const PG8_LAS bf16x8*)(lds + PG8_SA(b, h) + aoff + m * 2048 + k * 1024); } while (0)
; #define PG8_MMA(ai, bj, At, Bt) do { __builtin_amdgcn_s_setprio(1); _Pragma("unroll") for (int m = 0; m < 4; ++m) _Pragma("unroll") for (int n = 0; n < 2; ++n) _Pragma("unroll") for (int k = 0; k < 2; ++k) \
;         acc[ai][bj][m][n] = __builtin_amdgcn_mfma_f32_16x16x32_bf16(Bt[n][k], At[m][k], acc[ai][bj][m][n], 0, 0, 0); __builtin_amdgcn_s_setprio(0); } while (0)
; #define PG8_WAIT_V(n) asm volatile("s_waitcnt vmcnt(" #n ")" ::: "memory")
; #define PG8_WAIT_L(n) asm volatile("s_waitcnt lgkmcnt(" #n ")" ::: "memory")
; #define PG8_BAR __builtin_amdgcn_s_barrier()
; #define PG8_SCHED __builtin_amdgcn_sched_barrier(0)
; template <class Epi, class Sched, bool ALIGN_EPI = false, bool SP2 = false>
; __device__ __forceinline__ void gemm_phase(PG8_LAS unsigned char* lds, const Gemm g, const Sched& S, const Epi& E) {
;     ...
;             PG8_LDA(At, 1, 1); PG8_STAGE(PG8_SB(1, 0), b3, voffB); PG8_STAGE(PG8_SB(1, 1), b3 + hstep, voffB); PG8_STAGE(PG8_SA(1, 0), a3, voffA);
;             PG8_WAIT_V(8); PG8_WAIT_L(0); PG8_BAR; PG8_MMA(1, 0, At, B0); PG8_MMA(1, 1, At, B1); PG8_BAR; PG8_SCHED;
	s_mov_b32 m0, s71
	s_nop 0
	global_load_lds_dwordx4 v253, s[98:99]
	s_waitcnt vmcnt(8)
	s_waitcnt lgkmcnt(0)
	s_setprio 1
	s_barrier

; #define PG8_MMA(ai, bj, At, Bt) do { __builtin_amdgcn_s_setprio(1); _Pragma("unroll") for (int m = 0; m < 4; ++m) _Pragma("unroll") for (int n = 0; n < 2; ++n) _Pragma("unroll") for (int k = 0; k < 2; ++k) \
;         acc[ai][bj][m][n] = __builtin_amdgcn_mfma_f32_16x16x32_bf16(Bt[n][k], At[m][k], acc[ai][bj][m][n], 0, 0, 0); __builtin_amdgcn_s_setprio(0); } while (0)
; #define PG8_WAIT_V(n) asm volatile("s_waitcnt vmcnt(" #n ")" ::: "memory")
; #define PG8_WAIT_L(n) asm volatile("s_waitcnt lgkmcnt(" #n ")" ::: "memory")
; #define PG8_BAR __builtin_amdgcn_s_barrier()
; #define PG8_SCHED __builtin_amdgcn_sched_barrier(0)
; template <class Epi, class Sched, bool ALIGN_EPI = false, bool SP2 = false>
; __device__ __forceinline__ void gemm_phase(PG8_LAS unsigned char* lds, const Gemm g, const Sched& S, const Epi& E) {
;     ...
;             PG8_WAIT_V(8); PG8_WAIT_L(0); PG8_BAR; PG8_MMA(1, 0, At, B0); PG8_MMA(1, 1, At, B1); PG8_BAR; PG8_SCHED;
	v_mfma_f32_16x16x32_bf16 v[60:63], v[64:67], v[176:179], v[60:63]
	v_mfma_f32_16x16x32_bf16 v[56:59], v[72:75], v[176:179], v[56:59]
	v_mfma_f32_16x16x32_bf16 v[44:47], v[64:67], v[184:187], v[44:47]
	v_mfma_f32_16x16x32_bf16 v[40:43], v[72:75], v[184:187], v[40:43]
	v_mfma_f32_16x16x32_bf16 v[28:31], v[64:67], v[192:195], v[28:31]
	v_mfma_f32_16x16x32_bf16 v[24:27], v[72:75], v[192:195], v[24:27]
	v_mfma_f32_16x16x32_bf16 v[12:15], v[64:67], v[200:203], v[12:15]
	v_mfma_f32_16x16x32_bf16 v[8:11], v[72:75], v[200:203], v[8:11]
	v_mfma_f32_16x16x32_bf16 v[60:63], v[68:71], v[180:183], v[60:63]
	v_mfma_f32_16x16x32_bf16 v[56:59], v[76:79], v[180:183], v[56:59]
	v_mfma_f32_16x16x32_bf16 v[44:47], v[68:71], v[188:191], v[44:47]
	v_mfma_f32_16x16x32_bf16 v[40:43], v[76:79], v[188:191], v[40:43]
	v_mfma_f32_16x16x32_bf16 v[28:31], v[68:71], v[196:199], v[28:31]
	v_mfma_f32_16x16x32_bf16 v[24:27], v[76:79], v[196:199], v[24:27]
	v_mfma_f32_16x16x32_bf16 v[12:15], v[68:71], v[204:207], v[12:15]
	v_mfma_f32_16x16x32_bf16 v[8:11], v[76:79], v[204:207], v[8:11]


; #define PG8_MMA(ai, bj, At, Bt) do { __builtin_amdgcn_s_setprio(1); _Pragma("unroll") for (int m = 0; m < 4; ++m) _Pragma("unroll") for (int n = 0; n < 2; ++n) _Pragma("unroll") for (int k = 0; k < 2; ++k) \
;         acc[ai][bj][m][n] = __builtin_amdgcn_mfma_f32_16x16x32_bf16(Bt[n][k], At[m][k], acc[ai][bj][m][n], 0, 0, 0); __builtin_amdgcn_s_setprio(0); } while (0)
; #define PG8_WAIT_V(n) asm volatile("s_waitcnt vmcnt(" #n ")" ::: "memory")
; #define PG8_WAIT_L(n) asm volatile("s_waitcnt lgkmcnt(" #n ")" ::: "memory")
; #define PG8_BAR __builtin_amdgcn_s_barrier()
; #define PG8_SCHED __builtin_amdgcn_sched_barrier(0)
; template <class Epi, class Sched, bool ALIGN_EPI = false, bool SP2 = false>
; __device__ __forceinline__ void gemm_phase(PG8_LAS unsigned char* lds, const Gemm g, const Sched& S, const Epi& E) {
;     ...
;         for (int t = 0; t < nt; t += 2) {
;     ...
;             PG8_WAIT_V(8); PG8_WAIT_L(0); PG8_BAR; PG8_MMA(1, 0, At, B0); PG8_MMA(1, 1, At, B1); PG8_BAR; PG8_SCHED;
	v_mfma_f32_16x16x32_bf16 v[52:55], v[144:147], v[176:179], v[52:55]
	v_mfma_f32_16x16x32_bf16 v[48:51], v[152:155], v[176:179], v[48:51]
	v_mfma_f32_16x16x32_bf16 v[36:39], v[144:147], v[184:187], v[36:39]
	v_mfma_f32_16x16x32_bf16 v[32:35], v[152:155], v[184:187], v[32:35]
	v_mfma_f32_16x16x32_bf16 v[20:23], v[144:147], v[192:195], v[20:23]
	v_mfma_f32_16x16x32_bf16 v[16:19], v[152:155], v[192:195], v[16:19]
	v_mfma_f32_16x16x32_bf16 v[4:7], v[144:147], v[200:203], v[4:7]
	v_mfma_f32_16x16x32_bf16 v[0:3], v[152:155], v[200:203], v[0:3]
	v_mfma_f32_16x16x32_bf16 v[52:55], v[148:151], v[180:183], v[52:55]
	v_mfma_f32_16x16x32_bf16 v[48:51], v[156:159], v[180:183], v[48:51]
	v_mfma_f32_16x16x32_bf16 v[36:39], v[148:151], v[188:191], v[36:39]
	v_mfma_f32_16x16x32_bf16 v[32:35], v[156:159], v[188:191], v[32:35]
	v_mfma_f32_16x16x32_bf16 v[20:23], v[148:151], v[196:199], v[20:23]
	v_mfma_f32_16x16x32_bf16 v[16:19], v[156:159], v[196:199], v[16:19]
	v_mfma_f32_16x16x32_bf16 v[4:7], v[148:151], v[204:207], v[4:7]
	v_mfma_f32_16x16x32_bf16 v[0:3], v[156:159], v[204:207], v[0:3]
	s_setprio 0
	s_add_i32 s81, s81, 2
	s_add_u32 s58, s58, 0x100
	s_addc_u32 s59, s59, 0
	s_add_u32 s79, s79, 0x100
	s_addc_u32 s80, s80, 0
	s_cmp_gt_u32 s81, 29
	s_barrier


; #define PG8_BAR __builtin_amdgcn_s_barrier()
; template <class Epi, class Sched, bool ALIGN_EPI = false, bool SP2 = false>
; __device__ __forceinline__ void gemm_phase(PG8_LAS unsigned char* lds, const Gemm g, const Sched& S, const Epi& E) {
;     ...
;         for (int t = 0; t < nt; t += 2) {
;     ...
;         if constexpr (ALIGN_EPI) { if (wr == 0) PG8_BAR; }
	s_cbranch_scc0 .LBB0_939
	s_and_b64 vcc, exec, s[42:43]
	s_cbranch_vccz .LBB0_942
	s_barrier

; #define PG8_STAGE(bufoff, gbase, voff) do { _Pragma("unroll") for (int _i = 0; _i < 2; ++_i) \
;         __builtin_amdgcn_global_load_lds((const unsigned*)((const char*)(gbase) + (voff)[_i]), (PG8_LAS unsigned*)(lds + (bufoff) + ldsw + _i * 8192), 16, 0, 0); } while (0)
; #define PG8_LDA(dst, b, h) do { _Pragma("unroll") for (int m = 0; m < 4; ++m) _Pragma("unroll") for (int k = 0; k < 2; ++k) dst[m][k] = *(const PG8_LAS bf16x8*)(lds + PG8_SA(b, h) + aoff + m * 2048 + k * 1024); } while (0)
; #define PG8_LDB(dst, b, h) do { _Pragma("unroll") for (int n = 0; n < 2; ++n) _Pragma("unroll") for (int k = 0; k < 2; ++k) dst[n][k] = *(const PG8_LAS bf16x8*)(lds + PG8_SB(b, h) + boff + n * 2048 + k * 1024); } while (0)
; #define PG8_SCHED __builtin_amdgcn_sched_barrier(0)
; template <class Epi, class Sched, bool ALIGN_EPI = false, bool SP2 = false>
; __device__ __forceinline__ void gemm_phase(PG8_LAS unsigned char* lds, const Gemm g, const Sched& S, const Epi& E) {
;     ...
;         const char* nA = has_next ? (const char*)g.A + (size_t)nxt.pm * tstep : cA; const char* nB = has_next ? (const char*)g.Bt + (size_t)nxt.pn * tstep : cB;
;         for (int t = 0; t < nt; t += 2) {
;             const bool last = (t == nt - 2);
;             const char* a1 = cA + (size_t)(t + 1) * kstep;
;             const char* a2 = last ? nA : cA + (size_t)(t + 2) * kstep; const char* b2 = last ? nB : cB + (size_t)(t + 2) * kstep;
;             const char* a3 = a2 + kstep; const char* b3 = b2 + kstep;
;             if (last && has_next) S.a_ready(nxt);
;             if constexpr (SP2) {
;             PG8_LDB(B0, 0, 0); PG8_LDB(B1, 0, 1); PG8_SCHED; PG8_LDA(At, 0, 0); PG8_STAGE(PG8_SA(1, 1), a1 + hstep, voffA);
.LBB0_1034:
	ds_read_b128 v[128:131], v201
	ds_read_b128 v[132:135], v201 offset:1024
	ds_read_b128 v[136:139], v201 offset:2048
	ds_read_b128 v[140:143], v201 offset:3072
	ds_read_b128 v[144:147], v205
	ds_read_b128 v[148:151], v205 offset:1024
	ds_read_b128 v[152:155], v205 offset:2048
	ds_read_b128 v[156:159], v205 offset:3072
	s_add_u32 s12, s10, 0xfff80080
	s_addc_u32 s13, s11, -1
	s_cmp_eq_u32 s83, 28
	s_cselect_b32 s59, s53, s13
	s_cselect_b32 s58, s79, s12
	s_cselect_b32 s13, s51, s82
	s_cselect_b32 s12, s80, s81

; #define PG8_STAGE(bufoff, gbase, voff) do { _Pragma("unroll") for (int _i = 0; _i < 2; ++_i) \
;         __builtin_amdgcn_global_load_lds((const unsigned*)((const char*)(gbase) + (voff)[_i]), (PG8_LAS unsigned*)(lds + (bufoff) + ldsw + _i * 8192), 16, 0, 0); } while (0)
; #define PG8_LDA(dst, b, h) do { _Pragma("unroll") for (int m = 0; m < 4; ++m) _Pragma("unroll") for (int k = 0; k < 2; ++k) dst[m][k] = *(const PG8_LAS bf16x8*)(lds + PG8_SA(b, h) + aoff + m * 2048 + k * 1024); } while (0)
; #define PG8_LDB(dst, b, h) do { _Pragma("unroll") for (int n = 0; n < 2; ++n) _Pragma("unroll") for (int k = 0; k < 2; ++k) dst[n][k] = *(const PG8_LAS bf16x8*)(lds + PG8_SB(b, h) + boff + n * 2048 + k * 1024); } while (0)
; #define PG8_SCHED __builtin_amdgcn_sched_barrier(0)
; template <class Epi, class Sched, bool ALIGN_EPI = false, bool SP2 = false>
; __device__ __forceinline__ void gemm_phase(PG8_LAS unsigned char* lds, const Gemm g, const Sched& S, const Epi& E) {
;     ...
;             PG8_LDB(B0, 0, 0); PG8_LDB(B1, 0, 1); PG8_SCHED; PG8_LDA(At, 0, 0); PG8_STAGE(PG8_SA(1, 1), a1 + hstep, voffA);
	s_add_i32 m0, s63, 0xc000
	ds_read_b128 v[176:179], v207
	ds_read_b128 v[184:187], v207 offset:1024
	ds_read_b128 v[190:193], v207 offset:2048
	ds_read_b128 v[210:213], v207 offset:3072
	ds_read_b128 v[214:217], v207 offset:4096
	ds_read_b128 v[218:221], v207 offset:5120
	ds_read_b128 v[222:225], v207 offset:6144
	ds_read_b128 v[226:229], v207 offset:7168
	global_load_lds_dwordx4 v168, s[10:11]

; #define PG8_STAGE(bufoff, gbase, voff) do { _Pragma("unroll") for (int _i = 0; _i < 2; ++_i) \
;         __builtin_amdgcn_global_load_lds((const unsigned*)((const char*)(gbase) + (voff)[_i]), (PG8_LAS unsigned*)(lds + (bufoff) + ldsw + _i * 8192), 16, 0, 0); } while (0)
; #define PG8_LDA(dst, b, h) do { _Pragma("unroll") for (int m = 0; m < 4; ++m) _Pragma("unroll") for (int k = 0; k < 2; ++k) dst[m][k] = *(const PG8_LAS bf16x8*)(lds + PG8_SA(b, h) + aoff + m * 2048 + k * 1024); } while (0)
; #define PG8_LDB(dst, b, h) do { _Pragma("unroll") for (int n = 0; n < 2; ++n) _Pragma("unroll") for (int k = 0; k < 2; ++k) dst[n][k] = *(const PG8_LAS bf16x8*)(lds + PG8_SB(b, h) + boff + n * 2048 + k * 1024); } while (0)
; #define PG8_MMA(ai, bj, At, Bt) do { __builtin_amdgcn_s_setprio(1); _Pragma("unroll") for (int m = 0; m < 4; ++m) _Pragma("unroll") for (int n = 0; n < 2; ++n) _Pragma("unroll") for (int k = 0; k < 2; ++k) \
;         acc[ai][bj][m][n] = __builtin_amdgcn_mfma_f32_16x16x32_bf16(Bt[n][k], At[m][k], acc[ai][bj][m][n], 0, 0, 0); __builtin_amdgcn_s_setprio(0); } while (0)
; #define PG8_WAIT_V(n) asm volatile("s_waitcnt vmcnt(" #n ")" ::: "memory")
; #define PG8_WAIT_L(n) asm volatile("s_waitcnt lgkmcnt(" #n ")" ::: "memory")
; #define PG8_BAR __builtin_amdgcn_s_barrier()
; #define PG8_SCHED __builtin_amdgcn_sched_barrier(0)
; template <class Epi, class Sched, bool ALIGN_EPI = false, bool SP2 = false>
; __device__ __forceinline__ void gemm_phase(PG8_LAS unsigned char* lds, const Gemm g, const Sched& S, const Epi& E) {
;     ...
;             PG8_LDB(B0, 0, 0); PG8_LDB(B1, 0, 1); PG8_SCHED; PG8_LDA(At, 0, 0); PG8_STAGE(PG8_SA(1, 1), a1 + hstep, voffA);
;             PG8_WAIT_V(8); PG8_WAIT_L(0); PG8_BAR; PG8_MMA(0, 0, At, B0); PG8_MMA(0, 1, At, B1); PG8_BAR; PG8_SCHED;
	s_add_i32 m0, s63, 0xe000
	s_nop 0
	global_load_lds_dwordx4 v170, s[10:11]
	s_waitcnt vmcnt(8)
	s_waitcnt lgkmcnt(0)
	s_setprio 1
	s_barrier

; #define PG8_MMA(ai, bj, At, Bt) do { __builtin_amdgcn_s_setprio(1); _Pragma("unroll") for (int m = 0; m < 4; ++m) _Pragma("unroll") for (int n = 0; n < 2; ++n) _Pragma("unroll") for (int k = 0; k < 2; ++k) \
;         acc[ai][bj][m][n] = __builtin_amdgcn_mfma_f32_16x16x32_bf16(Bt[n][k], At[m][k], acc[ai][bj][m][n], 0, 0, 0); __builtin_amdgcn_s_setprio(0); } while (0)
; #define PG8_WAIT_V(n) asm volatile("s_waitcnt vmcnt(" #n ")" ::: "memory")
; #define PG8_WAIT_L(n) asm volatile("s_waitcnt lgkmcnt(" #n ")" ::: "memory")
; #define PG8_BAR __builtin_amdgcn_s_barrier()
; #define PG8_SCHED __builtin_amdgcn_sched_barrier(0)
; template <class Epi, class Sched, bool ALIGN_EPI = false, bool SP2 = false>
; __device__ __forceinline__ void gemm_phase(PG8_LAS unsigned char* lds, const Gemm g, const Sched& S, const Epi& E) {
;     ...
;             PG8_WAIT_V(8); PG8_WAIT_L(0); PG8_BAR; PG8_MMA(0, 0, At, B0); PG8_MMA(0, 1, At, B1); PG8_BAR; PG8_SCHED;
	v_mfma_f32_16x16x32_bf16 v[124:127], v[128:131], v[176:179], v[124:127]
	v_mfma_f32_16x16x32_bf16 v[120:123], v[136:139], v[176:179], v[120:123]
	v_mfma_f32_16x16x32_bf16 v[108:111], v[128:131], v[190:193], v[108:111]
	v_mfma_f32_16x16x32_bf16 v[104:107], v[136:139], v[190:193], v[104:107]
	v_mfma_f32_16x16x32_bf16 v[92:95], v[128:131], v[214:217], v[92:95]
	v_mfma_f32_16x16x32_bf16 v[88:91], v[136:139], v[214:217], v[88:91]
	v_mfma_f32_16x16x32_bf16 v[76:79], v[128:131], v[222:225], v[76:79]
	v_mfma_f32_16x16x32_bf16 v[72:75], v[136:139], v[222:225], v[72:75]
	v_mfma_f32_16x16x32_bf16 v[124:127], v[132:135], v[184:187], v[124:127]
	v_mfma_f32_16x16x32_bf16 v[120:123], v[140:143], v[184:187], v[120:123]
	v_mfma_f32_16x16x32_bf16 v[108:111], v[132:135], v[210:213], v[108:111]
	v_mfma_f32_16x16x32_bf16 v[104:107], v[140:143], v[210:213], v[104:107]
	v_mfma_f32_16x16x32_bf16 v[92:95], v[132:135], v[218:221], v[92:95]
	v_mfma_f32_16x16x32_bf16 v[88:91], v[140:143], v[218:221], v[88:91]
	v_mfma_f32_16x16x32_bf16 v[76:79], v[132:135], v[226:229], v[76:79]
	v_mfma_f32_16x16x32_bf16 v[72:75], v[140:143], v[226:229], v[72:75]


; #define PG8_STAGE(bufoff, gbase, voff) do { _Pragma("unroll") for (int _i = 0; _i < 2; ++_i) \
;         __builtin_amdgcn_global_load_lds((const unsigned*)((const char*)(gbase) + (voff)[_i]), (PG8_LAS unsigned*)(lds + (bufoff) + ldsw + _i * 8192), 16, 0, 0); } while (0)
; #define PG8_LDA(dst, b, h) do { _Pragma("unroll") for (int m = 0; m < 4; ++m) _Pragma("unroll") for (int k = 0; k < 2; ++k) dst[m][k] = *(const PG8_LAS bf16x8*)(lds + PG8_SA(b, h) + aoff + m * 2048 + k * 1024); } while (0)
; #define PG8_MMA(ai, bj, At, Bt) do { __builtin_amdgcn_s_setprio(1); _Pragma("unroll") for (int m = 0; m < 4; ++m) _Pragma("unroll") for (int n = 0; n < 2; ++n) _Pragma("unroll") for (int k = 0; k < 2; ++k) \
;         acc[ai][bj][m][n] = __builtin_amdgcn_mfma_f32_16x16x32_bf16(Bt[n][k], At[m][k], acc[ai][bj][m][n], 0, 0, 0); __builtin_amdgcn_s_setprio(0); } while (0)
; #define PG8_WAIT_V(n) asm volatile("s_waitcnt vmcnt(" #n ")" ::: "memory")
; #define PG8_WAIT_L(n) asm volatile("s_waitcnt lgkmcnt(" #n ")" ::: "memory")
; #define PG8_BAR __builtin_amdgcn_s_barrier()
; #define PG8_SCHED __builtin_amdgcn_sched_barrier(0)
; template <class Epi, class Sched, bool ALIGN_EPI = false, bool SP2 = false>
; __device__ __forceinline__ void gemm_phase(PG8_LAS unsigned char* lds, const Gemm g, const Sched& S, const Epi& E) {
;     ...
;             PG8_WAIT_V(8); PG8_WAIT_L(0); PG8_BAR; PG8_MMA(0, 0, At, B0); PG8_MMA(0, 1, At, B1); PG8_BAR; PG8_SCHED;
;             PG8_LDA(At, 0, 1); PG8_STAGE(PG8_SB(0, 0), b2, voffB); PG8_STAGE(PG8_SB(0, 1), b2 + hstep, voffB); PG8_STAGE(PG8_SA(0, 0), a2, voffA);
	v_mfma_f32_16x16x32_bf16 v[116:119], v[144:147], v[176:179], v[116:119]
	v_mfma_f32_16x16x32_bf16 v[112:115], v[152:155], v[176:179], v[112:115]
	v_mfma_f32_16x16x32_bf16 v[100:103], v[144:147], v[190:193], v[100:103]
	v_mfma_f32_16x16x32_bf16 v[96:99], v[152:155], v[190:193], v[96:99]
	v_mfma_f32_16x16x32_bf16 v[84:87], v[144:147], v[214:217], v[84:87]
	v_mfma_f32_16x16x32_bf16 v[80:83], v[152:155], v[214:217], v[80:83]
	v_mfma_f32_16x16x32_bf16 v[68:71], v[144:147], v[222:225], v[68:71]
	v_mfma_f32_16x16x32_bf16 v[64:67], v[152:155], v[222:225], v[64:67]
	v_mfma_f32_16x16x32_bf16 v[116:119], v[148:151], v[184:187], v[116:119]
	v_mfma_f32_16x16x32_bf16 v[112:115], v[156:159], v[184:187], v[112:115]
	v_mfma_f32_16x16x32_bf16 v[100:103], v[148:151], v[210:213], v[100:103]
	v_mfma_f32_16x16x32_bf16 v[96:99], v[156:159], v[210:213], v[96:99]
	v_mfma_f32_16x16x32_bf16 v[84:87], v[148:151], v[218:221], v[84:87]
	v_mfma_f32_16x16x32_bf16 v[80:83], v[156:159], v[218:221], v[80:83]
	v_mfma_f32_16x16x32_bf16 v[68:71], v[148:151], v[226:229], v[68:71]
	v_mfma_f32_16x16x32_bf16 v[64:67], v[156:159], v[226:229], v[64:67]
	s_setprio 0
	s_barrier
	s_add_i32 s84, s73, s62
	s_mov_b64 s[96:97], s[12:13]

; #define PG8_STAGE(bufoff, gbase, voff) do { _Pragma("unroll") for (int _i = 0; _i < 2; ++_i) \
;         __builtin_amdgcn_global_load_lds((const unsigned*)((const char*)(gbase) + (voff)[_i]), (PG8_LAS unsigned*)(lds + (bufoff) + ldsw + _i * 8192), 16, 0, 0); } while (0)
; #define PG8_LDA(dst, b, h) do { _Pragma("unroll") for (int m = 0; m < 4; ++m) _Pragma("unroll") for (int k = 0; k < 2; ++k) dst[m][k] = *(const PG8_LAS bf16x8*)(lds + PG8_SA(b, h) + aoff + m * 2048 + k * 1024); } while (0)
; template <class Epi, class Sched, bool ALIGN_EPI = false, bool SP2 = false>
; __device__ __forceinline__ void gemm_phase(PG8_LAS unsigned char* lds, const Gemm g, const Sched& S, const Epi& E) {
;     ...
;             PG8_LDA(At, 0, 1); PG8_STAGE(PG8_SB(0, 0), b2, voffB); PG8_STAGE(PG8_SB(0, 1), b2 + hstep, voffB); PG8_STAGE(PG8_SA(0, 0), a2, voffA);
	s_mov_b32 m0, s84
	ds_read_b128 v[176:179], v207 offset:16384
	ds_read_b128 v[184:187], v207 offset:17408
	ds_read_b128 v[190:193], v207 offset:18432
	ds_read_b128 v[210:213], v207 offset:19456
	ds_read_b128 v[214:217], v207 offset:20480
	ds_read_b128 v[218:221], v207 offset:21504
	ds_read_b128 v[222:225], v207 offset:22528
	ds_read_b128 v[226:229], v207 offset:23552
	global_load_lds_dwordx4 v162, s[12:13]
	s_add_i32 m0, s84, 0x2000
	s_add_u32 s84, s12, 0x80000

; #define PG8_STAGE(bufoff, gbase, voff) do { _Pragma("unroll") for (int _i = 0; _i < 2; ++_i) \
;         __builtin_amdgcn_global_load_lds((const unsigned*)((const char*)(gbase) + (voff)[_i]), (PG8_LAS unsigned*)(lds + (bufoff) + ldsw + _i * 8192), 16, 0, 0); } while (0)
; #define PG8_LDA(dst, b, h) do { _Pragma("unroll") for (int m = 0; m < 4; ++m) _Pragma("unroll") for (int k = 0; k < 2; ++k) dst[m][k] = *(const PG8_LAS bf16x8*)(lds + PG8_SA(b, h) + aoff + m * 2048 + k * 1024); } while (0)
; template <class Epi, class Sched, bool ALIGN_EPI = false, bool SP2 = false>
; __device__ __forceinline__ void gemm_phase(PG8_LAS unsigned char* lds, const Gemm g, const Sched& S, const Epi& E) {
;     ...
;             PG8_LDA(At, 0, 1); PG8_STAGE(PG8_SB(0, 0), b2, voffB); PG8_STAGE(PG8_SB(0, 1), b2 + hstep, voffB); PG8_STAGE(PG8_SA(0, 0), a2, voffA);
	s_addc_u32 s85, s13, 0
	s_add_i32 s86, s74, s62
	global_load_lds_dwordx4 v166, s[12:13]

; #define PG8_STAGE(bufoff, gbase, voff) do { _Pragma("unroll") for (int _i = 0; _i < 2; ++_i) \
;         __builtin_amdgcn_global_load_lds((const unsigned*)((const char*)(gbase) + (voff)[_i]), (PG8_LAS unsigned*)(lds + (bufoff) + ldsw + _i * 8192), 16, 0, 0); } while (0)
; #define PG8_LDA(dst, b, h) do { _Pragma("unroll") for (int m = 0; m < 4; ++m) _Pragma("unroll") for (int k = 0; k < 2; ++k) dst[m][k] = *(const PG8_LAS bf16x8*)(lds + PG8_SA(b, h) + aoff + m * 2048 + k * 1024); } while (0)
; template <class Epi, class Sched, bool ALIGN_EPI = false, bool SP2 = false>
; __device__ __forceinline__ void gemm_phase(PG8_LAS unsigned char* lds, const Gemm g, const Sched& S, const Epi& E) {
;     ...
;             PG8_LDA(At, 0, 1); PG8_STAGE(PG8_SB(0, 0), b2, voffB); PG8_STAGE(PG8_SB(0, 1), b2 + hstep, voffB); PG8_STAGE(PG8_SA(0, 0), a2, voffA);
	s_mov_b32 m0, s86
	s_nop 0
	global_load_lds_dwordx4 v162, s[84:85]

; #define PG8_STAGE(bufoff, gbase, voff) do { _Pragma("unroll") for (int _i = 0; _i < 2; ++_i) \
;         __builtin_amdgcn_global_load_lds((const unsigned*)((const char*)(gbase) + (voff)[_i]), (PG8_LAS unsigned*)(lds + (bufoff) + ldsw + _i * 8192), 16, 0, 0); } while (0)
; #define PG8_LDA(dst, b, h) do { _Pragma("unroll") for (int m = 0; m < 4; ++m) _Pragma("unroll") for (int k = 0; k < 2; ++k) dst[m][k] = *(const PG8_LAS bf16x8*)(lds + PG8_SA(b, h) + aoff + m * 2048 + k * 1024); } while (0)
; template <class Epi, class Sched, bool ALIGN_EPI = false, bool SP2 = false>
; __device__ __forceinline__ void gemm_phase(PG8_LAS unsigned char* lds, const Gemm g, const Sched& S, const Epi& E) {
;     ...
;             PG8_LDA(At, 0, 1); PG8_STAGE(PG8_SB(0, 0), b2, voffB); PG8_STAGE(PG8_SB(0, 1), b2 + hstep, voffB); PG8_STAGE(PG8_SA(0, 0), a2, voffA);
	s_add_i32 m0, s86, 0x2000
	s_nop 0
	global_load_lds_dwordx4 v166, s[84:85]
	s_mov_b64 s[98:99], s[58:59]

; #define PG8_STAGE(bufoff, gbase, voff) do { _Pragma("unroll") for (int _i = 0; _i < 2; ++_i) \
;         __builtin_amdgcn_global_load_lds((const unsigned*)((const char*)(gbase) + (voff)[_i]), (PG8_LAS unsigned*)(lds + (bufoff) + ldsw + _i * 8192), 16, 0, 0); } while (0)
; #define PG8_LDA(dst, b, h) do { _Pragma("unroll") for (int m = 0; m < 4; ++m) _Pragma("unroll") for (int k = 0; k < 2; ++k) dst[m][k] = *(const PG8_LAS bf16x8*)(lds + PG8_SA(b, h) + aoff + m * 2048 + k * 1024); } while (0)
; #define PG8_MMA(ai, bj, At, Bt) do { __builtin_amdgcn_s_setprio(1); _Pragma("unroll") for (int m = 0; m < 4; ++m) _Pragma("unroll") for (int n = 0; n < 2; ++n) _Pragma("unroll") for (int k = 0; k < 2; ++k) \
;         acc[ai][bj][m][n] = __builtin_amdgcn_mfma_f32_16x16x32_bf16(Bt[n][k], At[m][k], acc[ai][bj][m][n], 0, 0, 0); __builtin_amdgcn_s_setprio(0); } while (0)
; #define PG8_WAIT_V(n) asm volatile("s_waitcnt vmcnt(" #n ")" ::: "memory")
; #define PG8_WAIT_L(n) asm volatile("s_waitcnt lgkmcnt(" #n ")" ::: "memory")
; #define PG8_BAR __builtin_amdgcn_s_barrier()
; #define PG8_SCHED __builtin_amdgcn_sched_barrier(0)
; template <class Epi, class Sched, bool ALIGN_EPI = false, bool SP2 = false>
; __device__ __forceinline__ void gemm_phase(PG8_LAS unsigned char* lds, const Gemm g, const Sched& S, const Epi& E) {
;     ...
;             PG8_LDA(At, 0, 1); PG8_STAGE(PG8_SB(0, 0), b2, voffB); PG8_STAGE(PG8_SB(0, 1), b2 + hstep, voffB); PG8_STAGE(PG8_SA(0, 0), a2, voffA);
;             PG8_WAIT_V(8); PG8_WAIT_L(0); PG8_BAR; PG8_MMA(1, 0, At, B0); PG8_MMA(1, 1, At, B1); PG8_BAR; PG8_SCHED;
	s_mov_b32 m0, s63
	s_nop 0
	global_load_lds_dwordx4 v160, s[58:59]
	s_mov_b32 m0, s64
	s_nop 0
	global_load_lds_dwordx4 v164, s[58:59]
	s_waitcnt vmcnt(8)
	s_waitcnt lgkmcnt(0)
	s_setprio 1
	s_barrier

; #define PG8_MMA(ai, bj, At, Bt) do { __builtin_amdgcn_s_setprio(1); _Pragma("unroll") for (int m = 0; m < 4; ++m) _Pragma("unroll") for (int n = 0; n < 2; ++n) _Pragma("unroll") for (int k = 0; k < 2; ++k) \
;         acc[ai][bj][m][n] = __builtin_amdgcn_mfma_f32_16x16x32_bf16(Bt[n][k], At[m][k], acc[ai][bj][m][n], 0, 0, 0); __builtin_amdgcn_s_setprio(0); } while (0)
; #define PG8_WAIT_V(n) asm volatile("s_waitcnt vmcnt(" #n ")" ::: "memory")
; #define PG8_WAIT_L(n) asm volatile("s_waitcnt lgkmcnt(" #n ")" ::: "memory")
; #define PG8_BAR __builtin_amdgcn_s_barrier()
; #define PG8_SCHED __builtin_amdgcn_sched_barrier(0)
; template <class Epi, class Sched, bool ALIGN_EPI = false, bool SP2 = false>
; __device__ __forceinline__ void gemm_phase(PG8_LAS unsigned char* lds, const Gemm g, const Sched& S, const Epi& E) {
;     ...
;             PG8_WAIT_V(8); PG8_WAIT_L(0); PG8_BAR; PG8_MMA(1, 0, At, B0); PG8_MMA(1, 1, At, B1); PG8_BAR; PG8_SCHED;
	v_mfma_f32_16x16x32_bf16 v[60:63], v[128:131], v[176:179], v[60:63]
	v_mfma_f32_16x16x32_bf16 v[56:59], v[136:139], v[176:179], v[56:59]
	v_mfma_f32_16x16x32_bf16 v[44:47], v[128:131], v[190:193], v[44:47]
	v_mfma_f32_16x16x32_bf16 v[40:43], v[136:139], v[190:193], v[40:43]
	v_mfma_f32_16x16x32_bf16 v[28:31], v[128:131], v[214:217], v[28:31]
	v_mfma_f32_16x16x32_bf16 v[24:27], v[136:139], v[214:217], v[24:27]
	v_mfma_f32_16x16x32_bf16 v[12:15], v[128:131], v[222:225], v[12:15]
	v_mfma_f32_16x16x32_bf16 v[8:11], v[136:139], v[222:225], v[8:11]
	v_mfma_f32_16x16x32_bf16 v[60:63], v[132:135], v[184:187], v[60:63]
	v_mfma_f32_16x16x32_bf16 v[56:59], v[140:143], v[184:187], v[56:59]
	v_mfma_f32_16x16x32_bf16 v[44:47], v[132:135], v[210:213], v[44:47]
	v_mfma_f32_16x16x32_bf16 v[40:43], v[140:143], v[210:213], v[40:43]
	v_mfma_f32_16x16x32_bf16 v[28:31], v[132:135], v[218:221], v[28:31]
	v_mfma_f32_16x16x32_bf16 v[24:27], v[140:143], v[218:221], v[24:27]
	v_mfma_f32_16x16x32_bf16 v[12:15], v[132:135], v[226:229], v[12:15]
	v_mfma_f32_16x16x32_bf16 v[8:11], v[140:143], v[226:229], v[8:11]


; #define PG8_STAGE(bufoff, gbase, voff) do { _Pragma("unroll") for (int _i = 0; _i < 2; ++_i) \
;         __builtin_amdgcn_global_load_lds((const unsigned*)((const char*)(gbase) + (voff)[_i]), (PG8_LAS unsigned*)(lds + (bufoff) + ldsw + _i * 8192), 16, 0, 0); } while (0)
; #define PG8_LDA(dst, b, h) do { _Pragma("unroll") for (int m = 0; m < 4; ++m) _Pragma("unroll") for (int k = 0; k < 2; ++k) dst[m][k] = *(const PG8_LAS bf16x8*)(lds + PG8_SA(b, h) + aoff + m * 2048 + k * 1024); } while (0)
; #define PG8_MMA(ai, bj, At, Bt) do { __builtin_amdgcn_s_setprio(1); _Pragma("unroll") for (int m = 0; m < 4; ++m) _Pragma("unroll") for (int n = 0; n < 2; ++n) _Pragma("unroll") for (int k = 0; k < 2; ++k) \
;         acc[ai][bj][m][n] = __builtin_amdgcn_mfma_f32_16x16x32_bf16(Bt[n][k], At[m][k], acc[ai][bj][m][n], 0, 0, 0); __builtin_amdgcn_s_setprio(0); } while (0)
; #define PG8_WAIT_V(n) asm volatile("s_waitcnt vmcnt(" #n ")" ::: "memory")
; #define PG8_WAIT_L(n) asm volatile("s_waitcnt lgkmcnt(" #n ")" ::: "memory")
; #define PG8_BAR __builtin_amdgcn_s_barrier()
; #define PG8_SCHED __builtin_amdgcn_sched_barrier(0)
; template <class Epi, class Sched, bool ALIGN_EPI = false, bool SP2 = false>
; __device__ __forceinline__ void gemm_phase(PG8_LAS unsigned char* lds, const Gemm g, const Sched& S, const Epi& E) {
;     ...
;             PG8_WAIT_V(8); PG8_WAIT_L(0); PG8_BAR; PG8_MMA(1, 0, At, B0); PG8_MMA(1, 1, At, B1); PG8_BAR; PG8_SCHED;
;     ...
;             PG8_LDA(At, 1, 1); PG8_STAGE(PG8_SB(1, 0), b3, voffB); PG8_STAGE(PG8_SB(1, 1), b3 + hstep, voffB); PG8_STAGE(PG8_SA(1, 0), a3, voffA);
	v_mfma_f32_16x16x32_bf16 v[52:55], v[144:147], v[176:179], v[52:55]
	v_mfma_f32_16x16x32_bf16 v[48:51], v[152:155], v[176:179], v[48:51]
	v_mfma_f32_16x16x32_bf16 v[36:39], v[144:147], v[190:193], v[36:39]
	v_mfma_f32_16x16x32_bf16 v[32:35], v[152:155], v[190:193], v[32:35]
	v_mfma_f32_16x16x32_bf16 v[20:23], v[144:147], v[214:217], v[20:23]
	v_mfma_f32_16x16x32_bf16 v[16:19], v[152:155], v[214:217], v[16:19]
	v_mfma_f32_16x16x32_bf16 v[4:7], v[144:147], v[222:225], v[4:7]
	v_mfma_f32_16x16x32_bf16 v[0:3], v[152:155], v[222:225], v[0:3]
	v_mfma_f32_16x16x32_bf16 v[52:55], v[148:151], v[184:187], v[52:55]
	v_mfma_f32_16x16x32_bf16 v[48:51], v[156:159], v[184:187], v[48:51]
	v_mfma_f32_16x16x32_bf16 v[36:39], v[148:151], v[210:213], v[36:39]
	v_mfma_f32_16x16x32_bf16 v[32:35], v[156:159], v[210:213], v[32:35]
	v_mfma_f32_16x16x32_bf16 v[20:23], v[148:151], v[218:221], v[20:23]
	v_mfma_f32_16x16x32_bf16 v[16:19], v[156:159], v[218:221], v[16:19]
	v_mfma_f32_16x16x32_bf16 v[4:7], v[148:151], v[226:229], v[4:7]
	v_mfma_f32_16x16x32_bf16 v[0:3], v[156:159], v[226:229], v[0:3]
	s_setprio 0
	s_barrier
	s_add_i32 s84, 0, 0x18000
	s_add_i32 s85, 0, 0x1c000


; #define PG8_STAGE(bufoff, gbase, voff) do { _Pragma("unroll") for (int _i = 0; _i < 2; ++_i) \
;         __builtin_amdgcn_global_load_lds((const unsigned*)((const char*)(gbase) + (voff)[_i]), (PG8_LAS unsigned*)(lds + (bufoff) + ldsw + _i * 8192), 16, 0, 0); } while (0)
; #define PG8_LDA(dst, b, h) do { _Pragma("unroll") for (int m = 0; m < 4; ++m) _Pragma("unroll") for (int k = 0; k < 2; ++k) dst[m][k] = *(const PG8_LAS bf16x8*)(lds + PG8_SA(b, h) + aoff + m * 2048 + k * 1024); } while (0)
; #define PG8_LDB(dst, b, h) do { _Pragma("unroll") for (int n = 0; n < 2; ++n) _Pragma("unroll") for (int k = 0; k < 2; ++k) dst[n][k] = *(const PG8_LAS bf16x8*)(lds + PG8_SB(b, h) + boff + n * 2048 + k * 1024); } while (0)
; #define PG8_SCHED __builtin_amdgcn_sched_barrier(0)
; template <class Epi, class Sched, bool ALIGN_EPI = false, bool SP2 = false>
; __device__ __forceinline__ void gemm_phase(PG8_LAS unsigned char* lds, const Gemm g, const Sched& S, const Epi& E) {
;     ...
;             PG8_LDB(B0, 1, 0); PG8_LDB(B1, 1, 1); PG8_SCHED; PG8_LDA(At, 1, 0); PG8_STAGE(PG8_SA(0, 1), a2 + hstep, voffA);
	ds_read_b128 v[128:131], v254
	ds_read_b128 v[132:135], v254 offset:1024
	ds_read_b128 v[136:139], v254 offset:2048
	ds_read_b128 v[140:143], v254 offset:3072
	ds_read_b128 v[144:147], v255
	ds_read_b128 v[148:151], v255 offset:1024
	ds_read_b128 v[152:155], v255 offset:2048
	ds_read_b128 v[156:159], v255 offset:3072
	s_add_u32 s58, s58, 0x80000
	s_addc_u32 s59, s59, 0
	s_mov_b32 m0, s65

; #define PG8_STAGE(bufoff, gbase, voff) do { _Pragma("unroll") for (int _i = 0; _i < 2; ++_i) \
;         __builtin_amdgcn_global_load_lds((const unsigned*)((const char*)(gbase) + (voff)[_i]), (PG8_LAS unsigned*)(lds + (bufoff) + ldsw + _i * 8192), 16, 0, 0); } while (0)
; #define PG8_LDA(dst, b, h) do { _Pragma("unroll") for (int m = 0; m < 4; ++m) _Pragma("unroll") for (int k = 0; k < 2; ++k) dst[m][k] = *(const PG8_LAS bf16x8*)(lds + PG8_SA(b, h) + aoff + m * 2048 + k * 1024); } while (0)
; #define PG8_LDB(dst, b, h) do { _Pragma("unroll") for (int n = 0; n < 2; ++n) _Pragma("unroll") for (int k = 0; k < 2; ++k) dst[n][k] = *(const PG8_LAS bf16x8*)(lds + PG8_SB(b, h) + boff + n * 2048 + k * 1024); } while (0)
; #define PG8_SCHED __builtin_amdgcn_sched_barrier(0)
; template <class Epi, class Sched, bool ALIGN_EPI = false, bool SP2 = false>
; __device__ __forceinline__ void gemm_phase(PG8_LAS unsigned char* lds, const Gemm g, const Sched& S, const Epi& E) {
;     ...
;             PG8_LDB(B0, 1, 0); PG8_LDB(B1, 1, 1); PG8_SCHED; PG8_LDA(At, 1, 0); PG8_STAGE(PG8_SA(0, 1), a2 + hstep, voffA);
	ds_read_b128 v[176:179], v207 offset:32768
	ds_read_b128 v[184:187], v207 offset:33792
	ds_read_b128 v[190:193], v207 offset:34816
	ds_read_b128 v[210:213], v207 offset:35840
	ds_read_b128 v[214:217], v207 offset:36864
	ds_read_b128 v[218:221], v207 offset:37888
	ds_read_b128 v[222:225], v207 offset:38912
	ds_read_b128 v[226:229], v207 offset:39936
	global_load_lds_dwordx4 v160, s[58:59]

; #define PG8_STAGE(bufoff, gbase, voff) do { _Pragma("unroll") for (int _i = 0; _i < 2; ++_i) \
;         __builtin_amdgcn_global_load_lds((const unsigned*)((const char*)(gbase) + (voff)[_i]), (PG8_LAS unsigned*)(lds + (bufoff) + ldsw + _i * 8192), 16, 0, 0); } while (0)
; #define PG8_LDA(dst, b, h) do { _Pragma("unroll") for (int m = 0; m < 4; ++m) _Pragma("unroll") for (int k = 0; k < 2; ++k) dst[m][k] = *(const PG8_LAS bf16x8*)(lds + PG8_SA(b, h) + aoff + m * 2048 + k * 1024); } while (0)
; #define PG8_LDB(dst, b, h) do { _Pragma("unroll") for (int n = 0; n < 2; ++n) _Pragma("unroll") for (int k = 0; k < 2; ++k) dst[n][k] = *(const PG8_LAS bf16x8*)(lds + PG8_SB(b, h) + boff + n * 2048 + k * 1024); } while (0)
; #define PG8_MMA(ai, bj, At, Bt) do { __builtin_amdgcn_s_setprio(1); _Pragma("unroll") for (int m = 0; m < 4; ++m) _Pragma("unroll") for (int n = 0; n < 2; ++n) _Pragma("unroll") for (int k = 0; k < 2; ++k) \
;         acc[ai][bj][m][n] = __builtin_amdgcn_mfma_f32_16x16x32_bf16(Bt[n][k], At[m][k], acc[ai][bj][m][n], 0, 0, 0); __builtin_amdgcn_s_setprio(0); } while (0)
; #define PG8_WAIT_V(n) asm volatile("s_waitcnt vmcnt(" #n ")" ::: "memory")
; #define PG8_WAIT_L(n) asm volatile("s_waitcnt lgkmcnt(" #n ")" ::: "memory")
; #define PG8_BAR __builtin_amdgcn_s_barrier()
; #define PG8_SCHED __builtin_amdgcn_sched_barrier(0)
; template <class Epi, class Sched, bool ALIGN_EPI = false, bool SP2 = false>
; __device__ __forceinline__ void gemm_phase(PG8_LAS unsigned char* lds, const Gemm g, const Sched& S, const Epi& E) {
;     ...
;             PG8_LDB(B0, 1, 0); PG8_LDB(B1, 1, 1); PG8_SCHED; PG8_LDA(At, 1, 0); PG8_STAGE(PG8_SA(0, 1), a2 + hstep, voffA);
;             PG8_WAIT_V(8); PG8_WAIT_L(0); PG8_BAR; PG8_MMA(0, 0, At, B0); PG8_MMA(0, 1, At, B1); PG8_BAR; PG8_SCHED;
	s_mov_b32 m0, s67
	s_nop 0
	global_load_lds_dwordx4 v164, s[58:59]
	s_waitcnt vmcnt(8)
	s_waitcnt lgkmcnt(0)
	s_setprio 1
	s_barrier

; #define PG8_MMA(ai, bj, At, Bt) do { __builtin_amdgcn_s_setprio(1); _Pragma("unroll") for (int m = 0; m < 4; ++m) _Pragma("unroll") for (int n = 0; n < 2; ++n) _Pragma("unroll") for (int k = 0; k < 2; ++k) \
;         acc[ai][bj][m][n] = __builtin_amdgcn_mfma_f32_16x16x32_bf16(Bt[n][k], At[m][k], acc[ai][bj][m][n], 0, 0, 0); __builtin_amdgcn_s_setprio(0); } while (0)
; #define PG8_WAIT_V(n) asm volatile("s_waitcnt vmcnt(" #n ")" ::: "memory")
; #define PG8_WAIT_L(n) asm volatile("s_waitcnt lgkmcnt(" #n ")" ::: "memory")
; #define PG8_BAR __builtin_amdgcn_s_barrier()
; #define PG8_SCHED __builtin_amdgcn_sched_barrier(0)
; template <class Epi, class Sched, bool ALIGN_EPI = false, bool SP2 = false>
; __device__ __forceinline__ void gemm_phase(PG8_LAS unsigned char* lds, const Gemm g, const Sched& S, const Epi& E) {
;     ...
;             PG8_WAIT_V(8); PG8_WAIT_L(0); PG8_BAR; PG8_MMA(0, 0, At, B0); PG8_MMA(0, 1, At, B1); PG8_BAR; PG8_SCHED;
	v_mfma_f32_16x16x32_bf16 v[124:127], v[128:131], v[176:179], v[124:127]
	v_mfma_f32_16x16x32_bf16 v[120:123], v[136:139], v[176:179], v[120:123]
	v_mfma_f32_16x16x32_bf16 v[108:111], v[128:131], v[190:193], v[108:111]
	v_mfma_f32_16x16x32_bf16 v[104:107], v[136:139], v[190:193], v[104:107]
	v_mfma_f32_16x16x32_bf16 v[92:95], v[128:131], v[214:217], v[92:95]
	v_mfma_f32_16x16x32_bf16 v[88:91], v[136:139], v[214:217], v[88:91]
	v_mfma_f32_16x16x32_bf16 v[76:79], v[128:131], v[222:225], v[76:79]
	v_mfma_f32_16x16x32_bf16 v[72:75], v[136:139], v[222:225], v[72:75]
	v_mfma_f32_16x16x32_bf16 v[124:127], v[132:135], v[184:187], v[124:127]
	v_mfma_f32_16x16x32_bf16 v[120:123], v[140:143], v[184:187], v[120:123]
	v_mfma_f32_16x16x32_bf16 v[108:111], v[132:135], v[210:213], v[108:111]
	v_mfma_f32_16x16x32_bf16 v[104:107], v[140:143], v[210:213], v[104:107]
	v_mfma_f32_16x16x32_bf16 v[92:95], v[132:135], v[218:221], v[92:95]
	v_mfma_f32_16x16x32_bf16 v[88:91], v[140:143], v[218:221], v[88:91]
	v_mfma_f32_16x16x32_bf16 v[76:79], v[132:135], v[226:229], v[76:79]
	v_mfma_f32_16x16x32_bf16 v[72:75], v[140:143], v[226:229], v[72:75]


; #define PG8_STAGE(bufoff, gbase, voff) do { _Pragma("unroll") for (int _i = 0; _i < 2; ++_i) \
;         __builtin_amdgcn_global_load_lds((const unsigned*)((const char*)(gbase) + (voff)[_i]), (PG8_LAS unsigned*)(lds + (bufoff) + ldsw + _i * 8192), 16, 0, 0); } while (0)
; #define PG8_LDA(dst, b, h) do { _Pragma("unroll") for (int m = 0; m < 4; ++m) _Pragma("unroll") for (int k = 0; k < 2; ++k) dst[m][k] = *(const PG8_LAS bf16x8*)(lds + PG8_SA(b, h) + aoff + m * 2048 + k * 1024); } while (0)
; #define PG8_MMA(ai, bj, At, Bt) do { __builtin_amdgcn_s_setprio(1); _Pragma("unroll") for (int m = 0; m < 4; ++m) _Pragma("unroll") for (int n = 0; n < 2; ++n) _Pragma("unroll") for (int k = 0; k < 2; ++k) \
;         acc[ai][bj][m][n] = __builtin_amdgcn_mfma_f32_16x16x32_bf16(Bt[n][k], At[m][k], acc[ai][bj][m][n], 0, 0, 0); __builtin_amdgcn_s_setprio(0); } while (0)
; #define PG8_WAIT_V(n) asm volatile("s_waitcnt vmcnt(" #n ")" ::: "memory")
; #define PG8_WAIT_L(n) asm volatile("s_waitcnt lgkmcnt(" #n ")" ::: "memory")
; #define PG8_BAR __builtin_amdgcn_s_barrier()
; #define PG8_SCHED __builtin_amdgcn_sched_barrier(0)
; template <class Epi, class Sched, bool ALIGN_EPI = false, bool SP2 = false>
; __device__ __forceinline__ void gemm_phase(PG8_LAS unsigned char* lds, const Gemm g, const Sched& S, const Epi& E) {
;     ...
;             PG8_WAIT_V(8); PG8_WAIT_L(0); PG8_BAR; PG8_MMA(0, 0, At, B0); PG8_MMA(0, 1, At, B1); PG8_BAR; PG8_SCHED;
;             PG8_LDA(At, 1, 1); PG8_STAGE(PG8_SB(1, 0), b3, voffB); PG8_STAGE(PG8_SB(1, 1), b3 + hstep, voffB); PG8_STAGE(PG8_SA(1, 0), a3, voffA);
	v_mfma_f32_16x16x32_bf16 v[116:119], v[144:147], v[176:179], v[116:119]
	v_mfma_f32_16x16x32_bf16 v[112:115], v[152:155], v[176:179], v[112:115]
	v_mfma_f32_16x16x32_bf16 v[100:103], v[144:147], v[190:193], v[100:103]
	v_mfma_f32_16x16x32_bf16 v[96:99], v[152:155], v[190:193], v[96:99]
	v_mfma_f32_16x16x32_bf16 v[84:87], v[144:147], v[214:217], v[84:87]
	v_mfma_f32_16x16x32_bf16 v[80:83], v[152:155], v[214:217], v[80:83]
	v_mfma_f32_16x16x32_bf16 v[68:71], v[144:147], v[222:225], v[68:71]
	v_mfma_f32_16x16x32_bf16 v[64:67], v[152:155], v[222:225], v[64:67]
	v_mfma_f32_16x16x32_bf16 v[116:119], v[148:151], v[184:187], v[116:119]
	v_mfma_f32_16x16x32_bf16 v[112:115], v[156:159], v[184:187], v[112:115]
	v_mfma_f32_16x16x32_bf16 v[100:103], v[148:151], v[210:213], v[100:103]
	v_mfma_f32_16x16x32_bf16 v[96:99], v[156:159], v[210:213], v[96:99]
	v_mfma_f32_16x16x32_bf16 v[84:87], v[148:151], v[218:221], v[84:87]
	v_mfma_f32_16x16x32_bf16 v[80:83], v[156:159], v[218:221], v[80:83]
	v_mfma_f32_16x16x32_bf16 v[68:71], v[148:151], v[226:229], v[68:71]
	v_mfma_f32_16x16x32_bf16 v[64:67], v[156:159], v[226:229], v[64:67]
	s_setprio 0
	s_barrier
	s_add_i32 s58, s84, s62

; #define PG8_STAGE(bufoff, gbase, voff) do { _Pragma("unroll") for (int _i = 0; _i < 2; ++_i) \
;         __builtin_amdgcn_global_load_lds((const unsigned*)((const char*)(gbase) + (voff)[_i]), (PG8_LAS unsigned*)(lds + (bufoff) + ldsw + _i * 8192), 16, 0, 0); } while (0)
; #define PG8_LDA(dst, b, h) do { _Pragma("unroll") for (int m = 0; m < 4; ++m) _Pragma("unroll") for (int k = 0; k < 2; ++k) dst[m][k] = *(const PG8_LAS bf16x8*)(lds + PG8_SA(b, h) + aoff + m * 2048 + k * 1024); } while (0)
; template <class Epi, class Sched, bool ALIGN_EPI = false, bool SP2 = false>
; __device__ __forceinline__ void gemm_phase(PG8_LAS unsigned char* lds, const Gemm g, const Sched& S, const Epi& E) {
;     ...
;             PG8_LDA(At, 1, 1); PG8_STAGE(PG8_SB(1, 0), b3, voffB); PG8_STAGE(PG8_SB(1, 1), b3 + hstep, voffB); PG8_STAGE(PG8_SA(1, 0), a3, voffA);
	s_mov_b32 m0, s58
	ds_read_b128 v[176:179], v207 offset:49152
	ds_read_b128 v[184:187], v207 offset:50176
	ds_read_b128 v[190:193], v207 offset:51200
	ds_read_b128 v[210:213], v207 offset:52224
	ds_read_b128 v[214:217], v207 offset:53248
	ds_read_b128 v[218:221], v207 offset:54272
	ds_read_b128 v[222:225], v207 offset:55296
	ds_read_b128 v[226:229], v207 offset:56320
	global_load_lds_dwordx4 v250, s[96:97]
	s_add_i32 m0, s58, 0x2000
	s_add_u32 s12, s12, 0x80080

; #define PG8_STAGE(bufoff, gbase, voff) do { _Pragma("unroll") for (int _i = 0; _i < 2; ++_i) \
;         __builtin_amdgcn_global_load_lds((const unsigned*)((const char*)(gbase) + (voff)[_i]), (PG8_LAS unsigned*)(lds + (bufoff) + ldsw + _i * 8192), 16, 0, 0); } while (0)
; #define PG8_LDA(dst, b, h) do { _Pragma("unroll") for (int m = 0; m < 4; ++m) _Pragma("unroll") for (int k = 0; k < 2; ++k) dst[m][k] = *(const PG8_LAS bf16x8*)(lds + PG8_SA(b, h) + aoff + m * 2048 + k * 1024); } while (0)
; template <class Epi, class Sched, bool ALIGN_EPI = false, bool SP2 = false>
; __device__ __forceinline__ void gemm_phase(PG8_LAS unsigned char* lds, const Gemm g, const Sched& S, const Epi& E) {
;     ...
;             PG8_LDA(At, 1, 1); PG8_STAGE(PG8_SB(1, 0), b3, voffB); PG8_STAGE(PG8_SB(1, 1), b3 + hstep, voffB); PG8_STAGE(PG8_SA(1, 0), a3, voffA);
	s_addc_u32 s13, s13, 0
	s_add_i32 s58, s85, s62
	global_load_lds_dwordx4 v251, s[96:97]

; #define PG8_STAGE(bufoff, gbase, voff) do { _Pragma("unroll") for (int _i = 0; _i < 2; ++_i) \
;         __builtin_amdgcn_global_load_lds((const unsigned*)((const char*)(gbase) + (voff)[_i]), (PG8_LAS unsigned*)(lds + (bufoff) + ldsw + _i * 8192), 16, 0, 0); } while (0)
; #define PG8_LDA(dst, b, h) do { _Pragma("unroll") for (int m = 0; m < 4; ++m) _Pragma("unroll") for (int k = 0; k < 2; ++k) dst[m][k] = *(const PG8_LAS bf16x8*)(lds + PG8_SA(b, h) + aoff + m * 2048 + k * 1024); } while (0)
; template <class Epi, class Sched, bool ALIGN_EPI = false, bool SP2 = false>
; __device__ __forceinline__ void gemm_phase(PG8_LAS unsigned char* lds, const Gemm g, const Sched& S, const Epi& E) {
;     ...
;             PG8_LDA(At, 1, 1); PG8_STAGE(PG8_SB(1, 0), b3, voffB); PG8_STAGE(PG8_SB(1, 1), b3 + hstep, voffB); PG8_STAGE(PG8_SA(1, 0), a3, voffA);
	s_mov_b32 m0, s58
	s_nop 0
	global_load_lds_dwordx4 v162, s[12:13]

; #define PG8_STAGE(bufoff, gbase, voff) do { _Pragma("unroll") for (int _i = 0; _i < 2; ++_i) \
;         __builtin_amdgcn_global_load_lds((const unsigned*)((const char*)(gbase) + (voff)[_i]), (PG8_LAS unsigned*)(lds + (bufoff) + ldsw + _i * 8192), 16, 0, 0); } while (0)
; #define PG8_LDA(dst, b, h) do { _Pragma("unroll") for (int m = 0; m < 4; ++m) _Pragma("unroll") for (int k = 0; k < 2; ++k) dst[m][k] = *(const PG8_LAS bf16x8*)(lds + PG8_SA(b, h) + aoff + m * 2048 + k * 1024); } while (0)
; template <class Epi, class Sched, bool ALIGN_EPI = false, bool SP2 = false>
; __device__ __forceinline__ void gemm_phase(PG8_LAS unsigned char* lds, const Gemm g, const Sched& S, const Epi& E) {
;     ...
;             PG8_LDA(At, 1, 1); PG8_STAGE(PG8_SB(1, 0), b3, voffB); PG8_STAGE(PG8_SB(1, 1), b3 + hstep, voffB); PG8_STAGE(PG8_SA(1, 0), a3, voffA);
	s_add_i32 m0, s58, 0x2000
	s_nop 0
	global_load_lds_dwordx4 v166, s[12:13]

; #define PG8_STAGE(bufoff, gbase, voff) do { _Pragma("unroll") for (int _i = 0; _i < 2; ++_i) \
;         __builtin_amdgcn_global_load_lds((const unsigned*)((const char*)(gbase) + (voff)[_i]), (PG8_LAS unsigned*)(lds + (bufoff) + ldsw + _i * 8192), 16, 0, 0); } while (0)
; #define PG8_LDA(dst, b, h) do { _Pragma("unroll") for (int m = 0; m < 4; ++m) _Pragma("unroll") for (int k = 0; k < 2; ++k) dst[m][k] = *(const PG8_LAS bf16x8*)(lds + PG8_SA(b, h) + aoff + m * 2048 + k * 1024); } while (0)
; template <class Epi, class Sched, bool ALIGN_EPI = false, bool SP2 = false>
; __device__ __forceinline__ void gemm_phase(PG8_LAS unsigned char* lds, const Gemm g, const Sched& S, const Epi& E) {
;     ...
;             PG8_LDA(At, 1, 1); PG8_STAGE(PG8_SB(1, 0), b3, voffB); PG8_STAGE(PG8_SB(1, 1), b3 + hstep, voffB); PG8_STAGE(PG8_SA(1, 0), a3, voffA);
	s_mov_b32 m0, s69
	s_nop 0
	global_load_lds_dwordx4 v252, s[98:99]

; #define PG8_STAGE(bufoff, gbase, voff) do { _Pragma("unroll") for (int _i = 0; _i < 2; ++_i) \
;         __builtin_amdgcn_global_load_lds((const unsigned*)((const char*)(gbase) + (voff)[_i]), (PG8_LAS unsigned*)(lds + (bufoff) + ldsw + _i * 8192), 16, 0, 0); } while (0)
; #define PG8_LDA(dst, b, h) do { _Pragma("unroll") for (int m = 0; m < 4; ++m) _Pragma("unroll") for (int k = 0; k < 2; ++k) dst[m][k] = *(const PG8_LAS bf16x8*)(lds + PG8_SA(b, h) + aoff + m * 2048 + k * 1024); } while (0)
; #define PG8_MMA(ai, bj, At, Bt) do { __builtin_amdgcn_s_setprio(1); _Pragma("unroll") for (int m = 0; m < 4; ++m) _Pragma("unroll") for (int n = 0; n < 2; ++n) _Pragma("unroll") for (int k = 0; k < 2; ++k) \
;         acc[ai][bj][m][n] = __builtin_amdgcn_mfma_f32_16x16x32_bf16(Bt[n][k], At[m][k], acc[ai][bj][m][n], 0, 0, 0); __builtin_amdgcn_s_setprio(0); } while (0)
; #define PG8_WAIT_V(n) asm volatile("s_waitcnt vmcnt(" #n ")" ::: "memory")
; #define PG8_WAIT_L(n) asm volatile("s_waitcnt lgkmcnt(" #n ")" ::: "memory")
; #define PG8_BAR __builtin_amdgcn_s_barrier()
; #define PG8_SCHED __builtin_amdgcn_sched_barrier(0)
; template <class Epi, class Sched, bool ALIGN_EPI = false, bool SP2 = false>
; __device__ __forceinline__ void gemm_phase(PG8_LAS unsigned char* lds, const Gemm g, const Sched& S, const Epi& E) {
;     ...
;             PG8_LDA(At, 1, 1); PG8_STAGE(PG8_SB(1, 0), b3, voffB); PG8_STAGE(PG8_SB(1, 1), b3 + hstep, voffB); PG8_STAGE(PG8_SA(1, 0), a3, voffA);
;             PG8_WAIT_V(8); PG8_WAIT_L(0); PG8_BAR; PG8_MMA(1, 0, At, B0); PG8_MMA(1, 1, At, B1); PG8_BAR; PG8_SCHED;
	s_mov_b32 m0, s70
	s_nop 0
	global_load_lds_dwordx4 v253, s[98:99]
	s_waitcnt vmcnt(8)
	s_waitcnt lgkmcnt(0)
	s_setprio 1
	s_barrier

; #define PG8_MMA(ai, bj, At, Bt) do { __builtin_amdgcn_s_setprio(1); _Pragma("unroll") for (int m = 0; m < 4; ++m) _Pragma("unroll") for (int n = 0; n < 2; ++n) _Pragma("unroll") for (int k = 0; k < 2; ++k) \
;         acc[ai][bj][m][n] = __builtin_amdgcn_mfma_f32_16x16x32_bf16(Bt[n][k], At[m][k], acc[ai][bj][m][n], 0, 0, 0); __builtin_amdgcn_s_setprio(0); } while (0)
; #define PG8_WAIT_V(n) asm volatile("s_waitcnt vmcnt(" #n ")" ::: "memory")
; #define PG8_WAIT_L(n) asm volatile("s_waitcnt lgkmcnt(" #n ")" ::: "memory")
; #define PG8_BAR __builtin_amdgcn_s_barrier()
; #define PG8_SCHED __builtin_amdgcn_sched_barrier(0)
; template <class Epi, class Sched, bool ALIGN_EPI = false, bool SP2 = false>
; __device__ __forceinline__ void gemm_phase(PG8_LAS unsigned char* lds, const Gemm g, const Sched& S, const Epi& E) {
;     ...
;             PG8_WAIT_V(8); PG8_WAIT_L(0); PG8_BAR; PG8_MMA(1, 0, At, B0); PG8_MMA(1, 1, At, B1); PG8_BAR; PG8_SCHED;
	v_mfma_f32_16x16x32_bf16 v[60:63], v[128:131], v[176:179], v[60:63]
	v_mfma_f32_16x16x32_bf16 v[56:59], v[136:139], v[176:179], v[56:59]
	v_mfma_f32_16x16x32_bf16 v[44:47], v[128:131], v[190:193], v[44:47]
	v_mfma_f32_16x16x32_bf16 v[40:43], v[136:139], v[190:193], v[40:43]
	v_mfma_f32_16x16x32_bf16 v[28:31], v[128:131], v[214:217], v[28:31]
	v_mfma_f32_16x16x32_bf16 v[24:27], v[136:139], v[214:217], v[24:27]
	v_mfma_f32_16x16x32_bf16 v[12:15], v[128:131], v[222:225], v[12:15]
	v_mfma_f32_16x16x32_bf16 v[8:11], v[136:139], v[222:225], v[8:11]
	v_mfma_f32_16x16x32_bf16 v[60:63], v[132:135], v[184:187], v[60:63]
	v_mfma_f32_16x16x32_bf16 v[56:59], v[140:143], v[184:187], v[56:59]
	v_mfma_f32_16x16x32_bf16 v[44:47], v[132:135], v[210:213], v[44:47]
	v_mfma_f32_16x16x32_bf16 v[40:43], v[140:143], v[210:213], v[40:43]
	v_mfma_f32_16x16x32_bf16 v[28:31], v[132:135], v[218:221], v[28:31]
	v_mfma_f32_16x16x32_bf16 v[24:27], v[140:143], v[218:221], v[24:27]
	v_mfma_f32_16x16x32_bf16 v[12:15], v[132:135], v[226:229], v[12:15]
	v_mfma_f32_16x16x32_bf16 v[8:11], v[140:143], v[226:229], v[8:11]


; #define PG8_MMA(ai, bj, At, Bt) do { __builtin_amdgcn_s_setprio(1); _Pragma("unroll") for (int m = 0; m < 4; ++m) _Pragma("unroll") for (int n = 0; n < 2; ++n) _Pragma("unroll") for (int k = 0; k < 2; ++k) \
;         acc[ai][bj][m][n] = __builtin_amdgcn_mfma_f32_16x16x32_bf16(Bt[n][k], At[m][k], acc[ai][bj][m][n], 0, 0, 0); __builtin_amdgcn_s_setprio(0); } while (0)
; #define PG8_WAIT_V(n) asm volatile("s_waitcnt vmcnt(" #n ")" ::: "memory")
; #define PG8_WAIT_L(n) asm volatile("s_waitcnt lgkmcnt(" #n ")" ::: "memory")
; #define PG8_BAR __builtin_amdgcn_s_barrier()
; #define PG8_SCHED __builtin_amdgcn_sched_barrier(0)
; template <class Epi, class Sched, bool ALIGN_EPI = false, bool SP2 = false>
; __device__ __forceinline__ void gemm_phase(PG8_LAS unsigned char* lds, const Gemm g, const Sched& S, const Epi& E) {
;     ...
;         for (int t = 0; t < nt; t += 2) {
;     ...
;             PG8_WAIT_V(8); PG8_WAIT_L(0); PG8_BAR; PG8_MMA(1, 0, At, B0); PG8_MMA(1, 1, At, B1); PG8_BAR; PG8_SCHED;
	v_mfma_f32_16x16x32_bf16 v[52:55], v[144:147], v[176:179], v[52:55]
	v_mfma_f32_16x16x32_bf16 v[48:51], v[152:155], v[176:179], v[48:51]
	v_mfma_f32_16x16x32_bf16 v[36:39], v[144:147], v[190:193], v[36:39]
	v_mfma_f32_16x16x32_bf16 v[32:35], v[152:155], v[190:193], v[32:35]
	v_mfma_f32_16x16x32_bf16 v[20:23], v[144:147], v[214:217], v[20:23]
	v_mfma_f32_16x16x32_bf16 v[16:19], v[152:155], v[214:217], v[16:19]
	v_mfma_f32_16x16x32_bf16 v[4:7], v[144:147], v[222:225], v[4:7]
	v_mfma_f32_16x16x32_bf16 v[0:3], v[152:155], v[222:225], v[0:3]
	v_mfma_f32_16x16x32_bf16 v[52:55], v[148:151], v[184:187], v[52:55]
	v_mfma_f32_16x16x32_bf16 v[48:51], v[156:159], v[184:187], v[48:51]
	v_mfma_f32_16x16x32_bf16 v[36:39], v[148:151], v[210:213], v[36:39]
	v_mfma_f32_16x16x32_bf16 v[32:35], v[156:159], v[210:213], v[32:35]
	v_mfma_f32_16x16x32_bf16 v[20:23], v[148:151], v[218:221], v[20:23]
	v_mfma_f32_16x16x32_bf16 v[16:19], v[156:159], v[218:221], v[16:19]
	v_mfma_f32_16x16x32_bf16 v[4:7], v[148:151], v[226:229], v[4:7]
	v_mfma_f32_16x16x32_bf16 v[0:3], v[156:159], v[226:229], v[0:3]
	s_setprio 0
	s_add_i32 s83, s83, 2
	s_add_u32 s10, s10, 0x100
	s_addc_u32 s11, s11, 0
	s_add_u32 s81, s81, 0x100
	s_addc_u32 s82, s82, 0
	s_cmp_gt_u32 s83, 29
	s_barrier


; #define PG8_BAR __builtin_amdgcn_s_barrier()
; template <class Epi, class Sched, bool ALIGN_EPI = false, bool SP2 = false>
; __device__ __forceinline__ void gemm_phase(PG8_LAS unsigned char* lds, const Gemm g, const Sched& S, const Epi& E) {
;     ...
;         for (int t = 0; t < nt; t += 2) {
;     ...
;         if constexpr (ALIGN_EPI) { if (wr == 0) PG8_BAR; }
	s_cbranch_scc0 .LBB0_1034
	s_and_b64 vcc, exec, s[40:41]
	s_cbranch_vccz .LBB0_1037
	s_barrier

; #define PG8_STAGE(bufoff, gbase, voff) do { _Pragma("unroll") for (int _i = 0; _i < 2; ++_i) \
;         __builtin_amdgcn_global_load_lds((const unsigned*)((const char*)(gbase) + (voff)[_i]), (PG8_LAS unsigned*)(lds + (bufoff) + ldsw + _i * 8192), 16, 0, 0); } while (0)
; #define PG8_LDA(dst, b, h) do { _Pragma("unroll") for (int m = 0; m < 4; ++m) _Pragma("unroll") for (int k = 0; k < 2; ++k) dst[m][k] = *(const PG8_LAS bf16x8*)(lds + PG8_SA(b, h) + aoff + m * 2048 + k * 1024); } while (0)
; #define PG8_LDB(dst, b, h) do { _Pragma("unroll") for (int n = 0; n < 2; ++n) _Pragma("unroll") for (int k = 0; k < 2; ++k) dst[n][k] = *(const PG8_LAS bf16x8*)(lds + PG8_SB(b, h) + boff + n * 2048 + k * 1024); } while (0)
; #define PG8_SCHED __builtin_amdgcn_sched_barrier(0)
; template <class Epi, class Sched, bool ALIGN_EPI = false, bool SP2 = false>
; __device__ __forceinline__ void gemm_phase(PG8_LAS unsigned char* lds, const Gemm g, const Sched& S, const Epi& E) {
;     ...
;         const char* nA = has_next ? (const char*)g.A + (size_t)nxt.pm * tstep : cA; const char* nB = has_next ? (const char*)g.Bt + (size_t)nxt.pn * tstep : cB;
;         for (int t = 0; t < nt; t += 2) {
;             const bool last = (t == nt - 2);
;             const char* a1 = cA + (size_t)(t + 1) * kstep;
;             const char* a2 = last ? nA : cA + (size_t)(t + 2) * kstep; const char* b2 = last ? nB : cB + (size_t)(t + 2) * kstep;
;             const char* a3 = a2 + kstep; const char* b3 = b2 + kstep;
;             if (last && has_next) S.a_ready(nxt);
;             if constexpr (SP2) {
;             PG8_LDB(B0, 0, 0); PG8_LDB(B1, 0, 1); PG8_SCHED; PG8_LDA(At, 0, 0); PG8_STAGE(PG8_SA(1, 1), a1 + hstep, voffA);
.LBB0_1114:
	ds_read_b128 v[96:99], v197
	ds_read_b128 v[100:103], v197 offset:1024
	ds_read_b128 v[104:107], v197 offset:2048
	ds_read_b128 v[112:115], v197 offset:3072
	ds_read_b128 v[144:147], v198
	ds_read_b128 v[148:151], v198 offset:1024
	ds_read_b128 v[152:155], v198 offset:2048
	ds_read_b128 v[172:175], v198 offset:3072
	s_add_u32 s50, s48, 0xffe00080
	s_addc_u32 s51, s49, -1
	s_cmpk_eq_i32 s73, 0x7c
	s_cselect_b32 s53, s43, s51
	s_cselect_b32 s52, s69, s50
	s_cselect_b32 s51, s41, s72
	s_cselect_b32 s50, s70, s71

; #define PG8_STAGE(bufoff, gbase, voff) do { _Pragma("unroll") for (int _i = 0; _i < 2; ++_i) \
;         __builtin_amdgcn_global_load_lds((const unsigned*)((const char*)(gbase) + (voff)[_i]), (PG8_LAS unsigned*)(lds + (bufoff) + ldsw + _i * 8192), 16, 0, 0); } while (0)
; #define PG8_LDA(dst, b, h) do { _Pragma("unroll") for (int m = 0; m < 4; ++m) _Pragma("unroll") for (int k = 0; k < 2; ++k) dst[m][k] = *(const PG8_LAS bf16x8*)(lds + PG8_SA(b, h) + aoff + m * 2048 + k * 1024); } while (0)
; #define PG8_LDB(dst, b, h) do { _Pragma("unroll") for (int n = 0; n < 2; ++n) _Pragma("unroll") for (int k = 0; k < 2; ++k) dst[n][k] = *(const PG8_LAS bf16x8*)(lds + PG8_SB(b, h) + boff + n * 2048 + k * 1024); } while (0)
; #define PG8_SCHED __builtin_amdgcn_sched_barrier(0)
; template <class Epi, class Sched, bool ALIGN_EPI = false, bool SP2 = false>
; __device__ __forceinline__ void gemm_phase(PG8_LAS unsigned char* lds, const Gemm g, const Sched& S, const Epi& E) {
;     ...
;             PG8_LDB(B0, 0, 0); PG8_LDB(B1, 0, 1); PG8_SCHED; PG8_LDA(At, 0, 0); PG8_STAGE(PG8_SA(1, 1), a1 + hstep, voffA);
	s_add_i32 m0, s56, 0xc000
	ds_read_b128 v[176:179], v199
	ds_read_b128 v[180:183], v199 offset:1024
	ds_read_b128 v[184:187], v199 offset:2048
	ds_read_b128 v[188:191], v199 offset:3072
	ds_read_b128 v[202:205], v199 offset:4096
	ds_read_b128 v[206:209], v199 offset:5120
	ds_read_b128 v[210:213], v199 offset:6144
	ds_read_b128 v[214:217], v199 offset:7168
	global_load_lds_dwordx4 v164, s[48:49]

; #define PG8_STAGE(bufoff, gbase, voff) do { _Pragma("unroll") for (int _i = 0; _i < 2; ++_i) \
;         __builtin_amdgcn_global_load_lds((const unsigned*)((const char*)(gbase) + (voff)[_i]), (PG8_LAS unsigned*)(lds + (bufoff) + ldsw + _i * 8192), 16, 0, 0); } while (0)
; #define PG8_LDA(dst, b, h) do { _Pragma("unroll") for (int m = 0; m < 4; ++m) _Pragma("unroll") for (int k = 0; k < 2; ++k) dst[m][k] = *(const PG8_LAS bf16x8*)(lds + PG8_SA(b, h) + aoff + m * 2048 + k * 1024); } while (0)
; #define PG8_LDB(dst, b, h) do { _Pragma("unroll") for (int n = 0; n < 2; ++n) _Pragma("unroll") for (int k = 0; k < 2; ++k) dst[n][k] = *(const PG8_LAS bf16x8*)(lds + PG8_SB(b, h) + boff + n * 2048 + k * 1024); } while (0)
; #define PG8_MMA(ai, bj, At, Bt) do { __builtin_amdgcn_s_setprio(1); _Pragma("unroll") for (int m = 0; m < 4; ++m) _Pragma("unroll") for (int n = 0; n < 2; ++n) _Pragma("unroll") for (int k = 0; k < 2; ++k) \
;         acc[ai][bj][m][n] = __builtin_amdgcn_mfma_f32_16x16x32_bf16(Bt[n][k], At[m][k], acc[ai][bj][m][n], 0, 0, 0); __builtin_amdgcn_s_setprio(0); } while (0)
; #define PG8_WAIT_V(n) asm volatile("s_waitcnt vmcnt(" #n ")" ::: "memory")
; #define PG8_WAIT_L(n) asm volatile("s_waitcnt lgkmcnt(" #n ")" ::: "memory")
; #define PG8_BAR __builtin_amdgcn_s_barrier()
; #define PG8_SCHED __builtin_amdgcn_sched_barrier(0)
; template <class Epi, class Sched, bool ALIGN_EPI = false, bool SP2 = false>
; __device__ __forceinline__ void gemm_phase(PG8_LAS unsigned char* lds, const Gemm g, const Sched& S, const Epi& E) {
;     ...
;             PG8_LDB(B0, 0, 0); PG8_LDB(B1, 0, 1); PG8_SCHED; PG8_LDA(At, 0, 0); PG8_STAGE(PG8_SA(1, 1), a1 + hstep, voffA);
;             PG8_WAIT_V(8); PG8_WAIT_L(0); PG8_BAR; PG8_MMA(0, 0, At, B0); PG8_MMA(0, 1, At, B1); PG8_BAR; PG8_SCHED;
	s_add_i32 m0, s56, 0xe000
	s_nop 0
	global_load_lds_dwordx4 v166, s[48:49]
	s_waitcnt vmcnt(8)
	s_waitcnt lgkmcnt(0)
	s_setprio 1
	s_barrier

; #define PG8_MMA(ai, bj, At, Bt) do { __builtin_amdgcn_s_setprio(1); _Pragma("unroll") for (int m = 0; m < 4; ++m) _Pragma("unroll") for (int n = 0; n < 2; ++n) _Pragma("unroll") for (int k = 0; k < 2; ++k) \
;         acc[ai][bj][m][n] = __builtin_amdgcn_mfma_f32_16x16x32_bf16(Bt[n][k], At[m][k], acc[ai][bj][m][n], 0, 0, 0); __builtin_amdgcn_s_setprio(0); } while (0)
; #define PG8_WAIT_V(n) asm volatile("s_waitcnt vmcnt(" #n ")" ::: "memory")
; #define PG8_WAIT_L(n) asm volatile("s_waitcnt lgkmcnt(" #n ")" ::: "memory")
; #define PG8_BAR __builtin_amdgcn_s_barrier()
; #define PG8_SCHED __builtin_amdgcn_sched_barrier(0)
; template <class Epi, class Sched, bool ALIGN_EPI = false, bool SP2 = false>
; __device__ __forceinline__ void gemm_phase(PG8_LAS unsigned char* lds, const Gemm g, const Sched& S, const Epi& E) {
;     ...
;             PG8_WAIT_V(8); PG8_WAIT_L(0); PG8_BAR; PG8_MMA(0, 0, At, B0); PG8_MMA(0, 1, At, B1); PG8_BAR; PG8_SCHED;
	v_mfma_f32_16x16x32_bf16 v[140:143], v[96:99], v[176:179], v[140:143]
	v_mfma_f32_16x16x32_bf16 v[136:139], v[104:107], v[176:179], v[136:139]
	v_mfma_f32_16x16x32_bf16 v[124:127], v[96:99], v[184:187], v[124:127]
	v_mfma_f32_16x16x32_bf16 v[120:123], v[104:107], v[184:187], v[120:123]
	v_mfma_f32_16x16x32_bf16 v[92:95], v[96:99], v[202:205], v[92:95]
	v_mfma_f32_16x16x32_bf16 v[88:91], v[104:107], v[202:205], v[88:91]
	v_mfma_f32_16x16x32_bf16 v[76:79], v[96:99], v[210:213], v[76:79]
	v_mfma_f32_16x16x32_bf16 v[72:75], v[104:107], v[210:213], v[72:75]
	v_mfma_f32_16x16x32_bf16 v[140:143], v[100:103], v[180:183], v[140:143]
	v_mfma_f32_16x16x32_bf16 v[136:139], v[112:115], v[180:183], v[136:139]
	v_mfma_f32_16x16x32_bf16 v[124:127], v[100:103], v[188:191], v[124:127]
	v_mfma_f32_16x16x32_bf16 v[120:123], v[112:115], v[188:191], v[120:123]
	v_mfma_f32_16x16x32_bf16 v[92:95], v[100:103], v[206:209], v[92:95]
	v_mfma_f32_16x16x32_bf16 v[88:91], v[112:115], v[206:209], v[88:91]
	v_mfma_f32_16x16x32_bf16 v[76:79], v[100:103], v[214:217], v[76:79]
	v_mfma_f32_16x16x32_bf16 v[72:75], v[112:115], v[214:217], v[72:75]


; #define PG8_STAGE(bufoff, gbase, voff) do { _Pragma("unroll") for (int _i = 0; _i < 2; ++_i) \
;         __builtin_amdgcn_global_load_lds((const unsigned*)((const char*)(gbase) + (voff)[_i]), (PG8_LAS unsigned*)(lds + (bufoff) + ldsw + _i * 8192), 16, 0, 0); } while (0)
; #define PG8_LDA(dst, b, h) do { _Pragma("unroll") for (int m = 0; m < 4; ++m) _Pragma("unroll") for (int k = 0; k < 2; ++k) dst[m][k] = *(const PG8_LAS bf16x8*)(lds + PG8_SA(b, h) + aoff + m * 2048 + k * 1024); } while (0)
; #define PG8_MMA(ai, bj, At, Bt) do { __builtin_amdgcn_s_setprio(1); _Pragma("unroll") for (int m = 0; m < 4; ++m) _Pragma("unroll") for (int n = 0; n < 2; ++n) _Pragma("unroll") for (int k = 0; k < 2; ++k) \
;         acc[ai][bj][m][n] = __builtin_amdgcn_mfma_f32_16x16x32_bf16(Bt[n][k], At[m][k], acc[ai][bj][m][n], 0, 0, 0); __builtin_amdgcn_s_setprio(0); } while (0)
; #define PG8_WAIT_V(n) asm volatile("s_waitcnt vmcnt(" #n ")" ::: "memory")
; #define PG8_WAIT_L(n) asm volatile("s_waitcnt lgkmcnt(" #n ")" ::: "memory")
; #define PG8_BAR __builtin_amdgcn_s_barrier()
; #define PG8_SCHED __builtin_amdgcn_sched_barrier(0)
; template <class Epi, class Sched, bool ALIGN_EPI = false, bool SP2 = false>
; __device__ __forceinline__ void gemm_phase(PG8_LAS unsigned char* lds, const Gemm g, const Sched& S, const Epi& E) {
;     ...
;             PG8_WAIT_V(8); PG8_WAIT_L(0); PG8_BAR; PG8_MMA(0, 0, At, B0); PG8_MMA(0, 1, At, B1); PG8_BAR; PG8_SCHED;
;             PG8_LDA(At, 0, 1); PG8_STAGE(PG8_SB(0, 0), b2, voffB); PG8_STAGE(PG8_SB(0, 1), b2 + hstep, voffB); PG8_STAGE(PG8_SA(0, 0), a2, voffA);
	v_mfma_f32_16x16x32_bf16 v[132:135], v[144:147], v[176:179], v[132:135]
	v_mfma_f32_16x16x32_bf16 v[128:131], v[152:155], v[176:179], v[128:131]
	v_mfma_f32_16x16x32_bf16 v[116:119], v[144:147], v[184:187], v[116:119]
	v_mfma_f32_16x16x32_bf16 v[108:111], v[152:155], v[184:187], v[108:111]
	v_mfma_f32_16x16x32_bf16 v[84:87], v[144:147], v[202:205], v[84:87]
	v_mfma_f32_16x16x32_bf16 v[80:83], v[152:155], v[202:205], v[80:83]
	v_mfma_f32_16x16x32_bf16 v[68:71], v[144:147], v[210:213], v[68:71]
	v_mfma_f32_16x16x32_bf16 v[64:67], v[152:155], v[210:213], v[64:67]
	v_mfma_f32_16x16x32_bf16 v[132:135], v[148:151], v[180:183], v[132:135]
	v_mfma_f32_16x16x32_bf16 v[128:131], v[172:175], v[180:183], v[128:131]
	v_mfma_f32_16x16x32_bf16 v[116:119], v[148:151], v[188:191], v[116:119]
	v_mfma_f32_16x16x32_bf16 v[108:111], v[172:175], v[188:191], v[108:111]
	v_mfma_f32_16x16x32_bf16 v[84:87], v[148:151], v[206:209], v[84:87]
	v_mfma_f32_16x16x32_bf16 v[80:83], v[172:175], v[206:209], v[80:83]
	v_mfma_f32_16x16x32_bf16 v[68:71], v[148:151], v[214:217], v[68:71]
	v_mfma_f32_16x16x32_bf16 v[64:67], v[172:175], v[214:217], v[64:67]
	s_setprio 0
	s_barrier
	s_add_i32 s74, s65, s55
	s_mov_b64 s[96:97], s[50:51]

; #define PG8_STAGE(bufoff, gbase, voff) do { _Pragma("unroll") for (int _i = 0; _i < 2; ++_i) \
;         __builtin_amdgcn_global_load_lds((const unsigned*)((const char*)(gbase) + (voff)[_i]), (PG8_LAS unsigned*)(lds + (bufoff) + ldsw + _i * 8192), 16, 0, 0); } while (0)
; #define PG8_LDA(dst, b, h) do { _Pragma("unroll") for (int m = 0; m < 4; ++m) _Pragma("unroll") for (int k = 0; k < 2; ++k) dst[m][k] = *(const PG8_LAS bf16x8*)(lds + PG8_SA(b, h) + aoff + m * 2048 + k * 1024); } while (0)
; template <class Epi, class Sched, bool ALIGN_EPI = false, bool SP2 = false>
; __device__ __forceinline__ void gemm_phase(PG8_LAS unsigned char* lds, const Gemm g, const Sched& S, const Epi& E) {
;     ...
;             PG8_LDA(At, 0, 1); PG8_STAGE(PG8_SB(0, 0), b2, voffB); PG8_STAGE(PG8_SB(0, 1), b2 + hstep, voffB); PG8_STAGE(PG8_SA(0, 0), a2, voffA);
	s_mov_b32 m0, s74
	ds_read_b128 v[176:179], v199 offset:16384
	ds_read_b128 v[180:183], v199 offset:17408
	ds_read_b128 v[184:187], v199 offset:18432
	ds_read_b128 v[188:191], v199 offset:19456
	ds_read_b128 v[202:205], v199 offset:20480
	ds_read_b128 v[206:209], v199 offset:21504
	ds_read_b128 v[210:213], v199 offset:22528
	ds_read_b128 v[214:217], v199 offset:23552
	global_load_lds_dwordx4 v158, s[50:51]
	s_add_i32 m0, s74, 0x2000
	s_add_u32 s74, s50, 0x200000

; #define PG8_STAGE(bufoff, gbase, voff) do { _Pragma("unroll") for (int _i = 0; _i < 2; ++_i) \
;         __builtin_amdgcn_global_load_lds((const unsigned*)((const char*)(gbase) + (voff)[_i]), (PG8_LAS unsigned*)(lds + (bufoff) + ldsw + _i * 8192), 16, 0, 0); } while (0)
; #define PG8_LDA(dst, b, h) do { _Pragma("unroll") for (int m = 0; m < 4; ++m) _Pragma("unroll") for (int k = 0; k < 2; ++k) dst[m][k] = *(const PG8_LAS bf16x8*)(lds + PG8_SA(b, h) + aoff + m * 2048 + k * 1024); } while (0)
; template <class Epi, class Sched, bool ALIGN_EPI = false, bool SP2 = false>
; __device__ __forceinline__ void gemm_phase(PG8_LAS unsigned char* lds, const Gemm g, const Sched& S, const Epi& E) {
;     ...
;             PG8_LDA(At, 0, 1); PG8_STAGE(PG8_SB(0, 0), b2, voffB); PG8_STAGE(PG8_SB(0, 1), b2 + hstep, voffB); PG8_STAGE(PG8_SA(0, 0), a2, voffA);
	s_addc_u32 s75, s51, 0
	s_add_i32 s76, s67, s55
	global_load_lds_dwordx4 v162, s[50:51]

; #define PG8_STAGE(bufoff, gbase, voff) do { _Pragma("unroll") for (int _i = 0; _i < 2; ++_i) \
;         __builtin_amdgcn_global_load_lds((const unsigned*)((const char*)(gbase) + (voff)[_i]), (PG8_LAS unsigned*)(lds + (bufoff) + ldsw + _i * 8192), 16, 0, 0); } while (0)
; #define PG8_LDA(dst, b, h) do { _Pragma("unroll") for (int m = 0; m < 4; ++m) _Pragma("unroll") for (int k = 0; k < 2; ++k) dst[m][k] = *(const PG8_LAS bf16x8*)(lds + PG8_SA(b, h) + aoff + m * 2048 + k * 1024); } while (0)
; template <class Epi, class Sched, bool ALIGN_EPI = false, bool SP2 = false>
; __device__ __forceinline__ void gemm_phase(PG8_LAS unsigned char* lds, const Gemm g, const Sched& S, const Epi& E) {
;     ...
;             PG8_LDA(At, 0, 1); PG8_STAGE(PG8_SB(0, 0), b2, voffB); PG8_STAGE(PG8_SB(0, 1), b2 + hstep, voffB); PG8_STAGE(PG8_SA(0, 0), a2, voffA);
	s_mov_b32 m0, s76
	s_nop 0
	global_load_lds_dwordx4 v158, s[74:75]

; #define PG8_STAGE(bufoff, gbase, voff) do { _Pragma("unroll") for (int _i = 0; _i < 2; ++_i) \
;         __builtin_amdgcn_global_load_lds((const unsigned*)((const char*)(gbase) + (voff)[_i]), (PG8_LAS unsigned*)(lds + (bufoff) + ldsw + _i * 8192), 16, 0, 0); } while (0)
; #define PG8_LDA(dst, b, h) do { _Pragma("unroll") for (int m = 0; m < 4; ++m) _Pragma("unroll") for (int k = 0; k < 2; ++k) dst[m][k] = *(const PG8_LAS bf16x8*)(lds + PG8_SA(b, h) + aoff + m * 2048 + k * 1024); } while (0)
; template <class Epi, class Sched, bool ALIGN_EPI = false, bool SP2 = false>
; __device__ __forceinline__ void gemm_phase(PG8_LAS unsigned char* lds, const Gemm g, const Sched& S, const Epi& E) {
;     ...
;             PG8_LDA(At, 0, 1); PG8_STAGE(PG8_SB(0, 0), b2, voffB); PG8_STAGE(PG8_SB(0, 1), b2 + hstep, voffB); PG8_STAGE(PG8_SA(0, 0), a2, voffA);
	s_add_i32 m0, s76, 0x2000
	s_nop 0
	global_load_lds_dwordx4 v162, s[74:75]
	s_mov_b64 s[98:99], s[52:53]

; #define PG8_STAGE(bufoff, gbase, voff) do { _Pragma("unroll") for (int _i = 0; _i < 2; ++_i) \
;         __builtin_amdgcn_global_load_lds((const unsigned*)((const char*)(gbase) + (voff)[_i]), (PG8_LAS unsigned*)(lds + (bufoff) + ldsw + _i * 8192), 16, 0, 0); } while (0)
; #define PG8_LDA(dst, b, h) do { _Pragma("unroll") for (int m = 0; m < 4; ++m) _Pragma("unroll") for (int k = 0; k < 2; ++k) dst[m][k] = *(const PG8_LAS bf16x8*)(lds + PG8_SA(b, h) + aoff + m * 2048 + k * 1024); } while (0)
; #define PG8_MMA(ai, bj, At, Bt) do { __builtin_amdgcn_s_setprio(1); _Pragma("unroll") for (int m = 0; m < 4; ++m) _Pragma("unroll") for (int n = 0; n < 2; ++n) _Pragma("unroll") for (int k = 0; k < 2; ++k) \
;         acc[ai][bj][m][n] = __builtin_amdgcn_mfma_f32_16x16x32_bf16(Bt[n][k], At[m][k], acc[ai][bj][m][n], 0, 0, 0); __builtin_amdgcn_s_setprio(0); } while (0)
; #define PG8_WAIT_V(n) asm volatile("s_waitcnt vmcnt(" #n ")" ::: "memory")
; #define PG8_WAIT_L(n) asm volatile("s_waitcnt lgkmcnt(" #n ")" ::: "memory")
; #define PG8_BAR __builtin_amdgcn_s_barrier()
; #define PG8_SCHED __builtin_amdgcn_sched_barrier(0)
; template <class Epi, class Sched, bool ALIGN_EPI = false, bool SP2 = false>
; __device__ __forceinline__ void gemm_phase(PG8_LAS unsigned char* lds, const Gemm g, const Sched& S, const Epi& E) {
;     ...
;             PG8_LDA(At, 0, 1); PG8_STAGE(PG8_SB(0, 0), b2, voffB); PG8_STAGE(PG8_SB(0, 1), b2 + hstep, voffB); PG8_STAGE(PG8_SA(0, 0), a2, voffA);
;             PG8_WAIT_V(8); PG8_WAIT_L(0); PG8_BAR; PG8_MMA(1, 0, At, B0); PG8_MMA(1, 1, At, B1); PG8_BAR; PG8_SCHED;
	s_mov_b32 m0, s56
	s_nop 0
	global_load_lds_dwordx4 v156, s[52:53]
	s_mov_b32 m0, s57
	s_nop 0
	global_load_lds_dwordx4 v160, s[52:53]
	s_waitcnt vmcnt(8)
	s_waitcnt lgkmcnt(0)
	s_setprio 1
	s_barrier

; #define PG8_MMA(ai, bj, At, Bt) do { __builtin_amdgcn_s_setprio(1); _Pragma("unroll") for (int m = 0; m < 4; ++m) _Pragma("unroll") for (int n = 0; n < 2; ++n) _Pragma("unroll") for (int k = 0; k < 2; ++k) \
;         acc[ai][bj][m][n] = __builtin_amdgcn_mfma_f32_16x16x32_bf16(Bt[n][k], At[m][k], acc[ai][bj][m][n], 0, 0, 0); __builtin_amdgcn_s_setprio(0); } while (0)
; #define PG8_WAIT_V(n) asm volatile("s_waitcnt vmcnt(" #n ")" ::: "memory")
; #define PG8_WAIT_L(n) asm volatile("s_waitcnt lgkmcnt(" #n ")" ::: "memory")
; #define PG8_BAR __builtin_amdgcn_s_barrier()
; #define PG8_SCHED __builtin_amdgcn_sched_barrier(0)
; template <class Epi, class Sched, bool ALIGN_EPI = false, bool SP2 = false>
; __device__ __forceinline__ void gemm_phase(PG8_LAS unsigned char* lds, const Gemm g, const Sched& S, const Epi& E) {
;     ...
;             PG8_WAIT_V(8); PG8_WAIT_L(0); PG8_BAR; PG8_MMA(1, 0, At, B0); PG8_MMA(1, 1, At, B1); PG8_BAR; PG8_SCHED;
	v_mfma_f32_16x16x32_bf16 v[60:63], v[96:99], v[176:179], v[60:63]
	v_mfma_f32_16x16x32_bf16 v[56:59], v[104:107], v[176:179], v[56:59]
	v_mfma_f32_16x16x32_bf16 v[44:47], v[96:99], v[184:187], v[44:47]
	v_mfma_f32_16x16x32_bf16 v[40:43], v[104:107], v[184:187], v[40:43]
	v_mfma_f32_16x16x32_bf16 v[28:31], v[96:99], v[202:205], v[28:31]
	v_mfma_f32_16x16x32_bf16 v[24:27], v[104:107], v[202:205], v[24:27]
	v_mfma_f32_16x16x32_bf16 v[12:15], v[96:99], v[210:213], v[12:15]
	v_mfma_f32_16x16x32_bf16 v[8:11], v[104:107], v[210:213], v[8:11]
	v_mfma_f32_16x16x32_bf16 v[60:63], v[100:103], v[180:183], v[60:63]
	v_mfma_f32_16x16x32_bf16 v[56:59], v[112:115], v[180:183], v[56:59]
	v_mfma_f32_16x16x32_bf16 v[44:47], v[100:103], v[188:191], v[44:47]
	v_mfma_f32_16x16x32_bf16 v[40:43], v[112:115], v[188:191], v[40:43]
	v_mfma_f32_16x16x32_bf16 v[28:31], v[100:103], v[206:209], v[28:31]
	v_mfma_f32_16x16x32_bf16 v[24:27], v[112:115], v[206:209], v[24:27]
	v_mfma_f32_16x16x32_bf16 v[12:15], v[100:103], v[214:217], v[12:15]
	v_mfma_f32_16x16x32_bf16 v[8:11], v[112:115], v[214:217], v[8:11]


; #define PG8_STAGE(bufoff, gbase, voff) do { _Pragma("unroll") for (int _i = 0; _i < 2; ++_i) \
;         __builtin_amdgcn_global_load_lds((const unsigned*)((const char*)(gbase) + (voff)[_i]), (PG8_LAS unsigned*)(lds + (bufoff) + ldsw + _i * 8192), 16, 0, 0); } while (0)
; #define PG8_LDA(dst, b, h) do { _Pragma("unroll") for (int m = 0; m < 4; ++m) _Pragma("unroll") for (int k = 0; k < 2; ++k) dst[m][k] = *(const PG8_LAS bf16x8*)(lds + PG8_SA(b, h) + aoff + m * 2048 + k * 1024); } while (0)
; #define PG8_MMA(ai, bj, At, Bt) do { __builtin_amdgcn_s_setprio(1); _Pragma("unroll") for (int m = 0; m < 4; ++m) _Pragma("unroll") for (int n = 0; n < 2; ++n) _Pragma("unroll") for (int k = 0; k < 2; ++k) \
;         acc[ai][bj][m][n] = __builtin_amdgcn_mfma_f32_16x16x32_bf16(Bt[n][k], At[m][k], acc[ai][bj][m][n], 0, 0, 0); __builtin_amdgcn_s_setprio(0); } while (0)
; #define PG8_WAIT_V(n) asm volatile("s_waitcnt vmcnt(" #n ")" ::: "memory")
; #define PG8_WAIT_L(n) asm volatile("s_waitcnt lgkmcnt(" #n ")" ::: "memory")
; #define PG8_BAR __builtin_amdgcn_s_barrier()
; #define PG8_SCHED __builtin_amdgcn_sched_barrier(0)
; template <class Epi, class Sched, bool ALIGN_EPI = false, bool SP2 = false>
; __device__ __forceinline__ void gemm_phase(PG8_LAS unsigned char* lds, const Gemm g, const Sched& S, const Epi& E) {
;     ...
;             PG8_WAIT_V(8); PG8_WAIT_L(0); PG8_BAR; PG8_MMA(1, 0, At, B0); PG8_MMA(1, 1, At, B1); PG8_BAR; PG8_SCHED;
;     ...
;             PG8_LDA(At, 1, 1); PG8_STAGE(PG8_SB(1, 0), b3, voffB); PG8_STAGE(PG8_SB(1, 1), b3 + hstep, voffB); PG8_STAGE(PG8_SA(1, 0), a3, voffA);
	v_mfma_f32_16x16x32_bf16 v[52:55], v[144:147], v[176:179], v[52:55]
	v_mfma_f32_16x16x32_bf16 v[48:51], v[152:155], v[176:179], v[48:51]
	v_mfma_f32_16x16x32_bf16 v[36:39], v[144:147], v[184:187], v[36:39]
	v_mfma_f32_16x16x32_bf16 v[32:35], v[152:155], v[184:187], v[32:35]
	v_mfma_f32_16x16x32_bf16 v[20:23], v[144:147], v[202:205], v[20:23]
	v_mfma_f32_16x16x32_bf16 v[16:19], v[152:155], v[202:205], v[16:19]
	v_mfma_f32_16x16x32_bf16 v[4:7], v[144:147], v[210:213], v[4:7]
	v_mfma_f32_16x16x32_bf16 v[0:3], v[152:155], v[210:213], v[0:3]
	v_mfma_f32_16x16x32_bf16 v[52:55], v[148:151], v[180:183], v[52:55]
	v_mfma_f32_16x16x32_bf16 v[48:51], v[172:175], v[180:183], v[48:51]
	v_mfma_f32_16x16x32_bf16 v[36:39], v[148:151], v[188:191], v[36:39]
	v_mfma_f32_16x16x32_bf16 v[32:35], v[172:175], v[188:191], v[32:35]
	v_mfma_f32_16x16x32_bf16 v[20:23], v[148:151], v[206:209], v[20:23]
	v_mfma_f32_16x16x32_bf16 v[16:19], v[172:175], v[206:209], v[16:19]
	v_mfma_f32_16x16x32_bf16 v[4:7], v[148:151], v[214:217], v[4:7]
	v_mfma_f32_16x16x32_bf16 v[0:3], v[172:175], v[214:217], v[0:3]
	s_setprio 0
	s_barrier
	s_add_i32 s74, 0, 0x18000
	s_add_i32 s75, 0, 0x1c000


; #define PG8_STAGE(bufoff, gbase, voff) do { _Pragma("unroll") for (int _i = 0; _i < 2; ++_i) \
;         __builtin_amdgcn_global_load_lds((const unsigned*)((const char*)(gbase) + (voff)[_i]), (PG8_LAS unsigned*)(lds + (bufoff) + ldsw + _i * 8192), 16, 0, 0); } while (0)
; #define PG8_LDA(dst, b, h) do { _Pragma("unroll") for (int m = 0; m < 4; ++m) _Pragma("unroll") for (int k = 0; k < 2; ++k) dst[m][k] = *(const PG8_LAS bf16x8*)(lds + PG8_SA(b, h) + aoff + m * 2048 + k * 1024); } while (0)
; #define PG8_LDB(dst, b, h) do { _Pragma("unroll") for (int n = 0; n < 2; ++n) _Pragma("unroll") for (int k = 0; k < 2; ++k) dst[n][k] = *(const PG8_LAS bf16x8*)(lds + PG8_SB(b, h) + boff + n * 2048 + k * 1024); } while (0)
; #define PG8_SCHED __builtin_amdgcn_sched_barrier(0)
; template <class Epi, class Sched, bool ALIGN_EPI = false, bool SP2 = false>
; __device__ __forceinline__ void gemm_phase(PG8_LAS unsigned char* lds, const Gemm g, const Sched& S, const Epi& E) {
;     ...
;             PG8_LDB(B0, 1, 0); PG8_LDB(B1, 1, 1); PG8_SCHED; PG8_LDA(At, 1, 0); PG8_STAGE(PG8_SA(0, 1), a2 + hstep, voffA);
	ds_read_b128 v[96:99], v254
	ds_read_b128 v[100:103], v254 offset:1024
	ds_read_b128 v[104:107], v254 offset:2048
	ds_read_b128 v[112:115], v254 offset:3072
	ds_read_b128 v[144:147], v255
	ds_read_b128 v[148:151], v255 offset:1024
	ds_read_b128 v[152:155], v255 offset:2048
	ds_read_b128 v[172:175], v255 offset:3072
	s_add_u32 s52, s52, 0x200000
	s_addc_u32 s53, s53, 0
	s_mov_b32 m0, s58

; #define PG8_STAGE(bufoff, gbase, voff) do { _Pragma("unroll") for (int _i = 0; _i < 2; ++_i) \
;         __builtin_amdgcn_global_load_lds((const unsigned*)((const char*)(gbase) + (voff)[_i]), (PG8_LAS unsigned*)(lds + (bufoff) + ldsw + _i * 8192), 16, 0, 0); } while (0)
; #define PG8_LDA(dst, b, h) do { _Pragma("unroll") for (int m = 0; m < 4; ++m) _Pragma("unroll") for (int k = 0; k < 2; ++k) dst[m][k] = *(const PG8_LAS bf16x8*)(lds + PG8_SA(b, h) + aoff + m * 2048 + k * 1024); } while (0)
; #define PG8_LDB(dst, b, h) do { _Pragma("unroll") for (int n = 0; n < 2; ++n) _Pragma("unroll") for (int k = 0; k < 2; ++k) dst[n][k] = *(const PG8_LAS bf16x8*)(lds + PG8_SB(b, h) + boff + n * 2048 + k * 1024); } while (0)
; #define PG8_SCHED __builtin_amdgcn_sched_barrier(0)
; template <class Epi, class Sched, bool ALIGN_EPI = false, bool SP2 = false>
; __device__ __forceinline__ void gemm_phase(PG8_LAS unsigned char* lds, const Gemm g, const Sched& S, const Epi& E) {
;     ...
;             PG8_LDB(B0, 1, 0); PG8_LDB(B1, 1, 1); PG8_SCHED; PG8_LDA(At, 1, 0); PG8_STAGE(PG8_SA(0, 1), a2 + hstep, voffA);
	ds_read_b128 v[176:179], v199 offset:32768
	ds_read_b128 v[180:183], v199 offset:33792
	ds_read_b128 v[184:187], v199 offset:34816
	ds_read_b128 v[188:191], v199 offset:35840
	ds_read_b128 v[202:205], v199 offset:36864
	ds_read_b128 v[206:209], v199 offset:37888
	ds_read_b128 v[210:213], v199 offset:38912
	ds_read_b128 v[214:217], v199 offset:39936
	global_load_lds_dwordx4 v156, s[52:53]

; #define PG8_STAGE(bufoff, gbase, voff) do { _Pragma("unroll") for (int _i = 0; _i < 2; ++_i) \
;         __builtin_amdgcn_global_load_lds((const unsigned*)((const char*)(gbase) + (voff)[_i]), (PG8_LAS unsigned*)(lds + (bufoff) + ldsw + _i * 8192), 16, 0, 0); } while (0)
; #define PG8_LDA(dst, b, h) do { _Pragma("unroll") for (int m = 0; m < 4; ++m) _Pragma("unroll") for (int k = 0; k < 2; ++k) dst[m][k] = *(const PG8_LAS bf16x8*)(lds + PG8_SA(b, h) + aoff + m * 2048 + k * 1024); } while (0)
; #define PG8_LDB(dst, b, h) do { _Pragma("unroll") for (int n = 0; n < 2; ++n) _Pragma("unroll") for (int k = 0; k < 2; ++k) dst[n][k] = *(const PG8_LAS bf16x8*)(lds + PG8_SB(b, h) + boff + n * 2048 + k * 1024); } while (0)
; #define PG8_MMA(ai, bj, At, Bt) do { __builtin_amdgcn_s_setprio(1); _Pragma("unroll") for (int m = 0; m < 4; ++m) _Pragma("unroll") for (int n = 0; n < 2; ++n) _Pragma("unroll") for (int k = 0; k < 2; ++k) \
;         acc[ai][bj][m][n] = __builtin_amdgcn_mfma_f32_16x16x32_bf16(Bt[n][k], At[m][k], acc[ai][bj][m][n], 0, 0, 0); __builtin_amdgcn_s_setprio(0); } while (0)
; #define PG8_WAIT_V(n) asm volatile("s_waitcnt vmcnt(" #n ")" ::: "memory")
; #define PG8_WAIT_L(n) asm volatile("s_waitcnt lgkmcnt(" #n ")" ::: "memory")
; #define PG8_BAR __builtin_amdgcn_s_barrier()
; #define PG8_SCHED __builtin_amdgcn_sched_barrier(0)
; template <class Epi, class Sched, bool ALIGN_EPI = false, bool SP2 = false>
; __device__ __forceinline__ void gemm_phase(PG8_LAS unsigned char* lds, const Gemm g, const Sched& S, const Epi& E) {
;     ...
;             PG8_LDB(B0, 1, 0); PG8_LDB(B1, 1, 1); PG8_SCHED; PG8_LDA(At, 1, 0); PG8_STAGE(PG8_SA(0, 1), a2 + hstep, voffA);
;             PG8_WAIT_V(8); PG8_WAIT_L(0); PG8_BAR; PG8_MMA(0, 0, At, B0); PG8_MMA(0, 1, At, B1); PG8_BAR; PG8_SCHED;
	s_mov_b32 m0, s59
	s_nop 0
	global_load_lds_dwordx4 v160, s[52:53]
	s_waitcnt vmcnt(8)
	s_waitcnt lgkmcnt(0)
	s_setprio 1
	s_barrier

; #define PG8_MMA(ai, bj, At, Bt) do { __builtin_amdgcn_s_setprio(1); _Pragma("unroll") for (int m = 0; m < 4; ++m) _Pragma("unroll") for (int n = 0; n < 2; ++n) _Pragma("unroll") for (int k = 0; k < 2; ++k) \
;         acc[ai][bj][m][n] = __builtin_amdgcn_mfma_f32_16x16x32_bf16(Bt[n][k], At[m][k], acc[ai][bj][m][n], 0, 0, 0); __builtin_amdgcn_s_setprio(0); } while (0)
; #define PG8_WAIT_V(n) asm volatile("s_waitcnt vmcnt(" #n ")" ::: "memory")
; #define PG8_WAIT_L(n) asm volatile("s_waitcnt lgkmcnt(" #n ")" ::: "memory")
; #define PG8_BAR __builtin_amdgcn_s_barrier()
; #define PG8_SCHED __builtin_amdgcn_sched_barrier(0)
; template <class Epi, class Sched, bool ALIGN_EPI = false, bool SP2 = false>
; __device__ __forceinline__ void gemm_phase(PG8_LAS unsigned char* lds, const Gemm g, const Sched& S, const Epi& E) {
;     ...
;             PG8_WAIT_V(8); PG8_WAIT_L(0); PG8_BAR; PG8_MMA(0, 0, At, B0); PG8_MMA(0, 1, At, B1); PG8_BAR; PG8_SCHED;
	v_mfma_f32_16x16x32_bf16 v[140:143], v[96:99], v[176:179], v[140:143]
	v_mfma_f32_16x16x32_bf16 v[136:139], v[104:107], v[176:179], v[136:139]
	v_mfma_f32_16x16x32_bf16 v[124:127], v[96:99], v[184:187], v[124:127]
	v_mfma_f32_16x16x32_bf16 v[120:123], v[104:107], v[184:187], v[120:123]
	v_mfma_f32_16x16x32_bf16 v[92:95], v[96:99], v[202:205], v[92:95]
	v_mfma_f32_16x16x32_bf16 v[88:91], v[104:107], v[202:205], v[88:91]
	v_mfma_f32_16x16x32_bf16 v[76:79], v[96:99], v[210:213], v[76:79]
	v_mfma_f32_16x16x32_bf16 v[72:75], v[104:107], v[210:213], v[72:75]
	v_mfma_f32_16x16x32_bf16 v[140:143], v[100:103], v[180:183], v[140:143]
	v_mfma_f32_16x16x32_bf16 v[136:139], v[112:115], v[180:183], v[136:139]
	v_mfma_f32_16x16x32_bf16 v[124:127], v[100:103], v[188:191], v[124:127]
	v_mfma_f32_16x16x32_bf16 v[120:123], v[112:115], v[188:191], v[120:123]
	v_mfma_f32_16x16x32_bf16 v[92:95], v[100:103], v[206:209], v[92:95]
	v_mfma_f32_16x16x32_bf16 v[88:91], v[112:115], v[206:209], v[88:91]
	v_mfma_f32_16x16x32_bf16 v[76:79], v[100:103], v[214:217], v[76:79]
	v_mfma_f32_16x16x32_bf16 v[72:75], v[112:115], v[214:217], v[72:75]


; #define PG8_STAGE(bufoff, gbase, voff) do { _Pragma("unroll") for (int _i = 0; _i < 2; ++_i) \
;         __builtin_amdgcn_global_load_lds((const unsigned*)((const char*)(gbase) + (voff)[_i]), (PG8_LAS unsigned*)(lds + (bufoff) + ldsw + _i * 8192), 16, 0, 0); } while (0)
; #define PG8_LDA(dst, b, h) do { _Pragma("unroll") for (int m = 0; m < 4; ++m) _Pragma("unroll") for (int k = 0; k < 2; ++k) dst[m][k] = *(const PG8_LAS bf16x8*)(lds + PG8_SA(b, h) + aoff + m * 2048 + k * 1024); } while (0)
; #define PG8_MMA(ai, bj, At, Bt) do { __builtin_amdgcn_s_setprio(1); _Pragma("unroll") for (int m = 0; m < 4; ++m) _Pragma("unroll") for (int n = 0; n < 2; ++n) _Pragma("unroll") for (int k = 0; k < 2; ++k) \
;         acc[ai][bj][m][n] = __builtin_amdgcn_mfma_f32_16x16x32_bf16(Bt[n][k], At[m][k], acc[ai][bj][m][n], 0, 0, 0); __builtin_amdgcn_s_setprio(0); } while (0)
; #define PG8_WAIT_V(n) asm volatile("s_waitcnt vmcnt(" #n ")" ::: "memory")
; #define PG8_WAIT_L(n) asm volatile("s_waitcnt lgkmcnt(" #n ")" ::: "memory")
; #define PG8_BAR __builtin_amdgcn_s_barrier()
; #define PG8_SCHED __builtin_amdgcn_sched_barrier(0)
; template <class Epi, class Sched, bool ALIGN_EPI = false, bool SP2 = false>
; __device__ __forceinline__ void gemm_phase(PG8_LAS unsigned char* lds, const Gemm g, const Sched& S, const Epi& E) {
;     ...
;             PG8_WAIT_V(8); PG8_WAIT_L(0); PG8_BAR; PG8_MMA(0, 0, At, B0); PG8_MMA(0, 1, At, B1); PG8_BAR; PG8_SCHED;
;             PG8_LDA(At, 1, 1); PG8_STAGE(PG8_SB(1, 0), b3, voffB); PG8_STAGE(PG8_SB(1, 1), b3 + hstep, voffB); PG8_STAGE(PG8_SA(1, 0), a3, voffA);
	v_mfma_f32_16x16x32_bf16 v[132:135], v[144:147], v[176:179], v[132:135]
	v_mfma_f32_16x16x32_bf16 v[128:131], v[152:155], v[176:179], v[128:131]
	v_mfma_f32_16x16x32_bf16 v[116:119], v[144:147], v[184:187], v[116:119]
	v_mfma_f32_16x16x32_bf16 v[108:111], v[152:155], v[184:187], v[108:111]
	v_mfma_f32_16x16x32_bf16 v[84:87], v[144:147], v[202:205], v[84:87]
	v_mfma_f32_16x16x32_bf16 v[80:83], v[152:155], v[202:205], v[80:83]
	v_mfma_f32_16x16x32_bf16 v[68:71], v[144:147], v[210:213], v[68:71]
	v_mfma_f32_16x16x32_bf16 v[64:67], v[152:155], v[210:213], v[64:67]
	v_mfma_f32_16x16x32_bf16 v[132:135], v[148:151], v[180:183], v[132:135]
	v_mfma_f32_16x16x32_bf16 v[128:131], v[172:175], v[180:183], v[128:131]
	v_mfma_f32_16x16x32_bf16 v[116:119], v[148:151], v[188:191], v[116:119]
	v_mfma_f32_16x16x32_bf16 v[108:111], v[172:175], v[188:191], v[108:111]
	v_mfma_f32_16x16x32_bf16 v[84:87], v[148:151], v[206:209], v[84:87]
	v_mfma_f32_16x16x32_bf16 v[80:83], v[172:175], v[206:209], v[80:83]
	v_mfma_f32_16x16x32_bf16 v[68:71], v[148:151], v[214:217], v[68:71]
	v_mfma_f32_16x16x32_bf16 v[64:67], v[172:175], v[214:217], v[64:67]
	s_setprio 0
	s_barrier
	s_add_i32 s52, s74, s55

; #define PG8_STAGE(bufoff, gbase, voff) do { _Pragma("unroll") for (int _i = 0; _i < 2; ++_i) \
;         __builtin_amdgcn_global_load_lds((const unsigned*)((const char*)(gbase) + (voff)[_i]), (PG8_LAS unsigned*)(lds + (bufoff) + ldsw + _i * 8192), 16, 0, 0); } while (0)
; #define PG8_LDA(dst, b, h) do { _Pragma("unroll") for (int m = 0; m < 4; ++m) _Pragma("unroll") for (int k = 0; k < 2; ++k) dst[m][k] = *(const PG8_LAS bf16x8*)(lds + PG8_SA(b, h) + aoff + m * 2048 + k * 1024); } while (0)
; template <class Epi, class Sched, bool ALIGN_EPI = false, bool SP2 = false>
; __device__ __forceinline__ void gemm_phase(PG8_LAS unsigned char* lds, const Gemm g, const Sched& S, const Epi& E) {
;     ...
;             PG8_LDA(At, 1, 1); PG8_STAGE(PG8_SB(1, 0), b3, voffB); PG8_STAGE(PG8_SB(1, 1), b3 + hstep, voffB); PG8_STAGE(PG8_SA(1, 0), a3, voffA);
	s_mov_b32 m0, s52
	ds_read_b128 v[176:179], v199 offset:49152
	ds_read_b128 v[180:183], v199 offset:50176
	ds_read_b128 v[184:187], v199 offset:51200
	ds_read_b128 v[188:191], v199 offset:52224
	ds_read_b128 v[202:205], v199 offset:53248
	ds_read_b128 v[206:209], v199 offset:54272
	ds_read_b128 v[210:213], v199 offset:55296
	ds_read_b128 v[214:217], v199 offset:56320
	global_load_lds_dwordx4 v250, s[96:97]
	s_add_i32 m0, s52, 0x2000
	s_add_u32 s50, s50, 0x200080

; #define PG8_STAGE(bufoff, gbase, voff) do { _Pragma("unroll") for (int _i = 0; _i < 2; ++_i) \
;         __builtin_amdgcn_global_load_lds((const unsigned*)((const char*)(gbase) + (voff)[_i]), (PG8_LAS unsigned*)(lds + (bufoff) + ldsw + _i * 8192), 16, 0, 0); } while (0)
; #define PG8_LDA(dst, b, h) do { _Pragma("unroll") for (int m = 0; m < 4; ++m) _Pragma("unroll") for (int k = 0; k < 2; ++k) dst[m][k] = *(const PG8_LAS bf16x8*)(lds + PG8_SA(b, h) + aoff + m * 2048 + k * 1024); } while (0)
; template <class Epi, class Sched, bool ALIGN_EPI = false, bool SP2 = false>
; __device__ __forceinline__ void gemm_phase(PG8_LAS unsigned char* lds, const Gemm g, const Sched& S, const Epi& E) {
;     ...
;             PG8_LDA(At, 1, 1); PG8_STAGE(PG8_SB(1, 0), b3, voffB); PG8_STAGE(PG8_SB(1, 1), b3 + hstep, voffB); PG8_STAGE(PG8_SA(1, 0), a3, voffA);
	s_addc_u32 s51, s51, 0
	s_add_i32 s52, s75, s55
	global_load_lds_dwordx4 v251, s[96:97]

; #define PG8_STAGE(bufoff, gbase, voff) do { _Pragma("unroll") for (int _i = 0; _i < 2; ++_i) \
;         __builtin_amdgcn_global_load_lds((const unsigned*)((const char*)(gbase) + (voff)[_i]), (PG8_LAS unsigned*)(lds + (bufoff) + ldsw + _i * 8192), 16, 0, 0); } while (0)
; #define PG8_LDA(dst, b, h) do { _Pragma("unroll") for (int m = 0; m < 4; ++m) _Pragma("unroll") for (int k = 0; k < 2; ++k) dst[m][k] = *(const PG8_LAS bf16x8*)(lds + PG8_SA(b, h) + aoff + m * 2048 + k * 1024); } while (0)
; template <class Epi, class Sched, bool ALIGN_EPI = false, bool SP2 = false>
; __device__ __forceinline__ void gemm_phase(PG8_LAS unsigned char* lds, const Gemm g, const Sched& S, const Epi& E) {
;     ...
;             PG8_LDA(At, 1, 1); PG8_STAGE(PG8_SB(1, 0), b3, voffB); PG8_STAGE(PG8_SB(1, 1), b3 + hstep, voffB); PG8_STAGE(PG8_SA(1, 0), a3, voffA);
	s_mov_b32 m0, s52
	s_nop 0
	global_load_lds_dwordx4 v158, s[50:51]

; #define PG8_STAGE(bufoff, gbase, voff) do { _Pragma("unroll") for (int _i = 0; _i < 2; ++_i) \
;         __builtin_amdgcn_global_load_lds((const unsigned*)((const char*)(gbase) + (voff)[_i]), (PG8_LAS unsigned*)(lds + (bufoff) + ldsw + _i * 8192), 16, 0, 0); } while (0)
; #define PG8_LDA(dst, b, h) do { _Pragma("unroll") for (int m = 0; m < 4; ++m) _Pragma("unroll") for (int k = 0; k < 2; ++k) dst[m][k] = *(const PG8_LAS bf16x8*)(lds + PG8_SA(b, h) + aoff + m * 2048 + k * 1024); } while (0)
; template <class Epi, class Sched, bool ALIGN_EPI = false, bool SP2 = false>
; __device__ __forceinline__ void gemm_phase(PG8_LAS unsigned char* lds, const Gemm g, const Sched& S, const Epi& E) {
;     ...
;             PG8_LDA(At, 1, 1); PG8_STAGE(PG8_SB(1, 0), b3, voffB); PG8_STAGE(PG8_SB(1, 1), b3 + hstep, voffB); PG8_STAGE(PG8_SA(1, 0), a3, voffA);
	s_add_i32 m0, s52, 0x2000
	s_nop 0
	global_load_lds_dwordx4 v162, s[50:51]

; #define PG8_STAGE(bufoff, gbase, voff) do { _Pragma("unroll") for (int _i = 0; _i < 2; ++_i) \
;         __builtin_amdgcn_global_load_lds((const unsigned*)((const char*)(gbase) + (voff)[_i]), (PG8_LAS unsigned*)(lds + (bufoff) + ldsw + _i * 8192), 16, 0, 0); } while (0)
; #define PG8_LDA(dst, b, h) do { _Pragma("unroll") for (int m = 0; m < 4; ++m) _Pragma("unroll") for (int k = 0; k < 2; ++k) dst[m][k] = *(const PG8_LAS bf16x8*)(lds + PG8_SA(b, h) + aoff + m * 2048 + k * 1024); } while (0)
; template <class Epi, class Sched, bool ALIGN_EPI = false, bool SP2 = false>
; __device__ __forceinline__ void gemm_phase(PG8_LAS unsigned char* lds, const Gemm g, const Sched& S, const Epi& E) {
;     ...
;             PG8_LDA(At, 1, 1); PG8_STAGE(PG8_SB(1, 0), b3, voffB); PG8_STAGE(PG8_SB(1, 1), b3 + hstep, voffB); PG8_STAGE(PG8_SA(1, 0), a3, voffA);
	s_mov_b32 m0, s61
	s_nop 0
	global_load_lds_dwordx4 v252, s[98:99]

; #define PG8_STAGE(bufoff, gbase, voff) do { _Pragma("unroll") for (int _i = 0; _i < 2; ++_i) \
;         __builtin_amdgcn_global_load_lds((const unsigned*)((const char*)(gbase) + (voff)[_i]), (PG8_LAS unsigned*)(lds + (bufoff) + ldsw + _i * 8192), 16, 0, 0); } while (0)
; #define PG8_LDA(dst, b, h) do { _Pragma("unroll") for (int m = 0; m < 4; ++m) _Pragma("unroll") for (int k = 0; k < 2; ++k) dst[m][k] = *(const PG8_LAS bf16x8*)(lds + PG8_SA(b, h) + aoff + m * 2048 + k * 1024); } while (0)
; #define PG8_MMA(ai, bj, At, Bt) do { __builtin_amdgcn_s_setprio(1); _Pragma("unroll") for (int m = 0; m < 4; ++m) _Pragma("unroll") for (int n = 0; n < 2; ++n) _Pragma("unroll") for (int k = 0; k < 2; ++k) \
;         acc[ai][bj][m][n] = __builtin_amdgcn_mfma_f32_16x16x32_bf16(Bt[n][k], At[m][k], acc[ai][bj][m][n], 0, 0, 0); __builtin_amdgcn_s_setprio(0); } while (0)
; #define PG8_WAIT_V(n) asm volatile("s_waitcnt vmcnt(" #n ")" ::: "memory")
; #define PG8_WAIT_L(n) asm volatile("s_waitcnt lgkmcnt(" #n ")" ::: "memory")
; #define PG8_BAR __builtin_amdgcn_s_barrier()
; #define PG8_SCHED __builtin_amdgcn_sched_barrier(0)
; template <class Epi, class Sched, bool ALIGN_EPI = false, bool SP2 = false>
; __device__ __forceinline__ void gemm_phase(PG8_LAS unsigned char* lds, const Gemm g, const Sched& S, const Epi& E) {
;     ...
;             PG8_LDA(At, 1, 1); PG8_STAGE(PG8_SB(1, 0), b3, voffB); PG8_STAGE(PG8_SB(1, 1), b3 + hstep, voffB); PG8_STAGE(PG8_SA(1, 0), a3, voffA);
;             PG8_WAIT_V(8); PG8_WAIT_L(0); PG8_BAR; PG8_MMA(1, 0, At, B0); PG8_MMA(1, 1, At, B1); PG8_BAR; PG8_SCHED;
	s_mov_b32 m0, s62
	s_nop 0
	global_load_lds_dwordx4 v253, s[98:99]
	s_waitcnt vmcnt(8)
	s_waitcnt lgkmcnt(0)
	s_setprio 1
	s_barrier

; #define PG8_MMA(ai, bj, At, Bt) do { __builtin_amdgcn_s_setprio(1); _Pragma("unroll") for (int m = 0; m < 4; ++m) _Pragma("unroll") for (int n = 0; n < 2; ++n) _Pragma("unroll") for (int k = 0; k < 2; ++k) \
;         acc[ai][bj][m][n] = __builtin_amdgcn_mfma_f32_16x16x32_bf16(Bt[n][k], At[m][k], acc[ai][bj][m][n], 0, 0, 0); __builtin_amdgcn_s_setprio(0); } while (0)
; #define PG8_WAIT_V(n) asm volatile("s_waitcnt vmcnt(" #n ")" ::: "memory")
; #define PG8_WAIT_L(n) asm volatile("s_waitcnt lgkmcnt(" #n ")" ::: "memory")
; #define PG8_BAR __builtin_amdgcn_s_barrier()
; #define PG8_SCHED __builtin_amdgcn_sched_barrier(0)
; template <class Epi, class Sched, bool ALIGN_EPI = false, bool SP2 = false>
; __device__ __forceinline__ void gemm_phase(PG8_LAS unsigned char* lds, const Gemm g, const Sched& S, const Epi& E) {
;     ...
;             PG8_WAIT_V(8); PG8_WAIT_L(0); PG8_BAR; PG8_MMA(1, 0, At, B0); PG8_MMA(1, 1, At, B1); PG8_BAR; PG8_SCHED;
	v_mfma_f32_16x16x32_bf16 v[60:63], v[96:99], v[176:179], v[60:63]
	v_mfma_f32_16x16x32_bf16 v[56:59], v[104:107], v[176:179], v[56:59]
	v_mfma_f32_16x16x32_bf16 v[44:47], v[96:99], v[184:187], v[44:47]
	v_mfma_f32_16x16x32_bf16 v[40:43], v[104:107], v[184:187], v[40:43]
	v_mfma_f32_16x16x32_bf16 v[28:31], v[96:99], v[202:205], v[28:31]
	v_mfma_f32_16x16x32_bf16 v[24:27], v[104:107], v[202:205], v[24:27]
	v_mfma_f32_16x16x32_bf16 v[12:15], v[96:99], v[210:213], v[12:15]
	v_mfma_f32_16x16x32_bf16 v[8:11], v[104:107], v[210:213], v[8:11]
	v_mfma_f32_16x16x32_bf16 v[60:63], v[100:103], v[180:183], v[60:63]
	v_mfma_f32_16x16x32_bf16 v[56:59], v[112:115], v[180:183], v[56:59]
	v_mfma_f32_16x16x32_bf16 v[44:47], v[100:103], v[188:191], v[44:47]
	v_mfma_f32_16x16x32_bf16 v[40:43], v[112:115], v[188:191], v[40:43]
	v_mfma_f32_16x16x32_bf16 v[28:31], v[100:103], v[206:209], v[28:31]
	v_mfma_f32_16x16x32_bf16 v[24:27], v[112:115], v[206:209], v[24:27]
	v_mfma_f32_16x16x32_bf16 v[12:15], v[100:103], v[214:217], v[12:15]
	v_mfma_f32_16x16x32_bf16 v[8:11], v[112:115], v[214:217], v[8:11]


; #define PG8_MMA(ai, bj, At, Bt) do { __builtin_amdgcn_s_setprio(1); _Pragma("unroll") for (int m = 0; m < 4; ++m) _Pragma("unroll") for (int n = 0; n < 2; ++n) _Pragma("unroll") for (int k = 0; k < 2; ++k) \
;         acc[ai][bj][m][n] = __builtin_amdgcn_mfma_f32_16x16x32_bf16(Bt[n][k], At[m][k], acc[ai][bj][m][n], 0, 0, 0); __builtin_amdgcn_s_setprio(0); } while (0)
; #define PG8_WAIT_V(n) asm volatile("s_waitcnt vmcnt(" #n ")" ::: "memory")
; #define PG8_WAIT_L(n) asm volatile("s_waitcnt lgkmcnt(" #n ")" ::: "memory")
; #define PG8_BAR __builtin_amdgcn_s_barrier()
; #define PG8_SCHED __builtin_amdgcn_sched_barrier(0)
; template <class Epi, class Sched, bool ALIGN_EPI = false, bool SP2 = false>
; __device__ __forceinline__ void gemm_phase(PG8_LAS unsigned char* lds, const Gemm g, const Sched& S, const Epi& E) {
;     ...
;         for (int t = 0; t < nt; t += 2) {
;     ...
;             PG8_WAIT_V(8); PG8_WAIT_L(0); PG8_BAR; PG8_MMA(1, 0, At, B0); PG8_MMA(1, 1, At, B1); PG8_BAR; PG8_SCHED;
	v_mfma_f32_16x16x32_bf16 v[52:55], v[144:147], v[176:179], v[52:55]
	v_mfma_f32_16x16x32_bf16 v[48:51], v[152:155], v[176:179], v[48:51]
	v_mfma_f32_16x16x32_bf16 v[36:39], v[144:147], v[184:187], v[36:39]
	v_mfma_f32_16x16x32_bf16 v[32:35], v[152:155], v[184:187], v[32:35]
	v_mfma_f32_16x16x32_bf16 v[20:23], v[144:147], v[202:205], v[20:23]
	v_mfma_f32_16x16x32_bf16 v[16:19], v[152:155], v[202:205], v[16:19]
	v_mfma_f32_16x16x32_bf16 v[4:7], v[144:147], v[210:213], v[4:7]
	v_mfma_f32_16x16x32_bf16 v[0:3], v[152:155], v[210:213], v[0:3]
	v_mfma_f32_16x16x32_bf16 v[52:55], v[148:151], v[180:183], v[52:55]
	v_mfma_f32_16x16x32_bf16 v[48:51], v[172:175], v[180:183], v[48:51]
	v_mfma_f32_16x16x32_bf16 v[36:39], v[148:151], v[188:191], v[36:39]
	v_mfma_f32_16x16x32_bf16 v[32:35], v[172:175], v[188:191], v[32:35]
	v_mfma_f32_16x16x32_bf16 v[20:23], v[148:151], v[206:209], v[20:23]
	v_mfma_f32_16x16x32_bf16 v[16:19], v[172:175], v[206:209], v[16:19]
	v_mfma_f32_16x16x32_bf16 v[4:7], v[148:151], v[214:217], v[4:7]
	v_mfma_f32_16x16x32_bf16 v[0:3], v[172:175], v[214:217], v[0:3]
	s_setprio 0
	s_add_i32 s73, s73, 2
	s_add_u32 s48, s48, 0x100
	s_addc_u32 s49, s49, 0
	s_add_u32 s71, s71, 0x100
	s_addc_u32 s72, s72, 0
	s_cmpk_gt_u32 s73, 0x7d
	s_barrier


; #define PG8_BAR __builtin_amdgcn_s_barrier()
; template <class Epi, class Sched, bool ALIGN_EPI = false, bool SP2 = false>
; __device__ __forceinline__ void gemm_phase(PG8_LAS unsigned char* lds, const Gemm g, const Sched& S, const Epi& E) {
;     ...
;         for (int t = 0; t < nt; t += 2) {
;     ...
;         if constexpr (ALIGN_EPI) { if (wr == 0) PG8_BAR; }
	s_cbranch_scc0 .LBB0_1114
	s_and_b64 vcc, exec, s[34:35]
	s_cbranch_vccz .LBB0_1117
	s_barrier
